# hand-written pipelined GEMM tile bodies (reg-double-buffered LDS prefetch, 3-stage DMA) + row-pair-interleaved bf16 layout for xb/hb/w_in/w_gate_up so each LDS-DMA touches 8 full lines
# speedup vs baseline: 1.0845x; 1.0845x over previous
; DEVI unsigned pack2(float a, float b) { return __builtin_bit_cast(unsigned, __builtin_convertvector((f32x2_t){a, b}, bf16x2_t)); }
; DEVI void stnt4(float* p_, f32x4 v) { __builtin_nontemporal_store(v, (f32x4*)p_); }
;     ...
;     float s = 0.f, q = 0.f;
; #pragma unroll
;     for (int i = 0; i < 4; i++) {
;       s += v[i].x + v[i].y + v[i].z + v[i].w;
;       q += v[i].x * v[i].x + v[i].y * v[i].y + v[i].z * v[i].z + v[i].w * v[i].w;
;     }
; #pragma unroll
;     for (int o = 32; o > 0; o >>= 1) { const float s2 = __shfl_xor(s, o), q2 = __shfl_xor(q, o); s += s2; q += q2; }
;     const float mu = s * (1.f / 1024.f);
;     const float var = fmaxf(q * (1.f / 1024.f) - mu * mu, 0.f);
;     const float rs = rsqrtf(var + 1e-5f);
; #pragma unroll
;     for (int i = 0; i < 4; i++) {
;       float4 o;
;       o.x = (v[i].x - mu) * rs * gg[i].x + bb[i].x; o.y = (v[i].y - mu) * rs * gg[i].y + bb[i].y;
;       o.z = (v[i].z - mu) * rs * gg[i].z + bb[i].z; o.w = (v[i].w - mu) * rs * gg[i].w + bb[i].w;
;       uint2 pk; pk.x = pack2(o.x, o.y); pk.y = pack2(o.z, o.w);
;       if (mode != 2) ((uint2*)(xb + (size_t)r * 1024))[lane + 64 * i] = pk;
;       if (mode == 2) stnt4(p.out + O_Y + (size_t)r * 1024 + (size_t)(lane + 64 * i) * 4, (f32x4){o.x, o.y, o.z, o.w});
.LBB0_21:
	s_or_b64 exec, exec, s[6:7]
	s_waitcnt vmcnt(3)
	v_pk_add_f32 v[84:85], v[62:63], v[62:63] op_sel:[0,1] op_sel_hi:[1,0]
	v_pk_mul_f32 v[86:87], v[62:63], v[62:63]
	s_waitcnt vmcnt(2)
	v_mul_f32_e32 v0, v59, v59
	v_pk_mul_f32 v[88:89], v[64:65], v[64:65]
	v_pk_add_f32 v[90:91], v[58:59], v[58:59] op_sel_hi:[0,1]
	v_pk_fma_f32 v[92:93], v[58:59], v[58:59], v[0:1] op_sel_hi:[1,1,0]
	v_pk_mul_f32 v[94:95], v[60:61], v[60:61]
	s_waitcnt vmcnt(1)
	v_mul_f32_e32 v0, v55, v55
	v_mov_b32_e32 v116, v86
	v_mov_b32_e32 v117, v84
	v_pk_mov_b32 v[84:85], v[86:87], v[64:65] op_sel:[1,0]
	v_pk_fma_f32 v[98:99], v[54:55], v[54:55], v[0:1] op_sel_hi:[1,1,0]
	s_waitcnt vmcnt(0)
	v_mul_f32_e32 v0, v51, v51
	v_pk_add_f32 v[84:85], v[116:117], v[84:85]
	v_mov_b32_e32 v86, v88
	v_mov_b32_e32 v87, v65
	v_mov_b32_e32 v90, v94
	v_mov_b32_e32 v93, v60
	v_pk_add_f32 v[96:97], v[54:55], v[54:55] op_sel_hi:[0,1]
	v_pk_mul_f32 v[100:101], v[56:57], v[56:57]
	v_pk_fma_f32 v[104:105], v[50:51], v[50:51], v[0:1] op_sel_hi:[1,1,0]
	v_pk_add_f32 v[84:85], v[84:85], v[86:87]
	v_mov_b32_e32 v0, v89
	v_pk_add_f32 v[86:87], v[90:91], v[92:93]
	v_mov_b32_e32 v88, v95
	v_mov_b32_e32 v89, v61
	v_pk_add_f32 v[84:85], v[84:85], v[0:1]
	v_pk_add_f32 v[86:87], v[86:87], v[88:89]
	v_mov_b32_e32 v96, v100
	v_mov_b32_e32 v99, v56
	v_pk_add_f32 v[102:103], v[50:51], v[50:51] op_sel_hi:[0,1]
	v_pk_mul_f32 v[106:107], v[52:53], v[52:53]
	v_pk_add_f32 v[84:85], v[84:85], v[86:87]
	v_pk_add_f32 v[86:87], v[96:97], v[98:99]
	v_mov_b32_e32 v88, v101
	v_mov_b32_e32 v89, v57
	v_pk_add_f32 v[86:87], v[86:87], v[88:89]
	v_mov_b32_e32 v102, v106
	v_mov_b32_e32 v105, v52
	v_pk_add_f32 v[84:85], v[84:85], v[86:87]
	v_pk_add_f32 v[86:87], v[102:103], v[104:105]
	v_mov_b32_e32 v88, v107
	v_mov_b32_e32 v89, v53
	v_pk_add_f32 v[86:87], v[86:87], v[88:89]
	s_mov_b32 s2, 0x3a800000
	v_pk_add_f32 v[84:85], v[84:85], v[86:87]
	ds_bpermute_b32 v87, v108, v85
	ds_bpermute_b32 v86, v108, v84
	v_readlane_b32 s36, v250, 1
	v_readlane_b32 s40, v250, 5
	v_readlane_b32 s41, v250, 6
	v_readlane_b32 s37, v250, 2
	s_waitcnt lgkmcnt(0)
	v_pk_add_f32 v[84:85], v[84:85], v[86:87]
	ds_bpermute_b32 v87, v109, v85
	ds_bpermute_b32 v86, v109, v84
	v_lshl_add_u64 v[88:89], s[40:41], 0, v[70:71]
	v_lshrrev_b32_e32 v172, 25, v70
	v_xor_b32_e32 v172, 1, v172
	v_bfe_u32 v173, v70, 11, 1
	v_mul_u32_u24_e32 v173, 0x7c0, v173
	v_bfe_u32 v164, v145, 3, 3
	v_lshlrev_b32_e32 v164, 6, v164
	v_sub_u32_e32 v164, v164, v173
	v_mul_i32_i24_e32 v164, v164, v172
	v_lshlrev_b32_e32 v173, 9, v172
	v_add_u32_e32 v166, v164, v173
	v_add_u32_e32 v168, v166, v173
	v_add_u32_e32 v170, v168, v173
	v_ashrrev_i32_e32 v165, 31, v164
	v_ashrrev_i32_e32 v167, 31, v166
	v_ashrrev_i32_e32 v169, 31, v168
	v_ashrrev_i32_e32 v171, 31, v170
	v_readlane_b32 s38, v250, 3
	v_readlane_b32 s39, v250, 4
	v_readlane_b32 s42, v250, 7
	s_waitcnt lgkmcnt(0)
	v_pk_add_f32 v[84:85], v[84:85], v[86:87]
	ds_bpermute_b32 v87, v110, v85
	ds_bpermute_b32 v86, v110, v84
	v_readlane_b32 s43, v250, 8
	s_waitcnt lgkmcnt(0)
	v_pk_add_f32 v[84:85], v[84:85], v[86:87]
	ds_bpermute_b32 v87, v111, v85
	ds_bpermute_b32 v86, v111, v84
	s_waitcnt lgkmcnt(0)
	v_pk_add_f32 v[84:85], v[84:85], v[86:87]
	ds_bpermute_b32 v87, v112, v85
	ds_bpermute_b32 v86, v112, v84
	s_waitcnt lgkmcnt(0)
	v_pk_add_f32 v[84:85], v[84:85], v[86:87]
	ds_bpermute_b32 v87, v113, v85
	ds_bpermute_b32 v86, v113, v84
	s_waitcnt lgkmcnt(0)
	v_pk_add_f32 v[84:85], v[84:85], v[86:87]
	s_nop 0
	v_pk_mul_f32 v[84:85], v[84:85], s[2:3] op_sel_hi:[1,0]
	s_mov_b32 s2, 0x800000
	v_fma_f32 v0, -v85, v85, v84
	v_max_f32_e32 v0, 0, v0
	v_add_f32_e32 v0, 0x3727c5ac, v0
	v_mul_f32_e32 v77, 0x4b800000, v0
	v_cmp_gt_f32_e32 vcc, s2, v0
	v_pk_add_f32 v[62:63], v[62:63], v[84:85] op_sel:[0,1] neg_lo:[0,1] neg_hi:[0,1]
	v_pk_add_f32 v[64:65], v[64:65], v[84:85] op_sel:[0,1] neg_lo:[0,1] neg_hi:[0,1]
	v_cndmask_b32_e32 v0, v0, v77, vcc
	v_rsq_f32_e32 v0, v0
	s_mov_b64 s[2:3], -1
	v_mul_f32_e32 v77, 0x45800000, v0
	v_cndmask_b32_e32 v86, v0, v77, vcc
	v_pk_mul_f32 v[62:63], v[62:63], v[86:87] op_sel_hi:[1,0]
	v_pk_mul_f32 v[64:65], v[64:65], v[86:87] op_sel_hi:[1,0]
	v_cndmask_b32_e64 v0, 0, 1, s[10:11]
	v_pk_fma_f32 v[62:63], v[2:3], v[62:63], v[10:11]
	v_pk_fma_f32 v[64:65], v[4:5], v[64:65], v[12:13]
	v_cmp_ne_u32_e64 s[6:7], 1, v0
	s_andn2_b64 vcc, exec, s[10:11]
	s_cbranch_vccnz .LBB0_23
	v_add_co_u32_e32 v92, vcc, 0x4200000, v88
	v_cvt_pk_bf16_f32 v91, v64, v65
	v_cvt_pk_bf16_f32 v90, v62, v63
	v_addc_co_u32_e32 v93, vcc, 0, v89, vcc
	v_lshl_add_u64 v[92:93], v[92:93], 0, v[164:165]
	s_mov_b64 s[2:3], 0
	global_store_dwordx2 v[92:93], v[90:91], off

; DEVI unsigned pack2(float a, float b) { return __builtin_bit_cast(unsigned, __builtin_convertvector((f32x2_t){a, b}, bf16x2_t)); }
; DEVI void stnt4(float* p_, f32x4 v) { __builtin_nontemporal_store(v, (f32x4*)p_); }
;     ...
;     for (int i = 0; i < 4; i++) {
;       float4 o;
;       o.x = (v[i].x - mu) * rs * gg[i].x + bb[i].x; o.y = (v[i].y - mu) * rs * gg[i].y + bb[i].y;
;       o.z = (v[i].z - mu) * rs * gg[i].z + bb[i].z; o.w = (v[i].w - mu) * rs * gg[i].w + bb[i].w;
;       uint2 pk; pk.x = pack2(o.x, o.y); pk.y = pack2(o.z, o.w);
;       if (mode != 2) ((uint2*)(xb + (size_t)r * 1024))[lane + 64 * i] = pk;
;       if (mode == 2) stnt4(p.out + O_Y + (size_t)r * 1024 + (size_t)(lane + 64 * i) * 4, (f32x4){o.x, o.y, o.z, o.w});
.LBB0_25:
	v_mov_b32_e32 v84, v85
	v_mov_b32_e32 v87, v86
	v_pk_add_f32 v[58:59], v[58:59], v[84:85] neg_lo:[0,1] neg_hi:[0,1]
	v_pk_add_f32 v[60:61], v[60:61], v[84:85] neg_lo:[0,1] neg_hi:[0,1]
	v_pk_mul_f32 v[58:59], v[58:59], v[86:87]
	v_pk_mul_f32 v[60:61], v[60:61], v[86:87]
	v_pk_fma_f32 v[58:59], v[6:7], v[58:59], v[14:15]
	v_pk_fma_f32 v[60:61], v[8:9], v[60:61], v[16:17]
	s_and_b64 vcc, exec, s[6:7]
	s_mov_b64 s[2:3], -1
	s_cbranch_vccnz .LBB0_27
	v_add_co_u32_e32 v64, vcc, 0x4200000, v88
	v_cvt_pk_bf16_f32 v63, v60, v61
	v_cvt_pk_bf16_f32 v62, v58, v59
	v_addc_co_u32_e32 v65, vcc, 0, v89, vcc
	v_lshl_add_u64 v[64:65], v[64:65], 0, v[166:167]
	s_mov_b64 s[2:3], 0
	global_store_dwordx2 v[64:65], v[62:63], off offset:512

; DEVI unsigned pack2(float a, float b) { return __builtin_bit_cast(unsigned, __builtin_convertvector((f32x2_t){a, b}, bf16x2_t)); }
; DEVI void stnt4(float* p_, f32x4 v) { __builtin_nontemporal_store(v, (f32x4*)p_); }
;     ...
;     for (int i = 0; i < 4; i++) {
;       float4 o;
;       o.x = (v[i].x - mu) * rs * gg[i].x + bb[i].x; o.y = (v[i].y - mu) * rs * gg[i].y + bb[i].y;
;       o.z = (v[i].z - mu) * rs * gg[i].z + bb[i].z; o.w = (v[i].w - mu) * rs * gg[i].w + bb[i].w;
;       uint2 pk; pk.x = pack2(o.x, o.y); pk.y = pack2(o.z, o.w);
;       if (mode != 2) ((uint2*)(xb + (size_t)r * 1024))[lane + 64 * i] = pk;
;       if (mode == 2) stnt4(p.out + O_Y + (size_t)r * 1024 + (size_t)(lane + 64 * i) * 4, (f32x4){o.x, o.y, o.z, o.w});
.LBB0_29:
	v_pk_add_f32 v[54:55], v[54:55], v[84:85] neg_lo:[0,1] neg_hi:[0,1]
	v_pk_add_f32 v[56:57], v[56:57], v[84:85] neg_lo:[0,1] neg_hi:[0,1]
	v_pk_mul_f32 v[54:55], v[54:55], v[86:87]
	v_pk_mul_f32 v[56:57], v[56:57], v[86:87]
	v_pk_fma_f32 v[54:55], v[18:19], v[54:55], v[26:27]
	v_pk_fma_f32 v[56:57], v[20:21], v[56:57], v[28:29]
	s_and_b64 vcc, exec, s[6:7]
	s_mov_b64 s[2:3], -1
	s_cbranch_vccnz .LBB0_31
	v_add_co_u32_e32 v60, vcc, 0x4200000, v88
	v_cvt_pk_bf16_f32 v59, v56, v57
	v_cvt_pk_bf16_f32 v58, v54, v55
	v_addc_co_u32_e32 v61, vcc, 0, v89, vcc
	v_lshl_add_u64 v[60:61], v[60:61], 0, v[168:169]
	s_mov_b64 s[2:3], 0
	global_store_dwordx2 v[60:61], v[58:59], off offset:1024

; DEVI unsigned pack2(float a, float b) { return __builtin_bit_cast(unsigned, __builtin_convertvector((f32x2_t){a, b}, bf16x2_t)); }
; DEVI void stnt4(float* p_, f32x4 v) { __builtin_nontemporal_store(v, (f32x4*)p_); }
;     ...
;     for (int i = 0; i < 4; i++) {
;       float4 o;
;       o.x = (v[i].x - mu) * rs * gg[i].x + bb[i].x; o.y = (v[i].y - mu) * rs * gg[i].y + bb[i].y;
;       o.z = (v[i].z - mu) * rs * gg[i].z + bb[i].z; o.w = (v[i].w - mu) * rs * gg[i].w + bb[i].w;
;       uint2 pk; pk.x = pack2(o.x, o.y); pk.y = pack2(o.z, o.w);
;       if (mode != 2) ((uint2*)(xb + (size_t)r * 1024))[lane + 64 * i] = pk;
;       if (mode == 2) stnt4(p.out + O_Y + (size_t)r * 1024 + (size_t)(lane + 64 * i) * 4, (f32x4){o.x, o.y, o.z, o.w});
.LBB0_33:
	v_pk_add_f32 v[50:51], v[50:51], v[84:85] neg_lo:[0,1] neg_hi:[0,1]
	v_pk_add_f32 v[52:53], v[52:53], v[84:85] neg_lo:[0,1] neg_hi:[0,1]
	v_pk_mul_f32 v[50:51], v[50:51], v[86:87]
	v_pk_mul_f32 v[52:53], v[52:53], v[86:87]
	v_pk_fma_f32 v[50:51], v[22:23], v[50:51], v[30:31]
	v_pk_fma_f32 v[52:53], v[24:25], v[52:53], v[32:33]
	s_and_b64 vcc, exec, s[6:7]
	s_mov_b64 s[2:3], -1
	s_cbranch_vccnz .LBB0_35
	v_add_co_u32_e32 v56, vcc, 0x4200000, v88
	v_cvt_pk_bf16_f32 v55, v52, v53
	v_cvt_pk_bf16_f32 v54, v50, v51
	v_addc_co_u32_e32 v57, vcc, 0, v89, vcc
	v_lshl_add_u64 v[56:57], v[56:57], 0, v[170:171]
	s_mov_b64 s[2:3], 0
	global_store_dwordx2 v[56:57], v[54:55], off offset:1536

; #define LAS __attribute__((address_space(3)))
; DEVI int tidx() { int t = threadIdx.x; asm volatile("" : "+v"(t)); return t; }
;   const int tid = tidx(), lane = tid & 63, wid = tid >> 6;
;   const int wm = wid >> 1, wn = wid & 1, r16 = lane & 15, quad = lane >> 4;
;   f32x4 acc[4][8];
; #pragma unroll
;   for (int i = 0; i < 4; i++)
; #pragma unroll
;     for (int j = 0; j < 8; j++) acc[i][j] = (f32x4){0.f, 0.f, 0.f, 0.f};
;   const int nk = (nk_part < 0) ? (K >> 5) : nk_part;
;   const int lrow = tid >> 2, lpc = tid & 3;
;   const int lch = lpc ^ ((0x78 >> (((lrow >> 2) & 3) * 2)) & 3);
;   const u16* ga = A + (size_t)(m0 + lrow) * lda + kbeg + lch * 8;
;   const u16* gb = Bt + (size_t)(n0 + lrow) * K + kbeg + lch * 8;
;   const size_t ga1 = (size_t)64 * lda, gb1 = (size_t)64 * K;
;   const unsigned lds0 = (unsigned)(uintptr_t)(LAS char*)smem + (unsigned)__builtin_amdgcn_readfirstlane(wid) * 1024u;
; DEVI void tile_coords(int T, int MT, int NT, int& mt, int& nt) {
;   const int full = MT >> 3, band = T / (8 * NT);
;   if (band < full) { const int r = T - band * 8 * NT; nt = r >> 3; mt = band * 8 + (r & 7); }
;   else { const int MB = MT - full * 8; const int r = T - full * 8 * NT; nt = r / MB; mt = full * 8 + r % MB; }
; }
.LBB0_116:
	s_and_b64 vcc, exec, s[2:3]
	s_cbranch_vccz .LBB0_41
	s_lshr_b32 s45, s38, 6
	s_and_b32 s46, s38, 63
	s_lshr_b32 s42, s46, 3
	s_and_b32 s46, s46, 7
	s_lshl_b32 s45, s45, 3
	s_add_i32 s45, s45, s46
	s_cmp_lt_u32 s45, 64
	s_cselect_b32 s44, 1, 0
	v_readlane_b32 s2, v250, 5
	v_readlane_b32 s3, v250, 6
	v_readlane_b32 s46, v254, 62
	s_mul_i32 s40, s45, 0x160000
	s_add_u32 s4, s2, s40
	s_addc_u32 s5, s3, 0
	s_add_u32 s4, s4, 0xef40000
	s_addc_u32 s5, s5, 0
	s_mul_i32 s40, s46, 0x580000
	s_mul_i32 s41, s42, 0xb0000
	s_add_i32 s40, s40, s41
	s_add_u32 s10, s2, s40
	s_addc_u32 s11, s3, 0
	s_add_u32 s10, s10, 0x19a00000
	s_addc_u32 s11, s11, 0
	s_movk_i32 s39, 0x78
	v_lshrrev_b32_e32 v0, 2, v145
	v_and_b32_e32 v131, 3, v145
	v_bfe_u32 v136, v145, 4, 2
	v_lshlrev_b32_e32 v136, 1, v136
	v_lshrrev_b32_e64 v136, v136, s39
	v_and_b32_e32 v136, 3, v136
	v_xor_b32_e32 v131, v131, v136
	v_lshlrev_b32_e32 v131, 4, v131
	s_movk_i32 s41, 0x1600
	v_mad_u32_u24 v0, v0, s41, v131
	v_bfe_u32 v137, v145, 2, 1
	v_lshl_add_u64 v[134:135], s[10:11], 0, v[0:1]
	s_mul_i32 s41, s44, 0x15c0
	v_mul_u32_u24_e32 v136, s41, v137
	v_sub_u32_e32 v0, v0, v136
	s_lshl_b32 s12, s44, 6
	s_add_i32 s12, s12, 64
	s_mov_b32 s13, 0
	v_lshl_add_u64 v[132:133], s[4:5], 0, v[0:1]
	v_bfe_u32 v136, v145, 2, 2
	v_lshlrev_b32_e32 v136, 1, v136
	v_lshrrev_b32_e64 v136, v136, s39
	v_and_b32_e32 v136, 3, v136
	v_bfe_u32 v137, v145, 4, 2
	v_xor_b32_e32 v136, v136, v137
	v_lshlrev_b32_e32 v136, 4, v136
	v_and_b32_e32 v131, 15, v145
	v_lshl_or_b32 v136, v131, 6, v136
	v_bfe_u32 v137, v145, 6, 1
	v_lshl_or_b32 v137, v137, 12, v136
	v_lshrrev_b32_e32 v0, 7, v145
	v_lshl_or_b32 v136, v0, 13, v136
	v_and_b32_e32 v140, 1, v131
	v_lshl_or_b32 v131, v0, 7, v131
	v_bfe_u32 v0, v145, 4, 2
	v_lshlrev_b32_e32 v0, 3, v0
	v_bfe_u32 v141, v145, 6, 1
	s_lshl_b32 s40, s45, 19
	s_lshl_b32 s41, s42, 9
	s_add_i32 s40, s40, s41
	s_add_u32 s4, s2, s40
	s_addc_u32 s5, s3, 0
	s_add_u32 s4, s4, 0x4200000
	s_addc_u32 s5, s5, 0
	v_lshlrev_b32_e32 v138, 11, v131
	v_lshl_add_u32 v138, v141, 8, v138
	v_add_u32_e32 v138, v138, v0
	s_movk_i32 s41, 1984
	v_mul_u32_u24_e32 v139, s41, v140
	v_sub_u32_e32 v138, v138, v139
	v_mov_b32_e32 v139, 0
	v_lshl_add_u64 v[138:139], s[4:5], 0, v[138:139]
	s_lshl_b32 s40, s45, 20
	s_lshl_b32 s41, s42, 9
	s_add_i32 s40, s40, s41
	s_add_u32 s10, s2, s40
	s_addc_u32 s11, s3, 0
	v_lshlrev_b32_e32 v140, 12, v131
	v_lshl_add_u32 v140, v141, 8, v140
	v_lshl_add_u32 v140, v0, 1, v140
	v_mov_b32_e32 v141, 0
	v_lshl_add_u64 v[140:141], s[10:11], 0, v[140:141]
	s_mov_b32 s2, 0x58000
	s_mov_b32 s3, 0
	v_lshrrev_b32_e32 v0, 6, v145
	v_lshlrev_b32_e32 v0, 10, v0
	s_nop 0
	v_readfirstlane_b32 s46, v0
	s_mov_b32 s43, m0
	s_mov_b32 s4, 64
	s_mov_b32 s5, 0
	v_mov_b32_e32 v2, 0
	v_mov_b32_e32 v3, 0
	v_mov_b32_e32 v4, 0
	v_mov_b32_e32 v5, 0
	v_mov_b32_e32 v6, 0
	v_mov_b32_e32 v7, 0
	v_mov_b32_e32 v8, 0
	v_mov_b32_e32 v9, 0
	v_mov_b32_e32 v10, 0
	v_mov_b32_e32 v11, 0
	v_mov_b32_e32 v12, 0
	v_mov_b32_e32 v13, 0
	v_mov_b32_e32 v14, 0
	v_mov_b32_e32 v15, 0
	v_mov_b32_e32 v16, 0
	v_mov_b32_e32 v17, 0
	v_mov_b32_e32 v18, 0
	v_mov_b32_e32 v19, 0
	v_mov_b32_e32 v20, 0
	v_mov_b32_e32 v21, 0
	v_mov_b32_e32 v22, 0
	v_mov_b32_e32 v23, 0
	v_mov_b32_e32 v24, 0
	v_mov_b32_e32 v25, 0
	v_mov_b32_e32 v26, 0
	v_mov_b32_e32 v27, 0
	v_mov_b32_e32 v28, 0
	v_mov_b32_e32 v29, 0
	v_mov_b32_e32 v30, 0
	v_mov_b32_e32 v31, 0
	v_mov_b32_e32 v32, 0
	v_mov_b32_e32 v33, 0
	v_mov_b32_e32 v34, 0
	v_mov_b32_e32 v35, 0
	v_mov_b32_e32 v36, 0
	v_mov_b32_e32 v37, 0
	v_mov_b32_e32 v38, 0
	v_mov_b32_e32 v39, 0
	v_mov_b32_e32 v40, 0
	v_mov_b32_e32 v41, 0
	v_mov_b32_e32 v42, 0
	v_mov_b32_e32 v43, 0
	v_mov_b32_e32 v44, 0
	v_mov_b32_e32 v45, 0
	v_mov_b32_e32 v46, 0
	v_mov_b32_e32 v47, 0
	v_mov_b32_e32 v48, 0
	v_mov_b32_e32 v49, 0
	v_mov_b32_e32 v50, 0
	v_mov_b32_e32 v51, 0
	v_mov_b32_e32 v52, 0
	v_mov_b32_e32 v53, 0
	v_mov_b32_e32 v54, 0
	v_mov_b32_e32 v55, 0
	v_mov_b32_e32 v56, 0
	v_mov_b32_e32 v57, 0
	v_mov_b32_e32 v58, 0
	v_mov_b32_e32 v59, 0
	v_mov_b32_e32 v60, 0
	v_mov_b32_e32 v61, 0
	v_mov_b32_e32 v62, 0
	v_mov_b32_e32 v63, 0
	v_mov_b32_e32 v64, 0
	v_mov_b32_e32 v65, 0
	v_mov_b32_e32 v66, 0
	v_mov_b32_e32 v67, 0
	v_mov_b32_e32 v68, 0
	v_mov_b32_e32 v69, 0
	v_mov_b32_e32 v70, 0
	v_mov_b32_e32 v71, 0
	v_mov_b32_e32 v72, 0
	v_mov_b32_e32 v73, 0
	v_mov_b32_e32 v74, 0
	v_mov_b32_e32 v75, 0
	v_mov_b32_e32 v76, 0
	v_mov_b32_e32 v77, 0
	v_mov_b32_e32 v78, 0
	v_mov_b32_e32 v79, 0
	v_mov_b32_e32 v80, 0
	v_mov_b32_e32 v81, 0
	v_mov_b32_e32 v82, 0
	v_mov_b32_e32 v83, 0
	v_mov_b32_e32 v84, 0
	v_mov_b32_e32 v85, 0
	v_mov_b32_e32 v86, 0
	v_mov_b32_e32 v87, 0
	v_mov_b32_e32 v88, 0
	v_mov_b32_e32 v89, 0
	v_mov_b32_e32 v90, 0
	v_mov_b32_e32 v91, 0
	v_mov_b32_e32 v92, 0
	v_mov_b32_e32 v93, 0
	v_mov_b32_e32 v94, 0
	v_mov_b32_e32 v95, 0
	v_mov_b32_e32 v96, 0
	v_mov_b32_e32 v97, 0
	v_mov_b32_e32 v98, 0
	v_mov_b32_e32 v99, 0
	v_mov_b32_e32 v100, 0
	v_mov_b32_e32 v101, 0
	v_mov_b32_e32 v102, 0
	v_mov_b32_e32 v103, 0
	v_mov_b32_e32 v104, 0
	v_mov_b32_e32 v105, 0
	v_mov_b32_e32 v106, 0
	v_mov_b32_e32 v107, 0
	v_mov_b32_e32 v108, 0
	v_mov_b32_e32 v109, 0
	v_mov_b32_e32 v110, 0
	v_mov_b32_e32 v111, 0
	v_mov_b32_e32 v112, 0
	v_mov_b32_e32 v113, 0
	v_mov_b32_e32 v114, 0
	v_mov_b32_e32 v115, 0
	v_mov_b32_e32 v116, 0
	v_mov_b32_e32 v117, 0
	v_mov_b32_e32 v118, 0
	v_mov_b32_e32 v119, 0
	v_mov_b32_e32 v120, 0
	v_mov_b32_e32 v121, 0
	v_mov_b32_e32 v122, 0
	v_mov_b32_e32 v123, 0
	v_mov_b32_e32 v124, 0
	v_mov_b32_e32 v125, 0
	v_mov_b32_e32 v126, 0
	v_mov_b32_e32 v127, 0
	v_mov_b32_e32 v128, 0
	v_mov_b32_e32 v129, 0
	s_barrier
;     ...
;   __syncthreads();
;   G2_STAGE(0); G2_STAGE(1);
;   const int fsw = (0x78 >> (((r16 >> 2) & 3) * 2)) & 3;
;   const int aoff = (wm * 128 + r16) * 64 + ((quad ^ fsw) << 4);
;   const int boff = 16384 + (wn * 64 + r16) * 64 + ((quad ^ fsw) << 4);
;   for (int kt = 0; kt < nk; kt++) {
;     if (kt + 1 < nk) asm volatile("s_waitcnt vmcnt(6)" ::: "memory");
;     else asm volatile("s_waitcnt vmcnt(0)" ::: "memory");
;     __builtin_amdgcn_s_barrier();
;     asm volatile("" ::: "memory");
;     if (kt + 2 < nk) G2_STAGE(kt + 2);
;     const char* cS = smem + (kt % 3) * 24576;
;     bf16x8 xa[8], wb[4];
; #pragma unroll
;     for (int f = 0; f < 8; f++) xa[f] = *(const bf16x8*)(cS + aoff + f * 1024);
; #pragma unroll
;     for (int f = 0; f < 4; f++) wb[f] = *(const bf16x8*)(cS + boff + f * 1024);
; #pragma unroll
;     for (int nf = 0; nf < 4; nf++)
; #pragma unroll
;       for (int mf = 0; mf < 8; mf++)
;         acc[nf][mf] = __builtin_amdgcn_mfma_f32_16x16x32_bf16(wb[nf], xa[mf], acc[nf][mf], 0, 0, 0);
;   }
	s_add_i32 s42, s46, 0x0
	s_mov_b32 m0, s42
	v_lshl_add_u64 v[142:143], v[132:133], 0, s[2:3]
	global_load_lds_dwordx4 v[132:133], off
	s_addk_i32 m0, 0x1000
	s_nop 0
	global_load_lds_dwordx4 v[142:143], off
	v_lshl_add_u64 v[142:143], v[142:143], 0, s[2:3]
	s_addk_i32 m0, 0x1000
	s_nop 0
	global_load_lds_dwordx4 v[142:143], off
	v_lshl_add_u64 v[142:143], v[142:143], 0, s[2:3]
	s_addk_i32 m0, 0x1000
	s_nop 0
	global_load_lds_dwordx4 v[142:143], off
	s_addk_i32 m0, 0x1000
	v_lshl_add_u64 v[142:143], v[134:135], 0, s[2:3]
	s_nop 0
	global_load_lds_dwordx4 v[134:135], off
	s_addk_i32 m0, 0x1000
	v_lshl_add_u64 v[132:133], v[132:133], 0, s[12:13]
	s_nop 0
	global_load_lds_dwordx4 v[142:143], off
	v_lshl_add_u64 v[134:135], v[134:135], 0, s[4:5]
	s_nop 0
	s_add_i32 s42, s46, 0x6000
	s_mov_b32 m0, s42
	v_lshl_add_u64 v[142:143], v[132:133], 0, s[2:3]
	global_load_lds_dwordx4 v[132:133], off
	s_addk_i32 m0, 0x1000
	s_nop 0
	global_load_lds_dwordx4 v[142:143], off
	v_lshl_add_u64 v[142:143], v[142:143], 0, s[2:3]
	s_addk_i32 m0, 0x1000
	s_nop 0
	global_load_lds_dwordx4 v[142:143], off
	v_lshl_add_u64 v[142:143], v[142:143], 0, s[2:3]
	s_addk_i32 m0, 0x1000
	s_nop 0
	global_load_lds_dwordx4 v[142:143], off
	s_addk_i32 m0, 0x1000
	v_lshl_add_u64 v[142:143], v[134:135], 0, s[2:3]
	s_nop 0
	global_load_lds_dwordx4 v[134:135], off
	s_addk_i32 m0, 0x1000
	v_lshl_add_u64 v[132:133], v[132:133], 0, s[12:13]
	s_nop 0
	global_load_lds_dwordx4 v[142:143], off
	v_lshl_add_u64 v[134:135], v[134:135], 0, s[4:5]
	s_nop 0
	s_add_i32 s42, s46, 0xc000
	s_mov_b32 m0, s42
	v_lshl_add_u64 v[142:143], v[132:133], 0, s[2:3]
	global_load_lds_dwordx4 v[132:133], off
	s_addk_i32 m0, 0x1000
	s_nop 0
	global_load_lds_dwordx4 v[142:143], off
	v_lshl_add_u64 v[142:143], v[142:143], 0, s[2:3]
	s_addk_i32 m0, 0x1000
	s_nop 0
	global_load_lds_dwordx4 v[142:143], off
	v_lshl_add_u64 v[142:143], v[142:143], 0, s[2:3]
	s_addk_i32 m0, 0x1000
	s_nop 0
	global_load_lds_dwordx4 v[142:143], off
	s_addk_i32 m0, 0x1000
	v_lshl_add_u64 v[142:143], v[134:135], 0, s[2:3]
	s_nop 0
	global_load_lds_dwordx4 v[134:135], off
	s_addk_i32 m0, 0x1000
	v_lshl_add_u64 v[132:133], v[132:133], 0, s[12:13]
	s_nop 0
	global_load_lds_dwordx4 v[142:143], off
	v_lshl_add_u64 v[134:135], v[134:135], 0, s[4:5]
	s_nop 0
	s_waitcnt vmcnt(12)
	s_barrier
	ds_read_b128 v[146:149], v136 offset:0
	ds_read_b128 v[152:155], v136 offset:1024
	ds_read_b128 v[156:159], v136 offset:2048
	ds_read_b128 v[162:165], v136 offset:3072
	ds_read_b128 v[166:169], v136 offset:4096
	ds_read_b128 v[170:173], v136 offset:5120
	ds_read_b128 v[176:179], v136 offset:6144
	ds_read_b128 v[180:183], v136 offset:7168
	ds_read_b128 v[184:187], v137 offset:16384
	ds_read_b128 v[188:191], v137 offset:17408
	ds_read_b128 v[192:195], v137 offset:18432
	ds_read_b128 v[196:199], v137 offset:19456
	s_movk_i32 s40, 0x6000
	s_mov_b32 s41, 0
	s_movk_i32 s39, 42
.Lt11_loop:
	s_waitcnt vmcnt(6) lgkmcnt(0)
	s_barrier
	v_add_u32_e32 v144, s40, v136
	v_mfma_f32_16x16x32_bf16 v[126:129], v[184:187], v[146:149], v[126:129]
	ds_read_b128 v[200:203], v144 offset:0
	v_mfma_f32_16x16x32_bf16 v[122:125], v[184:187], v[152:155], v[122:125]
	ds_read_b128 v[204:207], v144 offset:1024
	v_mfma_f32_16x16x32_bf16 v[118:121], v[184:187], v[156:159], v[118:121]
	ds_read_b128 v[208:211], v144 offset:2048
	v_mfma_f32_16x16x32_bf16 v[114:117], v[184:187], v[162:165], v[114:117]
	ds_read_b128 v[212:215], v144 offset:3072
	v_mfma_f32_16x16x32_bf16 v[110:113], v[184:187], v[166:169], v[110:113]
	ds_read_b128 v[216:219], v144 offset:4096
	v_mfma_f32_16x16x32_bf16 v[106:109], v[184:187], v[170:173], v[106:109]
	ds_read_b128 v[220:223], v144 offset:5120
	v_mfma_f32_16x16x32_bf16 v[102:105], v[184:187], v[176:179], v[102:105]
	ds_read_b128 v[224:227], v144 offset:6144
	v_mfma_f32_16x16x32_bf16 v[98:101], v[184:187], v[180:183], v[98:101]
	ds_read_b128 v[228:231], v144 offset:7168
	v_mfma_f32_16x16x32_bf16 v[94:97], v[188:191], v[146:149], v[94:97]
	v_add_u32_e32 v144, s40, v137
	v_mfma_f32_16x16x32_bf16 v[90:93], v[188:191], v[152:155], v[90:93]
	v_mfma_f32_16x16x32_bf16 v[86:89], v[188:191], v[156:159], v[86:89]
	ds_read_b128 v[232:235], v144 offset:16384
	v_mfma_f32_16x16x32_bf16 v[82:85], v[188:191], v[162:165], v[82:85]
	ds_read_b128 v[236:239], v144 offset:17408
	v_mfma_f32_16x16x32_bf16 v[78:81], v[188:191], v[166:169], v[78:81]
	ds_read_b128 v[240:243], v144 offset:18432
	v_mfma_f32_16x16x32_bf16 v[74:77], v[188:191], v[170:173], v[74:77]
	ds_read_b128 v[244:247], v144 offset:19456
	s_add_i32 s42, s46, s41
	v_mfma_f32_16x16x32_bf16 v[70:73], v[188:191], v[176:179], v[70:73]
	s_mov_b32 m0, s42
	v_lshl_add_u64 v[142:143], v[132:133], 0, s[2:3]
	v_mfma_f32_16x16x32_bf16 v[66:69], v[188:191], v[180:183], v[66:69]
	global_load_lds_dwordx4 v[132:133], off
	s_addk_i32 m0, 0x1000
	v_mfma_f32_16x16x32_bf16 v[62:65], v[192:195], v[146:149], v[62:65]
	v_mfma_f32_16x16x32_bf16 v[58:61], v[192:195], v[152:155], v[58:61]
	v_mfma_f32_16x16x32_bf16 v[54:57], v[192:195], v[156:159], v[54:57]
	global_load_lds_dwordx4 v[142:143], off
	v_lshl_add_u64 v[142:143], v[142:143], 0, s[2:3]
	s_addk_i32 m0, 0x1000
	v_mfma_f32_16x16x32_bf16 v[50:53], v[192:195], v[162:165], v[50:53]
	v_mfma_f32_16x16x32_bf16 v[46:49], v[192:195], v[166:169], v[46:49]
	v_mfma_f32_16x16x32_bf16 v[42:45], v[192:195], v[170:173], v[42:45]
	global_load_lds_dwordx4 v[142:143], off
	v_lshl_add_u64 v[142:143], v[142:143], 0, s[2:3]
	s_addk_i32 m0, 0x1000
	v_mfma_f32_16x16x32_bf16 v[38:41], v[192:195], v[176:179], v[38:41]
	v_mfma_f32_16x16x32_bf16 v[34:37], v[192:195], v[180:183], v[34:37]
	v_mfma_f32_16x16x32_bf16 v[30:33], v[196:199], v[146:149], v[30:33]
	global_load_lds_dwordx4 v[142:143], off
	s_addk_i32 m0, 0x1000
	v_lshl_add_u64 v[142:143], v[134:135], 0, s[2:3]
	v_mfma_f32_16x16x32_bf16 v[26:29], v[196:199], v[152:155], v[26:29]
	v_mfma_f32_16x16x32_bf16 v[22:25], v[196:199], v[156:159], v[22:25]
	v_mfma_f32_16x16x32_bf16 v[18:21], v[196:199], v[162:165], v[18:21]
	global_load_lds_dwordx4 v[134:135], off
	s_addk_i32 m0, 0x1000
	v_lshl_add_u64 v[132:133], v[132:133], 0, s[12:13]
	v_mfma_f32_16x16x32_bf16 v[14:17], v[196:199], v[166:169], v[14:17]
	v_mfma_f32_16x16x32_bf16 v[10:13], v[196:199], v[170:173], v[10:13]
	v_mfma_f32_16x16x32_bf16 v[6:9], v[196:199], v[176:179], v[6:9]
	global_load_lds_dwordx4 v[142:143], off
	v_lshl_add_u64 v[134:135], v[134:135], 0, s[4:5]
	v_mfma_f32_16x16x32_bf16 v[2:5], v[196:199], v[180:183], v[2:5]
	s_mov_b32 s41, s40
	s_add_i32 s40, s40, 0x6000
	s_cmp_eq_u32 s40, 0x12000
	s_cselect_b32 s40, 0, s40
	s_waitcnt vmcnt(6) lgkmcnt(0)
	s_barrier
;     ...
;   for (int kt = 0; kt < nk; kt++) {
;     if (kt + 1 < nk) asm volatile("s_waitcnt vmcnt(6)" ::: "memory");
;     else asm volatile("s_waitcnt vmcnt(0)" ::: "memory");
;     __builtin_amdgcn_s_barrier();
;     asm volatile("" ::: "memory");
;     if (kt + 2 < nk) G2_STAGE(kt + 2);
;     const char* cS = smem + (kt % 3) * 24576;
;     bf16x8 xa[8], wb[4];
; #pragma unroll
;     for (int f = 0; f < 8; f++) xa[f] = *(const bf16x8*)(cS + aoff + f * 1024);
; #pragma unroll
;     for (int f = 0; f < 4; f++) wb[f] = *(const bf16x8*)(cS + boff + f * 1024);
; #pragma unroll
;     for (int nf = 0; nf < 4; nf++)
; #pragma unroll
;       for (int mf = 0; mf < 8; mf++)
;         acc[nf][mf] = __builtin_amdgcn_mfma_f32_16x16x32_bf16(wb[nf], xa[mf], acc[nf][mf], 0, 0, 0);
;   }
	v_add_u32_e32 v144, s40, v136
	v_mfma_f32_16x16x32_bf16 v[126:129], v[232:235], v[200:203], v[126:129]
	ds_read_b128 v[146:149], v144 offset:0
	v_mfma_f32_16x16x32_bf16 v[122:125], v[232:235], v[204:207], v[122:125]
	ds_read_b128 v[152:155], v144 offset:1024
	v_mfma_f32_16x16x32_bf16 v[118:121], v[232:235], v[208:211], v[118:121]
	ds_read_b128 v[156:159], v144 offset:2048
	v_mfma_f32_16x16x32_bf16 v[114:117], v[232:235], v[212:215], v[114:117]
	ds_read_b128 v[162:165], v144 offset:3072
	v_mfma_f32_16x16x32_bf16 v[110:113], v[232:235], v[216:219], v[110:113]
	ds_read_b128 v[166:169], v144 offset:4096
	v_mfma_f32_16x16x32_bf16 v[106:109], v[232:235], v[220:223], v[106:109]
	ds_read_b128 v[170:173], v144 offset:5120
	v_mfma_f32_16x16x32_bf16 v[102:105], v[232:235], v[224:227], v[102:105]
	ds_read_b128 v[176:179], v144 offset:6144
	v_mfma_f32_16x16x32_bf16 v[98:101], v[232:235], v[228:231], v[98:101]
	ds_read_b128 v[180:183], v144 offset:7168
	v_mfma_f32_16x16x32_bf16 v[94:97], v[236:239], v[200:203], v[94:97]
	v_add_u32_e32 v144, s40, v137
	v_mfma_f32_16x16x32_bf16 v[90:93], v[236:239], v[204:207], v[90:93]
	v_mfma_f32_16x16x32_bf16 v[86:89], v[236:239], v[208:211], v[86:89]
	ds_read_b128 v[184:187], v144 offset:16384
	v_mfma_f32_16x16x32_bf16 v[82:85], v[236:239], v[212:215], v[82:85]
	ds_read_b128 v[188:191], v144 offset:17408
	v_mfma_f32_16x16x32_bf16 v[78:81], v[236:239], v[216:219], v[78:81]
	ds_read_b128 v[192:195], v144 offset:18432
	v_mfma_f32_16x16x32_bf16 v[74:77], v[236:239], v[220:223], v[74:77]
	ds_read_b128 v[196:199], v144 offset:19456
	s_add_i32 s42, s46, s41
	v_mfma_f32_16x16x32_bf16 v[70:73], v[236:239], v[224:227], v[70:73]
	s_mov_b32 m0, s42
	v_lshl_add_u64 v[142:143], v[132:133], 0, s[2:3]
	v_mfma_f32_16x16x32_bf16 v[66:69], v[236:239], v[228:231], v[66:69]
	global_load_lds_dwordx4 v[132:133], off
	s_addk_i32 m0, 0x1000
	v_mfma_f32_16x16x32_bf16 v[62:65], v[240:243], v[200:203], v[62:65]
	v_mfma_f32_16x16x32_bf16 v[58:61], v[240:243], v[204:207], v[58:61]
	v_mfma_f32_16x16x32_bf16 v[54:57], v[240:243], v[208:211], v[54:57]
	global_load_lds_dwordx4 v[142:143], off
	v_lshl_add_u64 v[142:143], v[142:143], 0, s[2:3]
	s_addk_i32 m0, 0x1000
	v_mfma_f32_16x16x32_bf16 v[50:53], v[240:243], v[212:215], v[50:53]
	v_mfma_f32_16x16x32_bf16 v[46:49], v[240:243], v[216:219], v[46:49]
	v_mfma_f32_16x16x32_bf16 v[42:45], v[240:243], v[220:223], v[42:45]
	global_load_lds_dwordx4 v[142:143], off
	v_lshl_add_u64 v[142:143], v[142:143], 0, s[2:3]
	s_addk_i32 m0, 0x1000
	v_mfma_f32_16x16x32_bf16 v[38:41], v[240:243], v[224:227], v[38:41]
	v_mfma_f32_16x16x32_bf16 v[34:37], v[240:243], v[228:231], v[34:37]
	v_mfma_f32_16x16x32_bf16 v[30:33], v[244:247], v[200:203], v[30:33]
	global_load_lds_dwordx4 v[142:143], off
	s_addk_i32 m0, 0x1000
	v_lshl_add_u64 v[142:143], v[134:135], 0, s[2:3]
	v_mfma_f32_16x16x32_bf16 v[26:29], v[244:247], v[204:207], v[26:29]
	v_mfma_f32_16x16x32_bf16 v[22:25], v[244:247], v[208:211], v[22:25]
	v_mfma_f32_16x16x32_bf16 v[18:21], v[244:247], v[212:215], v[18:21]
	global_load_lds_dwordx4 v[134:135], off
	s_addk_i32 m0, 0x1000
	v_lshl_add_u64 v[132:133], v[132:133], 0, s[12:13]
	v_mfma_f32_16x16x32_bf16 v[14:17], v[244:247], v[216:219], v[14:17]
	v_mfma_f32_16x16x32_bf16 v[10:13], v[244:247], v[220:223], v[10:13]
	v_mfma_f32_16x16x32_bf16 v[6:9], v[244:247], v[224:227], v[6:9]
	global_load_lds_dwordx4 v[142:143], off
	v_lshl_add_u64 v[134:135], v[134:135], 0, s[4:5]
	v_mfma_f32_16x16x32_bf16 v[2:5], v[244:247], v[228:231], v[2:5]
	s_mov_b32 s41, s40
	s_add_i32 s40, s40, 0x6000
	s_cmp_eq_u32 s40, 0x12000
	s_cselect_b32 s40, 0, s40
	s_sub_i32 s39, s39, 1
	s_cmp_lg_u32 s39, 0
	s_cbranch_scc1 .Lt11_loop
	s_waitcnt vmcnt(6) lgkmcnt(0)
	s_barrier
	v_add_u32_e32 v144, s40, v136
	v_mfma_f32_16x16x32_bf16 v[126:129], v[184:187], v[146:149], v[126:129]
	ds_read_b128 v[200:203], v144 offset:0
	v_mfma_f32_16x16x32_bf16 v[122:125], v[184:187], v[152:155], v[122:125]
	ds_read_b128 v[204:207], v144 offset:1024
	v_mfma_f32_16x16x32_bf16 v[118:121], v[184:187], v[156:159], v[118:121]
	ds_read_b128 v[208:211], v144 offset:2048
	v_mfma_f32_16x16x32_bf16 v[114:117], v[184:187], v[162:165], v[114:117]
	ds_read_b128 v[212:215], v144 offset:3072
	v_mfma_f32_16x16x32_bf16 v[110:113], v[184:187], v[166:169], v[110:113]
	ds_read_b128 v[216:219], v144 offset:4096
	v_mfma_f32_16x16x32_bf16 v[106:109], v[184:187], v[170:173], v[106:109]
	ds_read_b128 v[220:223], v144 offset:5120
	v_mfma_f32_16x16x32_bf16 v[102:105], v[184:187], v[176:179], v[102:105]
	ds_read_b128 v[224:227], v144 offset:6144
	v_mfma_f32_16x16x32_bf16 v[98:101], v[184:187], v[180:183], v[98:101]
	ds_read_b128 v[228:231], v144 offset:7168
	v_mfma_f32_16x16x32_bf16 v[94:97], v[188:191], v[146:149], v[94:97]
	v_add_u32_e32 v144, s40, v137
	v_mfma_f32_16x16x32_bf16 v[90:93], v[188:191], v[152:155], v[90:93]
	v_mfma_f32_16x16x32_bf16 v[86:89], v[188:191], v[156:159], v[86:89]
	ds_read_b128 v[232:235], v144 offset:16384
	v_mfma_f32_16x16x32_bf16 v[82:85], v[188:191], v[162:165], v[82:85]
	ds_read_b128 v[236:239], v144 offset:17408
	v_mfma_f32_16x16x32_bf16 v[78:81], v[188:191], v[166:169], v[78:81]
	ds_read_b128 v[240:243], v144 offset:18432
	v_mfma_f32_16x16x32_bf16 v[74:77], v[188:191], v[170:173], v[74:77]
	ds_read_b128 v[244:247], v144 offset:19456
	s_add_i32 s42, s46, s41
	v_mfma_f32_16x16x32_bf16 v[70:73], v[188:191], v[176:179], v[70:73]
	s_mov_b32 m0, s42
	v_lshl_add_u64 v[142:143], v[132:133], 0, s[2:3]
	v_mfma_f32_16x16x32_bf16 v[66:69], v[188:191], v[180:183], v[66:69]
	global_load_lds_dwordx4 v[132:133], off
	s_addk_i32 m0, 0x1000
	v_mfma_f32_16x16x32_bf16 v[62:65], v[192:195], v[146:149], v[62:65]
;     ...
;   for (int kt = 0; kt < nk; kt++) {
;     if (kt + 1 < nk) asm volatile("s_waitcnt vmcnt(6)" ::: "memory");
;     else asm volatile("s_waitcnt vmcnt(0)" ::: "memory");
;     __builtin_amdgcn_s_barrier();
;     asm volatile("" ::: "memory");
;     if (kt + 2 < nk) G2_STAGE(kt + 2);
;     const char* cS = smem + (kt % 3) * 24576;
;     bf16x8 xa[8], wb[4];
; #pragma unroll
;     for (int f = 0; f < 8; f++) xa[f] = *(const bf16x8*)(cS + aoff + f * 1024);
; #pragma unroll
;     for (int f = 0; f < 4; f++) wb[f] = *(const bf16x8*)(cS + boff + f * 1024);
; #pragma unroll
;     for (int nf = 0; nf < 4; nf++)
; #pragma unroll
;       for (int mf = 0; mf < 8; mf++)
;         acc[nf][mf] = __builtin_amdgcn_mfma_f32_16x16x32_bf16(wb[nf], xa[mf], acc[nf][mf], 0, 0, 0);
;   }
	v_mfma_f32_16x16x32_bf16 v[58:61], v[192:195], v[152:155], v[58:61]
	v_mfma_f32_16x16x32_bf16 v[54:57], v[192:195], v[156:159], v[54:57]
	global_load_lds_dwordx4 v[142:143], off
	v_lshl_add_u64 v[142:143], v[142:143], 0, s[2:3]
	s_addk_i32 m0, 0x1000
	v_mfma_f32_16x16x32_bf16 v[50:53], v[192:195], v[162:165], v[50:53]
	v_mfma_f32_16x16x32_bf16 v[46:49], v[192:195], v[166:169], v[46:49]
	v_mfma_f32_16x16x32_bf16 v[42:45], v[192:195], v[170:173], v[42:45]
	global_load_lds_dwordx4 v[142:143], off
	v_lshl_add_u64 v[142:143], v[142:143], 0, s[2:3]
	s_addk_i32 m0, 0x1000
	v_mfma_f32_16x16x32_bf16 v[38:41], v[192:195], v[176:179], v[38:41]
	v_mfma_f32_16x16x32_bf16 v[34:37], v[192:195], v[180:183], v[34:37]
	v_mfma_f32_16x16x32_bf16 v[30:33], v[196:199], v[146:149], v[30:33]
	global_load_lds_dwordx4 v[142:143], off
	s_addk_i32 m0, 0x1000
	v_lshl_add_u64 v[142:143], v[134:135], 0, s[2:3]
	v_mfma_f32_16x16x32_bf16 v[26:29], v[196:199], v[152:155], v[26:29]
	v_mfma_f32_16x16x32_bf16 v[22:25], v[196:199], v[156:159], v[22:25]
	v_mfma_f32_16x16x32_bf16 v[18:21], v[196:199], v[162:165], v[18:21]
	global_load_lds_dwordx4 v[134:135], off
	s_addk_i32 m0, 0x1000
	v_lshl_add_u64 v[132:133], v[132:133], 0, s[12:13]
	v_mfma_f32_16x16x32_bf16 v[14:17], v[196:199], v[166:169], v[14:17]
	v_mfma_f32_16x16x32_bf16 v[10:13], v[196:199], v[170:173], v[10:13]
	v_mfma_f32_16x16x32_bf16 v[6:9], v[196:199], v[176:179], v[6:9]
	global_load_lds_dwordx4 v[142:143], off
	v_lshl_add_u64 v[134:135], v[134:135], 0, s[4:5]
	v_mfma_f32_16x16x32_bf16 v[2:5], v[196:199], v[180:183], v[2:5]
	s_mov_b32 s41, s40
	s_add_i32 s40, s40, 0x6000
	s_cmp_eq_u32 s40, 0x12000
	s_cselect_b32 s40, 0, s40
	s_waitcnt vmcnt(6) lgkmcnt(0)
	s_barrier
	v_add_u32_e32 v144, s40, v136
	v_mfma_f32_16x16x32_bf16 v[126:129], v[232:235], v[200:203], v[126:129]
	ds_read_b128 v[146:149], v144 offset:0
	v_mfma_f32_16x16x32_bf16 v[122:125], v[232:235], v[204:207], v[122:125]
	ds_read_b128 v[152:155], v144 offset:1024
	v_mfma_f32_16x16x32_bf16 v[118:121], v[232:235], v[208:211], v[118:121]
	ds_read_b128 v[156:159], v144 offset:2048
	v_mfma_f32_16x16x32_bf16 v[114:117], v[232:235], v[212:215], v[114:117]
	ds_read_b128 v[162:165], v144 offset:3072
	v_mfma_f32_16x16x32_bf16 v[110:113], v[232:235], v[216:219], v[110:113]
	ds_read_b128 v[166:169], v144 offset:4096
	v_mfma_f32_16x16x32_bf16 v[106:109], v[232:235], v[220:223], v[106:109]
	ds_read_b128 v[170:173], v144 offset:5120
	v_mfma_f32_16x16x32_bf16 v[102:105], v[232:235], v[224:227], v[102:105]
	ds_read_b128 v[176:179], v144 offset:6144
	v_mfma_f32_16x16x32_bf16 v[98:101], v[232:235], v[228:231], v[98:101]
	ds_read_b128 v[180:183], v144 offset:7168
	v_mfma_f32_16x16x32_bf16 v[94:97], v[236:239], v[200:203], v[94:97]
	v_add_u32_e32 v144, s40, v137
	v_mfma_f32_16x16x32_bf16 v[90:93], v[236:239], v[204:207], v[90:93]
	v_mfma_f32_16x16x32_bf16 v[86:89], v[236:239], v[208:211], v[86:89]
	ds_read_b128 v[184:187], v144 offset:16384
	v_mfma_f32_16x16x32_bf16 v[82:85], v[236:239], v[212:215], v[82:85]
	ds_read_b128 v[188:191], v144 offset:17408
	v_mfma_f32_16x16x32_bf16 v[78:81], v[236:239], v[216:219], v[78:81]
	ds_read_b128 v[192:195], v144 offset:18432
	v_mfma_f32_16x16x32_bf16 v[74:77], v[236:239], v[220:223], v[74:77]
	ds_read_b128 v[196:199], v144 offset:19456
	v_mfma_f32_16x16x32_bf16 v[70:73], v[236:239], v[224:227], v[70:73]
	v_mfma_f32_16x16x32_bf16 v[66:69], v[236:239], v[228:231], v[66:69]
	v_mfma_f32_16x16x32_bf16 v[62:65], v[240:243], v[200:203], v[62:65]
	v_mfma_f32_16x16x32_bf16 v[58:61], v[240:243], v[204:207], v[58:61]
	v_mfma_f32_16x16x32_bf16 v[54:57], v[240:243], v[208:211], v[54:57]
	v_mfma_f32_16x16x32_bf16 v[50:53], v[240:243], v[212:215], v[50:53]
	v_mfma_f32_16x16x32_bf16 v[46:49], v[240:243], v[216:219], v[46:49]
	v_mfma_f32_16x16x32_bf16 v[42:45], v[240:243], v[220:223], v[42:45]
	v_mfma_f32_16x16x32_bf16 v[38:41], v[240:243], v[224:227], v[38:41]
	v_mfma_f32_16x16x32_bf16 v[34:37], v[240:243], v[228:231], v[34:37]
	v_mfma_f32_16x16x32_bf16 v[30:33], v[244:247], v[200:203], v[30:33]
	v_mfma_f32_16x16x32_bf16 v[26:29], v[244:247], v[204:207], v[26:29]
	v_mfma_f32_16x16x32_bf16 v[22:25], v[244:247], v[208:211], v[22:25]
	v_mfma_f32_16x16x32_bf16 v[18:21], v[244:247], v[212:215], v[18:21]
	v_mfma_f32_16x16x32_bf16 v[14:17], v[244:247], v[216:219], v[14:17]
	v_mfma_f32_16x16x32_bf16 v[10:13], v[244:247], v[220:223], v[10:13]
	v_mfma_f32_16x16x32_bf16 v[6:9], v[244:247], v[224:227], v[6:9]
	v_mfma_f32_16x16x32_bf16 v[2:5], v[244:247], v[228:231], v[2:5]
	s_mov_b32 s41, s40
	s_add_i32 s40, s40, 0x6000
	s_cmp_eq_u32 s40, 0x12000
	s_cselect_b32 s40, 0, s40
	s_waitcnt vmcnt(0) lgkmcnt(0)
	s_barrier
; DEVI float blo(unsigned u) { return __uint_as_float(u << 16); }
; DEVI float bhi(unsigned u) { return __uint_as_float(u & 0xffff0000u); }
;     ...
;     for (int f = 0; f < 4; f++) wb[f] = *(const bf16x8*)(cS + boff + f * 1024);
; #pragma unroll
;     for (int nf = 0; nf < 4; nf++)
; #pragma unroll
;       for (int mf = 0; mf < 8; mf++)
;         acc[nf][mf] = __builtin_amdgcn_mfma_f32_16x16x32_bf16(wb[nf], xa[mf], acc[nf][mf], 0, 0, 0);
;     ...
;         const int col = n0 + wn * 64 + nf * 16 + quad * 4;
;         f32x4 a = acc[nf][mf];
;         if (EPI == EPI_RESID || EPI == EPI_RESID_ATOMIC) {
;           f32x4 x = a;
;           if (EPI == EPI_RESID || kpart == 0) {
;             const u32x2 xr = *(const u32x2*)((const u16*)(p.ws + WS_XB) + (size_t)row * 1024 + col);
;             x[0] += ALPHA * blo(xr[0]); x[1] += ALPHA * bhi(xr[0]); x[2] += ALPHA * blo(xr[1]); x[3] += ALPHA * bhi(xr[1]);
;           }
;           if (EPI == EPI_RESID) *(f32x4*)((float*)(p.ws + WS_XF) + (size_t)row * 1024 + col) = x;
	v_add_u32_e32 v144, s40, v136
	v_mfma_f32_16x16x32_bf16 v[126:129], v[184:187], v[146:149], v[126:129]
	ds_read_b128 v[200:203], v144 offset:0
	v_mfma_f32_16x16x32_bf16 v[122:125], v[184:187], v[152:155], v[122:125]
	ds_read_b128 v[204:207], v144 offset:1024
	v_mfma_f32_16x16x32_bf16 v[118:121], v[184:187], v[156:159], v[118:121]
	ds_read_b128 v[208:211], v144 offset:2048
	v_mfma_f32_16x16x32_bf16 v[114:117], v[184:187], v[162:165], v[114:117]
	ds_read_b128 v[212:215], v144 offset:3072
	v_mfma_f32_16x16x32_bf16 v[110:113], v[184:187], v[166:169], v[110:113]
	ds_read_b128 v[216:219], v144 offset:4096
	v_mfma_f32_16x16x32_bf16 v[106:109], v[184:187], v[170:173], v[106:109]
	ds_read_b128 v[220:223], v144 offset:5120
	v_mfma_f32_16x16x32_bf16 v[102:105], v[184:187], v[176:179], v[102:105]
	ds_read_b128 v[224:227], v144 offset:6144
	v_mfma_f32_16x16x32_bf16 v[98:101], v[184:187], v[180:183], v[98:101]
	ds_read_b128 v[228:231], v144 offset:7168
	v_mfma_f32_16x16x32_bf16 v[94:97], v[188:191], v[146:149], v[94:97]
	v_add_u32_e32 v144, s40, v137
	v_mfma_f32_16x16x32_bf16 v[90:93], v[188:191], v[152:155], v[90:93]
	v_mfma_f32_16x16x32_bf16 v[86:89], v[188:191], v[156:159], v[86:89]
	ds_read_b128 v[232:235], v144 offset:16384
	v_mfma_f32_16x16x32_bf16 v[82:85], v[188:191], v[162:165], v[82:85]
	ds_read_b128 v[236:239], v144 offset:17408
	v_mfma_f32_16x16x32_bf16 v[78:81], v[188:191], v[166:169], v[78:81]
	ds_read_b128 v[240:243], v144 offset:18432
	v_mfma_f32_16x16x32_bf16 v[74:77], v[188:191], v[170:173], v[74:77]
	ds_read_b128 v[244:247], v144 offset:19456
	v_mfma_f32_16x16x32_bf16 v[70:73], v[188:191], v[176:179], v[70:73]
	v_mfma_f32_16x16x32_bf16 v[66:69], v[188:191], v[180:183], v[66:69]
	v_mfma_f32_16x16x32_bf16 v[62:65], v[192:195], v[146:149], v[62:65]
	v_mfma_f32_16x16x32_bf16 v[58:61], v[192:195], v[152:155], v[58:61]
	v_mfma_f32_16x16x32_bf16 v[54:57], v[192:195], v[156:159], v[54:57]
	v_mfma_f32_16x16x32_bf16 v[50:53], v[192:195], v[162:165], v[50:53]
	v_mfma_f32_16x16x32_bf16 v[46:49], v[192:195], v[166:169], v[46:49]
	v_mfma_f32_16x16x32_bf16 v[42:45], v[192:195], v[170:173], v[42:45]
	v_mfma_f32_16x16x32_bf16 v[38:41], v[192:195], v[176:179], v[38:41]
	v_mfma_f32_16x16x32_bf16 v[34:37], v[192:195], v[180:183], v[34:37]
	v_mfma_f32_16x16x32_bf16 v[30:33], v[196:199], v[146:149], v[30:33]
	v_mfma_f32_16x16x32_bf16 v[26:29], v[196:199], v[152:155], v[26:29]
	v_mfma_f32_16x16x32_bf16 v[22:25], v[196:199], v[156:159], v[22:25]
	v_mfma_f32_16x16x32_bf16 v[18:21], v[196:199], v[162:165], v[18:21]
	v_mfma_f32_16x16x32_bf16 v[14:17], v[196:199], v[166:169], v[14:17]
	v_mfma_f32_16x16x32_bf16 v[10:13], v[196:199], v[170:173], v[10:13]
	v_mfma_f32_16x16x32_bf16 v[6:9], v[196:199], v[176:179], v[6:9]
	v_mfma_f32_16x16x32_bf16 v[2:5], v[196:199], v[180:183], v[2:5]
	s_mov_b32 s41, s40
	s_add_i32 s40, s40, 0x6000
	s_cmp_eq_u32 s40, 0x12000
	s_cselect_b32 s40, 0, s40
	s_mov_b32 s4, 0x8000
	s_mov_b32 s5, 0
	s_mov_b32 s10, 0x10000
	s_mov_b32 s11, 0
	s_mov_b32 s44, 0x3fd744fd
	s_waitcnt lgkmcnt(0)
	v_mfma_f32_16x16x32_bf16 v[126:129], v[232:235], v[200:203], v[126:129]
	v_mfma_f32_16x16x32_bf16 v[122:125], v[232:235], v[204:207], v[122:125]
	v_mfma_f32_16x16x32_bf16 v[118:121], v[232:235], v[208:211], v[118:121]
	v_mfma_f32_16x16x32_bf16 v[114:117], v[232:235], v[212:215], v[114:117]
	v_mfma_f32_16x16x32_bf16 v[110:113], v[232:235], v[216:219], v[110:113]
	global_load_dwordx2 v[146:147], v[138:139], off offset:0
	v_mfma_f32_16x16x32_bf16 v[106:109], v[232:235], v[220:223], v[106:109]
	global_load_dwordx2 v[148:149], v[138:139], off offset:32
	v_mfma_f32_16x16x32_bf16 v[102:105], v[232:235], v[224:227], v[102:105]
	global_load_dwordx2 v[152:153], v[138:139], off offset:128
	v_mfma_f32_16x16x32_bf16 v[98:101], v[232:235], v[228:231], v[98:101]
	global_load_dwordx2 v[154:155], v[138:139], off offset:160
	v_lshl_add_u64 v[138:139], v[138:139], 0, s[4:5]
	v_mfma_f32_16x16x32_bf16 v[94:97], v[236:239], v[200:203], v[94:97]
	global_load_dwordx2 v[156:157], v[138:139], off offset:0
	v_mfma_f32_16x16x32_bf16 v[90:93], v[236:239], v[204:207], v[90:93]
	global_load_dwordx2 v[158:159], v[138:139], off offset:32
	v_mfma_f32_16x16x32_bf16 v[86:89], v[236:239], v[208:211], v[86:89]
	global_load_dwordx2 v[162:163], v[138:139], off offset:128
	v_mfma_f32_16x16x32_bf16 v[82:85], v[236:239], v[212:215], v[82:85]
	global_load_dwordx2 v[164:165], v[138:139], off offset:160
	v_lshl_add_u64 v[138:139], v[138:139], 0, s[4:5]
	v_mfma_f32_16x16x32_bf16 v[78:81], v[236:239], v[216:219], v[78:81]
	global_load_dwordx2 v[166:167], v[138:139], off offset:0
	v_mfma_f32_16x16x32_bf16 v[74:77], v[236:239], v[220:223], v[74:77]
	global_load_dwordx2 v[168:169], v[138:139], off offset:32
	v_mfma_f32_16x16x32_bf16 v[70:73], v[236:239], v[224:227], v[70:73]
	global_load_dwordx2 v[170:171], v[138:139], off offset:128
	v_mfma_f32_16x16x32_bf16 v[66:69], v[236:239], v[228:231], v[66:69]
	global_load_dwordx2 v[172:173], v[138:139], off offset:160
	v_lshl_add_u64 v[138:139], v[138:139], 0, s[4:5]
	v_mfma_f32_16x16x32_bf16 v[62:65], v[240:243], v[200:203], v[62:65]
	global_load_dwordx2 v[176:177], v[138:139], off offset:0
	v_mfma_f32_16x16x32_bf16 v[58:61], v[240:243], v[204:207], v[58:61]
	global_load_dwordx2 v[178:179], v[138:139], off offset:32
	v_mfma_f32_16x16x32_bf16 v[54:57], v[240:243], v[208:211], v[54:57]
	global_load_dwordx2 v[180:181], v[138:139], off offset:128
	v_mfma_f32_16x16x32_bf16 v[50:53], v[240:243], v[212:215], v[50:53]
	global_load_dwordx2 v[182:183], v[138:139], off offset:160
	v_lshl_add_u64 v[138:139], v[138:139], 0, s[4:5]
	v_mfma_f32_16x16x32_bf16 v[46:49], v[240:243], v[216:219], v[46:49]
; DEVI float blo(unsigned u) { return __uint_as_float(u << 16); }
; DEVI float bhi(unsigned u) { return __uint_as_float(u & 0xffff0000u); }
;     ...
;         const int col = n0 + wn * 64 + nf * 16 + quad * 4;
;         f32x4 a = acc[nf][mf];
;         if (EPI == EPI_RESID || EPI == EPI_RESID_ATOMIC) {
;           f32x4 x = a;
;           if (EPI == EPI_RESID || kpart == 0) {
;             const u32x2 xr = *(const u32x2*)((const u16*)(p.ws + WS_XB) + (size_t)row * 1024 + col);
;             x[0] += ALPHA * blo(xr[0]); x[1] += ALPHA * bhi(xr[0]); x[2] += ALPHA * blo(xr[1]); x[3] += ALPHA * bhi(xr[1]);
;           }
;           if (EPI == EPI_RESID) *(f32x4*)((float*)(p.ws + WS_XF) + (size_t)row * 1024 + col) = x;
	global_load_dwordx2 v[184:185], v[138:139], off offset:0
	v_mfma_f32_16x16x32_bf16 v[42:45], v[240:243], v[220:223], v[42:45]
	global_load_dwordx2 v[186:187], v[138:139], off offset:32
	v_mfma_f32_16x16x32_bf16 v[38:41], v[240:243], v[224:227], v[38:41]
	global_load_dwordx2 v[188:189], v[138:139], off offset:128
	v_mfma_f32_16x16x32_bf16 v[34:37], v[240:243], v[228:231], v[34:37]
	global_load_dwordx2 v[190:191], v[138:139], off offset:160
	v_lshl_add_u64 v[138:139], v[138:139], 0, s[4:5]
	v_mfma_f32_16x16x32_bf16 v[30:33], v[244:247], v[200:203], v[30:33]
	global_load_dwordx2 v[192:193], v[138:139], off offset:0
	v_mfma_f32_16x16x32_bf16 v[26:29], v[244:247], v[204:207], v[26:29]
	global_load_dwordx2 v[194:195], v[138:139], off offset:32
	v_mfma_f32_16x16x32_bf16 v[22:25], v[244:247], v[208:211], v[22:25]
	global_load_dwordx2 v[196:197], v[138:139], off offset:128
	v_mfma_f32_16x16x32_bf16 v[18:21], v[244:247], v[212:215], v[18:21]
	global_load_dwordx2 v[198:199], v[138:139], off offset:160
	v_lshl_add_u64 v[138:139], v[138:139], 0, s[4:5]
	v_mfma_f32_16x16x32_bf16 v[14:17], v[244:247], v[216:219], v[14:17]
	v_mfma_f32_16x16x32_bf16 v[10:13], v[244:247], v[220:223], v[10:13]
	v_mfma_f32_16x16x32_bf16 v[6:9], v[244:247], v[224:227], v[6:9]
	v_mfma_f32_16x16x32_bf16 v[2:5], v[244:247], v[228:231], v[2:5]
	s_mov_b32 m0, s43
	global_load_dwordx2 v[200:201], v[138:139], off offset:0
	global_load_dwordx2 v[202:203], v[138:139], off offset:32
	global_load_dwordx2 v[204:205], v[138:139], off offset:128
	global_load_dwordx2 v[206:207], v[138:139], off offset:160
	v_lshl_add_u64 v[138:139], v[138:139], 0, s[4:5]
	global_load_dwordx2 v[208:209], v[138:139], off offset:0
	global_load_dwordx2 v[210:211], v[138:139], off offset:32
	global_load_dwordx2 v[212:213], v[138:139], off offset:128
	global_load_dwordx2 v[214:215], v[138:139], off offset:160
	v_lshl_add_u64 v[138:139], v[138:139], 0, s[4:5]
	s_nop 7
	s_waitcnt vmcnt(31)
	v_lshlrev_b32_e32 v216, 16, v146
	v_and_b32_e32 v146, 0xffff0000, v146
	v_lshlrev_b32_e32 v217, 16, v147
	v_and_b32_e32 v147, 0xffff0000, v147
	v_fmac_f32_e32 v126, s44, v216
	v_fmac_f32_e32 v127, s44, v146
	v_fmac_f32_e32 v128, s44, v217
	v_fmac_f32_e32 v129, s44, v147
	global_store_dwordx4 v[140:141], v[126:129], off offset:0
	s_waitcnt vmcnt(31)
	v_lshlrev_b32_e32 v216, 16, v148
	v_and_b32_e32 v148, 0xffff0000, v148
	v_lshlrev_b32_e32 v217, 16, v149
	v_and_b32_e32 v149, 0xffff0000, v149
	v_fmac_f32_e32 v94, s44, v216
	v_fmac_f32_e32 v95, s44, v148
	v_fmac_f32_e32 v96, s44, v217
	v_fmac_f32_e32 v97, s44, v149
	global_store_dwordx4 v[140:141], v[94:97], off offset:64
	s_waitcnt vmcnt(31)
	v_lshlrev_b32_e32 v216, 16, v152
	v_and_b32_e32 v152, 0xffff0000, v152
	v_lshlrev_b32_e32 v217, 16, v153
	v_and_b32_e32 v153, 0xffff0000, v153
	v_fmac_f32_e32 v62, s44, v216
	v_fmac_f32_e32 v63, s44, v152
	v_fmac_f32_e32 v64, s44, v217
	v_fmac_f32_e32 v65, s44, v153
	global_store_dwordx4 v[140:141], v[62:65], off offset:128
	s_waitcnt vmcnt(31)
	v_lshlrev_b32_e32 v216, 16, v154
	v_and_b32_e32 v154, 0xffff0000, v154
	v_lshlrev_b32_e32 v217, 16, v155
	v_and_b32_e32 v155, 0xffff0000, v155
	v_fmac_f32_e32 v30, s44, v216
	v_fmac_f32_e32 v31, s44, v154
	v_fmac_f32_e32 v32, s44, v217
	v_fmac_f32_e32 v33, s44, v155
	global_store_dwordx4 v[140:141], v[30:33], off offset:192
	v_lshl_add_u64 v[140:141], v[140:141], 0, s[10:11]
	s_waitcnt vmcnt(31)
	v_lshlrev_b32_e32 v216, 16, v156
	v_and_b32_e32 v156, 0xffff0000, v156
	v_lshlrev_b32_e32 v217, 16, v157
	v_and_b32_e32 v157, 0xffff0000, v157
	v_fmac_f32_e32 v122, s44, v216
	v_fmac_f32_e32 v123, s44, v156
	v_fmac_f32_e32 v124, s44, v217
	v_fmac_f32_e32 v125, s44, v157
	global_store_dwordx4 v[140:141], v[122:125], off offset:0
	s_waitcnt vmcnt(31)
	v_lshlrev_b32_e32 v216, 16, v158
	v_and_b32_e32 v158, 0xffff0000, v158
	v_lshlrev_b32_e32 v217, 16, v159
	v_and_b32_e32 v159, 0xffff0000, v159
	v_fmac_f32_e32 v90, s44, v216
	v_fmac_f32_e32 v91, s44, v158
	v_fmac_f32_e32 v92, s44, v217
	v_fmac_f32_e32 v93, s44, v159
	global_store_dwordx4 v[140:141], v[90:93], off offset:64
	s_waitcnt vmcnt(31)
	v_lshlrev_b32_e32 v216, 16, v162
	v_and_b32_e32 v162, 0xffff0000, v162
	v_lshlrev_b32_e32 v217, 16, v163
	v_and_b32_e32 v163, 0xffff0000, v163
	v_fmac_f32_e32 v58, s44, v216
	v_fmac_f32_e32 v59, s44, v162
	v_fmac_f32_e32 v60, s44, v217
	v_fmac_f32_e32 v61, s44, v163
	global_store_dwordx4 v[140:141], v[58:61], off offset:128
	s_waitcnt vmcnt(31)
	v_lshlrev_b32_e32 v216, 16, v164
	v_and_b32_e32 v164, 0xffff0000, v164
	v_lshlrev_b32_e32 v217, 16, v165
	v_and_b32_e32 v165, 0xffff0000, v165
	v_fmac_f32_e32 v26, s44, v216
	v_fmac_f32_e32 v27, s44, v164
	v_fmac_f32_e32 v28, s44, v217
	v_fmac_f32_e32 v29, s44, v165
	global_store_dwordx4 v[140:141], v[26:29], off offset:192
	v_lshl_add_u64 v[140:141], v[140:141], 0, s[10:11]
	s_waitcnt vmcnt(31)
	v_lshlrev_b32_e32 v216, 16, v166
	v_and_b32_e32 v166, 0xffff0000, v166
	v_lshlrev_b32_e32 v217, 16, v167
	v_and_b32_e32 v167, 0xffff0000, v167
	v_fmac_f32_e32 v118, s44, v216
	v_fmac_f32_e32 v119, s44, v166
	v_fmac_f32_e32 v120, s44, v217
	v_fmac_f32_e32 v121, s44, v167
	global_store_dwordx4 v[140:141], v[118:121], off offset:0
	s_waitcnt vmcnt(31)
	v_lshlrev_b32_e32 v216, 16, v168
	v_and_b32_e32 v168, 0xffff0000, v168
	v_lshlrev_b32_e32 v217, 16, v169
	v_and_b32_e32 v169, 0xffff0000, v169
	v_fmac_f32_e32 v86, s44, v216
	v_fmac_f32_e32 v87, s44, v168
	v_fmac_f32_e32 v88, s44, v217
	v_fmac_f32_e32 v89, s44, v169
	global_store_dwordx4 v[140:141], v[86:89], off offset:64
	s_waitcnt vmcnt(31)
; DEVI float blo(unsigned u) { return __uint_as_float(u << 16); }
; DEVI float bhi(unsigned u) { return __uint_as_float(u & 0xffff0000u); }
;     ...
;         const int col = n0 + wn * 64 + nf * 16 + quad * 4;
;         f32x4 a = acc[nf][mf];
;         if (EPI == EPI_RESID || EPI == EPI_RESID_ATOMIC) {
;           f32x4 x = a;
;           if (EPI == EPI_RESID || kpart == 0) {
;             const u32x2 xr = *(const u32x2*)((const u16*)(p.ws + WS_XB) + (size_t)row * 1024 + col);
;             x[0] += ALPHA * blo(xr[0]); x[1] += ALPHA * bhi(xr[0]); x[2] += ALPHA * blo(xr[1]); x[3] += ALPHA * bhi(xr[1]);
;           }
;           if (EPI == EPI_RESID) *(f32x4*)((float*)(p.ws + WS_XF) + (size_t)row * 1024 + col) = x;
	v_lshlrev_b32_e32 v216, 16, v170
	v_and_b32_e32 v170, 0xffff0000, v170
	v_lshlrev_b32_e32 v217, 16, v171
	v_and_b32_e32 v171, 0xffff0000, v171
	v_fmac_f32_e32 v54, s44, v216
	v_fmac_f32_e32 v55, s44, v170
	v_fmac_f32_e32 v56, s44, v217
	v_fmac_f32_e32 v57, s44, v171
	global_store_dwordx4 v[140:141], v[54:57], off offset:128
	s_waitcnt vmcnt(31)
	v_lshlrev_b32_e32 v216, 16, v172
	v_and_b32_e32 v172, 0xffff0000, v172
	v_lshlrev_b32_e32 v217, 16, v173
	v_and_b32_e32 v173, 0xffff0000, v173
	v_fmac_f32_e32 v22, s44, v216
	v_fmac_f32_e32 v23, s44, v172
	v_fmac_f32_e32 v24, s44, v217
	v_fmac_f32_e32 v25, s44, v173
	global_store_dwordx4 v[140:141], v[22:25], off offset:192
	v_lshl_add_u64 v[140:141], v[140:141], 0, s[10:11]
	s_waitcnt vmcnt(31)
	v_lshlrev_b32_e32 v216, 16, v176
	v_and_b32_e32 v176, 0xffff0000, v176
	v_lshlrev_b32_e32 v217, 16, v177
	v_and_b32_e32 v177, 0xffff0000, v177
	v_fmac_f32_e32 v114, s44, v216
	v_fmac_f32_e32 v115, s44, v176
	v_fmac_f32_e32 v116, s44, v217
	v_fmac_f32_e32 v117, s44, v177
	global_store_dwordx4 v[140:141], v[114:117], off offset:0
	s_waitcnt vmcnt(31)
	v_lshlrev_b32_e32 v216, 16, v178
	v_and_b32_e32 v178, 0xffff0000, v178
	v_lshlrev_b32_e32 v217, 16, v179
	v_and_b32_e32 v179, 0xffff0000, v179
	v_fmac_f32_e32 v82, s44, v216
	v_fmac_f32_e32 v83, s44, v178
	v_fmac_f32_e32 v84, s44, v217
	v_fmac_f32_e32 v85, s44, v179
	global_store_dwordx4 v[140:141], v[82:85], off offset:64
	s_waitcnt vmcnt(31)
	v_lshlrev_b32_e32 v216, 16, v180
	v_and_b32_e32 v180, 0xffff0000, v180
	v_lshlrev_b32_e32 v217, 16, v181
	v_and_b32_e32 v181, 0xffff0000, v181
	v_fmac_f32_e32 v50, s44, v216
	v_fmac_f32_e32 v51, s44, v180
	v_fmac_f32_e32 v52, s44, v217
	v_fmac_f32_e32 v53, s44, v181
	global_store_dwordx4 v[140:141], v[50:53], off offset:128
	s_waitcnt vmcnt(31)
	v_lshlrev_b32_e32 v216, 16, v182
	v_and_b32_e32 v182, 0xffff0000, v182
	v_lshlrev_b32_e32 v217, 16, v183
	v_and_b32_e32 v183, 0xffff0000, v183
	v_fmac_f32_e32 v18, s44, v216
	v_fmac_f32_e32 v19, s44, v182
	v_fmac_f32_e32 v20, s44, v217
	v_fmac_f32_e32 v21, s44, v183
	global_store_dwordx4 v[140:141], v[18:21], off offset:192
	v_lshl_add_u64 v[140:141], v[140:141], 0, s[10:11]
	s_waitcnt vmcnt(31)
	v_lshlrev_b32_e32 v216, 16, v184
	v_and_b32_e32 v184, 0xffff0000, v184
	v_lshlrev_b32_e32 v217, 16, v185
	v_and_b32_e32 v185, 0xffff0000, v185
	v_fmac_f32_e32 v110, s44, v216
	v_fmac_f32_e32 v111, s44, v184
	v_fmac_f32_e32 v112, s44, v217
	v_fmac_f32_e32 v113, s44, v185
	global_store_dwordx4 v[140:141], v[110:113], off offset:0
	s_waitcnt vmcnt(31)
	v_lshlrev_b32_e32 v216, 16, v186
	v_and_b32_e32 v186, 0xffff0000, v186
	v_lshlrev_b32_e32 v217, 16, v187
	v_and_b32_e32 v187, 0xffff0000, v187
	v_fmac_f32_e32 v78, s44, v216
	v_fmac_f32_e32 v79, s44, v186
	v_fmac_f32_e32 v80, s44, v217
	v_fmac_f32_e32 v81, s44, v187
	global_store_dwordx4 v[140:141], v[78:81], off offset:64
	s_waitcnt vmcnt(31)
	v_lshlrev_b32_e32 v216, 16, v188
	v_and_b32_e32 v188, 0xffff0000, v188
	v_lshlrev_b32_e32 v217, 16, v189
	v_and_b32_e32 v189, 0xffff0000, v189
	v_fmac_f32_e32 v46, s44, v216
	v_fmac_f32_e32 v47, s44, v188
	v_fmac_f32_e32 v48, s44, v217
	v_fmac_f32_e32 v49, s44, v189
	global_store_dwordx4 v[140:141], v[46:49], off offset:128
	s_waitcnt vmcnt(31)
	v_lshlrev_b32_e32 v216, 16, v190
	v_and_b32_e32 v190, 0xffff0000, v190
	v_lshlrev_b32_e32 v217, 16, v191
	v_and_b32_e32 v191, 0xffff0000, v191
	v_fmac_f32_e32 v14, s44, v216
	v_fmac_f32_e32 v15, s44, v190
	v_fmac_f32_e32 v16, s44, v217
	v_fmac_f32_e32 v17, s44, v191
	global_store_dwordx4 v[140:141], v[14:17], off offset:192
	v_lshl_add_u64 v[140:141], v[140:141], 0, s[10:11]
	s_waitcnt vmcnt(31)
	v_lshlrev_b32_e32 v216, 16, v192
	v_and_b32_e32 v192, 0xffff0000, v192
	v_lshlrev_b32_e32 v217, 16, v193
	v_and_b32_e32 v193, 0xffff0000, v193
	v_fmac_f32_e32 v106, s44, v216
	v_fmac_f32_e32 v107, s44, v192
	v_fmac_f32_e32 v108, s44, v217
	v_fmac_f32_e32 v109, s44, v193
	global_store_dwordx4 v[140:141], v[106:109], off offset:0
	s_waitcnt vmcnt(31)
; DEVI float blo(unsigned u) { return __uint_as_float(u << 16); }
; DEVI float bhi(unsigned u) { return __uint_as_float(u & 0xffff0000u); }
;     ...
;         const int col = n0 + wn * 64 + nf * 16 + quad * 4;
;         f32x4 a = acc[nf][mf];
;         if (EPI == EPI_RESID || EPI == EPI_RESID_ATOMIC) {
;           f32x4 x = a;
;           if (EPI == EPI_RESID || kpart == 0) {
;             const u32x2 xr = *(const u32x2*)((const u16*)(p.ws + WS_XB) + (size_t)row * 1024 + col);
;             x[0] += ALPHA * blo(xr[0]); x[1] += ALPHA * bhi(xr[0]); x[2] += ALPHA * blo(xr[1]); x[3] += ALPHA * bhi(xr[1]);
;           }
;           if (EPI == EPI_RESID) *(f32x4*)((float*)(p.ws + WS_XF) + (size_t)row * 1024 + col) = x;
	v_lshlrev_b32_e32 v216, 16, v194
	v_and_b32_e32 v194, 0xffff0000, v194
	v_lshlrev_b32_e32 v217, 16, v195
	v_and_b32_e32 v195, 0xffff0000, v195
	v_fmac_f32_e32 v74, s44, v216
	v_fmac_f32_e32 v75, s44, v194
	v_fmac_f32_e32 v76, s44, v217
	v_fmac_f32_e32 v77, s44, v195
	global_store_dwordx4 v[140:141], v[74:77], off offset:64
	s_waitcnt vmcnt(31)
	v_lshlrev_b32_e32 v216, 16, v196
	v_and_b32_e32 v196, 0xffff0000, v196
	v_lshlrev_b32_e32 v217, 16, v197
	v_and_b32_e32 v197, 0xffff0000, v197
	v_fmac_f32_e32 v42, s44, v216
	v_fmac_f32_e32 v43, s44, v196
	v_fmac_f32_e32 v44, s44, v217
	v_fmac_f32_e32 v45, s44, v197
	global_store_dwordx4 v[140:141], v[42:45], off offset:128
	s_waitcnt vmcnt(31)
	v_lshlrev_b32_e32 v216, 16, v198
	v_and_b32_e32 v198, 0xffff0000, v198
	v_lshlrev_b32_e32 v217, 16, v199
	v_and_b32_e32 v199, 0xffff0000, v199
	v_fmac_f32_e32 v10, s44, v216
	v_fmac_f32_e32 v11, s44, v198
	v_fmac_f32_e32 v12, s44, v217
	v_fmac_f32_e32 v13, s44, v199
	global_store_dwordx4 v[140:141], v[10:13], off offset:192
	v_lshl_add_u64 v[140:141], v[140:141], 0, s[10:11]
	s_waitcnt vmcnt(31)
	v_lshlrev_b32_e32 v216, 16, v200
	v_and_b32_e32 v200, 0xffff0000, v200
	v_lshlrev_b32_e32 v217, 16, v201
	v_and_b32_e32 v201, 0xffff0000, v201
	v_fmac_f32_e32 v102, s44, v216
	v_fmac_f32_e32 v103, s44, v200
	v_fmac_f32_e32 v104, s44, v217
	v_fmac_f32_e32 v105, s44, v201
	global_store_dwordx4 v[140:141], v[102:105], off offset:0
	s_waitcnt vmcnt(31)
	v_lshlrev_b32_e32 v216, 16, v202
	v_and_b32_e32 v202, 0xffff0000, v202
	v_lshlrev_b32_e32 v217, 16, v203
	v_and_b32_e32 v203, 0xffff0000, v203
	v_fmac_f32_e32 v70, s44, v216
	v_fmac_f32_e32 v71, s44, v202
	v_fmac_f32_e32 v72, s44, v217
	v_fmac_f32_e32 v73, s44, v203
	global_store_dwordx4 v[140:141], v[70:73], off offset:64
	s_waitcnt vmcnt(31)
	v_lshlrev_b32_e32 v216, 16, v204
	v_and_b32_e32 v204, 0xffff0000, v204
	v_lshlrev_b32_e32 v217, 16, v205
	v_and_b32_e32 v205, 0xffff0000, v205
	v_fmac_f32_e32 v38, s44, v216
	v_fmac_f32_e32 v39, s44, v204
	v_fmac_f32_e32 v40, s44, v217
	v_fmac_f32_e32 v41, s44, v205
	global_store_dwordx4 v[140:141], v[38:41], off offset:128
	s_waitcnt vmcnt(31)
	v_lshlrev_b32_e32 v216, 16, v206
	v_and_b32_e32 v206, 0xffff0000, v206
	v_lshlrev_b32_e32 v217, 16, v207
	v_and_b32_e32 v207, 0xffff0000, v207
	v_fmac_f32_e32 v6, s44, v216
	v_fmac_f32_e32 v7, s44, v206
	v_fmac_f32_e32 v8, s44, v217
	v_fmac_f32_e32 v9, s44, v207
	global_store_dwordx4 v[140:141], v[6:9], off offset:192
	v_lshl_add_u64 v[140:141], v[140:141], 0, s[10:11]
	s_waitcnt vmcnt(31)
	v_lshlrev_b32_e32 v216, 16, v208
	v_and_b32_e32 v208, 0xffff0000, v208
	v_lshlrev_b32_e32 v217, 16, v209
	v_and_b32_e32 v209, 0xffff0000, v209
	v_fmac_f32_e32 v98, s44, v216
	v_fmac_f32_e32 v99, s44, v208
	v_fmac_f32_e32 v100, s44, v217
	v_fmac_f32_e32 v101, s44, v209
	global_store_dwordx4 v[140:141], v[98:101], off offset:0
	s_waitcnt vmcnt(31)
	v_lshlrev_b32_e32 v216, 16, v210
	v_and_b32_e32 v210, 0xffff0000, v210
	v_lshlrev_b32_e32 v217, 16, v211
	v_and_b32_e32 v211, 0xffff0000, v211
	v_fmac_f32_e32 v66, s44, v216
	v_fmac_f32_e32 v67, s44, v210
	v_fmac_f32_e32 v68, s44, v217
	v_fmac_f32_e32 v69, s44, v211
	global_store_dwordx4 v[140:141], v[66:69], off offset:64
	s_waitcnt vmcnt(31)
	v_lshlrev_b32_e32 v216, 16, v212
	v_and_b32_e32 v212, 0xffff0000, v212
	v_lshlrev_b32_e32 v217, 16, v213
	v_and_b32_e32 v213, 0xffff0000, v213
	v_fmac_f32_e32 v34, s44, v216
	v_fmac_f32_e32 v35, s44, v212
	v_fmac_f32_e32 v36, s44, v217
	v_fmac_f32_e32 v37, s44, v213
	global_store_dwordx4 v[140:141], v[34:37], off offset:128
	s_waitcnt vmcnt(31)
	v_lshlrev_b32_e32 v216, 16, v214
	v_and_b32_e32 v214, 0xffff0000, v214
	v_lshlrev_b32_e32 v217, 16, v215
	v_and_b32_e32 v215, 0xffff0000, v215
	v_fmac_f32_e32 v2, s44, v216
	v_fmac_f32_e32 v3, s44, v214
	v_fmac_f32_e32 v4, s44, v217
	v_fmac_f32_e32 v5, s44, v215
	global_store_dwordx4 v[140:141], v[2:5], off offset:192
	s_branch .LBB0_41

; #define LAS __attribute__((address_space(3)))
; DEVI int tidx() { int t = threadIdx.x; asm volatile("" : "+v"(t)); return t; }
;   const int tid = tidx(), lane = tid & 63, wid = tid >> 6;
;   const int wm = wid >> 1, wn = wid & 1, r16 = lane & 15, quad = lane >> 4;
;   f32x4 acc[4][8];
; #pragma unroll
;   for (int i = 0; i < 4; i++)
; #pragma unroll
;     for (int j = 0; j < 8; j++) acc[i][j] = (f32x4){0.f, 0.f, 0.f, 0.f};
;   const int nk = (nk_part < 0) ? (K >> 5) : nk_part;
;   const int lrow = tid >> 2, lpc = tid & 3;
;   const int lch = lpc ^ ((0x78 >> (((lrow >> 2) & 3) * 2)) & 3);
;   const u16* ga = A + (size_t)(m0 + lrow) * lda + kbeg + lch * 8;
;   const u16* gb = Bt + (size_t)(n0 + lrow) * K + kbeg + lch * 8;
;   const size_t ga1 = (size_t)64 * lda, gb1 = (size_t)64 * K;
;   const unsigned lds0 = (unsigned)(uintptr_t)(LAS char*)smem + (unsigned)__builtin_amdgcn_readfirstlane(wid) * 1024u;
; DEVI void tile_coords(int T, int MT, int NT, int& mt, int& nt) {
;   const int full = MT >> 3, band = T / (8 * NT);
;   if (band < full) { const int r = T - band * 8 * NT; nt = r >> 3; mt = band * 8 + (r & 7); }
;   else { const int MB = MT - full * 8; const int r = T - full * 8 * NT; nt = r / MB; mt = full * 8 + r % MB; }
; }
.LBB0_124:
	s_lshr_b32 s41, s8, 5
	s_mul_i32 s41, s41, 187
	s_lshr_b32 s41, s41, 11
	s_cmp_lt_u32 s41, 8
	s_cbranch_scc0 .Lt10_rem
	s_mul_i32 s43, s41, 352
	s_sub_i32 s43, s8, s43
	s_lshr_b32 s38, s43, 3
	s_and_b32 s43, s43, 7
	s_lshl_b32 s41, s41, 3
	s_add_i32 s41, s41, s43
	s_branch .Lt10_crd
.Lt10_rem:
	s_sub_i32 s43, s8, 2816
	s_lshr_b32 s38, s43, 1
	s_and_b32 s43, s43, 1
	s_add_i32 s41, s43, 64
.Lt10_crd:
	s_cmp_lt_u32 s41, 64
	s_cselect_b32 s40, 1, 0
	v_readlane_b32 s2, v250, 5
	v_readlane_b32 s3, v250, 6
	v_readlane_b32 s43, v254, 62
	s_mul_i32 s36, s41, 0x80000
	s_add_u32 s10, s2, s36
	s_addc_u32 s11, s3, 0
	s_add_u32 s10, s10, 0x4200000
	s_addc_u32 s11, s11, 0
	s_mul_i32 s36, s43, 0xb00000
	s_mul_i32 s37, s38, 0x40000
	s_add_i32 s36, s36, s37
	s_add_u32 s12, s2, s36
	s_addc_u32 s13, s3, 0
	s_add_u32 s12, s12, 0x16e00000
	s_addc_u32 s13, s13, 0
	s_movk_i32 s9, 0x78
	v_lshrrev_b32_e32 v0, 2, v145
	v_and_b32_e32 v131, 3, v145
	v_bfe_u32 v136, v145, 4, 2
	v_lshlrev_b32_e32 v136, 1, v136
	v_lshrrev_b32_e64 v136, v136, s9
	v_and_b32_e32 v136, 3, v136
	v_xor_b32_e32 v131, v131, v136
	v_lshlrev_b32_e32 v131, 4, v131
	s_movk_i32 s37, 0x800
	v_mad_u32_u24 v0, v0, s37, v131
	v_bfe_u32 v137, v145, 2, 1
	s_movk_i32 s37, 0x7c0
	v_mul_u32_u24_e32 v136, s37, v137
	v_sub_u32_e32 v136, v0, v136
	v_mov_b32_e32 v137, 0
	v_lshl_add_u64 v[134:135], s[12:13], 0, v[136:137]
	v_bfe_u32 v137, v145, 2, 1
	s_mul_i32 s37, s40, 0x7c0
	v_mul_u32_u24_e32 v136, s37, v137
	v_sub_u32_e32 v0, v0, v136
	s_lshl_b32 s14, s40, 6
	s_add_i32 s14, s14, 64
	s_mov_b32 s15, 0
	v_lshl_add_u64 v[132:133], s[10:11], 0, v[0:1]
	v_bfe_u32 v136, v145, 2, 2
	v_lshlrev_b32_e32 v136, 1, v136
	v_lshrrev_b32_e64 v136, v136, s9
	v_and_b32_e32 v136, 3, v136
	v_bfe_u32 v137, v145, 4, 2
	v_xor_b32_e32 v136, v136, v137
	v_lshlrev_b32_e32 v136, 4, v136
	v_and_b32_e32 v131, 15, v145
	v_lshl_or_b32 v136, v131, 6, v136
	v_bfe_u32 v137, v145, 6, 1
	v_lshl_or_b32 v137, v137, 12, v136
	v_lshrrev_b32_e32 v0, 7, v145
	v_lshl_or_b32 v136, v0, 13, v136
	v_and_b32_e32 v140, 1, v131
	v_lshl_or_b32 v131, v0, 7, v131
	v_bfe_u32 v0, v145, 4, 2
	v_lshlrev_b32_e32 v0, 3, v0
	v_bfe_u32 v141, v145, 6, 1
	s_mul_i32 s36, s41, 0x160000
	s_lshl_b32 s37, s38, 7
	s_lshl_b32 s37, s37, s40
	s_add_i32 s36, s36, s37
	s_add_u32 s12, s2, s36
	s_addc_u32 s13, s3, 0
	s_add_u32 s12, s12, 0xef40000
	s_addc_u32 s13, s13, 0
	s_movk_i32 s37, 5632
	v_mad_u32_u24 v138, v131, s37, v0
	v_lshlrev_b32_e32 v139, 6, v141
	v_lshlrev_b32_e64 v139, s40, v139
	v_add_u32_e32 v138, v138, v139
	s_mul_i32 s37, s40, 5568
	v_mul_u32_u24_e32 v139, s37, v140
	v_sub_u32_e32 v138, v138, v139
	v_mov_b32_e32 v139, 0
	v_lshl_add_u64 v[140:141], s[12:13], 0, v[138:139]
	s_mov_b32 s2, 0x20000
	s_mov_b32 s3, 0
	v_lshrrev_b32_e32 v0, 6, v145
	v_lshlrev_b32_e32 v0, 10, v0
	s_nop 0
	v_readfirstlane_b32 s43, v0
	s_mov_b32 s39, m0
	s_mov_b32 s10, 128
	s_mov_b32 s11, 0
	v_mov_b32_e32 v2, 0
	v_mov_b32_e32 v3, 0
	v_mov_b32_e32 v4, 0
	v_mov_b32_e32 v5, 0
	v_mov_b32_e32 v6, 0
	v_mov_b32_e32 v7, 0
	v_mov_b32_e32 v8, 0
	v_mov_b32_e32 v9, 0
	v_mov_b32_e32 v10, 0
	v_mov_b32_e32 v11, 0
	v_mov_b32_e32 v12, 0
	v_mov_b32_e32 v13, 0
	v_mov_b32_e32 v14, 0
	v_mov_b32_e32 v15, 0
	v_mov_b32_e32 v16, 0
	v_mov_b32_e32 v17, 0
	v_mov_b32_e32 v18, 0
	v_mov_b32_e32 v19, 0
	v_mov_b32_e32 v20, 0
	v_mov_b32_e32 v21, 0
	v_mov_b32_e32 v22, 0
	v_mov_b32_e32 v23, 0
	v_mov_b32_e32 v24, 0
	v_mov_b32_e32 v25, 0
	v_mov_b32_e32 v26, 0
	v_mov_b32_e32 v27, 0
	v_mov_b32_e32 v28, 0
	v_mov_b32_e32 v29, 0
	v_mov_b32_e32 v30, 0
	v_mov_b32_e32 v31, 0
	v_mov_b32_e32 v32, 0
	v_mov_b32_e32 v33, 0
	v_mov_b32_e32 v34, 0
	v_mov_b32_e32 v35, 0
	v_mov_b32_e32 v36, 0
	v_mov_b32_e32 v37, 0
	v_mov_b32_e32 v38, 0
	v_mov_b32_e32 v39, 0
	v_mov_b32_e32 v40, 0
	v_mov_b32_e32 v41, 0
	v_mov_b32_e32 v42, 0
	v_mov_b32_e32 v43, 0
	v_mov_b32_e32 v44, 0
	v_mov_b32_e32 v45, 0
	v_mov_b32_e32 v46, 0
	v_mov_b32_e32 v47, 0
	v_mov_b32_e32 v48, 0
	v_mov_b32_e32 v49, 0
	v_mov_b32_e32 v50, 0
	v_mov_b32_e32 v51, 0
	v_mov_b32_e32 v52, 0
	v_mov_b32_e32 v53, 0
	v_mov_b32_e32 v54, 0
	v_mov_b32_e32 v55, 0
	v_mov_b32_e32 v56, 0
	v_mov_b32_e32 v57, 0
	v_mov_b32_e32 v58, 0
	v_mov_b32_e32 v59, 0
	v_mov_b32_e32 v60, 0
	v_mov_b32_e32 v61, 0
	v_mov_b32_e32 v62, 0
	v_mov_b32_e32 v63, 0
	v_mov_b32_e32 v64, 0
	v_mov_b32_e32 v65, 0
	v_mov_b32_e32 v66, 0
	v_mov_b32_e32 v67, 0
	v_mov_b32_e32 v68, 0
	v_mov_b32_e32 v69, 0
	v_mov_b32_e32 v70, 0
	v_mov_b32_e32 v71, 0
	v_mov_b32_e32 v72, 0
	v_mov_b32_e32 v73, 0
	v_mov_b32_e32 v74, 0
	v_mov_b32_e32 v75, 0
	v_mov_b32_e32 v76, 0
	v_mov_b32_e32 v77, 0
	v_mov_b32_e32 v78, 0
	v_mov_b32_e32 v79, 0
	v_mov_b32_e32 v80, 0
	v_mov_b32_e32 v81, 0
	v_mov_b32_e32 v82, 0
	v_mov_b32_e32 v83, 0
	v_mov_b32_e32 v84, 0
	v_mov_b32_e32 v85, 0
	v_mov_b32_e32 v86, 0
	v_mov_b32_e32 v87, 0
	v_mov_b32_e32 v88, 0
	v_mov_b32_e32 v89, 0
	v_mov_b32_e32 v90, 0
	v_mov_b32_e32 v91, 0
	v_mov_b32_e32 v92, 0
	v_mov_b32_e32 v93, 0
	v_mov_b32_e32 v94, 0
	v_mov_b32_e32 v95, 0
	v_mov_b32_e32 v96, 0
	v_mov_b32_e32 v97, 0
	v_mov_b32_e32 v98, 0
	v_mov_b32_e32 v99, 0
	v_mov_b32_e32 v100, 0
	v_mov_b32_e32 v101, 0
	v_mov_b32_e32 v102, 0
	v_mov_b32_e32 v103, 0
	v_mov_b32_e32 v104, 0
	v_mov_b32_e32 v105, 0
	v_mov_b32_e32 v106, 0
	v_mov_b32_e32 v107, 0
	v_mov_b32_e32 v108, 0
	v_mov_b32_e32 v109, 0
	v_mov_b32_e32 v110, 0
	v_mov_b32_e32 v111, 0
	v_mov_b32_e32 v112, 0
	v_mov_b32_e32 v113, 0
	v_mov_b32_e32 v114, 0
	v_mov_b32_e32 v115, 0
	v_mov_b32_e32 v116, 0
	v_mov_b32_e32 v117, 0
	v_mov_b32_e32 v118, 0
	v_mov_b32_e32 v119, 0
	v_mov_b32_e32 v120, 0
	v_mov_b32_e32 v121, 0
	v_mov_b32_e32 v122, 0
	v_mov_b32_e32 v123, 0
	v_mov_b32_e32 v124, 0
	v_mov_b32_e32 v125, 0
	v_mov_b32_e32 v126, 0
	v_mov_b32_e32 v127, 0
	v_mov_b32_e32 v128, 0
	v_mov_b32_e32 v129, 0
	s_barrier
;     ...
;   __syncthreads();
;   G2_STAGE(0); G2_STAGE(1);
;   const int fsw = (0x78 >> (((r16 >> 2) & 3) * 2)) & 3;
;   const int aoff = (wm * 128 + r16) * 64 + ((quad ^ fsw) << 4);
;   const int boff = 16384 + (wn * 64 + r16) * 64 + ((quad ^ fsw) << 4);
;   for (int kt = 0; kt < nk; kt++) {
;     if (kt + 1 < nk) asm volatile("s_waitcnt vmcnt(6)" ::: "memory");
;     else asm volatile("s_waitcnt vmcnt(0)" ::: "memory");
;     __builtin_amdgcn_s_barrier();
;     asm volatile("" ::: "memory");
;     if (kt + 2 < nk) G2_STAGE(kt + 2);
;     const char* cS = smem + (kt % 3) * 24576;
;     bf16x8 xa[8], wb[4];
; #pragma unroll
;     for (int f = 0; f < 8; f++) xa[f] = *(const bf16x8*)(cS + aoff + f * 1024);
; #pragma unroll
;     for (int f = 0; f < 4; f++) wb[f] = *(const bf16x8*)(cS + boff + f * 1024);
; #pragma unroll
;     for (int nf = 0; nf < 4; nf++)
; #pragma unroll
;       for (int mf = 0; mf < 8; mf++)
;         acc[nf][mf] = __builtin_amdgcn_mfma_f32_16x16x32_bf16(wb[nf], xa[mf], acc[nf][mf], 0, 0, 0);
;   }
	s_add_i32 s38, s43, 0x0
	s_mov_b32 m0, s38
	v_lshl_add_u64 v[142:143], v[132:133], 0, s[2:3]
	global_load_lds_dwordx4 v[132:133], off
	s_addk_i32 m0, 0x1000
	s_nop 0
	global_load_lds_dwordx4 v[142:143], off
	v_lshl_add_u64 v[142:143], v[142:143], 0, s[2:3]
	s_addk_i32 m0, 0x1000
	s_nop 0
	global_load_lds_dwordx4 v[142:143], off
	v_lshl_add_u64 v[142:143], v[142:143], 0, s[2:3]
	s_addk_i32 m0, 0x1000
	s_nop 0
	global_load_lds_dwordx4 v[142:143], off
	s_addk_i32 m0, 0x1000
	v_lshl_add_u64 v[142:143], v[134:135], 0, s[2:3]
	s_nop 0
	global_load_lds_dwordx4 v[134:135], off
	s_addk_i32 m0, 0x1000
	v_lshl_add_u64 v[132:133], v[132:133], 0, s[14:15]
	s_nop 0
	global_load_lds_dwordx4 v[142:143], off
	v_lshl_add_u64 v[134:135], v[134:135], 0, s[10:11]
	s_nop 0
	s_add_i32 s38, s43, 0x6000
	s_mov_b32 m0, s38
	v_lshl_add_u64 v[142:143], v[132:133], 0, s[2:3]
	global_load_lds_dwordx4 v[132:133], off
	s_addk_i32 m0, 0x1000
	s_nop 0
	global_load_lds_dwordx4 v[142:143], off
	v_lshl_add_u64 v[142:143], v[142:143], 0, s[2:3]
	s_addk_i32 m0, 0x1000
	s_nop 0
	global_load_lds_dwordx4 v[142:143], off
	v_lshl_add_u64 v[142:143], v[142:143], 0, s[2:3]
	s_addk_i32 m0, 0x1000
	s_nop 0
	global_load_lds_dwordx4 v[142:143], off
	s_addk_i32 m0, 0x1000
	v_lshl_add_u64 v[142:143], v[134:135], 0, s[2:3]
	s_nop 0
	global_load_lds_dwordx4 v[134:135], off
	s_addk_i32 m0, 0x1000
	v_lshl_add_u64 v[132:133], v[132:133], 0, s[14:15]
	s_nop 0
	global_load_lds_dwordx4 v[142:143], off
	v_lshl_add_u64 v[134:135], v[134:135], 0, s[10:11]
	s_nop 0
	s_add_i32 s38, s43, 0xc000
	s_mov_b32 m0, s38
	v_lshl_add_u64 v[142:143], v[132:133], 0, s[2:3]
	global_load_lds_dwordx4 v[132:133], off
	s_addk_i32 m0, 0x1000
	s_nop 0
	global_load_lds_dwordx4 v[142:143], off
	v_lshl_add_u64 v[142:143], v[142:143], 0, s[2:3]
	s_addk_i32 m0, 0x1000
	s_nop 0
	global_load_lds_dwordx4 v[142:143], off
	v_lshl_add_u64 v[142:143], v[142:143], 0, s[2:3]
	s_addk_i32 m0, 0x1000
	s_nop 0
	global_load_lds_dwordx4 v[142:143], off
	s_addk_i32 m0, 0x1000
	v_lshl_add_u64 v[142:143], v[134:135], 0, s[2:3]
	s_nop 0
	global_load_lds_dwordx4 v[134:135], off
	s_addk_i32 m0, 0x1000
	v_lshl_add_u64 v[132:133], v[132:133], 0, s[14:15]
	s_nop 0
	global_load_lds_dwordx4 v[142:143], off
	v_lshl_add_u64 v[134:135], v[134:135], 0, s[10:11]
	s_nop 0
	s_waitcnt vmcnt(12)
	s_barrier
	ds_read_b128 v[146:149], v136 offset:0
	ds_read_b128 v[152:155], v136 offset:1024
	ds_read_b128 v[156:159], v136 offset:2048
	ds_read_b128 v[162:165], v136 offset:3072
	ds_read_b128 v[166:169], v136 offset:4096
	ds_read_b128 v[170:173], v136 offset:5120
	ds_read_b128 v[176:179], v136 offset:6144
	ds_read_b128 v[180:183], v136 offset:7168
	ds_read_b128 v[184:187], v137 offset:16384
	ds_read_b128 v[188:191], v137 offset:17408
	ds_read_b128 v[192:195], v137 offset:18432
	ds_read_b128 v[196:199], v137 offset:19456
	s_movk_i32 s36, 0x6000
	s_mov_b32 s37, 0
	s_movk_i32 s9, 14
.Lt10_loop:
	s_waitcnt vmcnt(6) lgkmcnt(0)
	s_barrier
	v_add_u32_e32 v144, s36, v136
	v_mfma_f32_16x16x32_bf16 v[126:129], v[184:187], v[146:149], v[126:129]
	ds_read_b128 v[200:203], v144 offset:0
	v_mfma_f32_16x16x32_bf16 v[122:125], v[184:187], v[152:155], v[122:125]
	ds_read_b128 v[204:207], v144 offset:1024
	v_mfma_f32_16x16x32_bf16 v[118:121], v[184:187], v[156:159], v[118:121]
	ds_read_b128 v[208:211], v144 offset:2048
	v_mfma_f32_16x16x32_bf16 v[114:117], v[184:187], v[162:165], v[114:117]
	ds_read_b128 v[212:215], v144 offset:3072
	v_mfma_f32_16x16x32_bf16 v[110:113], v[184:187], v[166:169], v[110:113]
	ds_read_b128 v[216:219], v144 offset:4096
	v_mfma_f32_16x16x32_bf16 v[106:109], v[184:187], v[170:173], v[106:109]
	ds_read_b128 v[220:223], v144 offset:5120
	v_mfma_f32_16x16x32_bf16 v[102:105], v[184:187], v[176:179], v[102:105]
	ds_read_b128 v[224:227], v144 offset:6144
	v_mfma_f32_16x16x32_bf16 v[98:101], v[184:187], v[180:183], v[98:101]
	ds_read_b128 v[228:231], v144 offset:7168
	v_mfma_f32_16x16x32_bf16 v[94:97], v[188:191], v[146:149], v[94:97]
	v_add_u32_e32 v144, s36, v137
	v_mfma_f32_16x16x32_bf16 v[90:93], v[188:191], v[152:155], v[90:93]
	v_mfma_f32_16x16x32_bf16 v[86:89], v[188:191], v[156:159], v[86:89]
	ds_read_b128 v[232:235], v144 offset:16384
	v_mfma_f32_16x16x32_bf16 v[82:85], v[188:191], v[162:165], v[82:85]
	ds_read_b128 v[236:239], v144 offset:17408
	v_mfma_f32_16x16x32_bf16 v[78:81], v[188:191], v[166:169], v[78:81]
	ds_read_b128 v[240:243], v144 offset:18432
	v_mfma_f32_16x16x32_bf16 v[74:77], v[188:191], v[170:173], v[74:77]
	ds_read_b128 v[244:247], v144 offset:19456
	s_add_i32 s38, s43, s37
	v_mfma_f32_16x16x32_bf16 v[70:73], v[188:191], v[176:179], v[70:73]
	s_mov_b32 m0, s38
	v_lshl_add_u64 v[142:143], v[132:133], 0, s[2:3]
	v_mfma_f32_16x16x32_bf16 v[66:69], v[188:191], v[180:183], v[66:69]
	global_load_lds_dwordx4 v[132:133], off
	s_addk_i32 m0, 0x1000
	v_mfma_f32_16x16x32_bf16 v[62:65], v[192:195], v[146:149], v[62:65]
	v_mfma_f32_16x16x32_bf16 v[58:61], v[192:195], v[152:155], v[58:61]
	v_mfma_f32_16x16x32_bf16 v[54:57], v[192:195], v[156:159], v[54:57]
	global_load_lds_dwordx4 v[142:143], off
	v_lshl_add_u64 v[142:143], v[142:143], 0, s[2:3]
	s_addk_i32 m0, 0x1000
	v_mfma_f32_16x16x32_bf16 v[50:53], v[192:195], v[162:165], v[50:53]
	v_mfma_f32_16x16x32_bf16 v[46:49], v[192:195], v[166:169], v[46:49]
	v_mfma_f32_16x16x32_bf16 v[42:45], v[192:195], v[170:173], v[42:45]
	global_load_lds_dwordx4 v[142:143], off
	v_lshl_add_u64 v[142:143], v[142:143], 0, s[2:3]
	s_addk_i32 m0, 0x1000
	v_mfma_f32_16x16x32_bf16 v[38:41], v[192:195], v[176:179], v[38:41]
	v_mfma_f32_16x16x32_bf16 v[34:37], v[192:195], v[180:183], v[34:37]
	v_mfma_f32_16x16x32_bf16 v[30:33], v[196:199], v[146:149], v[30:33]
	global_load_lds_dwordx4 v[142:143], off
	s_addk_i32 m0, 0x1000
	v_lshl_add_u64 v[142:143], v[134:135], 0, s[2:3]
	v_mfma_f32_16x16x32_bf16 v[26:29], v[196:199], v[152:155], v[26:29]
	v_mfma_f32_16x16x32_bf16 v[22:25], v[196:199], v[156:159], v[22:25]
	v_mfma_f32_16x16x32_bf16 v[18:21], v[196:199], v[162:165], v[18:21]
	global_load_lds_dwordx4 v[134:135], off
	s_addk_i32 m0, 0x1000
	v_lshl_add_u64 v[132:133], v[132:133], 0, s[14:15]
	v_mfma_f32_16x16x32_bf16 v[14:17], v[196:199], v[166:169], v[14:17]
	v_mfma_f32_16x16x32_bf16 v[10:13], v[196:199], v[170:173], v[10:13]
	v_mfma_f32_16x16x32_bf16 v[6:9], v[196:199], v[176:179], v[6:9]
	global_load_lds_dwordx4 v[142:143], off
	v_lshl_add_u64 v[134:135], v[134:135], 0, s[10:11]
	v_mfma_f32_16x16x32_bf16 v[2:5], v[196:199], v[180:183], v[2:5]
	s_mov_b32 s37, s36
	s_add_i32 s36, s36, 0x6000
	s_cmp_eq_u32 s36, 0x12000
	s_cselect_b32 s36, 0, s36
	s_waitcnt vmcnt(6) lgkmcnt(0)
	s_barrier
;     ...
;   for (int kt = 0; kt < nk; kt++) {
;     if (kt + 1 < nk) asm volatile("s_waitcnt vmcnt(6)" ::: "memory");
;     else asm volatile("s_waitcnt vmcnt(0)" ::: "memory");
;     __builtin_amdgcn_s_barrier();
;     asm volatile("" ::: "memory");
;     if (kt + 2 < nk) G2_STAGE(kt + 2);
;     const char* cS = smem + (kt % 3) * 24576;
;     bf16x8 xa[8], wb[4];
; #pragma unroll
;     for (int f = 0; f < 8; f++) xa[f] = *(const bf16x8*)(cS + aoff + f * 1024);
; #pragma unroll
;     for (int f = 0; f < 4; f++) wb[f] = *(const bf16x8*)(cS + boff + f * 1024);
; #pragma unroll
;     for (int nf = 0; nf < 4; nf++)
; #pragma unroll
;       for (int mf = 0; mf < 8; mf++)
;         acc[nf][mf] = __builtin_amdgcn_mfma_f32_16x16x32_bf16(wb[nf], xa[mf], acc[nf][mf], 0, 0, 0);
;   }
	v_add_u32_e32 v144, s36, v136
	v_mfma_f32_16x16x32_bf16 v[126:129], v[232:235], v[200:203], v[126:129]
	ds_read_b128 v[146:149], v144 offset:0
	v_mfma_f32_16x16x32_bf16 v[122:125], v[232:235], v[204:207], v[122:125]
	ds_read_b128 v[152:155], v144 offset:1024
	v_mfma_f32_16x16x32_bf16 v[118:121], v[232:235], v[208:211], v[118:121]
	ds_read_b128 v[156:159], v144 offset:2048
	v_mfma_f32_16x16x32_bf16 v[114:117], v[232:235], v[212:215], v[114:117]
	ds_read_b128 v[162:165], v144 offset:3072
	v_mfma_f32_16x16x32_bf16 v[110:113], v[232:235], v[216:219], v[110:113]
	ds_read_b128 v[166:169], v144 offset:4096
	v_mfma_f32_16x16x32_bf16 v[106:109], v[232:235], v[220:223], v[106:109]
	ds_read_b128 v[170:173], v144 offset:5120
	v_mfma_f32_16x16x32_bf16 v[102:105], v[232:235], v[224:227], v[102:105]
	ds_read_b128 v[176:179], v144 offset:6144
	v_mfma_f32_16x16x32_bf16 v[98:101], v[232:235], v[228:231], v[98:101]
	ds_read_b128 v[180:183], v144 offset:7168
	v_mfma_f32_16x16x32_bf16 v[94:97], v[236:239], v[200:203], v[94:97]
	v_add_u32_e32 v144, s36, v137
	v_mfma_f32_16x16x32_bf16 v[90:93], v[236:239], v[204:207], v[90:93]
	v_mfma_f32_16x16x32_bf16 v[86:89], v[236:239], v[208:211], v[86:89]
	ds_read_b128 v[184:187], v144 offset:16384
	v_mfma_f32_16x16x32_bf16 v[82:85], v[236:239], v[212:215], v[82:85]
	ds_read_b128 v[188:191], v144 offset:17408
	v_mfma_f32_16x16x32_bf16 v[78:81], v[236:239], v[216:219], v[78:81]
	ds_read_b128 v[192:195], v144 offset:18432
	v_mfma_f32_16x16x32_bf16 v[74:77], v[236:239], v[220:223], v[74:77]
	ds_read_b128 v[196:199], v144 offset:19456
	s_add_i32 s38, s43, s37
	v_mfma_f32_16x16x32_bf16 v[70:73], v[236:239], v[224:227], v[70:73]
	s_mov_b32 m0, s38
	v_lshl_add_u64 v[142:143], v[132:133], 0, s[2:3]
	v_mfma_f32_16x16x32_bf16 v[66:69], v[236:239], v[228:231], v[66:69]
	global_load_lds_dwordx4 v[132:133], off
	s_addk_i32 m0, 0x1000
	v_mfma_f32_16x16x32_bf16 v[62:65], v[240:243], v[200:203], v[62:65]
	v_mfma_f32_16x16x32_bf16 v[58:61], v[240:243], v[204:207], v[58:61]
	v_mfma_f32_16x16x32_bf16 v[54:57], v[240:243], v[208:211], v[54:57]
	global_load_lds_dwordx4 v[142:143], off
	v_lshl_add_u64 v[142:143], v[142:143], 0, s[2:3]
	s_addk_i32 m0, 0x1000
	v_mfma_f32_16x16x32_bf16 v[50:53], v[240:243], v[212:215], v[50:53]
	v_mfma_f32_16x16x32_bf16 v[46:49], v[240:243], v[216:219], v[46:49]
	v_mfma_f32_16x16x32_bf16 v[42:45], v[240:243], v[220:223], v[42:45]
	global_load_lds_dwordx4 v[142:143], off
	v_lshl_add_u64 v[142:143], v[142:143], 0, s[2:3]
	s_addk_i32 m0, 0x1000
	v_mfma_f32_16x16x32_bf16 v[38:41], v[240:243], v[224:227], v[38:41]
	v_mfma_f32_16x16x32_bf16 v[34:37], v[240:243], v[228:231], v[34:37]
	v_mfma_f32_16x16x32_bf16 v[30:33], v[244:247], v[200:203], v[30:33]
	global_load_lds_dwordx4 v[142:143], off
	s_addk_i32 m0, 0x1000
	v_lshl_add_u64 v[142:143], v[134:135], 0, s[2:3]
	v_mfma_f32_16x16x32_bf16 v[26:29], v[244:247], v[204:207], v[26:29]
	v_mfma_f32_16x16x32_bf16 v[22:25], v[244:247], v[208:211], v[22:25]
	v_mfma_f32_16x16x32_bf16 v[18:21], v[244:247], v[212:215], v[18:21]
	global_load_lds_dwordx4 v[134:135], off
	s_addk_i32 m0, 0x1000
	v_lshl_add_u64 v[132:133], v[132:133], 0, s[14:15]
	v_mfma_f32_16x16x32_bf16 v[14:17], v[244:247], v[216:219], v[14:17]
	v_mfma_f32_16x16x32_bf16 v[10:13], v[244:247], v[220:223], v[10:13]
	v_mfma_f32_16x16x32_bf16 v[6:9], v[244:247], v[224:227], v[6:9]
	global_load_lds_dwordx4 v[142:143], off
	v_lshl_add_u64 v[134:135], v[134:135], 0, s[10:11]
	v_mfma_f32_16x16x32_bf16 v[2:5], v[244:247], v[228:231], v[2:5]
	s_mov_b32 s37, s36
	s_add_i32 s36, s36, 0x6000
	s_cmp_eq_u32 s36, 0x12000
	s_cselect_b32 s36, 0, s36
	s_sub_i32 s9, s9, 1
	s_cmp_lg_u32 s9, 0
	s_cbranch_scc1 .Lt10_loop
	s_waitcnt vmcnt(6) lgkmcnt(0)
	s_barrier
	v_add_u32_e32 v144, s36, v136
	v_mfma_f32_16x16x32_bf16 v[126:129], v[184:187], v[146:149], v[126:129]
	ds_read_b128 v[200:203], v144 offset:0
	v_mfma_f32_16x16x32_bf16 v[122:125], v[184:187], v[152:155], v[122:125]
	ds_read_b128 v[204:207], v144 offset:1024
	v_mfma_f32_16x16x32_bf16 v[118:121], v[184:187], v[156:159], v[118:121]
	ds_read_b128 v[208:211], v144 offset:2048
	v_mfma_f32_16x16x32_bf16 v[114:117], v[184:187], v[162:165], v[114:117]
	ds_read_b128 v[212:215], v144 offset:3072
	v_mfma_f32_16x16x32_bf16 v[110:113], v[184:187], v[166:169], v[110:113]
	ds_read_b128 v[216:219], v144 offset:4096
	v_mfma_f32_16x16x32_bf16 v[106:109], v[184:187], v[170:173], v[106:109]
	ds_read_b128 v[220:223], v144 offset:5120
	v_mfma_f32_16x16x32_bf16 v[102:105], v[184:187], v[176:179], v[102:105]
	ds_read_b128 v[224:227], v144 offset:6144
	v_mfma_f32_16x16x32_bf16 v[98:101], v[184:187], v[180:183], v[98:101]
	ds_read_b128 v[228:231], v144 offset:7168
	v_mfma_f32_16x16x32_bf16 v[94:97], v[188:191], v[146:149], v[94:97]
	v_add_u32_e32 v144, s36, v137
	v_mfma_f32_16x16x32_bf16 v[90:93], v[188:191], v[152:155], v[90:93]
	v_mfma_f32_16x16x32_bf16 v[86:89], v[188:191], v[156:159], v[86:89]
	ds_read_b128 v[232:235], v144 offset:16384
	v_mfma_f32_16x16x32_bf16 v[82:85], v[188:191], v[162:165], v[82:85]
	ds_read_b128 v[236:239], v144 offset:17408
	v_mfma_f32_16x16x32_bf16 v[78:81], v[188:191], v[166:169], v[78:81]
	ds_read_b128 v[240:243], v144 offset:18432
	v_mfma_f32_16x16x32_bf16 v[74:77], v[188:191], v[170:173], v[74:77]
	ds_read_b128 v[244:247], v144 offset:19456
	s_add_i32 s38, s43, s37
	v_mfma_f32_16x16x32_bf16 v[70:73], v[188:191], v[176:179], v[70:73]
	s_mov_b32 m0, s38
	v_lshl_add_u64 v[142:143], v[132:133], 0, s[2:3]
	v_mfma_f32_16x16x32_bf16 v[66:69], v[188:191], v[180:183], v[66:69]
	global_load_lds_dwordx4 v[132:133], off
	s_addk_i32 m0, 0x1000
	v_mfma_f32_16x16x32_bf16 v[62:65], v[192:195], v[146:149], v[62:65]
;     ...
;   for (int kt = 0; kt < nk; kt++) {
;     if (kt + 1 < nk) asm volatile("s_waitcnt vmcnt(6)" ::: "memory");
;     else asm volatile("s_waitcnt vmcnt(0)" ::: "memory");
;     __builtin_amdgcn_s_barrier();
;     asm volatile("" ::: "memory");
;     if (kt + 2 < nk) G2_STAGE(kt + 2);
;     const char* cS = smem + (kt % 3) * 24576;
;     bf16x8 xa[8], wb[4];
; #pragma unroll
;     for (int f = 0; f < 8; f++) xa[f] = *(const bf16x8*)(cS + aoff + f * 1024);
; #pragma unroll
;     for (int f = 0; f < 4; f++) wb[f] = *(const bf16x8*)(cS + boff + f * 1024);
; #pragma unroll
;     for (int nf = 0; nf < 4; nf++)
; #pragma unroll
;       for (int mf = 0; mf < 8; mf++)
;         acc[nf][mf] = __builtin_amdgcn_mfma_f32_16x16x32_bf16(wb[nf], xa[mf], acc[nf][mf], 0, 0, 0);
;   }
	v_mfma_f32_16x16x32_bf16 v[58:61], v[192:195], v[152:155], v[58:61]
	v_mfma_f32_16x16x32_bf16 v[54:57], v[192:195], v[156:159], v[54:57]
	global_load_lds_dwordx4 v[142:143], off
	v_lshl_add_u64 v[142:143], v[142:143], 0, s[2:3]
	s_addk_i32 m0, 0x1000
	v_mfma_f32_16x16x32_bf16 v[50:53], v[192:195], v[162:165], v[50:53]
	v_mfma_f32_16x16x32_bf16 v[46:49], v[192:195], v[166:169], v[46:49]
	v_mfma_f32_16x16x32_bf16 v[42:45], v[192:195], v[170:173], v[42:45]
	global_load_lds_dwordx4 v[142:143], off
	v_lshl_add_u64 v[142:143], v[142:143], 0, s[2:3]
	s_addk_i32 m0, 0x1000
	v_mfma_f32_16x16x32_bf16 v[38:41], v[192:195], v[176:179], v[38:41]
	v_mfma_f32_16x16x32_bf16 v[34:37], v[192:195], v[180:183], v[34:37]
	v_mfma_f32_16x16x32_bf16 v[30:33], v[196:199], v[146:149], v[30:33]
	global_load_lds_dwordx4 v[142:143], off
	s_addk_i32 m0, 0x1000
	v_lshl_add_u64 v[142:143], v[134:135], 0, s[2:3]
	v_mfma_f32_16x16x32_bf16 v[26:29], v[196:199], v[152:155], v[26:29]
	v_mfma_f32_16x16x32_bf16 v[22:25], v[196:199], v[156:159], v[22:25]
	v_mfma_f32_16x16x32_bf16 v[18:21], v[196:199], v[162:165], v[18:21]
	global_load_lds_dwordx4 v[134:135], off
	s_addk_i32 m0, 0x1000
	v_lshl_add_u64 v[132:133], v[132:133], 0, s[14:15]
	v_mfma_f32_16x16x32_bf16 v[14:17], v[196:199], v[166:169], v[14:17]
	v_mfma_f32_16x16x32_bf16 v[10:13], v[196:199], v[170:173], v[10:13]
	v_mfma_f32_16x16x32_bf16 v[6:9], v[196:199], v[176:179], v[6:9]
	global_load_lds_dwordx4 v[142:143], off
	v_lshl_add_u64 v[134:135], v[134:135], 0, s[10:11]
	v_mfma_f32_16x16x32_bf16 v[2:5], v[196:199], v[180:183], v[2:5]
	s_mov_b32 s37, s36
	s_add_i32 s36, s36, 0x6000
	s_cmp_eq_u32 s36, 0x12000
	s_cselect_b32 s36, 0, s36
	s_waitcnt vmcnt(6) lgkmcnt(0)
	s_barrier
	v_add_u32_e32 v144, s36, v136
	v_mfma_f32_16x16x32_bf16 v[126:129], v[232:235], v[200:203], v[126:129]
	ds_read_b128 v[146:149], v144 offset:0
	v_mfma_f32_16x16x32_bf16 v[122:125], v[232:235], v[204:207], v[122:125]
	ds_read_b128 v[152:155], v144 offset:1024
	v_mfma_f32_16x16x32_bf16 v[118:121], v[232:235], v[208:211], v[118:121]
	ds_read_b128 v[156:159], v144 offset:2048
	v_mfma_f32_16x16x32_bf16 v[114:117], v[232:235], v[212:215], v[114:117]
	ds_read_b128 v[162:165], v144 offset:3072
	v_mfma_f32_16x16x32_bf16 v[110:113], v[232:235], v[216:219], v[110:113]
	ds_read_b128 v[166:169], v144 offset:4096
	v_mfma_f32_16x16x32_bf16 v[106:109], v[232:235], v[220:223], v[106:109]
	ds_read_b128 v[170:173], v144 offset:5120
	v_mfma_f32_16x16x32_bf16 v[102:105], v[232:235], v[224:227], v[102:105]
	ds_read_b128 v[176:179], v144 offset:6144
	v_mfma_f32_16x16x32_bf16 v[98:101], v[232:235], v[228:231], v[98:101]
	ds_read_b128 v[180:183], v144 offset:7168
	v_mfma_f32_16x16x32_bf16 v[94:97], v[236:239], v[200:203], v[94:97]
	v_add_u32_e32 v144, s36, v137
	v_mfma_f32_16x16x32_bf16 v[90:93], v[236:239], v[204:207], v[90:93]
	v_mfma_f32_16x16x32_bf16 v[86:89], v[236:239], v[208:211], v[86:89]
	ds_read_b128 v[184:187], v144 offset:16384
	v_mfma_f32_16x16x32_bf16 v[82:85], v[236:239], v[212:215], v[82:85]
	ds_read_b128 v[188:191], v144 offset:17408
	v_mfma_f32_16x16x32_bf16 v[78:81], v[236:239], v[216:219], v[78:81]
	ds_read_b128 v[192:195], v144 offset:18432
	v_mfma_f32_16x16x32_bf16 v[74:77], v[236:239], v[220:223], v[74:77]
	ds_read_b128 v[196:199], v144 offset:19456
	v_mfma_f32_16x16x32_bf16 v[70:73], v[236:239], v[224:227], v[70:73]
	v_mfma_f32_16x16x32_bf16 v[66:69], v[236:239], v[228:231], v[66:69]
	v_mfma_f32_16x16x32_bf16 v[62:65], v[240:243], v[200:203], v[62:65]
	v_mfma_f32_16x16x32_bf16 v[58:61], v[240:243], v[204:207], v[58:61]
	v_mfma_f32_16x16x32_bf16 v[54:57], v[240:243], v[208:211], v[54:57]
	v_mfma_f32_16x16x32_bf16 v[50:53], v[240:243], v[212:215], v[50:53]
	v_mfma_f32_16x16x32_bf16 v[46:49], v[240:243], v[216:219], v[46:49]
	v_mfma_f32_16x16x32_bf16 v[42:45], v[240:243], v[220:223], v[42:45]
	v_mfma_f32_16x16x32_bf16 v[38:41], v[240:243], v[224:227], v[38:41]
	v_mfma_f32_16x16x32_bf16 v[34:37], v[240:243], v[228:231], v[34:37]
	v_mfma_f32_16x16x32_bf16 v[30:33], v[244:247], v[200:203], v[30:33]
	v_mfma_f32_16x16x32_bf16 v[26:29], v[244:247], v[204:207], v[26:29]
	v_mfma_f32_16x16x32_bf16 v[22:25], v[244:247], v[208:211], v[22:25]
	v_mfma_f32_16x16x32_bf16 v[18:21], v[244:247], v[212:215], v[18:21]
	v_mfma_f32_16x16x32_bf16 v[14:17], v[244:247], v[216:219], v[14:17]
	v_mfma_f32_16x16x32_bf16 v[10:13], v[244:247], v[220:223], v[10:13]
	v_mfma_f32_16x16x32_bf16 v[6:9], v[244:247], v[224:227], v[6:9]
	v_mfma_f32_16x16x32_bf16 v[2:5], v[244:247], v[228:231], v[2:5]
	s_mov_b32 s37, s36
	s_add_i32 s36, s36, 0x6000
	s_cmp_eq_u32 s36, 0x12000
	s_cselect_b32 s36, 0, s36
	s_waitcnt vmcnt(0) lgkmcnt(0)
	s_barrier
; DEVI unsigned pack2(float a, float b) { return __builtin_bit_cast(unsigned, __builtin_convertvector((f32x2_t){a, b}, bf16x2_t)); }
; DEVI float siluf_(float x) { return x * __builtin_amdgcn_rcpf(1.f + __expf(-x)); }
;     ...
;     for (int f = 0; f < 4; f++) wb[f] = *(const bf16x8*)(cS + boff + f * 1024);
; #pragma unroll
;     for (int nf = 0; nf < 4; nf++)
; #pragma unroll
;       for (int mf = 0; mf < 8; mf++)
;         acc[nf][mf] = __builtin_amdgcn_mfma_f32_16x16x32_bf16(wb[nf], xa[mf], acc[nf][mf], 0, 0, 0);
;     ...
;     if (EPI == EPI_SWIGLU) {
; #pragma unroll
;       for (int nf = 0; nf < 2; nf++) {
;         const int hcol = (n0 >> 1) + wn * 32 + nf * 16 + quad * 4;
;         f32x4 g = acc[nf][mf], u = acc[nf + 2][mf];
;         u32x2 pk;
;         pk[0] = pack2(siluf_(g[0]) * u[0], siluf_(g[1]) * u[1]);
;         pk[1] = pack2(siluf_(g[2]) * u[2], siluf_(g[3]) * u[3]);
;         *(u32x2*)(outb + (size_t)row * DFF + hcol) = pk;
;       }
	v_add_u32_e32 v144, s36, v136
	v_mfma_f32_16x16x32_bf16 v[126:129], v[184:187], v[146:149], v[126:129]
	ds_read_b128 v[200:203], v144 offset:0
	v_mfma_f32_16x16x32_bf16 v[122:125], v[184:187], v[152:155], v[122:125]
	ds_read_b128 v[204:207], v144 offset:1024
	v_mfma_f32_16x16x32_bf16 v[118:121], v[184:187], v[156:159], v[118:121]
	ds_read_b128 v[208:211], v144 offset:2048
	v_mfma_f32_16x16x32_bf16 v[114:117], v[184:187], v[162:165], v[114:117]
	ds_read_b128 v[212:215], v144 offset:3072
	v_mfma_f32_16x16x32_bf16 v[110:113], v[184:187], v[166:169], v[110:113]
	ds_read_b128 v[216:219], v144 offset:4096
	v_mfma_f32_16x16x32_bf16 v[106:109], v[184:187], v[170:173], v[106:109]
	ds_read_b128 v[220:223], v144 offset:5120
	v_mfma_f32_16x16x32_bf16 v[102:105], v[184:187], v[176:179], v[102:105]
	ds_read_b128 v[224:227], v144 offset:6144
	v_mfma_f32_16x16x32_bf16 v[98:101], v[184:187], v[180:183], v[98:101]
	ds_read_b128 v[228:231], v144 offset:7168
	v_mfma_f32_16x16x32_bf16 v[94:97], v[188:191], v[146:149], v[94:97]
	v_add_u32_e32 v144, s36, v137
	v_mfma_f32_16x16x32_bf16 v[90:93], v[188:191], v[152:155], v[90:93]
	v_mfma_f32_16x16x32_bf16 v[86:89], v[188:191], v[156:159], v[86:89]
	ds_read_b128 v[232:235], v144 offset:16384
	v_mfma_f32_16x16x32_bf16 v[82:85], v[188:191], v[162:165], v[82:85]
	ds_read_b128 v[236:239], v144 offset:17408
	v_mfma_f32_16x16x32_bf16 v[78:81], v[188:191], v[166:169], v[78:81]
	ds_read_b128 v[240:243], v144 offset:18432
	v_mfma_f32_16x16x32_bf16 v[74:77], v[188:191], v[170:173], v[74:77]
	ds_read_b128 v[244:247], v144 offset:19456
	v_mfma_f32_16x16x32_bf16 v[70:73], v[188:191], v[176:179], v[70:73]
	v_mfma_f32_16x16x32_bf16 v[66:69], v[188:191], v[180:183], v[66:69]
	v_mfma_f32_16x16x32_bf16 v[62:65], v[192:195], v[146:149], v[62:65]
	v_mfma_f32_16x16x32_bf16 v[58:61], v[192:195], v[152:155], v[58:61]
	v_mfma_f32_16x16x32_bf16 v[54:57], v[192:195], v[156:159], v[54:57]
	v_mfma_f32_16x16x32_bf16 v[50:53], v[192:195], v[162:165], v[50:53]
	v_mfma_f32_16x16x32_bf16 v[46:49], v[192:195], v[166:169], v[46:49]
	v_mfma_f32_16x16x32_bf16 v[42:45], v[192:195], v[170:173], v[42:45]
	v_mfma_f32_16x16x32_bf16 v[38:41], v[192:195], v[176:179], v[38:41]
	v_mfma_f32_16x16x32_bf16 v[34:37], v[192:195], v[180:183], v[34:37]
	v_mfma_f32_16x16x32_bf16 v[30:33], v[196:199], v[146:149], v[30:33]
	v_mfma_f32_16x16x32_bf16 v[26:29], v[196:199], v[152:155], v[26:29]
	v_mfma_f32_16x16x32_bf16 v[22:25], v[196:199], v[156:159], v[22:25]
	v_mfma_f32_16x16x32_bf16 v[18:21], v[196:199], v[162:165], v[18:21]
	v_mfma_f32_16x16x32_bf16 v[14:17], v[196:199], v[166:169], v[14:17]
	v_mfma_f32_16x16x32_bf16 v[10:13], v[196:199], v[170:173], v[10:13]
	v_mfma_f32_16x16x32_bf16 v[6:9], v[196:199], v[176:179], v[6:9]
	v_mfma_f32_16x16x32_bf16 v[2:5], v[196:199], v[180:183], v[2:5]
	s_mov_b32 s37, s36
	s_add_i32 s36, s36, 0x6000
	s_cmp_eq_u32 s36, 0x12000
	s_cselect_b32 s36, 0, s36
	s_waitcnt lgkmcnt(0)
	v_mfma_f32_16x16x32_bf16 v[126:129], v[232:235], v[200:203], v[126:129]
	v_mfma_f32_16x16x32_bf16 v[122:125], v[232:235], v[204:207], v[122:125]
	v_mfma_f32_16x16x32_bf16 v[118:121], v[232:235], v[208:211], v[118:121]
	v_mfma_f32_16x16x32_bf16 v[114:117], v[232:235], v[212:215], v[114:117]
	v_mfma_f32_16x16x32_bf16 v[110:113], v[232:235], v[216:219], v[110:113]
	v_mfma_f32_16x16x32_bf16 v[106:109], v[232:235], v[220:223], v[106:109]
	v_mfma_f32_16x16x32_bf16 v[102:105], v[232:235], v[224:227], v[102:105]
	v_mfma_f32_16x16x32_bf16 v[98:101], v[232:235], v[228:231], v[98:101]
	v_mfma_f32_16x16x32_bf16 v[94:97], v[236:239], v[200:203], v[94:97]
	v_mfma_f32_16x16x32_bf16 v[90:93], v[236:239], v[204:207], v[90:93]
	v_mfma_f32_16x16x32_bf16 v[86:89], v[236:239], v[208:211], v[86:89]
	v_mfma_f32_16x16x32_bf16 v[82:85], v[236:239], v[212:215], v[82:85]
	v_mfma_f32_16x16x32_bf16 v[78:81], v[236:239], v[216:219], v[78:81]
	v_mfma_f32_16x16x32_bf16 v[74:77], v[236:239], v[220:223], v[74:77]
	v_mfma_f32_16x16x32_bf16 v[70:73], v[236:239], v[224:227], v[70:73]
	v_mfma_f32_16x16x32_bf16 v[66:69], v[236:239], v[228:231], v[66:69]
	v_mfma_f32_16x16x32_bf16 v[62:65], v[240:243], v[200:203], v[62:65]
	v_mfma_f32_16x16x32_bf16 v[58:61], v[240:243], v[204:207], v[58:61]
	v_mfma_f32_16x16x32_bf16 v[54:57], v[240:243], v[208:211], v[54:57]
	v_mfma_f32_16x16x32_bf16 v[50:53], v[240:243], v[212:215], v[50:53]
	v_mfma_f32_16x16x32_bf16 v[46:49], v[240:243], v[216:219], v[46:49]
	v_mfma_f32_16x16x32_bf16 v[42:45], v[240:243], v[220:223], v[42:45]
	v_mfma_f32_16x16x32_bf16 v[38:41], v[240:243], v[224:227], v[38:41]
	v_mfma_f32_16x16x32_bf16 v[34:37], v[240:243], v[228:231], v[34:37]
	v_mfma_f32_16x16x32_bf16 v[30:33], v[244:247], v[200:203], v[30:33]
	v_mfma_f32_16x16x32_bf16 v[26:29], v[244:247], v[204:207], v[26:29]
	v_mfma_f32_16x16x32_bf16 v[22:25], v[244:247], v[208:211], v[22:25]
	v_mfma_f32_16x16x32_bf16 v[18:21], v[244:247], v[212:215], v[18:21]
	v_mfma_f32_16x16x32_bf16 v[14:17], v[244:247], v[216:219], v[14:17]
	v_mfma_f32_16x16x32_bf16 v[10:13], v[244:247], v[220:223], v[10:13]
	v_mfma_f32_16x16x32_bf16 v[6:9], v[244:247], v[224:227], v[6:9]
	v_mfma_f32_16x16x32_bf16 v[2:5], v[244:247], v[228:231], v[2:5]
	s_mov_b32 m0, s39
	s_mov_b32 s10, 0x16000
	s_mov_b32 s11, 0
	s_mov_b32 s40, 0xbfb8aa3b
	s_nop 7
	v_mul_f32_e32 v216, s40, v126
	v_mul_f32_e32 v217, s40, v127
	v_mul_f32_e32 v218, s40, v128
	v_mul_f32_e32 v219, s40, v129
	v_exp_f32_e32 v216, v216
	v_exp_f32_e32 v217, v217
	v_exp_f32_e32 v218, v218
	v_exp_f32_e32 v219, v219
	v_add_f32_e32 v216, 1.0, v216
	v_add_f32_e32 v217, 1.0, v217
	v_add_f32_e32 v218, 1.0, v218
	v_add_f32_e32 v219, 1.0, v219
	v_rcp_f32_e32 v216, v216
; DEVI unsigned pack2(float a, float b) { return __builtin_bit_cast(unsigned, __builtin_convertvector((f32x2_t){a, b}, bf16x2_t)); }
; DEVI float siluf_(float x) { return x * __builtin_amdgcn_rcpf(1.f + __expf(-x)); }
;     ...
;     if (EPI == EPI_SWIGLU) {
; #pragma unroll
;       for (int nf = 0; nf < 2; nf++) {
;         const int hcol = (n0 >> 1) + wn * 32 + nf * 16 + quad * 4;
;         f32x4 g = acc[nf][mf], u = acc[nf + 2][mf];
;         u32x2 pk;
;         pk[0] = pack2(siluf_(g[0]) * u[0], siluf_(g[1]) * u[1]);
;         pk[1] = pack2(siluf_(g[2]) * u[2], siluf_(g[3]) * u[3]);
;         *(u32x2*)(outb + (size_t)row * DFF + hcol) = pk;
;       }
	v_rcp_f32_e32 v217, v217
	v_rcp_f32_e32 v218, v218
	v_rcp_f32_e32 v219, v219
	v_mul_f32_e32 v126, v126, v216
	v_mul_f32_e32 v127, v127, v217
	v_mul_f32_e32 v128, v128, v218
	v_mul_f32_e32 v129, v129, v219
	v_mul_f32_e32 v126, v126, v62
	v_mul_f32_e32 v127, v127, v63
	v_mul_f32_e32 v128, v128, v64
	v_mul_f32_e32 v129, v129, v65
	v_cvt_pk_bf16_f32 v126, v126, v127
	v_cvt_pk_bf16_f32 v127, v128, v129
	global_store_dwordx2 v[140:141], v[126:127], off offset:0
	v_mul_f32_e32 v216, s40, v94
	v_mul_f32_e32 v217, s40, v95
	v_mul_f32_e32 v218, s40, v96
	v_mul_f32_e32 v219, s40, v97
	v_exp_f32_e32 v216, v216
	v_exp_f32_e32 v217, v217
	v_exp_f32_e32 v218, v218
	v_exp_f32_e32 v219, v219
	v_add_f32_e32 v216, 1.0, v216
	v_add_f32_e32 v217, 1.0, v217
	v_add_f32_e32 v218, 1.0, v218
	v_add_f32_e32 v219, 1.0, v219
	v_rcp_f32_e32 v216, v216
	v_rcp_f32_e32 v217, v217
	v_rcp_f32_e32 v218, v218
	v_rcp_f32_e32 v219, v219
	v_mul_f32_e32 v94, v94, v216
	v_mul_f32_e32 v95, v95, v217
	v_mul_f32_e32 v96, v96, v218
	v_mul_f32_e32 v97, v97, v219
	v_mul_f32_e32 v94, v94, v30
	v_mul_f32_e32 v95, v95, v31
	v_mul_f32_e32 v96, v96, v32
	v_mul_f32_e32 v97, v97, v33
	v_cvt_pk_bf16_f32 v94, v94, v95
	v_cvt_pk_bf16_f32 v95, v96, v97
	global_store_dwordx2 v[140:141], v[94:95], off offset:32
	v_lshl_add_u64 v[140:141], v[140:141], 0, s[10:11]
	v_mul_f32_e32 v216, s40, v122
	v_mul_f32_e32 v217, s40, v123
	v_mul_f32_e32 v218, s40, v124
	v_mul_f32_e32 v219, s40, v125
	v_exp_f32_e32 v216, v216
	v_exp_f32_e32 v217, v217
	v_exp_f32_e32 v218, v218
	v_exp_f32_e32 v219, v219
	v_add_f32_e32 v216, 1.0, v216
	v_add_f32_e32 v217, 1.0, v217
	v_add_f32_e32 v218, 1.0, v218
	v_add_f32_e32 v219, 1.0, v219
	v_rcp_f32_e32 v216, v216
	v_rcp_f32_e32 v217, v217
	v_rcp_f32_e32 v218, v218
	v_rcp_f32_e32 v219, v219
	v_mul_f32_e32 v122, v122, v216
	v_mul_f32_e32 v123, v123, v217
	v_mul_f32_e32 v124, v124, v218
	v_mul_f32_e32 v125, v125, v219
	v_mul_f32_e32 v122, v122, v58
	v_mul_f32_e32 v123, v123, v59
	v_mul_f32_e32 v124, v124, v60
	v_mul_f32_e32 v125, v125, v61
	v_cvt_pk_bf16_f32 v122, v122, v123
	v_cvt_pk_bf16_f32 v123, v124, v125
	global_store_dwordx2 v[140:141], v[122:123], off offset:0
	v_mul_f32_e32 v216, s40, v90
	v_mul_f32_e32 v217, s40, v91
	v_mul_f32_e32 v218, s40, v92
	v_mul_f32_e32 v219, s40, v93
	v_exp_f32_e32 v216, v216
	v_exp_f32_e32 v217, v217
	v_exp_f32_e32 v218, v218
	v_exp_f32_e32 v219, v219
	v_add_f32_e32 v216, 1.0, v216
	v_add_f32_e32 v217, 1.0, v217
	v_add_f32_e32 v218, 1.0, v218
	v_add_f32_e32 v219, 1.0, v219
	v_rcp_f32_e32 v216, v216
	v_rcp_f32_e32 v217, v217
	v_rcp_f32_e32 v218, v218
	v_rcp_f32_e32 v219, v219
	v_mul_f32_e32 v90, v90, v216
	v_mul_f32_e32 v91, v91, v217
	v_mul_f32_e32 v92, v92, v218
	v_mul_f32_e32 v93, v93, v219
	v_mul_f32_e32 v90, v90, v26
	v_mul_f32_e32 v91, v91, v27
	v_mul_f32_e32 v92, v92, v28
	v_mul_f32_e32 v93, v93, v29
	v_cvt_pk_bf16_f32 v90, v90, v91
	v_cvt_pk_bf16_f32 v91, v92, v93
	global_store_dwordx2 v[140:141], v[90:91], off offset:32
	v_lshl_add_u64 v[140:141], v[140:141], 0, s[10:11]
	v_mul_f32_e32 v216, s40, v118
	v_mul_f32_e32 v217, s40, v119
	v_mul_f32_e32 v218, s40, v120
	v_mul_f32_e32 v219, s40, v121
	v_exp_f32_e32 v216, v216
	v_exp_f32_e32 v217, v217
	v_exp_f32_e32 v218, v218
	v_exp_f32_e32 v219, v219
	v_add_f32_e32 v216, 1.0, v216
	v_add_f32_e32 v217, 1.0, v217
	v_add_f32_e32 v218, 1.0, v218
	v_add_f32_e32 v219, 1.0, v219
	v_rcp_f32_e32 v216, v216
	v_rcp_f32_e32 v217, v217
	v_rcp_f32_e32 v218, v218
	v_rcp_f32_e32 v219, v219
	v_mul_f32_e32 v118, v118, v216
	v_mul_f32_e32 v119, v119, v217
	v_mul_f32_e32 v120, v120, v218
	v_mul_f32_e32 v121, v121, v219
	v_mul_f32_e32 v118, v118, v54
	v_mul_f32_e32 v119, v119, v55
	v_mul_f32_e32 v120, v120, v56
	v_mul_f32_e32 v121, v121, v57
	v_cvt_pk_bf16_f32 v118, v118, v119
	v_cvt_pk_bf16_f32 v119, v120, v121
	global_store_dwordx2 v[140:141], v[118:119], off offset:0
	v_mul_f32_e32 v216, s40, v86
	v_mul_f32_e32 v217, s40, v87
	v_mul_f32_e32 v218, s40, v88
	v_mul_f32_e32 v219, s40, v89
	v_exp_f32_e32 v216, v216
	v_exp_f32_e32 v217, v217
	v_exp_f32_e32 v218, v218
	v_exp_f32_e32 v219, v219
	v_add_f32_e32 v216, 1.0, v216
	v_add_f32_e32 v217, 1.0, v217
	v_add_f32_e32 v218, 1.0, v218
	v_add_f32_e32 v219, 1.0, v219
	v_rcp_f32_e32 v216, v216
	v_rcp_f32_e32 v217, v217
	v_rcp_f32_e32 v218, v218
	v_rcp_f32_e32 v219, v219
	v_mul_f32_e32 v86, v86, v216
	v_mul_f32_e32 v87, v87, v217
	v_mul_f32_e32 v88, v88, v218
	v_mul_f32_e32 v89, v89, v219
	v_mul_f32_e32 v86, v86, v22
	v_mul_f32_e32 v87, v87, v23
	v_mul_f32_e32 v88, v88, v24
	v_mul_f32_e32 v89, v89, v25
	v_cvt_pk_bf16_f32 v86, v86, v87
	v_cvt_pk_bf16_f32 v87, v88, v89
	global_store_dwordx2 v[140:141], v[86:87], off offset:32
	v_lshl_add_u64 v[140:141], v[140:141], 0, s[10:11]
	v_mul_f32_e32 v216, s40, v114
	v_mul_f32_e32 v217, s40, v115
	v_mul_f32_e32 v218, s40, v116
	v_mul_f32_e32 v219, s40, v117
	v_exp_f32_e32 v216, v216
	v_exp_f32_e32 v217, v217
	v_exp_f32_e32 v218, v218
	v_exp_f32_e32 v219, v219
	v_add_f32_e32 v216, 1.0, v216
	v_add_f32_e32 v217, 1.0, v217
	v_add_f32_e32 v218, 1.0, v218
	v_add_f32_e32 v219, 1.0, v219
	v_rcp_f32_e32 v216, v216
	v_rcp_f32_e32 v217, v217
	v_rcp_f32_e32 v218, v218
	v_rcp_f32_e32 v219, v219
	v_mul_f32_e32 v114, v114, v216
	v_mul_f32_e32 v115, v115, v217
	v_mul_f32_e32 v116, v116, v218
	v_mul_f32_e32 v117, v117, v219
	v_mul_f32_e32 v114, v114, v50
	v_mul_f32_e32 v115, v115, v51
	v_mul_f32_e32 v116, v116, v52
	v_mul_f32_e32 v117, v117, v53
	v_cvt_pk_bf16_f32 v114, v114, v115
	v_cvt_pk_bf16_f32 v115, v116, v117
	global_store_dwordx2 v[140:141], v[114:115], off offset:0
	v_mul_f32_e32 v216, s40, v82
	v_mul_f32_e32 v217, s40, v83
; DEVI unsigned pack2(float a, float b) { return __builtin_bit_cast(unsigned, __builtin_convertvector((f32x2_t){a, b}, bf16x2_t)); }
; DEVI float siluf_(float x) { return x * __builtin_amdgcn_rcpf(1.f + __expf(-x)); }
;     ...
;     if (EPI == EPI_SWIGLU) {
; #pragma unroll
;       for (int nf = 0; nf < 2; nf++) {
;         const int hcol = (n0 >> 1) + wn * 32 + nf * 16 + quad * 4;
;         f32x4 g = acc[nf][mf], u = acc[nf + 2][mf];
;         u32x2 pk;
;         pk[0] = pack2(siluf_(g[0]) * u[0], siluf_(g[1]) * u[1]);
;         pk[1] = pack2(siluf_(g[2]) * u[2], siluf_(g[3]) * u[3]);
;         *(u32x2*)(outb + (size_t)row * DFF + hcol) = pk;
;       }
	v_mul_f32_e32 v218, s40, v84
	v_mul_f32_e32 v219, s40, v85
	v_exp_f32_e32 v216, v216
	v_exp_f32_e32 v217, v217
	v_exp_f32_e32 v218, v218
	v_exp_f32_e32 v219, v219
	v_add_f32_e32 v216, 1.0, v216
	v_add_f32_e32 v217, 1.0, v217
	v_add_f32_e32 v218, 1.0, v218
	v_add_f32_e32 v219, 1.0, v219
	v_rcp_f32_e32 v216, v216
	v_rcp_f32_e32 v217, v217
	v_rcp_f32_e32 v218, v218
	v_rcp_f32_e32 v219, v219
	v_mul_f32_e32 v82, v82, v216
	v_mul_f32_e32 v83, v83, v217
	v_mul_f32_e32 v84, v84, v218
	v_mul_f32_e32 v85, v85, v219
	v_mul_f32_e32 v82, v82, v18
	v_mul_f32_e32 v83, v83, v19
	v_mul_f32_e32 v84, v84, v20
	v_mul_f32_e32 v85, v85, v21
	v_cvt_pk_bf16_f32 v82, v82, v83
	v_cvt_pk_bf16_f32 v83, v84, v85
	global_store_dwordx2 v[140:141], v[82:83], off offset:32
	v_lshl_add_u64 v[140:141], v[140:141], 0, s[10:11]
	v_mul_f32_e32 v216, s40, v110
	v_mul_f32_e32 v217, s40, v111
	v_mul_f32_e32 v218, s40, v112
	v_mul_f32_e32 v219, s40, v113
	v_exp_f32_e32 v216, v216
	v_exp_f32_e32 v217, v217
	v_exp_f32_e32 v218, v218
	v_exp_f32_e32 v219, v219
	v_add_f32_e32 v216, 1.0, v216
	v_add_f32_e32 v217, 1.0, v217
	v_add_f32_e32 v218, 1.0, v218
	v_add_f32_e32 v219, 1.0, v219
	v_rcp_f32_e32 v216, v216
	v_rcp_f32_e32 v217, v217
	v_rcp_f32_e32 v218, v218
	v_rcp_f32_e32 v219, v219
	v_mul_f32_e32 v110, v110, v216
	v_mul_f32_e32 v111, v111, v217
	v_mul_f32_e32 v112, v112, v218
	v_mul_f32_e32 v113, v113, v219
	v_mul_f32_e32 v110, v110, v46
	v_mul_f32_e32 v111, v111, v47
	v_mul_f32_e32 v112, v112, v48
	v_mul_f32_e32 v113, v113, v49
	v_cvt_pk_bf16_f32 v110, v110, v111
	v_cvt_pk_bf16_f32 v111, v112, v113
	global_store_dwordx2 v[140:141], v[110:111], off offset:0
	v_mul_f32_e32 v216, s40, v78
	v_mul_f32_e32 v217, s40, v79
	v_mul_f32_e32 v218, s40, v80
	v_mul_f32_e32 v219, s40, v81
	v_exp_f32_e32 v216, v216
	v_exp_f32_e32 v217, v217
	v_exp_f32_e32 v218, v218
	v_exp_f32_e32 v219, v219
	v_add_f32_e32 v216, 1.0, v216
	v_add_f32_e32 v217, 1.0, v217
	v_add_f32_e32 v218, 1.0, v218
	v_add_f32_e32 v219, 1.0, v219
	v_rcp_f32_e32 v216, v216
	v_rcp_f32_e32 v217, v217
	v_rcp_f32_e32 v218, v218
	v_rcp_f32_e32 v219, v219
	v_mul_f32_e32 v78, v78, v216
	v_mul_f32_e32 v79, v79, v217
	v_mul_f32_e32 v80, v80, v218
	v_mul_f32_e32 v81, v81, v219
	v_mul_f32_e32 v78, v78, v14
	v_mul_f32_e32 v79, v79, v15
	v_mul_f32_e32 v80, v80, v16
	v_mul_f32_e32 v81, v81, v17
	v_cvt_pk_bf16_f32 v78, v78, v79
	v_cvt_pk_bf16_f32 v79, v80, v81
	global_store_dwordx2 v[140:141], v[78:79], off offset:32
	v_lshl_add_u64 v[140:141], v[140:141], 0, s[10:11]
	v_mul_f32_e32 v216, s40, v106
	v_mul_f32_e32 v217, s40, v107
	v_mul_f32_e32 v218, s40, v108
	v_mul_f32_e32 v219, s40, v109
	v_exp_f32_e32 v216, v216
	v_exp_f32_e32 v217, v217
	v_exp_f32_e32 v218, v218
	v_exp_f32_e32 v219, v219
	v_add_f32_e32 v216, 1.0, v216
	v_add_f32_e32 v217, 1.0, v217
	v_add_f32_e32 v218, 1.0, v218
	v_add_f32_e32 v219, 1.0, v219
	v_rcp_f32_e32 v216, v216
	v_rcp_f32_e32 v217, v217
	v_rcp_f32_e32 v218, v218
	v_rcp_f32_e32 v219, v219
	v_mul_f32_e32 v106, v106, v216
	v_mul_f32_e32 v107, v107, v217
	v_mul_f32_e32 v108, v108, v218
	v_mul_f32_e32 v109, v109, v219
	v_mul_f32_e32 v106, v106, v42
	v_mul_f32_e32 v107, v107, v43
	v_mul_f32_e32 v108, v108, v44
	v_mul_f32_e32 v109, v109, v45
	v_cvt_pk_bf16_f32 v106, v106, v107
	v_cvt_pk_bf16_f32 v107, v108, v109
	global_store_dwordx2 v[140:141], v[106:107], off offset:0
	v_mul_f32_e32 v216, s40, v74
	v_mul_f32_e32 v217, s40, v75
	v_mul_f32_e32 v218, s40, v76
	v_mul_f32_e32 v219, s40, v77
	v_exp_f32_e32 v216, v216
	v_exp_f32_e32 v217, v217
	v_exp_f32_e32 v218, v218
	v_exp_f32_e32 v219, v219
	v_add_f32_e32 v216, 1.0, v216
	v_add_f32_e32 v217, 1.0, v217
	v_add_f32_e32 v218, 1.0, v218
	v_add_f32_e32 v219, 1.0, v219
	v_rcp_f32_e32 v216, v216
	v_rcp_f32_e32 v217, v217
	v_rcp_f32_e32 v218, v218
	v_rcp_f32_e32 v219, v219
	v_mul_f32_e32 v74, v74, v216
; DEVI unsigned pack2(float a, float b) { return __builtin_bit_cast(unsigned, __builtin_convertvector((f32x2_t){a, b}, bf16x2_t)); }
; DEVI float siluf_(float x) { return x * __builtin_amdgcn_rcpf(1.f + __expf(-x)); }
; DEVI int xcd_first_tile() { return (blockIdx.x & 7) * (gridDim.x >> 3) + (blockIdx.x >> 3); }
;     ...
;     if (EPI == EPI_SWIGLU) {
; #pragma unroll
;       for (int nf = 0; nf < 2; nf++) {
;         const int hcol = (n0 >> 1) + wn * 32 + nf * 16 + quad * 4;
;         f32x4 g = acc[nf][mf], u = acc[nf + 2][mf];
;         u32x2 pk;
;         pk[0] = pack2(siluf_(g[0]) * u[0], siluf_(g[1]) * u[1]);
;         pk[1] = pack2(siluf_(g[2]) * u[2], siluf_(g[3]) * u[3]);
;         *(u32x2*)(outb + (size_t)row * DFF + hcol) = pk;
;       }
; DEVI void run_phase(const Params& p, int ph, char* smem) {
;     ...
;       for (int t = xcd_first_tile(); t < 66 * 44; t += xcd_tile_step()) {
;         int mt_, nt_; tile_coords(t, 66, 44, mt_, nt_);
;         gemm_tile256<EPI_SWIGLU>(p, xb, 1024, Bt, 1024, mt_ * 256, nt_ * 128, hb, DFF, smem);
;       }
	v_mul_f32_e32 v75, v75, v217
	v_mul_f32_e32 v76, v76, v218
	v_mul_f32_e32 v77, v77, v219
	v_mul_f32_e32 v74, v74, v10
	v_mul_f32_e32 v75, v75, v11
	v_mul_f32_e32 v76, v76, v12
	v_mul_f32_e32 v77, v77, v13
	v_cvt_pk_bf16_f32 v74, v74, v75
	v_cvt_pk_bf16_f32 v75, v76, v77
	global_store_dwordx2 v[140:141], v[74:75], off offset:32
	v_lshl_add_u64 v[140:141], v[140:141], 0, s[10:11]
	v_mul_f32_e32 v216, s40, v102
	v_mul_f32_e32 v217, s40, v103
	v_mul_f32_e32 v218, s40, v104
	v_mul_f32_e32 v219, s40, v105
	v_exp_f32_e32 v216, v216
	v_exp_f32_e32 v217, v217
	v_exp_f32_e32 v218, v218
	v_exp_f32_e32 v219, v219
	v_add_f32_e32 v216, 1.0, v216
	v_add_f32_e32 v217, 1.0, v217
	v_add_f32_e32 v218, 1.0, v218
	v_add_f32_e32 v219, 1.0, v219
	v_rcp_f32_e32 v216, v216
	v_rcp_f32_e32 v217, v217
	v_rcp_f32_e32 v218, v218
	v_rcp_f32_e32 v219, v219
	v_mul_f32_e32 v102, v102, v216
	v_mul_f32_e32 v103, v103, v217
	v_mul_f32_e32 v104, v104, v218
	v_mul_f32_e32 v105, v105, v219
	v_mul_f32_e32 v102, v102, v38
	v_mul_f32_e32 v103, v103, v39
	v_mul_f32_e32 v104, v104, v40
	v_mul_f32_e32 v105, v105, v41
	v_cvt_pk_bf16_f32 v102, v102, v103
	v_cvt_pk_bf16_f32 v103, v104, v105
	global_store_dwordx2 v[140:141], v[102:103], off offset:0
	v_mul_f32_e32 v216, s40, v70
	v_mul_f32_e32 v217, s40, v71
	v_mul_f32_e32 v218, s40, v72
	v_mul_f32_e32 v219, s40, v73
	v_exp_f32_e32 v216, v216
	v_exp_f32_e32 v217, v217
	v_exp_f32_e32 v218, v218
	v_exp_f32_e32 v219, v219
	v_add_f32_e32 v216, 1.0, v216
	v_add_f32_e32 v217, 1.0, v217
	v_add_f32_e32 v218, 1.0, v218
	v_add_f32_e32 v219, 1.0, v219
	v_rcp_f32_e32 v216, v216
	v_rcp_f32_e32 v217, v217
	v_rcp_f32_e32 v218, v218
	v_rcp_f32_e32 v219, v219
	v_mul_f32_e32 v70, v70, v216
	v_mul_f32_e32 v71, v71, v217
	v_mul_f32_e32 v72, v72, v218
	v_mul_f32_e32 v73, v73, v219
	v_mul_f32_e32 v70, v70, v6
	v_mul_f32_e32 v71, v71, v7
	v_mul_f32_e32 v72, v72, v8
	v_mul_f32_e32 v73, v73, v9
	v_cvt_pk_bf16_f32 v70, v70, v71
	v_cvt_pk_bf16_f32 v71, v72, v73
	global_store_dwordx2 v[140:141], v[70:71], off offset:32
	v_lshl_add_u64 v[140:141], v[140:141], 0, s[10:11]
	v_mul_f32_e32 v216, s40, v98
	v_mul_f32_e32 v217, s40, v99
	v_mul_f32_e32 v218, s40, v100
	v_mul_f32_e32 v219, s40, v101
	v_exp_f32_e32 v216, v216
	v_exp_f32_e32 v217, v217
	v_exp_f32_e32 v218, v218
	v_exp_f32_e32 v219, v219
	v_add_f32_e32 v216, 1.0, v216
	v_add_f32_e32 v217, 1.0, v217
	v_add_f32_e32 v218, 1.0, v218
	v_add_f32_e32 v219, 1.0, v219
	v_rcp_f32_e32 v216, v216
	v_rcp_f32_e32 v217, v217
	v_rcp_f32_e32 v218, v218
	v_rcp_f32_e32 v219, v219
	v_mul_f32_e32 v98, v98, v216
	v_mul_f32_e32 v99, v99, v217
	v_mul_f32_e32 v100, v100, v218
	v_mul_f32_e32 v101, v101, v219
	v_mul_f32_e32 v98, v98, v34
	v_mul_f32_e32 v99, v99, v35
	v_mul_f32_e32 v100, v100, v36
	v_mul_f32_e32 v101, v101, v37
	v_cvt_pk_bf16_f32 v98, v98, v99
	v_cvt_pk_bf16_f32 v99, v100, v101
	global_store_dwordx2 v[140:141], v[98:99], off offset:0
	v_mul_f32_e32 v216, s40, v66
	v_mul_f32_e32 v217, s40, v67
	v_mul_f32_e32 v218, s40, v68
	v_mul_f32_e32 v219, s40, v69
	v_exp_f32_e32 v216, v216
	v_exp_f32_e32 v217, v217
	v_exp_f32_e32 v218, v218
	v_exp_f32_e32 v219, v219
	v_add_f32_e32 v216, 1.0, v216
	v_add_f32_e32 v217, 1.0, v217
	v_add_f32_e32 v218, 1.0, v218
	v_add_f32_e32 v219, 1.0, v219
	v_rcp_f32_e32 v216, v216
	v_rcp_f32_e32 v217, v217
	v_rcp_f32_e32 v218, v218
	v_rcp_f32_e32 v219, v219
	v_mul_f32_e32 v66, v66, v216
	v_mul_f32_e32 v67, v67, v217
	v_mul_f32_e32 v68, v68, v218
	v_mul_f32_e32 v69, v69, v219
	v_mul_f32_e32 v66, v66, v2
	v_mul_f32_e32 v67, v67, v3
	v_mul_f32_e32 v68, v68, v4
	v_mul_f32_e32 v69, v69, v5
	v_cvt_pk_bf16_f32 v66, v66, v67
	v_cvt_pk_bf16_f32 v67, v68, v69
	global_store_dwordx2 v[140:141], v[66:67], off offset:32
	v_readlane_b32 s42, v250, 7
	s_add_i32 s8, s8, s42
	s_cmpk_gt_i32 s8, 0xb57
	s_cbranch_scc0 .LBB0_124
	s_branch .LBB0_131

; DEVI unsigned pack2(float a, float b) { return __builtin_bit_cast(unsigned, __builtin_convertvector((f32x2_t){a, b}, bf16x2_t)); }
; DEVI void stnt4(float* p_, f32x4 v) { __builtin_nontemporal_store(v, (f32x4*)p_); }
;     ...
;     float s = 0.f, q = 0.f;
; #pragma unroll
;     for (int i = 0; i < 4; i++) {
;       s += v[i].x + v[i].y + v[i].z + v[i].w;
;       q += v[i].x * v[i].x + v[i].y * v[i].y + v[i].z * v[i].z + v[i].w * v[i].w;
;     }
; #pragma unroll
;     for (int o = 32; o > 0; o >>= 1) { const float s2 = __shfl_xor(s, o), q2 = __shfl_xor(q, o); s += s2; q += q2; }
;     const float mu = s * (1.f / 1024.f);
;     const float var = fmaxf(q * (1.f / 1024.f) - mu * mu, 0.f);
;     const float rs = rsqrtf(var + 1e-5f);
; #pragma unroll
;     for (int i = 0; i < 4; i++) {
;       float4 o;
;       o.x = (v[i].x - mu) * rs * gg[i].x + bb[i].x; o.y = (v[i].y - mu) * rs * gg[i].y + bb[i].y;
;       o.z = (v[i].z - mu) * rs * gg[i].z + bb[i].z; o.w = (v[i].w - mu) * rs * gg[i].w + bb[i].w;
;       uint2 pk; pk.x = pack2(o.x, o.y); pk.y = pack2(o.z, o.w);
;       if (mode != 2) ((uint2*)(xb + (size_t)r * 1024))[lane + 64 * i] = pk;
;       if (mode == 2) stnt4(p.out + O_Y + (size_t)r * 1024 + (size_t)(lane + 64 * i) * 4, (f32x4){o.x, o.y, o.z, o.w});
.LBB0_137:
	s_or_b64 exec, exec, s[10:11]
	s_waitcnt vmcnt(2)
	v_mul_f32_e32 v0, v51, v51
	v_pk_fma_f32 v[88:89], v[50:51], v[50:51], v[0:1] op_sel_hi:[1,1,0]
	s_waitcnt vmcnt(1)
	v_mul_f32_e32 v0, v55, v55
	v_pk_fma_f32 v[92:93], v[54:55], v[54:55], v[0:1] op_sel_hi:[1,1,0]
	s_waitcnt vmcnt(0)
	v_mov_b32_e32 v102, v64
	v_mov_b32_e32 v103, v62
	v_mul_f32_e32 v0, v63, v63
	v_pk_fma_f32 v[104:105], v[62:63], v[62:63], v[0:1] op_sel_hi:[1,1,0]
	v_pk_mul_f32 v[106:107], v[64:65], v[64:65]
	v_pk_add_f32 v[102:103], v[102:103], v[62:63]
	v_mov_b32_e32 v105, v64
	v_mov_b32_e32 v107, v103
	v_mul_f32_e32 v94, v65, v65
	v_pk_add_f32 v[96:97], v[58:59], v[58:59] op_sel:[0,1] op_sel_hi:[1,0]
	v_pk_mul_f32 v[98:99], v[58:59], v[58:59]
	v_pk_mul_f32 v[100:101], v[60:61], v[60:61]
	v_pk_add_f32 v[102:103], v[106:107], v[104:105]
	v_mov_b32_e32 v95, v65
	v_pk_add_f32 v[86:87], v[50:51], v[50:51] op_sel_hi:[0,1]
	v_pk_add_f32 v[94:95], v[102:103], v[94:95]
	v_mov_b32_e32 v102, v98
	v_mov_b32_e32 v103, v96
	v_pk_mov_b32 v[96:97], v[98:99], v[60:61] op_sel:[1,0]
	v_mov_b32_e32 v98, v100
	v_mov_b32_e32 v0, v101
	v_pk_mul_f32 v[100:101], v[52:53], v[52:53]
	v_mov_b32_e32 v89, v52
	v_mov_b32_e32 v86, v100
	v_pk_add_f32 v[86:87], v[86:87], v[88:89]
	v_mov_b32_e32 v88, v101
	v_mov_b32_e32 v89, v53
	v_pk_add_f32 v[90:91], v[54:55], v[54:55] op_sel_hi:[0,1]
	v_pk_add_f32 v[96:97], v[102:103], v[96:97]
	v_mov_b32_e32 v99, v61
	v_pk_add_f32 v[86:87], v[86:87], v[88:89]
	v_pk_mul_f32 v[88:89], v[56:57], v[56:57]
	v_pk_add_f32 v[96:97], v[96:97], v[98:99]
	v_mov_b32_e32 v90, v88
	v_mov_b32_e32 v93, v56
	v_pk_add_f32 v[96:97], v[96:97], v[0:1]
	v_pk_add_f32 v[90:91], v[90:91], v[92:93]
	v_mov_b32_e32 v88, v89
	v_mov_b32_e32 v89, v57
	v_pk_add_f32 v[86:87], v[96:97], v[86:87]
	v_pk_add_f32 v[88:89], v[90:91], v[88:89]
	s_mov_b32 s0, 0x3a800000
	v_pk_add_f32 v[86:87], v[86:87], v[88:89]
	s_and_b64 s[2:3], exec, vcc
	v_pk_add_f32 v[86:87], v[86:87], v[94:95]
	ds_bpermute_b32 v89, v80, v87
	ds_bpermute_b32 v88, v80, v86
	v_readlane_b32 s36, v250, 1
	v_readlane_b32 s40, v250, 5
	v_readlane_b32 s41, v250, 6
	s_or_b64 s[8:9], s[2:3], s[8:9]
	s_waitcnt lgkmcnt(0)
	v_pk_add_f32 v[86:87], v[86:87], v[88:89]
	ds_bpermute_b32 v89, v81, v87
	ds_bpermute_b32 v88, v81, v86
	v_lshl_add_u64 v[98:99], s[40:41], 0, v[66:67]
	v_lshrrev_b32_e32 v118, 25, v66
	v_xor_b32_e32 v118, 1, v118
	v_bfe_u32 v119, v66, 11, 1
	v_mul_u32_u24_e32 v119, 0x7c0, v119
	v_bfe_u32 v110, v145, 3, 3
	v_lshlrev_b32_e32 v110, 6, v110
	v_sub_u32_e32 v110, v110, v119
	v_mul_i32_i24_e32 v110, v110, v118
	v_lshlrev_b32_e32 v119, 9, v118
	v_add_u32_e32 v112, v110, v119
	v_add_u32_e32 v114, v112, v119
	v_add_u32_e32 v116, v114, v119
	v_ashrrev_i32_e32 v111, 31, v110
	v_ashrrev_i32_e32 v113, 31, v112
	v_ashrrev_i32_e32 v115, 31, v114
	v_ashrrev_i32_e32 v117, 31, v116
	v_readlane_b32 s2, v254, 19
	v_readlane_b32 s3, v254, 20
	v_mov_b32_e32 v78, v79
	s_waitcnt lgkmcnt(0)
	v_pk_add_f32 v[86:87], v[86:87], v[88:89]
	ds_bpermute_b32 v89, v82, v87
	ds_bpermute_b32 v88, v82, v86
	v_lshl_add_u64 v[66:67], v[66:67], 0, s[2:3]
	v_readlane_b32 s2, v254, 17
	v_readlane_b32 s3, v254, 18
	v_readlane_b32 s37, v250, 2
	s_waitcnt lgkmcnt(0)
	v_pk_add_f32 v[86:87], v[86:87], v[88:89]
	ds_bpermute_b32 v89, v83, v87
	ds_bpermute_b32 v88, v83, v86
	v_lshl_add_u64 v[68:69], v[68:69], 0, s[2:3]
	v_readlane_b32 s38, v250, 3
	v_readlane_b32 s39, v250, 4
	v_readlane_b32 s42, v250, 7
	s_waitcnt lgkmcnt(0)
	v_pk_add_f32 v[86:87], v[86:87], v[88:89]
	ds_bpermute_b32 v89, v84, v87
	ds_bpermute_b32 v88, v84, v86
	v_readlane_b32 s43, v250, 8
	s_waitcnt lgkmcnt(0)
	v_pk_add_f32 v[86:87], v[86:87], v[88:89]
	ds_bpermute_b32 v89, v85, v87
	ds_bpermute_b32 v88, v85, v86
	s_waitcnt lgkmcnt(0)
	v_pk_add_f32 v[86:87], v[86:87], v[88:89]
	s_nop 0
	v_pk_mul_f32 v[86:87], v[86:87], s[0:1] op_sel_hi:[1,0]
	s_mov_b32 s0, 0x800000
	v_fma_f32 v0, -v87, v87, v86
	v_max_f32_e32 v0, 0, v0
	v_add_f32_e32 v0, 0x3727c5ac, v0
	v_cmp_gt_f32_e32 vcc, s0, v0
	v_mul_f32_e32 v71, 0x4b800000, v0
	v_pk_add_f32 v[58:59], v[58:59], v[86:87] op_sel:[0,1] neg_lo:[0,1] neg_hi:[0,1]
	v_cndmask_b32_e32 v0, v0, v71, vcc
	v_rsq_f32_e32 v0, v0
	v_pk_add_f32 v[60:61], v[60:61], v[86:87] op_sel:[0,1] neg_lo:[0,1] neg_hi:[0,1]
	v_pk_add_f32 v[50:51], v[50:51], v[86:87] op_sel:[0,1] neg_lo:[0,1] neg_hi:[0,1]
	v_pk_add_f32 v[52:53], v[52:53], v[86:87] op_sel:[0,1] neg_lo:[0,1] neg_hi:[0,1]
	v_mul_f32_e32 v71, 0x45800000, v0
	v_cndmask_b32_e32 v0, v0, v71, vcc
	v_pk_mul_f32 v[58:59], v[58:59], v[0:1] op_sel_hi:[1,0]
	v_pk_mul_f32 v[60:61], v[60:61], v[0:1] op_sel_hi:[1,0]
	v_pk_fma_f32 v[58:59], v[2:3], v[58:59], v[10:11]
	v_pk_fma_f32 v[60:61], v[4:5], v[60:61], v[12:13]
	s_mov_b32 s0, 0x4200000
	v_pk_mul_f32 v[50:51], v[50:51], v[0:1] op_sel_hi:[1,0]
	v_pk_mul_f32 v[52:53], v[52:53], v[0:1] op_sel_hi:[1,0]
	v_cvt_pk_bf16_f32 v61, v60, v61
	v_cvt_pk_bf16_f32 v60, v58, v59
	v_add_co_u32_e32 v58, vcc, s0, v98
	v_pk_fma_f32 v[50:51], v[6:7], v[50:51], v[14:15]
	v_pk_fma_f32 v[52:53], v[8:9], v[52:53], v[16:17]
	v_addc_co_u32_e32 v59, vcc, 0, v99, vcc
	v_cvt_pk_bf16_f32 v53, v52, v53
	v_cvt_pk_bf16_f32 v52, v50, v51
	v_lshl_add_u64 v[118:119], v[58:59], 0, v[112:113]
	global_store_dwordx2 v[118:119], v[52:53], off offset:512
	v_pk_add_f32 v[50:51], v[54:55], v[86:87] op_sel:[0,1] neg_lo:[0,1] neg_hi:[0,1]
	v_pk_add_f32 v[52:53], v[56:57], v[86:87] op_sel:[0,1] neg_lo:[0,1] neg_hi:[0,1]
	v_pk_mul_f32 v[50:51], v[50:51], v[0:1] op_sel_hi:[1,0]
	v_pk_mul_f32 v[52:53], v[52:53], v[0:1] op_sel_hi:[1,0]
	v_pk_fma_f32 v[50:51], v[18:19], v[50:51], v[26:27]
	v_pk_fma_f32 v[52:53], v[20:21], v[52:53], v[28:29]
	v_lshl_add_u64 v[118:119], v[58:59], 0, v[110:111]
	global_store_dwordx2 v[118:119], v[60:61], off
	v_cvt_pk_bf16_f32 v53, v52, v53
	v_cvt_pk_bf16_f32 v52, v50, v51
	v_lshl_add_u64 v[118:119], v[58:59], 0, v[114:115]
	global_store_dwordx2 v[118:119], v[52:53], off offset:1024
	v_pk_add_f32 v[50:51], v[62:63], v[86:87] op_sel:[0,1] neg_lo:[0,1] neg_hi:[0,1]
	v_pk_add_f32 v[52:53], v[64:65], v[86:87] op_sel:[0,1] neg_lo:[0,1] neg_hi:[0,1]
	v_pk_mul_f32 v[50:51], v[50:51], v[0:1] op_sel_hi:[1,0]
	v_pk_mul_f32 v[52:53], v[52:53], v[0:1] op_sel_hi:[1,0]
	v_pk_fma_f32 v[50:51], v[22:23], v[50:51], v[30:31]
	v_pk_fma_f32 v[52:53], v[24:25], v[52:53], v[32:33]
	v_mov_b64_e32 v[60:61], v[36:37]
	v_cvt_pk_bf16_f32 v53, v52, v53
	v_cvt_pk_bf16_f32 v52, v50, v51
	v_lshl_add_u64 v[118:119], v[58:59], 0, v[116:117]
	global_store_dwordx2 v[118:119], v[52:53], off offset:1536
	v_mov_b64_e32 v[58:59], v[34:35]
	v_mov_b64_e32 v[50:51], v[38:39]
	v_mov_b64_e32 v[52:53], v[40:41]
	v_mov_b64_e32 v[54:55], v[42:43]
	v_mov_b64_e32 v[56:57], v[44:45]
	v_mov_b64_e32 v[62:63], v[46:47]
	v_mov_b64_e32 v[64:65], v[48:49]
	s_andn2_b64 exec, exec, s[8:9]
	s_cbranch_execz .LBB0_142

; #define LAS __attribute__((address_space(3)))
; DEVI int tidx() { int t = threadIdx.x; asm volatile("" : "+v"(t)); return t; }
; DEVI int xcd_first_tile() { return (blockIdx.x & 7) * (gridDim.x >> 3) + (blockIdx.x >> 3); }
;   const int tid = tidx(), lane = tid & 63, wid = tid >> 6;
;   const int wm = wid >> 1, wn = wid & 1, r16 = lane & 15, quad = lane >> 4;
;   f32x4 acc[4][8];
; #pragma unroll
;   for (int i = 0; i < 4; i++)
; #pragma unroll
;     for (int j = 0; j < 8; j++) acc[i][j] = (f32x4){0.f, 0.f, 0.f, 0.f};
;   const int nk = (nk_part < 0) ? (K >> 5) : nk_part;
;   const int lrow = tid >> 2, lpc = tid & 3;
;   const int lch = lpc ^ ((0x78 >> (((lrow >> 2) & 3) * 2)) & 3);
;   const u16* ga = A + (size_t)(m0 + lrow) * lda + kbeg + lch * 8;
;   const u16* gb = Bt + (size_t)(n0 + lrow) * K + kbeg + lch * 8;
;   const size_t ga1 = (size_t)64 * lda, gb1 = (size_t)64 * K;
;   const unsigned lds0 = (unsigned)(uintptr_t)(LAS char*)smem + (unsigned)__builtin_amdgcn_readfirstlane(wid) * 1024u;
; DEVI void run_phase(const Params& p, int ph, char* smem) {
;     ...
;       for (int t = xcd_first_tile(); t < 512 + 16 * 2; t += xcd_tile_step()) {
;         if (t < 512) {
;           int mt_, nt_; tile_coords(t, 64, 8, mt_, nt_);
;           gemm_tile256<EPI_RESID>(p, ox, 256, Bt, 256, mt_ * 256, nt_ * 128, nullptr, 0, smem);
.LBB0_208:
	s_and_b64 vcc, exec, s[2:3]
	s_cbranch_vccz .LBB0_146
	s_lshr_b32 s45, s38, 6
	s_and_b32 s46, s38, 63
	s_lshr_b32 s42, s46, 3
	s_and_b32 s46, s46, 7
	s_lshl_b32 s45, s45, 3
	s_add_i32 s45, s45, s46
	v_readlane_b32 s2, v250, 5
	v_readlane_b32 s3, v250, 6
	v_readlane_b32 s46, v254, 62
	s_mul_i32 s40, s45, 0x20000
	s_add_u32 s4, s2, s40
	s_addc_u32 s5, s3, 0
	s_add_u32 s4, s4, 0xe700000
	s_addc_u32 s5, s5, 0
	s_mul_i32 s40, s46, 0x80000
	s_mul_i32 s41, s42, 0x10000
	s_add_i32 s40, s40, s41
	s_add_u32 s10, s2, s40
	s_addc_u32 s11, s3, 0
	s_add_u32 s10, s10, 0x16c00000
	s_addc_u32 s11, s11, 0
	s_movk_i32 s39, 0x78
	v_lshrrev_b32_e32 v0, 2, v145
	v_and_b32_e32 v131, 3, v145
	v_bfe_u32 v136, v145, 4, 2
	v_lshlrev_b32_e32 v136, 1, v136
	v_lshrrev_b32_e64 v136, v136, s39
	v_and_b32_e32 v136, 3, v136
	v_xor_b32_e32 v131, v131, v136
	v_lshlrev_b32_e32 v131, 4, v131
	s_movk_i32 s41, 0x200
	v_mad_u32_u24 v0, v0, s41, v131
	v_bfe_u32 v137, v145, 2, 1
	v_lshl_add_u64 v[134:135], s[10:11], 0, v[0:1]
	s_mov_b32 s12, 64
	s_mov_b32 s13, 0
	v_lshl_add_u64 v[132:133], s[4:5], 0, v[0:1]
	v_bfe_u32 v136, v145, 2, 2
	v_lshlrev_b32_e32 v136, 1, v136
	v_lshrrev_b32_e64 v136, v136, s39
	v_and_b32_e32 v136, 3, v136
	v_bfe_u32 v137, v145, 4, 2
	v_xor_b32_e32 v136, v136, v137
	v_lshlrev_b32_e32 v136, 4, v136
	v_and_b32_e32 v131, 15, v145
	v_lshl_or_b32 v136, v131, 6, v136
	v_bfe_u32 v137, v145, 6, 1
	v_lshl_or_b32 v137, v137, 12, v136
	v_lshrrev_b32_e32 v0, 7, v145
	v_lshl_or_b32 v136, v0, 13, v136
	v_and_b32_e32 v140, 1, v131
	v_lshl_or_b32 v131, v0, 7, v131
	v_bfe_u32 v0, v145, 4, 2
	v_lshlrev_b32_e32 v0, 3, v0
	v_bfe_u32 v141, v145, 6, 1
	s_lshl_b32 s40, s45, 19
	s_lshl_b32 s41, s42, 8
	s_add_i32 s40, s40, s41
	s_add_u32 s4, s2, s40
	s_addc_u32 s5, s3, 0
	s_add_u32 s4, s4, 0x4200000
	s_addc_u32 s5, s5, 0
	v_lshlrev_b32_e32 v138, 11, v131
	v_lshl_add_u32 v138, v141, 7, v138
	v_add_u32_e32 v138, v138, v0
	v_mov_b32_e32 v139, 0
	v_lshl_add_u64 v[138:139], s[4:5], 0, v[138:139]
	s_lshl_b32 s40, s45, 20
	s_lshl_b32 s41, s42, 9
	s_add_i32 s40, s40, s41
	s_add_u32 s10, s2, s40
	s_addc_u32 s11, s3, 0
	v_lshlrev_b32_e32 v140, 12, v131
	v_lshl_add_u32 v140, v141, 8, v140
	v_lshl_add_u32 v140, v0, 1, v140
	v_mov_b32_e32 v141, 0
	v_lshl_add_u64 v[140:141], s[10:11], 0, v[140:141]
	s_mov_b32 s2, 0x8000
	s_mov_b32 s3, 0
	v_lshrrev_b32_e32 v0, 6, v145
	v_lshlrev_b32_e32 v0, 10, v0
	s_nop 0
	v_readfirstlane_b32 s46, v0
	s_mov_b32 s43, m0
	s_mov_b32 s4, 64
	s_mov_b32 s5, 0
	v_mov_b32_e32 v2, 0
	v_mov_b32_e32 v3, 0
	v_mov_b32_e32 v4, 0
	v_mov_b32_e32 v5, 0
	v_mov_b32_e32 v6, 0
	v_mov_b32_e32 v7, 0
	v_mov_b32_e32 v8, 0
	v_mov_b32_e32 v9, 0
	v_mov_b32_e32 v10, 0
	v_mov_b32_e32 v11, 0
	v_mov_b32_e32 v12, 0
	v_mov_b32_e32 v13, 0
	v_mov_b32_e32 v14, 0
	v_mov_b32_e32 v15, 0
	v_mov_b32_e32 v16, 0
	v_mov_b32_e32 v17, 0
	v_mov_b32_e32 v18, 0
	v_mov_b32_e32 v19, 0
	v_mov_b32_e32 v20, 0
	v_mov_b32_e32 v21, 0
	v_mov_b32_e32 v22, 0
	v_mov_b32_e32 v23, 0
	v_mov_b32_e32 v24, 0
	v_mov_b32_e32 v25, 0
	v_mov_b32_e32 v26, 0
	v_mov_b32_e32 v27, 0
	v_mov_b32_e32 v28, 0
	v_mov_b32_e32 v29, 0
	v_mov_b32_e32 v30, 0
	v_mov_b32_e32 v31, 0
	v_mov_b32_e32 v32, 0
	v_mov_b32_e32 v33, 0
	v_mov_b32_e32 v34, 0
	v_mov_b32_e32 v35, 0
	v_mov_b32_e32 v36, 0
	v_mov_b32_e32 v37, 0
	v_mov_b32_e32 v38, 0
	v_mov_b32_e32 v39, 0
	v_mov_b32_e32 v40, 0
	v_mov_b32_e32 v41, 0
	v_mov_b32_e32 v42, 0
	v_mov_b32_e32 v43, 0
	v_mov_b32_e32 v44, 0
	v_mov_b32_e32 v45, 0
	v_mov_b32_e32 v46, 0
	v_mov_b32_e32 v47, 0
	v_mov_b32_e32 v48, 0
	v_mov_b32_e32 v49, 0
	v_mov_b32_e32 v50, 0
	v_mov_b32_e32 v51, 0
	v_mov_b32_e32 v52, 0
	v_mov_b32_e32 v53, 0
	v_mov_b32_e32 v54, 0
	v_mov_b32_e32 v55, 0
	v_mov_b32_e32 v56, 0
	v_mov_b32_e32 v57, 0
	v_mov_b32_e32 v58, 0
	v_mov_b32_e32 v59, 0
	v_mov_b32_e32 v60, 0
	v_mov_b32_e32 v61, 0
	v_mov_b32_e32 v62, 0
	v_mov_b32_e32 v63, 0
	v_mov_b32_e32 v64, 0
	v_mov_b32_e32 v65, 0
	v_mov_b32_e32 v66, 0
	v_mov_b32_e32 v67, 0
	v_mov_b32_e32 v68, 0
	v_mov_b32_e32 v69, 0
	v_mov_b32_e32 v70, 0
	v_mov_b32_e32 v71, 0
	v_mov_b32_e32 v72, 0
	v_mov_b32_e32 v73, 0
	v_mov_b32_e32 v74, 0
	v_mov_b32_e32 v75, 0
	v_mov_b32_e32 v76, 0
	v_mov_b32_e32 v77, 0
	v_mov_b32_e32 v78, 0
	v_mov_b32_e32 v79, 0
	v_mov_b32_e32 v80, 0
	v_mov_b32_e32 v81, 0
	v_mov_b32_e32 v82, 0
	v_mov_b32_e32 v83, 0
	v_mov_b32_e32 v84, 0
	v_mov_b32_e32 v85, 0
	v_mov_b32_e32 v86, 0
	v_mov_b32_e32 v87, 0
	v_mov_b32_e32 v88, 0
	v_mov_b32_e32 v89, 0
	v_mov_b32_e32 v90, 0
	v_mov_b32_e32 v91, 0
	v_mov_b32_e32 v92, 0
	v_mov_b32_e32 v93, 0
	v_mov_b32_e32 v94, 0
	v_mov_b32_e32 v95, 0
	v_mov_b32_e32 v96, 0
	v_mov_b32_e32 v97, 0
	v_mov_b32_e32 v98, 0
	v_mov_b32_e32 v99, 0
	v_mov_b32_e32 v100, 0
	v_mov_b32_e32 v101, 0
	v_mov_b32_e32 v102, 0
	v_mov_b32_e32 v103, 0
	v_mov_b32_e32 v104, 0
	v_mov_b32_e32 v105, 0
	v_mov_b32_e32 v106, 0
	v_mov_b32_e32 v107, 0
	v_mov_b32_e32 v108, 0
	v_mov_b32_e32 v109, 0
	v_mov_b32_e32 v110, 0
	v_mov_b32_e32 v111, 0
	v_mov_b32_e32 v112, 0
	v_mov_b32_e32 v113, 0
	v_mov_b32_e32 v114, 0
	v_mov_b32_e32 v115, 0
	v_mov_b32_e32 v116, 0
	v_mov_b32_e32 v117, 0
	v_mov_b32_e32 v118, 0
	v_mov_b32_e32 v119, 0
	v_mov_b32_e32 v120, 0
	v_mov_b32_e32 v121, 0
	v_mov_b32_e32 v122, 0
	v_mov_b32_e32 v123, 0
	v_mov_b32_e32 v124, 0
	v_mov_b32_e32 v125, 0
	v_mov_b32_e32 v126, 0
	v_mov_b32_e32 v127, 0
	v_mov_b32_e32 v128, 0
	v_mov_b32_e32 v129, 0
	s_barrier
;     ...
;   __syncthreads();
;   G2_STAGE(0); G2_STAGE(1);
;   const int fsw = (0x78 >> (((r16 >> 2) & 3) * 2)) & 3;
;   const int aoff = (wm * 128 + r16) * 64 + ((quad ^ fsw) << 4);
;   const int boff = 16384 + (wn * 64 + r16) * 64 + ((quad ^ fsw) << 4);
;   for (int kt = 0; kt < nk; kt++) {
;     if (kt + 1 < nk) asm volatile("s_waitcnt vmcnt(6)" ::: "memory");
;     else asm volatile("s_waitcnt vmcnt(0)" ::: "memory");
;     __builtin_amdgcn_s_barrier();
;     asm volatile("" ::: "memory");
;     if (kt + 2 < nk) G2_STAGE(kt + 2);
;     const char* cS = smem + (kt % 3) * 24576;
;     bf16x8 xa[8], wb[4];
; #pragma unroll
;     for (int f = 0; f < 8; f++) xa[f] = *(const bf16x8*)(cS + aoff + f * 1024);
; #pragma unroll
;     for (int f = 0; f < 4; f++) wb[f] = *(const bf16x8*)(cS + boff + f * 1024);
; #pragma unroll
;     for (int nf = 0; nf < 4; nf++)
; #pragma unroll
;       for (int mf = 0; mf < 8; mf++)
;         acc[nf][mf] = __builtin_amdgcn_mfma_f32_16x16x32_bf16(wb[nf], xa[mf], acc[nf][mf], 0, 0, 0);
;   }
	s_add_i32 s42, s46, 0x0
	s_mov_b32 m0, s42
	v_lshl_add_u64 v[142:143], v[132:133], 0, s[2:3]
	global_load_lds_dwordx4 v[132:133], off
	s_addk_i32 m0, 0x1000
	s_nop 0
	global_load_lds_dwordx4 v[142:143], off
	v_lshl_add_u64 v[142:143], v[142:143], 0, s[2:3]
	s_addk_i32 m0, 0x1000
	s_nop 0
	global_load_lds_dwordx4 v[142:143], off
	v_lshl_add_u64 v[142:143], v[142:143], 0, s[2:3]
	s_addk_i32 m0, 0x1000
	s_nop 0
	global_load_lds_dwordx4 v[142:143], off
	s_addk_i32 m0, 0x1000
	v_lshl_add_u64 v[142:143], v[134:135], 0, s[2:3]
	s_nop 0
	global_load_lds_dwordx4 v[134:135], off
	s_addk_i32 m0, 0x1000
	v_lshl_add_u64 v[132:133], v[132:133], 0, s[12:13]
	s_nop 0
	global_load_lds_dwordx4 v[142:143], off
	v_lshl_add_u64 v[134:135], v[134:135], 0, s[4:5]
	s_nop 0
	s_add_i32 s42, s46, 0x6000
	s_mov_b32 m0, s42
	v_lshl_add_u64 v[142:143], v[132:133], 0, s[2:3]
	global_load_lds_dwordx4 v[132:133], off
	s_addk_i32 m0, 0x1000
	s_nop 0
	global_load_lds_dwordx4 v[142:143], off
	v_lshl_add_u64 v[142:143], v[142:143], 0, s[2:3]
	s_addk_i32 m0, 0x1000
	s_nop 0
	global_load_lds_dwordx4 v[142:143], off
	v_lshl_add_u64 v[142:143], v[142:143], 0, s[2:3]
	s_addk_i32 m0, 0x1000
	s_nop 0
	global_load_lds_dwordx4 v[142:143], off
	s_addk_i32 m0, 0x1000
	v_lshl_add_u64 v[142:143], v[134:135], 0, s[2:3]
	s_nop 0
	global_load_lds_dwordx4 v[134:135], off
	s_addk_i32 m0, 0x1000
	v_lshl_add_u64 v[132:133], v[132:133], 0, s[12:13]
	s_nop 0
	global_load_lds_dwordx4 v[142:143], off
	v_lshl_add_u64 v[134:135], v[134:135], 0, s[4:5]
	s_nop 0
	s_add_i32 s42, s46, 0xc000
	s_mov_b32 m0, s42
	v_lshl_add_u64 v[142:143], v[132:133], 0, s[2:3]
	global_load_lds_dwordx4 v[132:133], off
	s_addk_i32 m0, 0x1000
	s_nop 0
	global_load_lds_dwordx4 v[142:143], off
	v_lshl_add_u64 v[142:143], v[142:143], 0, s[2:3]
	s_addk_i32 m0, 0x1000
	s_nop 0
	global_load_lds_dwordx4 v[142:143], off
	v_lshl_add_u64 v[142:143], v[142:143], 0, s[2:3]
	s_addk_i32 m0, 0x1000
	s_nop 0
	global_load_lds_dwordx4 v[142:143], off
	s_addk_i32 m0, 0x1000
	v_lshl_add_u64 v[142:143], v[134:135], 0, s[2:3]
	s_nop 0
	global_load_lds_dwordx4 v[134:135], off
	s_addk_i32 m0, 0x1000
	v_lshl_add_u64 v[132:133], v[132:133], 0, s[12:13]
	s_nop 0
	global_load_lds_dwordx4 v[142:143], off
	v_lshl_add_u64 v[134:135], v[134:135], 0, s[4:5]
	s_nop 0
	s_waitcnt vmcnt(12)
	s_barrier
	ds_read_b128 v[146:149], v136 offset:0
	ds_read_b128 v[152:155], v136 offset:1024
	ds_read_b128 v[156:159], v136 offset:2048
	ds_read_b128 v[162:165], v136 offset:3072
	ds_read_b128 v[166:169], v136 offset:4096
	ds_read_b128 v[170:173], v136 offset:5120
	ds_read_b128 v[176:179], v136 offset:6144
	ds_read_b128 v[180:183], v136 offset:7168
	ds_read_b128 v[184:187], v137 offset:16384
	ds_read_b128 v[188:191], v137 offset:17408
	ds_read_b128 v[192:195], v137 offset:18432
	ds_read_b128 v[196:199], v137 offset:19456
	s_movk_i32 s40, 0x6000
	s_mov_b32 s41, 0
	s_movk_i32 s39, 2
.Lt8_loop:
	s_waitcnt vmcnt(6) lgkmcnt(0)
	s_barrier
	v_add_u32_e32 v144, s40, v136
	v_mfma_f32_16x16x32_bf16 v[126:129], v[184:187], v[146:149], v[126:129]
	ds_read_b128 v[200:203], v144 offset:0
	v_mfma_f32_16x16x32_bf16 v[122:125], v[184:187], v[152:155], v[122:125]
	ds_read_b128 v[204:207], v144 offset:1024
	v_mfma_f32_16x16x32_bf16 v[118:121], v[184:187], v[156:159], v[118:121]
	ds_read_b128 v[208:211], v144 offset:2048
	v_mfma_f32_16x16x32_bf16 v[114:117], v[184:187], v[162:165], v[114:117]
	ds_read_b128 v[212:215], v144 offset:3072
	v_mfma_f32_16x16x32_bf16 v[110:113], v[184:187], v[166:169], v[110:113]
	ds_read_b128 v[216:219], v144 offset:4096
	v_mfma_f32_16x16x32_bf16 v[106:109], v[184:187], v[170:173], v[106:109]
	ds_read_b128 v[220:223], v144 offset:5120
	v_mfma_f32_16x16x32_bf16 v[102:105], v[184:187], v[176:179], v[102:105]
	ds_read_b128 v[224:227], v144 offset:6144
	v_mfma_f32_16x16x32_bf16 v[98:101], v[184:187], v[180:183], v[98:101]
	ds_read_b128 v[228:231], v144 offset:7168
	v_mfma_f32_16x16x32_bf16 v[94:97], v[188:191], v[146:149], v[94:97]
	v_add_u32_e32 v144, s40, v137
	v_mfma_f32_16x16x32_bf16 v[90:93], v[188:191], v[152:155], v[90:93]
	v_mfma_f32_16x16x32_bf16 v[86:89], v[188:191], v[156:159], v[86:89]
	ds_read_b128 v[232:235], v144 offset:16384
	v_mfma_f32_16x16x32_bf16 v[82:85], v[188:191], v[162:165], v[82:85]
	ds_read_b128 v[236:239], v144 offset:17408
	v_mfma_f32_16x16x32_bf16 v[78:81], v[188:191], v[166:169], v[78:81]
	ds_read_b128 v[240:243], v144 offset:18432
	v_mfma_f32_16x16x32_bf16 v[74:77], v[188:191], v[170:173], v[74:77]
	ds_read_b128 v[244:247], v144 offset:19456
	s_add_i32 s42, s46, s41
	v_mfma_f32_16x16x32_bf16 v[70:73], v[188:191], v[176:179], v[70:73]
	s_mov_b32 m0, s42
	v_lshl_add_u64 v[142:143], v[132:133], 0, s[2:3]
	v_mfma_f32_16x16x32_bf16 v[66:69], v[188:191], v[180:183], v[66:69]
	global_load_lds_dwordx4 v[132:133], off
	s_addk_i32 m0, 0x1000
	v_mfma_f32_16x16x32_bf16 v[62:65], v[192:195], v[146:149], v[62:65]
	v_mfma_f32_16x16x32_bf16 v[58:61], v[192:195], v[152:155], v[58:61]
	v_mfma_f32_16x16x32_bf16 v[54:57], v[192:195], v[156:159], v[54:57]
	global_load_lds_dwordx4 v[142:143], off
	v_lshl_add_u64 v[142:143], v[142:143], 0, s[2:3]
	s_addk_i32 m0, 0x1000
	v_mfma_f32_16x16x32_bf16 v[50:53], v[192:195], v[162:165], v[50:53]
	v_mfma_f32_16x16x32_bf16 v[46:49], v[192:195], v[166:169], v[46:49]
	v_mfma_f32_16x16x32_bf16 v[42:45], v[192:195], v[170:173], v[42:45]
	global_load_lds_dwordx4 v[142:143], off
	v_lshl_add_u64 v[142:143], v[142:143], 0, s[2:3]
	s_addk_i32 m0, 0x1000
	v_mfma_f32_16x16x32_bf16 v[38:41], v[192:195], v[176:179], v[38:41]
	v_mfma_f32_16x16x32_bf16 v[34:37], v[192:195], v[180:183], v[34:37]
	v_mfma_f32_16x16x32_bf16 v[30:33], v[196:199], v[146:149], v[30:33]
	global_load_lds_dwordx4 v[142:143], off
	s_addk_i32 m0, 0x1000
	v_lshl_add_u64 v[142:143], v[134:135], 0, s[2:3]
	v_mfma_f32_16x16x32_bf16 v[26:29], v[196:199], v[152:155], v[26:29]
	v_mfma_f32_16x16x32_bf16 v[22:25], v[196:199], v[156:159], v[22:25]
	v_mfma_f32_16x16x32_bf16 v[18:21], v[196:199], v[162:165], v[18:21]
	global_load_lds_dwordx4 v[134:135], off
	s_addk_i32 m0, 0x1000
	v_lshl_add_u64 v[132:133], v[132:133], 0, s[12:13]
	v_mfma_f32_16x16x32_bf16 v[14:17], v[196:199], v[166:169], v[14:17]
	v_mfma_f32_16x16x32_bf16 v[10:13], v[196:199], v[170:173], v[10:13]
	v_mfma_f32_16x16x32_bf16 v[6:9], v[196:199], v[176:179], v[6:9]
	global_load_lds_dwordx4 v[142:143], off
	v_lshl_add_u64 v[134:135], v[134:135], 0, s[4:5]
	v_mfma_f32_16x16x32_bf16 v[2:5], v[196:199], v[180:183], v[2:5]
	s_mov_b32 s41, s40
	s_add_i32 s40, s40, 0x6000
	s_cmp_eq_u32 s40, 0x12000
	s_cselect_b32 s40, 0, s40
	s_waitcnt vmcnt(6) lgkmcnt(0)
	s_barrier
;     ...
;   __syncthreads();
;   G2_STAGE(0); G2_STAGE(1);
;   const int fsw = (0x78 >> (((r16 >> 2) & 3) * 2)) & 3;
;   const int aoff = (wm * 128 + r16) * 64 + ((quad ^ fsw) << 4);
;   const int boff = 16384 + (wn * 64 + r16) * 64 + ((quad ^ fsw) << 4);
;   for (int kt = 0; kt < nk; kt++) {
;     if (kt + 1 < nk) asm volatile("s_waitcnt vmcnt(6)" ::: "memory");
;     else asm volatile("s_waitcnt vmcnt(0)" ::: "memory");
;     __builtin_amdgcn_s_barrier();
;     asm volatile("" ::: "memory");
;     if (kt + 2 < nk) G2_STAGE(kt + 2);
;     const char* cS = smem + (kt % 3) * 24576;
;     bf16x8 xa[8], wb[4];
; #pragma unroll
;     for (int f = 0; f < 8; f++) xa[f] = *(const bf16x8*)(cS + aoff + f * 1024);
; #pragma unroll
;     for (int f = 0; f < 4; f++) wb[f] = *(const bf16x8*)(cS + boff + f * 1024);
; #pragma unroll
;     for (int nf = 0; nf < 4; nf++)
; #pragma unroll
;       for (int mf = 0; mf < 8; mf++)
;         acc[nf][mf] = __builtin_amdgcn_mfma_f32_16x16x32_bf16(wb[nf], xa[mf], acc[nf][mf], 0, 0, 0);
;   }
	v_add_u32_e32 v144, s40, v136
	v_mfma_f32_16x16x32_bf16 v[126:129], v[232:235], v[200:203], v[126:129]
	ds_read_b128 v[146:149], v144 offset:0
	v_mfma_f32_16x16x32_bf16 v[122:125], v[232:235], v[204:207], v[122:125]
	ds_read_b128 v[152:155], v144 offset:1024
	v_mfma_f32_16x16x32_bf16 v[118:121], v[232:235], v[208:211], v[118:121]
	ds_read_b128 v[156:159], v144 offset:2048
	v_mfma_f32_16x16x32_bf16 v[114:117], v[232:235], v[212:215], v[114:117]
	ds_read_b128 v[162:165], v144 offset:3072
	v_mfma_f32_16x16x32_bf16 v[110:113], v[232:235], v[216:219], v[110:113]
	ds_read_b128 v[166:169], v144 offset:4096
	v_mfma_f32_16x16x32_bf16 v[106:109], v[232:235], v[220:223], v[106:109]
	ds_read_b128 v[170:173], v144 offset:5120
	v_mfma_f32_16x16x32_bf16 v[102:105], v[232:235], v[224:227], v[102:105]
	ds_read_b128 v[176:179], v144 offset:6144
	v_mfma_f32_16x16x32_bf16 v[98:101], v[232:235], v[228:231], v[98:101]
	ds_read_b128 v[180:183], v144 offset:7168
	v_mfma_f32_16x16x32_bf16 v[94:97], v[236:239], v[200:203], v[94:97]
	v_add_u32_e32 v144, s40, v137
	v_mfma_f32_16x16x32_bf16 v[90:93], v[236:239], v[204:207], v[90:93]
	v_mfma_f32_16x16x32_bf16 v[86:89], v[236:239], v[208:211], v[86:89]
	ds_read_b128 v[184:187], v144 offset:16384
	v_mfma_f32_16x16x32_bf16 v[82:85], v[236:239], v[212:215], v[82:85]
	ds_read_b128 v[188:191], v144 offset:17408
	v_mfma_f32_16x16x32_bf16 v[78:81], v[236:239], v[216:219], v[78:81]
	ds_read_b128 v[192:195], v144 offset:18432
	v_mfma_f32_16x16x32_bf16 v[74:77], v[236:239], v[220:223], v[74:77]
	ds_read_b128 v[196:199], v144 offset:19456
	s_add_i32 s42, s46, s41
	v_mfma_f32_16x16x32_bf16 v[70:73], v[236:239], v[224:227], v[70:73]
	s_mov_b32 m0, s42
	v_lshl_add_u64 v[142:143], v[132:133], 0, s[2:3]
	v_mfma_f32_16x16x32_bf16 v[66:69], v[236:239], v[228:231], v[66:69]
	global_load_lds_dwordx4 v[132:133], off
	s_addk_i32 m0, 0x1000
	v_mfma_f32_16x16x32_bf16 v[62:65], v[240:243], v[200:203], v[62:65]
	v_mfma_f32_16x16x32_bf16 v[58:61], v[240:243], v[204:207], v[58:61]
	v_mfma_f32_16x16x32_bf16 v[54:57], v[240:243], v[208:211], v[54:57]
	global_load_lds_dwordx4 v[142:143], off
	v_lshl_add_u64 v[142:143], v[142:143], 0, s[2:3]
	s_addk_i32 m0, 0x1000
	v_mfma_f32_16x16x32_bf16 v[50:53], v[240:243], v[212:215], v[50:53]
	v_mfma_f32_16x16x32_bf16 v[46:49], v[240:243], v[216:219], v[46:49]
	v_mfma_f32_16x16x32_bf16 v[42:45], v[240:243], v[220:223], v[42:45]
	global_load_lds_dwordx4 v[142:143], off
	v_lshl_add_u64 v[142:143], v[142:143], 0, s[2:3]
	s_addk_i32 m0, 0x1000
	v_mfma_f32_16x16x32_bf16 v[38:41], v[240:243], v[224:227], v[38:41]
	v_mfma_f32_16x16x32_bf16 v[34:37], v[240:243], v[228:231], v[34:37]
	v_mfma_f32_16x16x32_bf16 v[30:33], v[244:247], v[200:203], v[30:33]
	global_load_lds_dwordx4 v[142:143], off
	s_addk_i32 m0, 0x1000
	v_lshl_add_u64 v[142:143], v[134:135], 0, s[2:3]
	v_mfma_f32_16x16x32_bf16 v[26:29], v[244:247], v[204:207], v[26:29]
	v_mfma_f32_16x16x32_bf16 v[22:25], v[244:247], v[208:211], v[22:25]
	v_mfma_f32_16x16x32_bf16 v[18:21], v[244:247], v[212:215], v[18:21]
	global_load_lds_dwordx4 v[134:135], off
	s_addk_i32 m0, 0x1000
	v_lshl_add_u64 v[132:133], v[132:133], 0, s[12:13]
	v_mfma_f32_16x16x32_bf16 v[14:17], v[244:247], v[216:219], v[14:17]
	v_mfma_f32_16x16x32_bf16 v[10:13], v[244:247], v[220:223], v[10:13]
	v_mfma_f32_16x16x32_bf16 v[6:9], v[244:247], v[224:227], v[6:9]
	global_load_lds_dwordx4 v[142:143], off
	v_lshl_add_u64 v[134:135], v[134:135], 0, s[4:5]
	v_mfma_f32_16x16x32_bf16 v[2:5], v[244:247], v[228:231], v[2:5]
	s_mov_b32 s41, s40
	s_add_i32 s40, s40, 0x6000
	s_cmp_eq_u32 s40, 0x12000
	s_cselect_b32 s40, 0, s40
	s_sub_i32 s39, s39, 1
	s_cmp_lg_u32 s39, 0
	s_cbranch_scc1 .Lt8_loop
	s_waitcnt vmcnt(6) lgkmcnt(0)
	s_barrier
	v_add_u32_e32 v144, s40, v136
	v_mfma_f32_16x16x32_bf16 v[126:129], v[184:187], v[146:149], v[126:129]
	ds_read_b128 v[200:203], v144 offset:0
	v_mfma_f32_16x16x32_bf16 v[122:125], v[184:187], v[152:155], v[122:125]
	ds_read_b128 v[204:207], v144 offset:1024
	v_mfma_f32_16x16x32_bf16 v[118:121], v[184:187], v[156:159], v[118:121]
	ds_read_b128 v[208:211], v144 offset:2048
	v_mfma_f32_16x16x32_bf16 v[114:117], v[184:187], v[162:165], v[114:117]
	ds_read_b128 v[212:215], v144 offset:3072
	v_mfma_f32_16x16x32_bf16 v[110:113], v[184:187], v[166:169], v[110:113]
	ds_read_b128 v[216:219], v144 offset:4096
	v_mfma_f32_16x16x32_bf16 v[106:109], v[184:187], v[170:173], v[106:109]
	ds_read_b128 v[220:223], v144 offset:5120
	v_mfma_f32_16x16x32_bf16 v[102:105], v[184:187], v[176:179], v[102:105]
	ds_read_b128 v[224:227], v144 offset:6144
	v_mfma_f32_16x16x32_bf16 v[98:101], v[184:187], v[180:183], v[98:101]
	ds_read_b128 v[228:231], v144 offset:7168
	v_mfma_f32_16x16x32_bf16 v[94:97], v[188:191], v[146:149], v[94:97]
	v_add_u32_e32 v144, s40, v137
	v_mfma_f32_16x16x32_bf16 v[90:93], v[188:191], v[152:155], v[90:93]
	v_mfma_f32_16x16x32_bf16 v[86:89], v[188:191], v[156:159], v[86:89]
	ds_read_b128 v[232:235], v144 offset:16384
	v_mfma_f32_16x16x32_bf16 v[82:85], v[188:191], v[162:165], v[82:85]
	ds_read_b128 v[236:239], v144 offset:17408
	v_mfma_f32_16x16x32_bf16 v[78:81], v[188:191], v[166:169], v[78:81]
	ds_read_b128 v[240:243], v144 offset:18432
	v_mfma_f32_16x16x32_bf16 v[74:77], v[188:191], v[170:173], v[74:77]
	ds_read_b128 v[244:247], v144 offset:19456
	s_add_i32 s42, s46, s41
	v_mfma_f32_16x16x32_bf16 v[70:73], v[188:191], v[176:179], v[70:73]
	s_mov_b32 m0, s42
	v_lshl_add_u64 v[142:143], v[132:133], 0, s[2:3]
	v_mfma_f32_16x16x32_bf16 v[66:69], v[188:191], v[180:183], v[66:69]
	global_load_lds_dwordx4 v[132:133], off
	s_addk_i32 m0, 0x1000
	v_mfma_f32_16x16x32_bf16 v[62:65], v[192:195], v[146:149], v[62:65]
;     ...
;   for (int kt = 0; kt < nk; kt++) {
;     if (kt + 1 < nk) asm volatile("s_waitcnt vmcnt(6)" ::: "memory");
;     else asm volatile("s_waitcnt vmcnt(0)" ::: "memory");
;     __builtin_amdgcn_s_barrier();
;     asm volatile("" ::: "memory");
;     if (kt + 2 < nk) G2_STAGE(kt + 2);
;     const char* cS = smem + (kt % 3) * 24576;
;     bf16x8 xa[8], wb[4];
; #pragma unroll
;     for (int f = 0; f < 8; f++) xa[f] = *(const bf16x8*)(cS + aoff + f * 1024);
; #pragma unroll
;     for (int f = 0; f < 4; f++) wb[f] = *(const bf16x8*)(cS + boff + f * 1024);
; #pragma unroll
;     for (int nf = 0; nf < 4; nf++)
; #pragma unroll
;       for (int mf = 0; mf < 8; mf++)
;         acc[nf][mf] = __builtin_amdgcn_mfma_f32_16x16x32_bf16(wb[nf], xa[mf], acc[nf][mf], 0, 0, 0);
;   }
	v_mfma_f32_16x16x32_bf16 v[58:61], v[192:195], v[152:155], v[58:61]
	v_mfma_f32_16x16x32_bf16 v[54:57], v[192:195], v[156:159], v[54:57]
	global_load_lds_dwordx4 v[142:143], off
	v_lshl_add_u64 v[142:143], v[142:143], 0, s[2:3]
	s_addk_i32 m0, 0x1000
	v_mfma_f32_16x16x32_bf16 v[50:53], v[192:195], v[162:165], v[50:53]
	v_mfma_f32_16x16x32_bf16 v[46:49], v[192:195], v[166:169], v[46:49]
	v_mfma_f32_16x16x32_bf16 v[42:45], v[192:195], v[170:173], v[42:45]
	global_load_lds_dwordx4 v[142:143], off
	v_lshl_add_u64 v[142:143], v[142:143], 0, s[2:3]
	s_addk_i32 m0, 0x1000
	v_mfma_f32_16x16x32_bf16 v[38:41], v[192:195], v[176:179], v[38:41]
	v_mfma_f32_16x16x32_bf16 v[34:37], v[192:195], v[180:183], v[34:37]
	v_mfma_f32_16x16x32_bf16 v[30:33], v[196:199], v[146:149], v[30:33]
	global_load_lds_dwordx4 v[142:143], off
	s_addk_i32 m0, 0x1000
	v_lshl_add_u64 v[142:143], v[134:135], 0, s[2:3]
	v_mfma_f32_16x16x32_bf16 v[26:29], v[196:199], v[152:155], v[26:29]
	v_mfma_f32_16x16x32_bf16 v[22:25], v[196:199], v[156:159], v[22:25]
	v_mfma_f32_16x16x32_bf16 v[18:21], v[196:199], v[162:165], v[18:21]
	global_load_lds_dwordx4 v[134:135], off
	s_addk_i32 m0, 0x1000
	v_lshl_add_u64 v[132:133], v[132:133], 0, s[12:13]
	v_mfma_f32_16x16x32_bf16 v[14:17], v[196:199], v[166:169], v[14:17]
	v_mfma_f32_16x16x32_bf16 v[10:13], v[196:199], v[170:173], v[10:13]
	v_mfma_f32_16x16x32_bf16 v[6:9], v[196:199], v[176:179], v[6:9]
	global_load_lds_dwordx4 v[142:143], off
	v_lshl_add_u64 v[134:135], v[134:135], 0, s[4:5]
	v_mfma_f32_16x16x32_bf16 v[2:5], v[196:199], v[180:183], v[2:5]
	s_mov_b32 s41, s40
	s_add_i32 s40, s40, 0x6000
	s_cmp_eq_u32 s40, 0x12000
	s_cselect_b32 s40, 0, s40
	s_waitcnt vmcnt(6) lgkmcnt(0)
	s_barrier
	v_add_u32_e32 v144, s40, v136
	v_mfma_f32_16x16x32_bf16 v[126:129], v[232:235], v[200:203], v[126:129]
	ds_read_b128 v[146:149], v144 offset:0
	v_mfma_f32_16x16x32_bf16 v[122:125], v[232:235], v[204:207], v[122:125]
	ds_read_b128 v[152:155], v144 offset:1024
	v_mfma_f32_16x16x32_bf16 v[118:121], v[232:235], v[208:211], v[118:121]
	ds_read_b128 v[156:159], v144 offset:2048
	v_mfma_f32_16x16x32_bf16 v[114:117], v[232:235], v[212:215], v[114:117]
	ds_read_b128 v[162:165], v144 offset:3072
	v_mfma_f32_16x16x32_bf16 v[110:113], v[232:235], v[216:219], v[110:113]
	ds_read_b128 v[166:169], v144 offset:4096
	v_mfma_f32_16x16x32_bf16 v[106:109], v[232:235], v[220:223], v[106:109]
	ds_read_b128 v[170:173], v144 offset:5120
	v_mfma_f32_16x16x32_bf16 v[102:105], v[232:235], v[224:227], v[102:105]
	ds_read_b128 v[176:179], v144 offset:6144
	v_mfma_f32_16x16x32_bf16 v[98:101], v[232:235], v[228:231], v[98:101]
	ds_read_b128 v[180:183], v144 offset:7168
	v_mfma_f32_16x16x32_bf16 v[94:97], v[236:239], v[200:203], v[94:97]
	v_add_u32_e32 v144, s40, v137
	v_mfma_f32_16x16x32_bf16 v[90:93], v[236:239], v[204:207], v[90:93]
	v_mfma_f32_16x16x32_bf16 v[86:89], v[236:239], v[208:211], v[86:89]
	ds_read_b128 v[184:187], v144 offset:16384
	v_mfma_f32_16x16x32_bf16 v[82:85], v[236:239], v[212:215], v[82:85]
	ds_read_b128 v[188:191], v144 offset:17408
	v_mfma_f32_16x16x32_bf16 v[78:81], v[236:239], v[216:219], v[78:81]
	ds_read_b128 v[192:195], v144 offset:18432
	v_mfma_f32_16x16x32_bf16 v[74:77], v[236:239], v[220:223], v[74:77]
	ds_read_b128 v[196:199], v144 offset:19456
	v_mfma_f32_16x16x32_bf16 v[70:73], v[236:239], v[224:227], v[70:73]
	v_mfma_f32_16x16x32_bf16 v[66:69], v[236:239], v[228:231], v[66:69]
	v_mfma_f32_16x16x32_bf16 v[62:65], v[240:243], v[200:203], v[62:65]
	v_mfma_f32_16x16x32_bf16 v[58:61], v[240:243], v[204:207], v[58:61]
	v_mfma_f32_16x16x32_bf16 v[54:57], v[240:243], v[208:211], v[54:57]
	v_mfma_f32_16x16x32_bf16 v[50:53], v[240:243], v[212:215], v[50:53]
	v_mfma_f32_16x16x32_bf16 v[46:49], v[240:243], v[216:219], v[46:49]
	v_mfma_f32_16x16x32_bf16 v[42:45], v[240:243], v[220:223], v[42:45]
	v_mfma_f32_16x16x32_bf16 v[38:41], v[240:243], v[224:227], v[38:41]
	v_mfma_f32_16x16x32_bf16 v[34:37], v[240:243], v[228:231], v[34:37]
	v_mfma_f32_16x16x32_bf16 v[30:33], v[244:247], v[200:203], v[30:33]
	v_mfma_f32_16x16x32_bf16 v[26:29], v[244:247], v[204:207], v[26:29]
	v_mfma_f32_16x16x32_bf16 v[22:25], v[244:247], v[208:211], v[22:25]
	v_mfma_f32_16x16x32_bf16 v[18:21], v[244:247], v[212:215], v[18:21]
	v_mfma_f32_16x16x32_bf16 v[14:17], v[244:247], v[216:219], v[14:17]
	v_mfma_f32_16x16x32_bf16 v[10:13], v[244:247], v[220:223], v[10:13]
	v_mfma_f32_16x16x32_bf16 v[6:9], v[244:247], v[224:227], v[6:9]
	v_mfma_f32_16x16x32_bf16 v[2:5], v[244:247], v[228:231], v[2:5]
	s_mov_b32 s41, s40
	s_add_i32 s40, s40, 0x6000
	s_cmp_eq_u32 s40, 0x12000
	s_cselect_b32 s40, 0, s40
	s_waitcnt vmcnt(0) lgkmcnt(0)
	s_barrier
; DEVI unsigned pack2(float a, float b) { return __builtin_bit_cast(unsigned, __builtin_convertvector((f32x2_t){a, b}, bf16x2_t)); }
; DEVI float blo(unsigned u) { return __uint_as_float(u << 16); }
; DEVI float bhi(unsigned u) { return __uint_as_float(u & 0xffff0000u); }
; DEVI float siluf_(float x) { return x * __builtin_amdgcn_rcpf(1.f + __expf(-x)); }
;     ...
;   for (int kt = 0; kt < nk; kt++) {
;     if (kt + 1 < nk) asm volatile("s_waitcnt vmcnt(6)" ::: "memory");
;     else asm volatile("s_waitcnt vmcnt(0)" ::: "memory");
;     __builtin_amdgcn_s_barrier();
;     asm volatile("" ::: "memory");
;     if (kt + 2 < nk) G2_STAGE(kt + 2);
;     const char* cS = smem + (kt % 3) * 24576;
;     bf16x8 xa[8], wb[4];
; #pragma unroll
;     for (int f = 0; f < 8; f++) xa[f] = *(const bf16x8*)(cS + aoff + f * 1024);
; #pragma unroll
;     for (int f = 0; f < 4; f++) wb[f] = *(const bf16x8*)(cS + boff + f * 1024);
; #pragma unroll
;     for (int nf = 0; nf < 4; nf++)
; #pragma unroll
;       for (int mf = 0; mf < 8; mf++)
;         acc[nf][mf] = __builtin_amdgcn_mfma_f32_16x16x32_bf16(wb[nf], xa[mf], acc[nf][mf], 0, 0, 0);
;   }
;     ...
; #pragma unroll
;   for (int mf = 0; mf < 8; mf++) {
;     const int row = m0 + wm * 128 + mf * 16 + r16;
;     if (EPI == EPI_SWIGLU) {
; #pragma unroll
;       for (int nf = 0; nf < 2; nf++) {
;         const int hcol = (n0 >> 1) + wn * 32 + nf * 16 + quad * 4;
;         f32x4 g = acc[nf][mf], u = acc[nf + 2][mf];
;         u32x2 pk;
;         pk[0] = pack2(siluf_(g[0]) * u[0], siluf_(g[1]) * u[1]);
;         pk[1] = pack2(siluf_(g[2]) * u[2], siluf_(g[3]) * u[3]);
;         *(u32x2*)(outb + (size_t)row * DFF + hcol) = pk;
;       }
;     } else {
; #pragma unroll
;       for (int nf = 0; nf < 4; nf++) {
;         const int col = n0 + wn * 64 + nf * 16 + quad * 4;
;         f32x4 a = acc[nf][mf];
;         if (EPI == EPI_RESID || EPI == EPI_RESID_ATOMIC) {
;           f32x4 x = a;
;           if (EPI == EPI_RESID || kpart == 0) {
;             const u32x2 xr = *(const u32x2*)((const u16*)(p.ws + WS_XB) + (size_t)row * 1024 + col);
;             x[0] += ALPHA * blo(xr[0]); x[1] += ALPHA * bhi(xr[0]); x[2] += ALPHA * blo(xr[1]); x[3] += ALPHA * bhi(xr[1]);
;           }
;           if (EPI == EPI_RESID) *(f32x4*)((float*)(p.ws + WS_XF) + (size_t)row * 1024 + col) = x;
	v_add_u32_e32 v144, s40, v136
	v_mfma_f32_16x16x32_bf16 v[126:129], v[184:187], v[146:149], v[126:129]
	ds_read_b128 v[200:203], v144 offset:0
	v_mfma_f32_16x16x32_bf16 v[122:125], v[184:187], v[152:155], v[122:125]
	ds_read_b128 v[204:207], v144 offset:1024
	v_mfma_f32_16x16x32_bf16 v[118:121], v[184:187], v[156:159], v[118:121]
	ds_read_b128 v[208:211], v144 offset:2048
	v_mfma_f32_16x16x32_bf16 v[114:117], v[184:187], v[162:165], v[114:117]
	ds_read_b128 v[212:215], v144 offset:3072
	v_mfma_f32_16x16x32_bf16 v[110:113], v[184:187], v[166:169], v[110:113]
	ds_read_b128 v[216:219], v144 offset:4096
	v_mfma_f32_16x16x32_bf16 v[106:109], v[184:187], v[170:173], v[106:109]
	ds_read_b128 v[220:223], v144 offset:5120
	v_mfma_f32_16x16x32_bf16 v[102:105], v[184:187], v[176:179], v[102:105]
	ds_read_b128 v[224:227], v144 offset:6144
	v_mfma_f32_16x16x32_bf16 v[98:101], v[184:187], v[180:183], v[98:101]
	ds_read_b128 v[228:231], v144 offset:7168
	v_mfma_f32_16x16x32_bf16 v[94:97], v[188:191], v[146:149], v[94:97]
	v_add_u32_e32 v144, s40, v137
	v_mfma_f32_16x16x32_bf16 v[90:93], v[188:191], v[152:155], v[90:93]
	v_mfma_f32_16x16x32_bf16 v[86:89], v[188:191], v[156:159], v[86:89]
	ds_read_b128 v[232:235], v144 offset:16384
	v_mfma_f32_16x16x32_bf16 v[82:85], v[188:191], v[162:165], v[82:85]
	ds_read_b128 v[236:239], v144 offset:17408
	v_mfma_f32_16x16x32_bf16 v[78:81], v[188:191], v[166:169], v[78:81]
	ds_read_b128 v[240:243], v144 offset:18432
	v_mfma_f32_16x16x32_bf16 v[74:77], v[188:191], v[170:173], v[74:77]
	ds_read_b128 v[244:247], v144 offset:19456
	v_mfma_f32_16x16x32_bf16 v[70:73], v[188:191], v[176:179], v[70:73]
	v_mfma_f32_16x16x32_bf16 v[66:69], v[188:191], v[180:183], v[66:69]
	v_mfma_f32_16x16x32_bf16 v[62:65], v[192:195], v[146:149], v[62:65]
	v_mfma_f32_16x16x32_bf16 v[58:61], v[192:195], v[152:155], v[58:61]
	v_mfma_f32_16x16x32_bf16 v[54:57], v[192:195], v[156:159], v[54:57]
	v_mfma_f32_16x16x32_bf16 v[50:53], v[192:195], v[162:165], v[50:53]
	v_mfma_f32_16x16x32_bf16 v[46:49], v[192:195], v[166:169], v[46:49]
	v_mfma_f32_16x16x32_bf16 v[42:45], v[192:195], v[170:173], v[42:45]
	v_mfma_f32_16x16x32_bf16 v[38:41], v[192:195], v[176:179], v[38:41]
	v_mfma_f32_16x16x32_bf16 v[34:37], v[192:195], v[180:183], v[34:37]
	v_mfma_f32_16x16x32_bf16 v[30:33], v[196:199], v[146:149], v[30:33]
	v_mfma_f32_16x16x32_bf16 v[26:29], v[196:199], v[152:155], v[26:29]
	v_mfma_f32_16x16x32_bf16 v[22:25], v[196:199], v[156:159], v[22:25]
	v_mfma_f32_16x16x32_bf16 v[18:21], v[196:199], v[162:165], v[18:21]
	v_mfma_f32_16x16x32_bf16 v[14:17], v[196:199], v[166:169], v[14:17]
	v_mfma_f32_16x16x32_bf16 v[10:13], v[196:199], v[170:173], v[10:13]
	v_mfma_f32_16x16x32_bf16 v[6:9], v[196:199], v[176:179], v[6:9]
	v_mfma_f32_16x16x32_bf16 v[2:5], v[196:199], v[180:183], v[2:5]
	s_mov_b32 s41, s40
	s_add_i32 s40, s40, 0x6000
	s_cmp_eq_u32 s40, 0x12000
	s_cselect_b32 s40, 0, s40
	s_mov_b32 s4, 0x8000
	s_mov_b32 s5, 0
	s_mov_b32 s10, 0x10000
	s_mov_b32 s11, 0
	s_mov_b32 s44, 0x3fd744fd
	s_waitcnt lgkmcnt(0)
	v_mfma_f32_16x16x32_bf16 v[126:129], v[232:235], v[200:203], v[126:129]
	v_mfma_f32_16x16x32_bf16 v[122:125], v[232:235], v[204:207], v[122:125]
	v_mfma_f32_16x16x32_bf16 v[118:121], v[232:235], v[208:211], v[118:121]
	v_mfma_f32_16x16x32_bf16 v[114:117], v[232:235], v[212:215], v[114:117]
	v_mfma_f32_16x16x32_bf16 v[110:113], v[232:235], v[216:219], v[110:113]
	global_load_dwordx2 v[146:147], v[138:139], off offset:0
	v_mfma_f32_16x16x32_bf16 v[106:109], v[232:235], v[220:223], v[106:109]
	global_load_dwordx2 v[148:149], v[138:139], off offset:32
	v_mfma_f32_16x16x32_bf16 v[102:105], v[232:235], v[224:227], v[102:105]
	global_load_dwordx2 v[152:153], v[138:139], off offset:64
	v_mfma_f32_16x16x32_bf16 v[98:101], v[232:235], v[228:231], v[98:101]
	global_load_dwordx2 v[154:155], v[138:139], off offset:96
	v_lshl_add_u64 v[138:139], v[138:139], 0, s[4:5]
	v_mfma_f32_16x16x32_bf16 v[94:97], v[236:239], v[200:203], v[94:97]
	global_load_dwordx2 v[156:157], v[138:139], off offset:0
	v_mfma_f32_16x16x32_bf16 v[90:93], v[236:239], v[204:207], v[90:93]
	global_load_dwordx2 v[158:159], v[138:139], off offset:32
	v_mfma_f32_16x16x32_bf16 v[86:89], v[236:239], v[208:211], v[86:89]
	global_load_dwordx2 v[162:163], v[138:139], off offset:64
	v_mfma_f32_16x16x32_bf16 v[82:85], v[236:239], v[212:215], v[82:85]
	global_load_dwordx2 v[164:165], v[138:139], off offset:96
	v_lshl_add_u64 v[138:139], v[138:139], 0, s[4:5]
	v_mfma_f32_16x16x32_bf16 v[78:81], v[236:239], v[216:219], v[78:81]
	global_load_dwordx2 v[166:167], v[138:139], off offset:0
	v_mfma_f32_16x16x32_bf16 v[74:77], v[236:239], v[220:223], v[74:77]
	global_load_dwordx2 v[168:169], v[138:139], off offset:32
	v_mfma_f32_16x16x32_bf16 v[70:73], v[236:239], v[224:227], v[70:73]
	global_load_dwordx2 v[170:171], v[138:139], off offset:64
	v_mfma_f32_16x16x32_bf16 v[66:69], v[236:239], v[228:231], v[66:69]
	global_load_dwordx2 v[172:173], v[138:139], off offset:96
	v_lshl_add_u64 v[138:139], v[138:139], 0, s[4:5]
	v_mfma_f32_16x16x32_bf16 v[62:65], v[240:243], v[200:203], v[62:65]
	global_load_dwordx2 v[176:177], v[138:139], off offset:0
	v_mfma_f32_16x16x32_bf16 v[58:61], v[240:243], v[204:207], v[58:61]
	global_load_dwordx2 v[178:179], v[138:139], off offset:32
	v_mfma_f32_16x16x32_bf16 v[54:57], v[240:243], v[208:211], v[54:57]
	global_load_dwordx2 v[180:181], v[138:139], off offset:64
	v_mfma_f32_16x16x32_bf16 v[50:53], v[240:243], v[212:215], v[50:53]
	global_load_dwordx2 v[182:183], v[138:139], off offset:96
	v_lshl_add_u64 v[138:139], v[138:139], 0, s[4:5]
	v_mfma_f32_16x16x32_bf16 v[46:49], v[240:243], v[216:219], v[46:49]
; DEVI float blo(unsigned u) { return __uint_as_float(u << 16); }
; DEVI float bhi(unsigned u) { return __uint_as_float(u & 0xffff0000u); }
;     ...
;         if (EPI == EPI_RESID || EPI == EPI_RESID_ATOMIC) {
;           f32x4 x = a;
;           if (EPI == EPI_RESID || kpart == 0) {
;             const u32x2 xr = *(const u32x2*)((const u16*)(p.ws + WS_XB) + (size_t)row * 1024 + col);
;             x[0] += ALPHA * blo(xr[0]); x[1] += ALPHA * bhi(xr[0]); x[2] += ALPHA * blo(xr[1]); x[3] += ALPHA * bhi(xr[1]);
;           }
;           if (EPI == EPI_RESID) *(f32x4*)((float*)(p.ws + WS_XF) + (size_t)row * 1024 + col) = x;
;           else *(f32x4*)((float*)(p.ws + WS_SLAB) + ((size_t)kpart * 512 + (row - T_P)) * 1024 + col) = x;
	global_load_dwordx2 v[184:185], v[138:139], off offset:0
	v_mfma_f32_16x16x32_bf16 v[42:45], v[240:243], v[220:223], v[42:45]
	global_load_dwordx2 v[186:187], v[138:139], off offset:32
	v_mfma_f32_16x16x32_bf16 v[38:41], v[240:243], v[224:227], v[38:41]
	global_load_dwordx2 v[188:189], v[138:139], off offset:64
	v_mfma_f32_16x16x32_bf16 v[34:37], v[240:243], v[228:231], v[34:37]
	global_load_dwordx2 v[190:191], v[138:139], off offset:96
	v_lshl_add_u64 v[138:139], v[138:139], 0, s[4:5]
	v_mfma_f32_16x16x32_bf16 v[30:33], v[244:247], v[200:203], v[30:33]
	global_load_dwordx2 v[192:193], v[138:139], off offset:0
	v_mfma_f32_16x16x32_bf16 v[26:29], v[244:247], v[204:207], v[26:29]
	global_load_dwordx2 v[194:195], v[138:139], off offset:32
	v_mfma_f32_16x16x32_bf16 v[22:25], v[244:247], v[208:211], v[22:25]
	global_load_dwordx2 v[196:197], v[138:139], off offset:64
	v_mfma_f32_16x16x32_bf16 v[18:21], v[244:247], v[212:215], v[18:21]
	global_load_dwordx2 v[198:199], v[138:139], off offset:96
	v_lshl_add_u64 v[138:139], v[138:139], 0, s[4:5]
	v_mfma_f32_16x16x32_bf16 v[14:17], v[244:247], v[216:219], v[14:17]
	v_mfma_f32_16x16x32_bf16 v[10:13], v[244:247], v[220:223], v[10:13]
	v_mfma_f32_16x16x32_bf16 v[6:9], v[244:247], v[224:227], v[6:9]
	v_mfma_f32_16x16x32_bf16 v[2:5], v[244:247], v[228:231], v[2:5]
	s_mov_b32 m0, s43
	global_load_dwordx2 v[200:201], v[138:139], off offset:0
	global_load_dwordx2 v[202:203], v[138:139], off offset:32
	global_load_dwordx2 v[204:205], v[138:139], off offset:64
	global_load_dwordx2 v[206:207], v[138:139], off offset:96
	v_lshl_add_u64 v[138:139], v[138:139], 0, s[4:5]
	global_load_dwordx2 v[208:209], v[138:139], off offset:0
	global_load_dwordx2 v[210:211], v[138:139], off offset:32
	global_load_dwordx2 v[212:213], v[138:139], off offset:64
	global_load_dwordx2 v[214:215], v[138:139], off offset:96
	v_lshl_add_u64 v[138:139], v[138:139], 0, s[4:5]
	s_nop 7
	s_waitcnt vmcnt(31)
	v_lshlrev_b32_e32 v216, 16, v146
	v_and_b32_e32 v146, 0xffff0000, v146
	v_lshlrev_b32_e32 v217, 16, v147
	v_and_b32_e32 v147, 0xffff0000, v147
	v_fmac_f32_e32 v126, s44, v216
	v_fmac_f32_e32 v127, s44, v146
	v_fmac_f32_e32 v128, s44, v217
	v_fmac_f32_e32 v129, s44, v147
	global_store_dwordx4 v[140:141], v[126:129], off offset:0
	s_waitcnt vmcnt(31)
	v_lshlrev_b32_e32 v216, 16, v148
	v_and_b32_e32 v148, 0xffff0000, v148
	v_lshlrev_b32_e32 v217, 16, v149
	v_and_b32_e32 v149, 0xffff0000, v149
	v_fmac_f32_e32 v94, s44, v216
	v_fmac_f32_e32 v95, s44, v148
	v_fmac_f32_e32 v96, s44, v217
	v_fmac_f32_e32 v97, s44, v149
	global_store_dwordx4 v[140:141], v[94:97], off offset:64
	s_waitcnt vmcnt(31)
	v_lshlrev_b32_e32 v216, 16, v152
	v_and_b32_e32 v152, 0xffff0000, v152
	v_lshlrev_b32_e32 v217, 16, v153
	v_and_b32_e32 v153, 0xffff0000, v153
	v_fmac_f32_e32 v62, s44, v216
	v_fmac_f32_e32 v63, s44, v152
	v_fmac_f32_e32 v64, s44, v217
	v_fmac_f32_e32 v65, s44, v153
	global_store_dwordx4 v[140:141], v[62:65], off offset:128
	s_waitcnt vmcnt(31)
	v_lshlrev_b32_e32 v216, 16, v154
	v_and_b32_e32 v154, 0xffff0000, v154
	v_lshlrev_b32_e32 v217, 16, v155
	v_and_b32_e32 v155, 0xffff0000, v155
	v_fmac_f32_e32 v30, s44, v216
	v_fmac_f32_e32 v31, s44, v154
	v_fmac_f32_e32 v32, s44, v217
	v_fmac_f32_e32 v33, s44, v155
	global_store_dwordx4 v[140:141], v[30:33], off offset:192
	v_lshl_add_u64 v[140:141], v[140:141], 0, s[10:11]
	s_waitcnt vmcnt(31)
	v_lshlrev_b32_e32 v216, 16, v156
	v_and_b32_e32 v156, 0xffff0000, v156
	v_lshlrev_b32_e32 v217, 16, v157
	v_and_b32_e32 v157, 0xffff0000, v157
	v_fmac_f32_e32 v122, s44, v216
	v_fmac_f32_e32 v123, s44, v156
	v_fmac_f32_e32 v124, s44, v217
	v_fmac_f32_e32 v125, s44, v157
	global_store_dwordx4 v[140:141], v[122:125], off offset:0
	s_waitcnt vmcnt(31)
	v_lshlrev_b32_e32 v216, 16, v158
	v_and_b32_e32 v158, 0xffff0000, v158
	v_lshlrev_b32_e32 v217, 16, v159
	v_and_b32_e32 v159, 0xffff0000, v159
	v_fmac_f32_e32 v90, s44, v216
	v_fmac_f32_e32 v91, s44, v158
	v_fmac_f32_e32 v92, s44, v217
	v_fmac_f32_e32 v93, s44, v159
	global_store_dwordx4 v[140:141], v[90:93], off offset:64
	s_waitcnt vmcnt(31)
	v_lshlrev_b32_e32 v216, 16, v162
	v_and_b32_e32 v162, 0xffff0000, v162
	v_lshlrev_b32_e32 v217, 16, v163
	v_and_b32_e32 v163, 0xffff0000, v163
	v_fmac_f32_e32 v58, s44, v216
	v_fmac_f32_e32 v59, s44, v162
	v_fmac_f32_e32 v60, s44, v217
	v_fmac_f32_e32 v61, s44, v163
	global_store_dwordx4 v[140:141], v[58:61], off offset:128
	s_waitcnt vmcnt(31)
	v_lshlrev_b32_e32 v216, 16, v164
	v_and_b32_e32 v164, 0xffff0000, v164
	v_lshlrev_b32_e32 v217, 16, v165
	v_and_b32_e32 v165, 0xffff0000, v165
	v_fmac_f32_e32 v26, s44, v216
	v_fmac_f32_e32 v27, s44, v164
	v_fmac_f32_e32 v28, s44, v217
	v_fmac_f32_e32 v29, s44, v165
	global_store_dwordx4 v[140:141], v[26:29], off offset:192
	v_lshl_add_u64 v[140:141], v[140:141], 0, s[10:11]
	s_waitcnt vmcnt(31)
	v_lshlrev_b32_e32 v216, 16, v166
	v_and_b32_e32 v166, 0xffff0000, v166
	v_lshlrev_b32_e32 v217, 16, v167
	v_and_b32_e32 v167, 0xffff0000, v167
	v_fmac_f32_e32 v118, s44, v216
	v_fmac_f32_e32 v119, s44, v166
	v_fmac_f32_e32 v120, s44, v217
	v_fmac_f32_e32 v121, s44, v167
	global_store_dwordx4 v[140:141], v[118:121], off offset:0
	s_waitcnt vmcnt(31)
	v_lshlrev_b32_e32 v216, 16, v168
	v_and_b32_e32 v168, 0xffff0000, v168
	v_lshlrev_b32_e32 v217, 16, v169
	v_and_b32_e32 v169, 0xffff0000, v169
	v_fmac_f32_e32 v86, s44, v216
	v_fmac_f32_e32 v87, s44, v168
	v_fmac_f32_e32 v88, s44, v217
	v_fmac_f32_e32 v89, s44, v169
	global_store_dwordx4 v[140:141], v[86:89], off offset:64
	s_waitcnt vmcnt(31)
; DEVI float blo(unsigned u) { return __uint_as_float(u << 16); }
; DEVI float bhi(unsigned u) { return __uint_as_float(u & 0xffff0000u); }
;     ...
;         if (EPI == EPI_RESID || EPI == EPI_RESID_ATOMIC) {
;           f32x4 x = a;
;           if (EPI == EPI_RESID || kpart == 0) {
;             const u32x2 xr = *(const u32x2*)((const u16*)(p.ws + WS_XB) + (size_t)row * 1024 + col);
;             x[0] += ALPHA * blo(xr[0]); x[1] += ALPHA * bhi(xr[0]); x[2] += ALPHA * blo(xr[1]); x[3] += ALPHA * bhi(xr[1]);
;           }
;           if (EPI == EPI_RESID) *(f32x4*)((float*)(p.ws + WS_XF) + (size_t)row * 1024 + col) = x;
;           else *(f32x4*)((float*)(p.ws + WS_SLAB) + ((size_t)kpart * 512 + (row - T_P)) * 1024 + col) = x;
	v_lshlrev_b32_e32 v216, 16, v170
	v_and_b32_e32 v170, 0xffff0000, v170
	v_lshlrev_b32_e32 v217, 16, v171
	v_and_b32_e32 v171, 0xffff0000, v171
	v_fmac_f32_e32 v54, s44, v216
	v_fmac_f32_e32 v55, s44, v170
	v_fmac_f32_e32 v56, s44, v217
	v_fmac_f32_e32 v57, s44, v171
	global_store_dwordx4 v[140:141], v[54:57], off offset:128
	s_waitcnt vmcnt(31)
	v_lshlrev_b32_e32 v216, 16, v172
	v_and_b32_e32 v172, 0xffff0000, v172
	v_lshlrev_b32_e32 v217, 16, v173
	v_and_b32_e32 v173, 0xffff0000, v173
	v_fmac_f32_e32 v22, s44, v216
	v_fmac_f32_e32 v23, s44, v172
	v_fmac_f32_e32 v24, s44, v217
	v_fmac_f32_e32 v25, s44, v173
	global_store_dwordx4 v[140:141], v[22:25], off offset:192
	v_lshl_add_u64 v[140:141], v[140:141], 0, s[10:11]
	s_waitcnt vmcnt(31)
	v_lshlrev_b32_e32 v216, 16, v176
	v_and_b32_e32 v176, 0xffff0000, v176
	v_lshlrev_b32_e32 v217, 16, v177
	v_and_b32_e32 v177, 0xffff0000, v177
	v_fmac_f32_e32 v114, s44, v216
	v_fmac_f32_e32 v115, s44, v176
	v_fmac_f32_e32 v116, s44, v217
	v_fmac_f32_e32 v117, s44, v177
	global_store_dwordx4 v[140:141], v[114:117], off offset:0
	s_waitcnt vmcnt(31)
	v_lshlrev_b32_e32 v216, 16, v178
	v_and_b32_e32 v178, 0xffff0000, v178
	v_lshlrev_b32_e32 v217, 16, v179
	v_and_b32_e32 v179, 0xffff0000, v179
	v_fmac_f32_e32 v82, s44, v216
	v_fmac_f32_e32 v83, s44, v178
	v_fmac_f32_e32 v84, s44, v217
	v_fmac_f32_e32 v85, s44, v179
	global_store_dwordx4 v[140:141], v[82:85], off offset:64
	s_waitcnt vmcnt(31)
	v_lshlrev_b32_e32 v216, 16, v180
	v_and_b32_e32 v180, 0xffff0000, v180
	v_lshlrev_b32_e32 v217, 16, v181
	v_and_b32_e32 v181, 0xffff0000, v181
	v_fmac_f32_e32 v50, s44, v216
	v_fmac_f32_e32 v51, s44, v180
	v_fmac_f32_e32 v52, s44, v217
	v_fmac_f32_e32 v53, s44, v181
	global_store_dwordx4 v[140:141], v[50:53], off offset:128
	s_waitcnt vmcnt(31)
	v_lshlrev_b32_e32 v216, 16, v182
	v_and_b32_e32 v182, 0xffff0000, v182
	v_lshlrev_b32_e32 v217, 16, v183
	v_and_b32_e32 v183, 0xffff0000, v183
	v_fmac_f32_e32 v18, s44, v216
	v_fmac_f32_e32 v19, s44, v182
	v_fmac_f32_e32 v20, s44, v217
	v_fmac_f32_e32 v21, s44, v183
	global_store_dwordx4 v[140:141], v[18:21], off offset:192
	v_lshl_add_u64 v[140:141], v[140:141], 0, s[10:11]
	s_waitcnt vmcnt(31)
	v_lshlrev_b32_e32 v216, 16, v184
	v_and_b32_e32 v184, 0xffff0000, v184
	v_lshlrev_b32_e32 v217, 16, v185
	v_and_b32_e32 v185, 0xffff0000, v185
	v_fmac_f32_e32 v110, s44, v216
	v_fmac_f32_e32 v111, s44, v184
	v_fmac_f32_e32 v112, s44, v217
	v_fmac_f32_e32 v113, s44, v185
	global_store_dwordx4 v[140:141], v[110:113], off offset:0
	s_waitcnt vmcnt(31)
	v_lshlrev_b32_e32 v216, 16, v186
	v_and_b32_e32 v186, 0xffff0000, v186
	v_lshlrev_b32_e32 v217, 16, v187
	v_and_b32_e32 v187, 0xffff0000, v187
	v_fmac_f32_e32 v78, s44, v216
	v_fmac_f32_e32 v79, s44, v186
	v_fmac_f32_e32 v80, s44, v217
	v_fmac_f32_e32 v81, s44, v187
	global_store_dwordx4 v[140:141], v[78:81], off offset:64
	s_waitcnt vmcnt(31)
	v_lshlrev_b32_e32 v216, 16, v188
	v_and_b32_e32 v188, 0xffff0000, v188
	v_lshlrev_b32_e32 v217, 16, v189
	v_and_b32_e32 v189, 0xffff0000, v189
	v_fmac_f32_e32 v46, s44, v216
	v_fmac_f32_e32 v47, s44, v188
	v_fmac_f32_e32 v48, s44, v217
	v_fmac_f32_e32 v49, s44, v189
	global_store_dwordx4 v[140:141], v[46:49], off offset:128
	s_waitcnt vmcnt(31)
	v_lshlrev_b32_e32 v216, 16, v190
	v_and_b32_e32 v190, 0xffff0000, v190
	v_lshlrev_b32_e32 v217, 16, v191
	v_and_b32_e32 v191, 0xffff0000, v191
	v_fmac_f32_e32 v14, s44, v216
	v_fmac_f32_e32 v15, s44, v190
	v_fmac_f32_e32 v16, s44, v217
	v_fmac_f32_e32 v17, s44, v191
	global_store_dwordx4 v[140:141], v[14:17], off offset:192
	v_lshl_add_u64 v[140:141], v[140:141], 0, s[10:11]
	s_waitcnt vmcnt(31)
	v_lshlrev_b32_e32 v216, 16, v192
	v_and_b32_e32 v192, 0xffff0000, v192
	v_lshlrev_b32_e32 v217, 16, v193
	v_and_b32_e32 v193, 0xffff0000, v193
	v_fmac_f32_e32 v106, s44, v216
	v_fmac_f32_e32 v107, s44, v192
	v_fmac_f32_e32 v108, s44, v217
	v_fmac_f32_e32 v109, s44, v193
	global_store_dwordx4 v[140:141], v[106:109], off offset:0
	s_waitcnt vmcnt(31)
; DEVI unsigned pack2(float a, float b) { return __builtin_bit_cast(unsigned, __builtin_convertvector((f32x2_t){a, b}, bf16x2_t)); }
; DEVI float blo(unsigned u) { return __uint_as_float(u << 16); }
; DEVI float bhi(unsigned u) { return __uint_as_float(u & 0xffff0000u); }
; DEVI float siluf_(float x) { return x * __builtin_amdgcn_rcpf(1.f + __expf(-x)); }
;     ...
; #pragma unroll
;   for (int mf = 0; mf < 8; mf++) {
;     const int row = m0 + wm * 128 + mf * 16 + r16;
;     if (EPI == EPI_SWIGLU) {
; #pragma unroll
;       for (int nf = 0; nf < 2; nf++) {
;         const int hcol = (n0 >> 1) + wn * 32 + nf * 16 + quad * 4;
;         f32x4 g = acc[nf][mf], u = acc[nf + 2][mf];
;         u32x2 pk;
;         pk[0] = pack2(siluf_(g[0]) * u[0], siluf_(g[1]) * u[1]);
;         pk[1] = pack2(siluf_(g[2]) * u[2], siluf_(g[3]) * u[3]);
;         *(u32x2*)(outb + (size_t)row * DFF + hcol) = pk;
;       }
;     } else {
; #pragma unroll
;       for (int nf = 0; nf < 4; nf++) {
;         const int col = n0 + wn * 64 + nf * 16 + quad * 4;
;         f32x4 a = acc[nf][mf];
;         if (EPI == EPI_RESID || EPI == EPI_RESID_ATOMIC) {
;           f32x4 x = a;
;           if (EPI == EPI_RESID || kpart == 0) {
;             const u32x2 xr = *(const u32x2*)((const u16*)(p.ws + WS_XB) + (size_t)row * 1024 + col);
;             x[0] += ALPHA * blo(xr[0]); x[1] += ALPHA * bhi(xr[0]); x[2] += ALPHA * blo(xr[1]); x[3] += ALPHA * bhi(xr[1]);
;           }
;           if (EPI == EPI_RESID) *(f32x4*)((float*)(p.ws + WS_XF) + (size_t)row * 1024 + col) = x;
;           else *(f32x4*)((float*)(p.ws + WS_SLAB) + ((size_t)kpart * 512 + (row - T_P)) * 1024 + col) = x;
	v_lshlrev_b32_e32 v216, 16, v194
	v_and_b32_e32 v194, 0xffff0000, v194
	v_lshlrev_b32_e32 v217, 16, v195
	v_and_b32_e32 v195, 0xffff0000, v195
	v_fmac_f32_e32 v74, s44, v216
	v_fmac_f32_e32 v75, s44, v194
	v_fmac_f32_e32 v76, s44, v217
	v_fmac_f32_e32 v77, s44, v195
	global_store_dwordx4 v[140:141], v[74:77], off offset:64
	s_waitcnt vmcnt(31)
	v_lshlrev_b32_e32 v216, 16, v196
	v_and_b32_e32 v196, 0xffff0000, v196
	v_lshlrev_b32_e32 v217, 16, v197
	v_and_b32_e32 v197, 0xffff0000, v197
	v_fmac_f32_e32 v42, s44, v216
	v_fmac_f32_e32 v43, s44, v196
	v_fmac_f32_e32 v44, s44, v217
	v_fmac_f32_e32 v45, s44, v197
	global_store_dwordx4 v[140:141], v[42:45], off offset:128
	s_waitcnt vmcnt(31)
	v_lshlrev_b32_e32 v216, 16, v198
	v_and_b32_e32 v198, 0xffff0000, v198
	v_lshlrev_b32_e32 v217, 16, v199
	v_and_b32_e32 v199, 0xffff0000, v199
	v_fmac_f32_e32 v10, s44, v216
	v_fmac_f32_e32 v11, s44, v198
	v_fmac_f32_e32 v12, s44, v217
	v_fmac_f32_e32 v13, s44, v199
	global_store_dwordx4 v[140:141], v[10:13], off offset:192
	v_lshl_add_u64 v[140:141], v[140:141], 0, s[10:11]
	s_waitcnt vmcnt(31)
	v_lshlrev_b32_e32 v216, 16, v200
	v_and_b32_e32 v200, 0xffff0000, v200
	v_lshlrev_b32_e32 v217, 16, v201
	v_and_b32_e32 v201, 0xffff0000, v201
	v_fmac_f32_e32 v102, s44, v216
	v_fmac_f32_e32 v103, s44, v200
	v_fmac_f32_e32 v104, s44, v217
	v_fmac_f32_e32 v105, s44, v201
	global_store_dwordx4 v[140:141], v[102:105], off offset:0
	s_waitcnt vmcnt(31)
	v_lshlrev_b32_e32 v216, 16, v202
	v_and_b32_e32 v202, 0xffff0000, v202
	v_lshlrev_b32_e32 v217, 16, v203
	v_and_b32_e32 v203, 0xffff0000, v203
	v_fmac_f32_e32 v70, s44, v216
	v_fmac_f32_e32 v71, s44, v202
	v_fmac_f32_e32 v72, s44, v217
	v_fmac_f32_e32 v73, s44, v203
	global_store_dwordx4 v[140:141], v[70:73], off offset:64
	s_waitcnt vmcnt(31)
	v_lshlrev_b32_e32 v216, 16, v204
	v_and_b32_e32 v204, 0xffff0000, v204
	v_lshlrev_b32_e32 v217, 16, v205
	v_and_b32_e32 v205, 0xffff0000, v205
	v_fmac_f32_e32 v38, s44, v216
	v_fmac_f32_e32 v39, s44, v204
	v_fmac_f32_e32 v40, s44, v217
	v_fmac_f32_e32 v41, s44, v205
	global_store_dwordx4 v[140:141], v[38:41], off offset:128
	s_waitcnt vmcnt(31)
	v_lshlrev_b32_e32 v216, 16, v206
	v_and_b32_e32 v206, 0xffff0000, v206
	v_lshlrev_b32_e32 v217, 16, v207
	v_and_b32_e32 v207, 0xffff0000, v207
	v_fmac_f32_e32 v6, s44, v216
	v_fmac_f32_e32 v7, s44, v206
	v_fmac_f32_e32 v8, s44, v217
	v_fmac_f32_e32 v9, s44, v207
	global_store_dwordx4 v[140:141], v[6:9], off offset:192
	v_lshl_add_u64 v[140:141], v[140:141], 0, s[10:11]
	s_waitcnt vmcnt(31)
	v_lshlrev_b32_e32 v216, 16, v208
	v_and_b32_e32 v208, 0xffff0000, v208
	v_lshlrev_b32_e32 v217, 16, v209
	v_and_b32_e32 v209, 0xffff0000, v209
	v_fmac_f32_e32 v98, s44, v216
	v_fmac_f32_e32 v99, s44, v208
	v_fmac_f32_e32 v100, s44, v217
	v_fmac_f32_e32 v101, s44, v209
	global_store_dwordx4 v[140:141], v[98:101], off offset:0
	s_waitcnt vmcnt(31)
	v_lshlrev_b32_e32 v216, 16, v210
	v_and_b32_e32 v210, 0xffff0000, v210
	v_lshlrev_b32_e32 v217, 16, v211
	v_and_b32_e32 v211, 0xffff0000, v211
	v_fmac_f32_e32 v66, s44, v216
	v_fmac_f32_e32 v67, s44, v210
	v_fmac_f32_e32 v68, s44, v217
	v_fmac_f32_e32 v69, s44, v211
	global_store_dwordx4 v[140:141], v[66:69], off offset:64
	s_waitcnt vmcnt(31)
	v_lshlrev_b32_e32 v216, 16, v212
	v_and_b32_e32 v212, 0xffff0000, v212
	v_lshlrev_b32_e32 v217, 16, v213
	v_and_b32_e32 v213, 0xffff0000, v213
	v_fmac_f32_e32 v34, s44, v216
	v_fmac_f32_e32 v35, s44, v212
	v_fmac_f32_e32 v36, s44, v217
	v_fmac_f32_e32 v37, s44, v213
	global_store_dwordx4 v[140:141], v[34:37], off offset:128
	s_waitcnt vmcnt(31)
	v_lshlrev_b32_e32 v216, 16, v214
	v_and_b32_e32 v214, 0xffff0000, v214
	v_lshlrev_b32_e32 v217, 16, v215
	v_and_b32_e32 v215, 0xffff0000, v215
	v_fmac_f32_e32 v2, s44, v216
	v_fmac_f32_e32 v3, s44, v214
	v_fmac_f32_e32 v4, s44, v217
	v_fmac_f32_e32 v5, s44, v215
	global_store_dwordx4 v[140:141], v[2:5], off offset:192
	s_branch .LBB0_146

; #define LAS __attribute__((address_space(3)))
; DEVI int tidx() { int t = threadIdx.x; asm volatile("" : "+v"(t)); return t; }
; DEVI int xcd_first_tile() { return (blockIdx.x & 7) * (gridDim.x >> 3) + (blockIdx.x >> 3); }
;   const int tid = tidx(), lane = tid & 63, wid = tid >> 6;
;   const int wm = wid >> 1, wn = wid & 1, r16 = lane & 15, quad = lane >> 4;
;   f32x4 acc[4][8];
; #pragma unroll
;   for (int i = 0; i < 4; i++)
; #pragma unroll
;     for (int j = 0; j < 8; j++) acc[i][j] = (f32x4){0.f, 0.f, 0.f, 0.f};
;   const int nk = (nk_part < 0) ? (K >> 5) : nk_part;
;   const int lrow = tid >> 2, lpc = tid & 3;
;   const int lch = lpc ^ ((0x78 >> (((lrow >> 2) & 3) * 2)) & 3);
;   const u16* ga = A + (size_t)(m0 + lrow) * lda + kbeg + lch * 8;
;   const u16* gb = Bt + (size_t)(n0 + lrow) * K + kbeg + lch * 8;
;   const size_t ga1 = (size_t)64 * lda, gb1 = (size_t)64 * K;
;   const unsigned lds0 = (unsigned)(uintptr_t)(LAS char*)smem + (unsigned)__builtin_amdgcn_readfirstlane(wid) * 1024u;
;     ...
;   __syncthreads();
;   G2_STAGE(0); G2_STAGE(1);
;   const int fsw = (0x78 >> (((r16 >> 2) & 3) * 2)) & 3;
;   const int aoff = (wm * 128 + r16) * 64 + ((quad ^ fsw) << 4);
;   const int boff = 16384 + (wn * 64 + r16) * 64 + ((quad ^ fsw) << 4);
; DEVI void run_phase(const Params& p, int ph, char* smem) {
;     ...
;       const u16* Bt = (const u16*)(p.ws + WS_WO) + (size_t)l * 1024 * 1024;
;       for (int t = xcd_first_tile(); t < 512 + 16 * 8; t += xcd_tile_step()) {
;         if (t < 512) {
;           int mt_, nt_; tile_coords(t, 64, 8, mt_, nt_);
;           gemm_tile256<EPI_RESID>(p, mix, 1024, Bt, 1024, mt_ * 256, nt_ * 128, nullptr, 0, smem);
.LBB0_812:
	s_and_b64 vcc, exec, s[2:3]
	s_cbranch_vccz .LBB0_757
	s_lshr_b32 s46, s39, 6
	s_and_b32 s47, s39, 63
	s_lshr_b32 s43, s47, 3
	s_and_b32 s47, s47, 7
	s_lshl_b32 s46, s46, 3
	s_add_i32 s46, s46, s47
	v_readlane_b32 s2, v250, 5
	v_readlane_b32 s3, v250, 6
	v_readlane_b32 s47, v254, 62
	s_mul_i32 s41, s46, 0x80000
	s_add_u32 s4, s2, s41
	s_addc_u32 s5, s3, 0
	s_add_u32 s4, s4, 0xb580000
	s_addc_u32 s5, s5, 0
	s_mul_i32 s41, s47, 0x200000
	s_mul_i32 s42, s43, 0x40000
	s_add_i32 s41, s41, s42
	s_add_u32 s10, s2, s41
	s_addc_u32 s11, s3, 0
	s_add_u32 s10, s10, 0x15e00000
	s_addc_u32 s11, s11, 0
	s_movk_i32 s40, 0x78
	v_lshrrev_b32_e32 v0, 2, v145
	v_and_b32_e32 v131, 3, v145
	v_bfe_u32 v136, v145, 4, 2
	v_lshlrev_b32_e32 v136, 1, v136
	v_lshrrev_b32_e64 v136, v136, s40
	v_and_b32_e32 v136, 3, v136
	v_xor_b32_e32 v131, v131, v136
	v_lshlrev_b32_e32 v131, 4, v131
	s_movk_i32 s42, 0x800
	v_mad_u32_u24 v0, v0, s42, v131
	v_bfe_u32 v137, v145, 2, 1
	v_lshl_add_u64 v[134:135], s[10:11], 0, v[0:1]
	s_mov_b32 s12, 64
	s_mov_b32 s13, 0
	v_lshl_add_u64 v[132:133], s[4:5], 0, v[0:1]
	v_bfe_u32 v136, v145, 2, 2
	v_lshlrev_b32_e32 v136, 1, v136
	v_lshrrev_b32_e64 v136, v136, s40
	v_and_b32_e32 v136, 3, v136
	v_bfe_u32 v137, v145, 4, 2
	v_xor_b32_e32 v136, v136, v137
	v_lshlrev_b32_e32 v136, 4, v136
	v_and_b32_e32 v131, 15, v145
	v_lshl_or_b32 v136, v131, 6, v136
	v_bfe_u32 v137, v145, 6, 1
	v_lshl_or_b32 v137, v137, 12, v136
	v_lshrrev_b32_e32 v0, 7, v145
	v_lshl_or_b32 v136, v0, 13, v136
	v_and_b32_e32 v140, 1, v131
	v_lshl_or_b32 v131, v0, 7, v131
	v_bfe_u32 v0, v145, 4, 2
	v_lshlrev_b32_e32 v0, 3, v0
	v_bfe_u32 v141, v145, 6, 1
	s_lshl_b32 s41, s46, 19
	s_lshl_b32 s42, s43, 9
	s_add_i32 s41, s41, s42
	s_add_u32 s4, s2, s41
	s_addc_u32 s5, s3, 0
	s_add_u32 s4, s4, 0x4200000
	s_addc_u32 s5, s5, 0
	v_lshlrev_b32_e32 v138, 11, v131
	v_lshl_add_u32 v138, v141, 8, v138
	v_add_u32_e32 v138, v138, v0
	s_movk_i32 s42, 1984
	v_mul_u32_u24_e32 v139, s42, v140
	v_sub_u32_e32 v138, v138, v139
	v_mov_b32_e32 v139, 0
	v_lshl_add_u64 v[138:139], s[4:5], 0, v[138:139]
	s_lshl_b32 s41, s46, 20
	s_lshl_b32 s42, s43, 9
	s_add_i32 s41, s41, s42
	s_add_u32 s10, s2, s41
	s_addc_u32 s11, s3, 0
	v_lshlrev_b32_e32 v140, 12, v131
	v_lshl_add_u32 v140, v141, 8, v140
	v_lshl_add_u32 v140, v0, 1, v140
	v_mov_b32_e32 v141, 0
	v_lshl_add_u64 v[140:141], s[10:11], 0, v[140:141]
	s_mov_b32 s2, 0x20000
	s_mov_b32 s3, 0
	v_lshrrev_b32_e32 v0, 6, v145
	v_lshlrev_b32_e32 v0, 10, v0
	s_nop 0
	v_readfirstlane_b32 s47, v0
	s_mov_b32 s44, m0
	s_mov_b32 s4, 64
	s_mov_b32 s5, 0
	v_mov_b32_e32 v2, 0
	v_mov_b32_e32 v3, 0
	v_mov_b32_e32 v4, 0
	v_mov_b32_e32 v5, 0
	v_mov_b32_e32 v6, 0
	v_mov_b32_e32 v7, 0
	v_mov_b32_e32 v8, 0
	v_mov_b32_e32 v9, 0
	v_mov_b32_e32 v10, 0
	v_mov_b32_e32 v11, 0
	v_mov_b32_e32 v12, 0
	v_mov_b32_e32 v13, 0
	v_mov_b32_e32 v14, 0
	v_mov_b32_e32 v15, 0
	v_mov_b32_e32 v16, 0
	v_mov_b32_e32 v17, 0
	v_mov_b32_e32 v18, 0
	v_mov_b32_e32 v19, 0
	v_mov_b32_e32 v20, 0
	v_mov_b32_e32 v21, 0
	v_mov_b32_e32 v22, 0
	v_mov_b32_e32 v23, 0
	v_mov_b32_e32 v24, 0
	v_mov_b32_e32 v25, 0
	v_mov_b32_e32 v26, 0
	v_mov_b32_e32 v27, 0
	v_mov_b32_e32 v28, 0
	v_mov_b32_e32 v29, 0
	v_mov_b32_e32 v30, 0
	v_mov_b32_e32 v31, 0
	v_mov_b32_e32 v32, 0
	v_mov_b32_e32 v33, 0
	v_mov_b32_e32 v34, 0
	v_mov_b32_e32 v35, 0
	v_mov_b32_e32 v36, 0
	v_mov_b32_e32 v37, 0
	v_mov_b32_e32 v38, 0
	v_mov_b32_e32 v39, 0
	v_mov_b32_e32 v40, 0
	v_mov_b32_e32 v41, 0
	v_mov_b32_e32 v42, 0
	v_mov_b32_e32 v43, 0
	v_mov_b32_e32 v44, 0
	v_mov_b32_e32 v45, 0
	v_mov_b32_e32 v46, 0
	v_mov_b32_e32 v47, 0
	v_mov_b32_e32 v48, 0
	v_mov_b32_e32 v49, 0
	v_mov_b32_e32 v50, 0
	v_mov_b32_e32 v51, 0
	v_mov_b32_e32 v52, 0
	v_mov_b32_e32 v53, 0
	v_mov_b32_e32 v54, 0
	v_mov_b32_e32 v55, 0
	v_mov_b32_e32 v56, 0
	v_mov_b32_e32 v57, 0
	v_mov_b32_e32 v58, 0
	v_mov_b32_e32 v59, 0
	v_mov_b32_e32 v60, 0
	v_mov_b32_e32 v61, 0
	v_mov_b32_e32 v62, 0
	v_mov_b32_e32 v63, 0
	v_mov_b32_e32 v64, 0
	v_mov_b32_e32 v65, 0
	v_mov_b32_e32 v66, 0
	v_mov_b32_e32 v67, 0
	v_mov_b32_e32 v68, 0
	v_mov_b32_e32 v69, 0
	v_mov_b32_e32 v70, 0
	v_mov_b32_e32 v71, 0
	v_mov_b32_e32 v72, 0
	v_mov_b32_e32 v73, 0
	v_mov_b32_e32 v74, 0
	v_mov_b32_e32 v75, 0
	v_mov_b32_e32 v76, 0
	v_mov_b32_e32 v77, 0
	v_mov_b32_e32 v78, 0
	v_mov_b32_e32 v79, 0
	v_mov_b32_e32 v80, 0
	v_mov_b32_e32 v81, 0
	v_mov_b32_e32 v82, 0
	v_mov_b32_e32 v83, 0
	v_mov_b32_e32 v84, 0
	v_mov_b32_e32 v85, 0
	v_mov_b32_e32 v86, 0
	v_mov_b32_e32 v87, 0
	v_mov_b32_e32 v88, 0
	v_mov_b32_e32 v89, 0
	v_mov_b32_e32 v90, 0
	v_mov_b32_e32 v91, 0
	v_mov_b32_e32 v92, 0
	v_mov_b32_e32 v93, 0
	v_mov_b32_e32 v94, 0
	v_mov_b32_e32 v95, 0
	v_mov_b32_e32 v96, 0
	v_mov_b32_e32 v97, 0
	v_mov_b32_e32 v98, 0
	v_mov_b32_e32 v99, 0
	v_mov_b32_e32 v100, 0
	v_mov_b32_e32 v101, 0
	v_mov_b32_e32 v102, 0
	v_mov_b32_e32 v103, 0
	v_mov_b32_e32 v104, 0
	v_mov_b32_e32 v105, 0
	v_mov_b32_e32 v106, 0
	v_mov_b32_e32 v107, 0
	v_mov_b32_e32 v108, 0
	v_mov_b32_e32 v109, 0
	v_mov_b32_e32 v110, 0
	v_mov_b32_e32 v111, 0
	v_mov_b32_e32 v112, 0
	v_mov_b32_e32 v113, 0
	v_mov_b32_e32 v114, 0
	v_mov_b32_e32 v115, 0
	v_mov_b32_e32 v116, 0
	v_mov_b32_e32 v117, 0
	v_mov_b32_e32 v118, 0
	v_mov_b32_e32 v119, 0
	v_mov_b32_e32 v120, 0
	v_mov_b32_e32 v121, 0
	v_mov_b32_e32 v122, 0
	v_mov_b32_e32 v123, 0
	v_mov_b32_e32 v124, 0
	v_mov_b32_e32 v125, 0
	v_mov_b32_e32 v126, 0
	v_mov_b32_e32 v127, 0
	v_mov_b32_e32 v128, 0
	v_mov_b32_e32 v129, 0
	s_barrier
;     ...
;   __syncthreads();
;   G2_STAGE(0); G2_STAGE(1);
;   const int fsw = (0x78 >> (((r16 >> 2) & 3) * 2)) & 3;
;   const int aoff = (wm * 128 + r16) * 64 + ((quad ^ fsw) << 4);
;   const int boff = 16384 + (wn * 64 + r16) * 64 + ((quad ^ fsw) << 4);
;   for (int kt = 0; kt < nk; kt++) {
;     if (kt + 1 < nk) asm volatile("s_waitcnt vmcnt(6)" ::: "memory");
;     else asm volatile("s_waitcnt vmcnt(0)" ::: "memory");
;     __builtin_amdgcn_s_barrier();
;     asm volatile("" ::: "memory");
;     if (kt + 2 < nk) G2_STAGE(kt + 2);
;     const char* cS = smem + (kt % 3) * 24576;
;     bf16x8 xa[8], wb[4];
; #pragma unroll
;     for (int f = 0; f < 8; f++) xa[f] = *(const bf16x8*)(cS + aoff + f * 1024);
; #pragma unroll
;     for (int f = 0; f < 4; f++) wb[f] = *(const bf16x8*)(cS + boff + f * 1024);
; #pragma unroll
;     for (int nf = 0; nf < 4; nf++)
; #pragma unroll
;       for (int mf = 0; mf < 8; mf++)
;         acc[nf][mf] = __builtin_amdgcn_mfma_f32_16x16x32_bf16(wb[nf], xa[mf], acc[nf][mf], 0, 0, 0);
;   }
	s_add_i32 s43, s47, 0x0
	s_mov_b32 m0, s43
	v_lshl_add_u64 v[142:143], v[132:133], 0, s[2:3]
	global_load_lds_dwordx4 v[132:133], off
	s_addk_i32 m0, 0x1000
	s_nop 0
	global_load_lds_dwordx4 v[142:143], off
	v_lshl_add_u64 v[142:143], v[142:143], 0, s[2:3]
	s_addk_i32 m0, 0x1000
	s_nop 0
	global_load_lds_dwordx4 v[142:143], off
	v_lshl_add_u64 v[142:143], v[142:143], 0, s[2:3]
	s_addk_i32 m0, 0x1000
	s_nop 0
	global_load_lds_dwordx4 v[142:143], off
	s_addk_i32 m0, 0x1000
	v_lshl_add_u64 v[142:143], v[134:135], 0, s[2:3]
	s_nop 0
	global_load_lds_dwordx4 v[134:135], off
	s_addk_i32 m0, 0x1000
	v_lshl_add_u64 v[132:133], v[132:133], 0, s[12:13]
	s_nop 0
	global_load_lds_dwordx4 v[142:143], off
	v_lshl_add_u64 v[134:135], v[134:135], 0, s[4:5]
	s_nop 0
	s_add_i32 s43, s47, 0x6000
	s_mov_b32 m0, s43
	v_lshl_add_u64 v[142:143], v[132:133], 0, s[2:3]
	global_load_lds_dwordx4 v[132:133], off
	s_addk_i32 m0, 0x1000
	s_nop 0
	global_load_lds_dwordx4 v[142:143], off
	v_lshl_add_u64 v[142:143], v[142:143], 0, s[2:3]
	s_addk_i32 m0, 0x1000
	s_nop 0
	global_load_lds_dwordx4 v[142:143], off
	v_lshl_add_u64 v[142:143], v[142:143], 0, s[2:3]
	s_addk_i32 m0, 0x1000
	s_nop 0
	global_load_lds_dwordx4 v[142:143], off
	s_addk_i32 m0, 0x1000
	v_lshl_add_u64 v[142:143], v[134:135], 0, s[2:3]
	s_nop 0
	global_load_lds_dwordx4 v[134:135], off
	s_addk_i32 m0, 0x1000
	v_lshl_add_u64 v[132:133], v[132:133], 0, s[12:13]
	s_nop 0
	global_load_lds_dwordx4 v[142:143], off
	v_lshl_add_u64 v[134:135], v[134:135], 0, s[4:5]
	s_nop 0
	s_add_i32 s43, s47, 0xc000
	s_mov_b32 m0, s43
	v_lshl_add_u64 v[142:143], v[132:133], 0, s[2:3]
	global_load_lds_dwordx4 v[132:133], off
	s_addk_i32 m0, 0x1000
	s_nop 0
	global_load_lds_dwordx4 v[142:143], off
	v_lshl_add_u64 v[142:143], v[142:143], 0, s[2:3]
	s_addk_i32 m0, 0x1000
	s_nop 0
	global_load_lds_dwordx4 v[142:143], off
	v_lshl_add_u64 v[142:143], v[142:143], 0, s[2:3]
	s_addk_i32 m0, 0x1000
	s_nop 0
	global_load_lds_dwordx4 v[142:143], off
	s_addk_i32 m0, 0x1000
	v_lshl_add_u64 v[142:143], v[134:135], 0, s[2:3]
	s_nop 0
	global_load_lds_dwordx4 v[134:135], off
	s_addk_i32 m0, 0x1000
	v_lshl_add_u64 v[132:133], v[132:133], 0, s[12:13]
	s_nop 0
	global_load_lds_dwordx4 v[142:143], off
	v_lshl_add_u64 v[134:135], v[134:135], 0, s[4:5]
	s_nop 0
	s_waitcnt vmcnt(12)
	s_barrier
	ds_read_b128 v[146:149], v136 offset:0
	ds_read_b128 v[152:155], v136 offset:1024
	ds_read_b128 v[156:159], v136 offset:2048
	ds_read_b128 v[162:165], v136 offset:3072
	ds_read_b128 v[166:169], v136 offset:4096
	ds_read_b128 v[170:173], v136 offset:5120
	ds_read_b128 v[176:179], v136 offset:6144
	ds_read_b128 v[180:183], v136 offset:7168
	ds_read_b128 v[184:187], v137 offset:16384
	ds_read_b128 v[188:191], v137 offset:17408
	ds_read_b128 v[192:195], v137 offset:18432
	ds_read_b128 v[196:199], v137 offset:19456
	s_movk_i32 s41, 0x6000
	s_mov_b32 s42, 0
	s_movk_i32 s40, 14
.Lt4_loop:
	s_waitcnt vmcnt(6) lgkmcnt(0)
	s_barrier
	v_add_u32_e32 v144, s41, v136
	v_mfma_f32_16x16x32_bf16 v[126:129], v[184:187], v[146:149], v[126:129]
	ds_read_b128 v[200:203], v144 offset:0
	v_mfma_f32_16x16x32_bf16 v[122:125], v[184:187], v[152:155], v[122:125]
	ds_read_b128 v[204:207], v144 offset:1024
	v_mfma_f32_16x16x32_bf16 v[118:121], v[184:187], v[156:159], v[118:121]
	ds_read_b128 v[208:211], v144 offset:2048
	v_mfma_f32_16x16x32_bf16 v[114:117], v[184:187], v[162:165], v[114:117]
	ds_read_b128 v[212:215], v144 offset:3072
	v_mfma_f32_16x16x32_bf16 v[110:113], v[184:187], v[166:169], v[110:113]
	ds_read_b128 v[216:219], v144 offset:4096
	v_mfma_f32_16x16x32_bf16 v[106:109], v[184:187], v[170:173], v[106:109]
	ds_read_b128 v[220:223], v144 offset:5120
	v_mfma_f32_16x16x32_bf16 v[102:105], v[184:187], v[176:179], v[102:105]
	ds_read_b128 v[224:227], v144 offset:6144
	v_mfma_f32_16x16x32_bf16 v[98:101], v[184:187], v[180:183], v[98:101]
	ds_read_b128 v[228:231], v144 offset:7168
	v_mfma_f32_16x16x32_bf16 v[94:97], v[188:191], v[146:149], v[94:97]
	v_add_u32_e32 v144, s41, v137
	v_mfma_f32_16x16x32_bf16 v[90:93], v[188:191], v[152:155], v[90:93]
	v_mfma_f32_16x16x32_bf16 v[86:89], v[188:191], v[156:159], v[86:89]
	ds_read_b128 v[232:235], v144 offset:16384
	v_mfma_f32_16x16x32_bf16 v[82:85], v[188:191], v[162:165], v[82:85]
	ds_read_b128 v[236:239], v144 offset:17408
	v_mfma_f32_16x16x32_bf16 v[78:81], v[188:191], v[166:169], v[78:81]
	ds_read_b128 v[240:243], v144 offset:18432
	v_mfma_f32_16x16x32_bf16 v[74:77], v[188:191], v[170:173], v[74:77]
	ds_read_b128 v[244:247], v144 offset:19456
	s_add_i32 s43, s47, s42
	v_mfma_f32_16x16x32_bf16 v[70:73], v[188:191], v[176:179], v[70:73]
	s_mov_b32 m0, s43
	v_lshl_add_u64 v[142:143], v[132:133], 0, s[2:3]
	v_mfma_f32_16x16x32_bf16 v[66:69], v[188:191], v[180:183], v[66:69]
	global_load_lds_dwordx4 v[132:133], off
	s_addk_i32 m0, 0x1000
	v_mfma_f32_16x16x32_bf16 v[62:65], v[192:195], v[146:149], v[62:65]
	v_mfma_f32_16x16x32_bf16 v[58:61], v[192:195], v[152:155], v[58:61]
	v_mfma_f32_16x16x32_bf16 v[54:57], v[192:195], v[156:159], v[54:57]
	global_load_lds_dwordx4 v[142:143], off
	v_lshl_add_u64 v[142:143], v[142:143], 0, s[2:3]
	s_addk_i32 m0, 0x1000
	v_mfma_f32_16x16x32_bf16 v[50:53], v[192:195], v[162:165], v[50:53]
	v_mfma_f32_16x16x32_bf16 v[46:49], v[192:195], v[166:169], v[46:49]
	v_mfma_f32_16x16x32_bf16 v[42:45], v[192:195], v[170:173], v[42:45]
	global_load_lds_dwordx4 v[142:143], off
	v_lshl_add_u64 v[142:143], v[142:143], 0, s[2:3]
	s_addk_i32 m0, 0x1000
	v_mfma_f32_16x16x32_bf16 v[38:41], v[192:195], v[176:179], v[38:41]
	v_mfma_f32_16x16x32_bf16 v[34:37], v[192:195], v[180:183], v[34:37]
	v_mfma_f32_16x16x32_bf16 v[30:33], v[196:199], v[146:149], v[30:33]
	global_load_lds_dwordx4 v[142:143], off
	s_addk_i32 m0, 0x1000
	v_lshl_add_u64 v[142:143], v[134:135], 0, s[2:3]
	v_mfma_f32_16x16x32_bf16 v[26:29], v[196:199], v[152:155], v[26:29]
	v_mfma_f32_16x16x32_bf16 v[22:25], v[196:199], v[156:159], v[22:25]
	v_mfma_f32_16x16x32_bf16 v[18:21], v[196:199], v[162:165], v[18:21]
	global_load_lds_dwordx4 v[134:135], off
	s_addk_i32 m0, 0x1000
	v_lshl_add_u64 v[132:133], v[132:133], 0, s[12:13]
	v_mfma_f32_16x16x32_bf16 v[14:17], v[196:199], v[166:169], v[14:17]
	v_mfma_f32_16x16x32_bf16 v[10:13], v[196:199], v[170:173], v[10:13]
	v_mfma_f32_16x16x32_bf16 v[6:9], v[196:199], v[176:179], v[6:9]
	global_load_lds_dwordx4 v[142:143], off
	v_lshl_add_u64 v[134:135], v[134:135], 0, s[4:5]
	v_mfma_f32_16x16x32_bf16 v[2:5], v[196:199], v[180:183], v[2:5]
	s_mov_b32 s42, s41
	s_add_i32 s41, s41, 0x6000
	s_cmp_eq_u32 s41, 0x12000
	s_cselect_b32 s41, 0, s41
	s_waitcnt vmcnt(6) lgkmcnt(0)
	s_barrier
;     ...
;   __syncthreads();
;   G2_STAGE(0); G2_STAGE(1);
;   const int fsw = (0x78 >> (((r16 >> 2) & 3) * 2)) & 3;
;   const int aoff = (wm * 128 + r16) * 64 + ((quad ^ fsw) << 4);
;   const int boff = 16384 + (wn * 64 + r16) * 64 + ((quad ^ fsw) << 4);
;   for (int kt = 0; kt < nk; kt++) {
;     if (kt + 1 < nk) asm volatile("s_waitcnt vmcnt(6)" ::: "memory");
;     else asm volatile("s_waitcnt vmcnt(0)" ::: "memory");
;     __builtin_amdgcn_s_barrier();
;     asm volatile("" ::: "memory");
;     if (kt + 2 < nk) G2_STAGE(kt + 2);
;     const char* cS = smem + (kt % 3) * 24576;
;     bf16x8 xa[8], wb[4];
; #pragma unroll
;     for (int f = 0; f < 8; f++) xa[f] = *(const bf16x8*)(cS + aoff + f * 1024);
; #pragma unroll
;     for (int f = 0; f < 4; f++) wb[f] = *(const bf16x8*)(cS + boff + f * 1024);
; #pragma unroll
;     for (int nf = 0; nf < 4; nf++)
; #pragma unroll
;       for (int mf = 0; mf < 8; mf++)
;         acc[nf][mf] = __builtin_amdgcn_mfma_f32_16x16x32_bf16(wb[nf], xa[mf], acc[nf][mf], 0, 0, 0);
;   }
	v_add_u32_e32 v144, s41, v136
	v_mfma_f32_16x16x32_bf16 v[126:129], v[232:235], v[200:203], v[126:129]
	ds_read_b128 v[146:149], v144 offset:0
	v_mfma_f32_16x16x32_bf16 v[122:125], v[232:235], v[204:207], v[122:125]
	ds_read_b128 v[152:155], v144 offset:1024
	v_mfma_f32_16x16x32_bf16 v[118:121], v[232:235], v[208:211], v[118:121]
	ds_read_b128 v[156:159], v144 offset:2048
	v_mfma_f32_16x16x32_bf16 v[114:117], v[232:235], v[212:215], v[114:117]
	ds_read_b128 v[162:165], v144 offset:3072
	v_mfma_f32_16x16x32_bf16 v[110:113], v[232:235], v[216:219], v[110:113]
	ds_read_b128 v[166:169], v144 offset:4096
	v_mfma_f32_16x16x32_bf16 v[106:109], v[232:235], v[220:223], v[106:109]
	ds_read_b128 v[170:173], v144 offset:5120
	v_mfma_f32_16x16x32_bf16 v[102:105], v[232:235], v[224:227], v[102:105]
	ds_read_b128 v[176:179], v144 offset:6144
	v_mfma_f32_16x16x32_bf16 v[98:101], v[232:235], v[228:231], v[98:101]
	ds_read_b128 v[180:183], v144 offset:7168
	v_mfma_f32_16x16x32_bf16 v[94:97], v[236:239], v[200:203], v[94:97]
	v_add_u32_e32 v144, s41, v137
	v_mfma_f32_16x16x32_bf16 v[90:93], v[236:239], v[204:207], v[90:93]
	v_mfma_f32_16x16x32_bf16 v[86:89], v[236:239], v[208:211], v[86:89]
	ds_read_b128 v[184:187], v144 offset:16384
	v_mfma_f32_16x16x32_bf16 v[82:85], v[236:239], v[212:215], v[82:85]
	ds_read_b128 v[188:191], v144 offset:17408
	v_mfma_f32_16x16x32_bf16 v[78:81], v[236:239], v[216:219], v[78:81]
	ds_read_b128 v[192:195], v144 offset:18432
	v_mfma_f32_16x16x32_bf16 v[74:77], v[236:239], v[220:223], v[74:77]
	ds_read_b128 v[196:199], v144 offset:19456
	s_add_i32 s43, s47, s42
	v_mfma_f32_16x16x32_bf16 v[70:73], v[236:239], v[224:227], v[70:73]
	s_mov_b32 m0, s43
	v_lshl_add_u64 v[142:143], v[132:133], 0, s[2:3]
	v_mfma_f32_16x16x32_bf16 v[66:69], v[236:239], v[228:231], v[66:69]
	global_load_lds_dwordx4 v[132:133], off
	s_addk_i32 m0, 0x1000
	v_mfma_f32_16x16x32_bf16 v[62:65], v[240:243], v[200:203], v[62:65]
	v_mfma_f32_16x16x32_bf16 v[58:61], v[240:243], v[204:207], v[58:61]
	v_mfma_f32_16x16x32_bf16 v[54:57], v[240:243], v[208:211], v[54:57]
	global_load_lds_dwordx4 v[142:143], off
	v_lshl_add_u64 v[142:143], v[142:143], 0, s[2:3]
	s_addk_i32 m0, 0x1000
	v_mfma_f32_16x16x32_bf16 v[50:53], v[240:243], v[212:215], v[50:53]
	v_mfma_f32_16x16x32_bf16 v[46:49], v[240:243], v[216:219], v[46:49]
	v_mfma_f32_16x16x32_bf16 v[42:45], v[240:243], v[220:223], v[42:45]
	global_load_lds_dwordx4 v[142:143], off
	v_lshl_add_u64 v[142:143], v[142:143], 0, s[2:3]
	s_addk_i32 m0, 0x1000
	v_mfma_f32_16x16x32_bf16 v[38:41], v[240:243], v[224:227], v[38:41]
	v_mfma_f32_16x16x32_bf16 v[34:37], v[240:243], v[228:231], v[34:37]
	v_mfma_f32_16x16x32_bf16 v[30:33], v[244:247], v[200:203], v[30:33]
	global_load_lds_dwordx4 v[142:143], off
	s_addk_i32 m0, 0x1000
	v_lshl_add_u64 v[142:143], v[134:135], 0, s[2:3]
	v_mfma_f32_16x16x32_bf16 v[26:29], v[244:247], v[204:207], v[26:29]
	v_mfma_f32_16x16x32_bf16 v[22:25], v[244:247], v[208:211], v[22:25]
	v_mfma_f32_16x16x32_bf16 v[18:21], v[244:247], v[212:215], v[18:21]
	global_load_lds_dwordx4 v[134:135], off
	s_addk_i32 m0, 0x1000
	v_lshl_add_u64 v[132:133], v[132:133], 0, s[12:13]
	v_mfma_f32_16x16x32_bf16 v[14:17], v[244:247], v[216:219], v[14:17]
	v_mfma_f32_16x16x32_bf16 v[10:13], v[244:247], v[220:223], v[10:13]
	v_mfma_f32_16x16x32_bf16 v[6:9], v[244:247], v[224:227], v[6:9]
	global_load_lds_dwordx4 v[142:143], off
	v_lshl_add_u64 v[134:135], v[134:135], 0, s[4:5]
	v_mfma_f32_16x16x32_bf16 v[2:5], v[244:247], v[228:231], v[2:5]
	s_mov_b32 s42, s41
	s_add_i32 s41, s41, 0x6000
	s_cmp_eq_u32 s41, 0x12000
	s_cselect_b32 s41, 0, s41
	s_sub_i32 s40, s40, 1
	s_cmp_lg_u32 s40, 0
	s_cbranch_scc1 .Lt4_loop
	s_waitcnt vmcnt(6) lgkmcnt(0)
	s_barrier
	v_add_u32_e32 v144, s41, v136
	v_mfma_f32_16x16x32_bf16 v[126:129], v[184:187], v[146:149], v[126:129]
	ds_read_b128 v[200:203], v144 offset:0
	v_mfma_f32_16x16x32_bf16 v[122:125], v[184:187], v[152:155], v[122:125]
	ds_read_b128 v[204:207], v144 offset:1024
	v_mfma_f32_16x16x32_bf16 v[118:121], v[184:187], v[156:159], v[118:121]
	ds_read_b128 v[208:211], v144 offset:2048
	v_mfma_f32_16x16x32_bf16 v[114:117], v[184:187], v[162:165], v[114:117]
	ds_read_b128 v[212:215], v144 offset:3072
	v_mfma_f32_16x16x32_bf16 v[110:113], v[184:187], v[166:169], v[110:113]
	ds_read_b128 v[216:219], v144 offset:4096
	v_mfma_f32_16x16x32_bf16 v[106:109], v[184:187], v[170:173], v[106:109]
	ds_read_b128 v[220:223], v144 offset:5120
	v_mfma_f32_16x16x32_bf16 v[102:105], v[184:187], v[176:179], v[102:105]
	ds_read_b128 v[224:227], v144 offset:6144
	v_mfma_f32_16x16x32_bf16 v[98:101], v[184:187], v[180:183], v[98:101]
	ds_read_b128 v[228:231], v144 offset:7168
	v_mfma_f32_16x16x32_bf16 v[94:97], v[188:191], v[146:149], v[94:97]
	v_add_u32_e32 v144, s41, v137
	v_mfma_f32_16x16x32_bf16 v[90:93], v[188:191], v[152:155], v[90:93]
	v_mfma_f32_16x16x32_bf16 v[86:89], v[188:191], v[156:159], v[86:89]
	ds_read_b128 v[232:235], v144 offset:16384
	v_mfma_f32_16x16x32_bf16 v[82:85], v[188:191], v[162:165], v[82:85]
	ds_read_b128 v[236:239], v144 offset:17408
	v_mfma_f32_16x16x32_bf16 v[78:81], v[188:191], v[166:169], v[78:81]
	ds_read_b128 v[240:243], v144 offset:18432
	v_mfma_f32_16x16x32_bf16 v[74:77], v[188:191], v[170:173], v[74:77]
	ds_read_b128 v[244:247], v144 offset:19456
	s_add_i32 s43, s47, s42
	v_mfma_f32_16x16x32_bf16 v[70:73], v[188:191], v[176:179], v[70:73]
	s_mov_b32 m0, s43
	v_lshl_add_u64 v[142:143], v[132:133], 0, s[2:3]
	v_mfma_f32_16x16x32_bf16 v[66:69], v[188:191], v[180:183], v[66:69]
	global_load_lds_dwordx4 v[132:133], off
	s_addk_i32 m0, 0x1000
	v_mfma_f32_16x16x32_bf16 v[62:65], v[192:195], v[146:149], v[62:65]
;     ...
;   for (int kt = 0; kt < nk; kt++) {
;     if (kt + 1 < nk) asm volatile("s_waitcnt vmcnt(6)" ::: "memory");
;     else asm volatile("s_waitcnt vmcnt(0)" ::: "memory");
;     __builtin_amdgcn_s_barrier();
;     asm volatile("" ::: "memory");
;     if (kt + 2 < nk) G2_STAGE(kt + 2);
;     const char* cS = smem + (kt % 3) * 24576;
;     bf16x8 xa[8], wb[4];
; #pragma unroll
;     for (int f = 0; f < 8; f++) xa[f] = *(const bf16x8*)(cS + aoff + f * 1024);
; #pragma unroll
;     for (int f = 0; f < 4; f++) wb[f] = *(const bf16x8*)(cS + boff + f * 1024);
; #pragma unroll
;     for (int nf = 0; nf < 4; nf++)
; #pragma unroll
;       for (int mf = 0; mf < 8; mf++)
;         acc[nf][mf] = __builtin_amdgcn_mfma_f32_16x16x32_bf16(wb[nf], xa[mf], acc[nf][mf], 0, 0, 0);
;   }
	v_mfma_f32_16x16x32_bf16 v[58:61], v[192:195], v[152:155], v[58:61]
	v_mfma_f32_16x16x32_bf16 v[54:57], v[192:195], v[156:159], v[54:57]
	global_load_lds_dwordx4 v[142:143], off
	v_lshl_add_u64 v[142:143], v[142:143], 0, s[2:3]
	s_addk_i32 m0, 0x1000
	v_mfma_f32_16x16x32_bf16 v[50:53], v[192:195], v[162:165], v[50:53]
	v_mfma_f32_16x16x32_bf16 v[46:49], v[192:195], v[166:169], v[46:49]
	v_mfma_f32_16x16x32_bf16 v[42:45], v[192:195], v[170:173], v[42:45]
	global_load_lds_dwordx4 v[142:143], off
	v_lshl_add_u64 v[142:143], v[142:143], 0, s[2:3]
	s_addk_i32 m0, 0x1000
	v_mfma_f32_16x16x32_bf16 v[38:41], v[192:195], v[176:179], v[38:41]
	v_mfma_f32_16x16x32_bf16 v[34:37], v[192:195], v[180:183], v[34:37]
	v_mfma_f32_16x16x32_bf16 v[30:33], v[196:199], v[146:149], v[30:33]
	global_load_lds_dwordx4 v[142:143], off
	s_addk_i32 m0, 0x1000
	v_lshl_add_u64 v[142:143], v[134:135], 0, s[2:3]
	v_mfma_f32_16x16x32_bf16 v[26:29], v[196:199], v[152:155], v[26:29]
	v_mfma_f32_16x16x32_bf16 v[22:25], v[196:199], v[156:159], v[22:25]
	v_mfma_f32_16x16x32_bf16 v[18:21], v[196:199], v[162:165], v[18:21]
	global_load_lds_dwordx4 v[134:135], off
	s_addk_i32 m0, 0x1000
	v_lshl_add_u64 v[132:133], v[132:133], 0, s[12:13]
	v_mfma_f32_16x16x32_bf16 v[14:17], v[196:199], v[166:169], v[14:17]
	v_mfma_f32_16x16x32_bf16 v[10:13], v[196:199], v[170:173], v[10:13]
	v_mfma_f32_16x16x32_bf16 v[6:9], v[196:199], v[176:179], v[6:9]
	global_load_lds_dwordx4 v[142:143], off
	v_lshl_add_u64 v[134:135], v[134:135], 0, s[4:5]
	v_mfma_f32_16x16x32_bf16 v[2:5], v[196:199], v[180:183], v[2:5]
	s_mov_b32 s42, s41
	s_add_i32 s41, s41, 0x6000
	s_cmp_eq_u32 s41, 0x12000
	s_cselect_b32 s41, 0, s41
	s_waitcnt vmcnt(6) lgkmcnt(0)
	s_barrier
	v_add_u32_e32 v144, s41, v136
	v_mfma_f32_16x16x32_bf16 v[126:129], v[232:235], v[200:203], v[126:129]
	ds_read_b128 v[146:149], v144 offset:0
	v_mfma_f32_16x16x32_bf16 v[122:125], v[232:235], v[204:207], v[122:125]
	ds_read_b128 v[152:155], v144 offset:1024
	v_mfma_f32_16x16x32_bf16 v[118:121], v[232:235], v[208:211], v[118:121]
	ds_read_b128 v[156:159], v144 offset:2048
	v_mfma_f32_16x16x32_bf16 v[114:117], v[232:235], v[212:215], v[114:117]
	ds_read_b128 v[162:165], v144 offset:3072
	v_mfma_f32_16x16x32_bf16 v[110:113], v[232:235], v[216:219], v[110:113]
	ds_read_b128 v[166:169], v144 offset:4096
	v_mfma_f32_16x16x32_bf16 v[106:109], v[232:235], v[220:223], v[106:109]
	ds_read_b128 v[170:173], v144 offset:5120
	v_mfma_f32_16x16x32_bf16 v[102:105], v[232:235], v[224:227], v[102:105]
	ds_read_b128 v[176:179], v144 offset:6144
	v_mfma_f32_16x16x32_bf16 v[98:101], v[232:235], v[228:231], v[98:101]
	ds_read_b128 v[180:183], v144 offset:7168
	v_mfma_f32_16x16x32_bf16 v[94:97], v[236:239], v[200:203], v[94:97]
	v_add_u32_e32 v144, s41, v137
	v_mfma_f32_16x16x32_bf16 v[90:93], v[236:239], v[204:207], v[90:93]
	v_mfma_f32_16x16x32_bf16 v[86:89], v[236:239], v[208:211], v[86:89]
	ds_read_b128 v[184:187], v144 offset:16384
	v_mfma_f32_16x16x32_bf16 v[82:85], v[236:239], v[212:215], v[82:85]
	ds_read_b128 v[188:191], v144 offset:17408
	v_mfma_f32_16x16x32_bf16 v[78:81], v[236:239], v[216:219], v[78:81]
	ds_read_b128 v[192:195], v144 offset:18432
	v_mfma_f32_16x16x32_bf16 v[74:77], v[236:239], v[220:223], v[74:77]
	ds_read_b128 v[196:199], v144 offset:19456
	v_mfma_f32_16x16x32_bf16 v[70:73], v[236:239], v[224:227], v[70:73]
	v_mfma_f32_16x16x32_bf16 v[66:69], v[236:239], v[228:231], v[66:69]
	v_mfma_f32_16x16x32_bf16 v[62:65], v[240:243], v[200:203], v[62:65]
	v_mfma_f32_16x16x32_bf16 v[58:61], v[240:243], v[204:207], v[58:61]
	v_mfma_f32_16x16x32_bf16 v[54:57], v[240:243], v[208:211], v[54:57]
	v_mfma_f32_16x16x32_bf16 v[50:53], v[240:243], v[212:215], v[50:53]
	v_mfma_f32_16x16x32_bf16 v[46:49], v[240:243], v[216:219], v[46:49]
	v_mfma_f32_16x16x32_bf16 v[42:45], v[240:243], v[220:223], v[42:45]
	v_mfma_f32_16x16x32_bf16 v[38:41], v[240:243], v[224:227], v[38:41]
	v_mfma_f32_16x16x32_bf16 v[34:37], v[240:243], v[228:231], v[34:37]
	v_mfma_f32_16x16x32_bf16 v[30:33], v[244:247], v[200:203], v[30:33]
	v_mfma_f32_16x16x32_bf16 v[26:29], v[244:247], v[204:207], v[26:29]
	v_mfma_f32_16x16x32_bf16 v[22:25], v[244:247], v[208:211], v[22:25]
	v_mfma_f32_16x16x32_bf16 v[18:21], v[244:247], v[212:215], v[18:21]
	v_mfma_f32_16x16x32_bf16 v[14:17], v[244:247], v[216:219], v[14:17]
	v_mfma_f32_16x16x32_bf16 v[10:13], v[244:247], v[220:223], v[10:13]
	v_mfma_f32_16x16x32_bf16 v[6:9], v[244:247], v[224:227], v[6:9]
	v_mfma_f32_16x16x32_bf16 v[2:5], v[244:247], v[228:231], v[2:5]
	s_mov_b32 s42, s41
	s_add_i32 s41, s41, 0x6000
	s_cmp_eq_u32 s41, 0x12000
	s_cselect_b32 s41, 0, s41
	s_waitcnt vmcnt(0) lgkmcnt(0)
	s_barrier
; DEVI unsigned pack2(float a, float b) { return __builtin_bit_cast(unsigned, __builtin_convertvector((f32x2_t){a, b}, bf16x2_t)); }
; DEVI float blo(unsigned u) { return __uint_as_float(u << 16); }
; DEVI float bhi(unsigned u) { return __uint_as_float(u & 0xffff0000u); }
; DEVI float siluf_(float x) { return x * __builtin_amdgcn_rcpf(1.f + __expf(-x)); }
;     ...
;   for (int kt = 0; kt < nk; kt++) {
;     if (kt + 1 < nk) asm volatile("s_waitcnt vmcnt(6)" ::: "memory");
;     else asm volatile("s_waitcnt vmcnt(0)" ::: "memory");
;     __builtin_amdgcn_s_barrier();
;     asm volatile("" ::: "memory");
;     if (kt + 2 < nk) G2_STAGE(kt + 2);
;     const char* cS = smem + (kt % 3) * 24576;
;     bf16x8 xa[8], wb[4];
; #pragma unroll
;     for (int f = 0; f < 8; f++) xa[f] = *(const bf16x8*)(cS + aoff + f * 1024);
; #pragma unroll
;     for (int f = 0; f < 4; f++) wb[f] = *(const bf16x8*)(cS + boff + f * 1024);
; #pragma unroll
;     for (int nf = 0; nf < 4; nf++)
; #pragma unroll
;       for (int mf = 0; mf < 8; mf++)
;         acc[nf][mf] = __builtin_amdgcn_mfma_f32_16x16x32_bf16(wb[nf], xa[mf], acc[nf][mf], 0, 0, 0);
;   }
;     ...
; #pragma unroll
;   for (int mf = 0; mf < 8; mf++) {
;     const int row = m0 + wm * 128 + mf * 16 + r16;
;     if (EPI == EPI_SWIGLU) {
; #pragma unroll
;       for (int nf = 0; nf < 2; nf++) {
;         const int hcol = (n0 >> 1) + wn * 32 + nf * 16 + quad * 4;
;         f32x4 g = acc[nf][mf], u = acc[nf + 2][mf];
;         u32x2 pk;
;         pk[0] = pack2(siluf_(g[0]) * u[0], siluf_(g[1]) * u[1]);
;         pk[1] = pack2(siluf_(g[2]) * u[2], siluf_(g[3]) * u[3]);
;         *(u32x2*)(outb + (size_t)row * DFF + hcol) = pk;
;       }
;     } else {
; #pragma unroll
;       for (int nf = 0; nf < 4; nf++) {
;         const int col = n0 + wn * 64 + nf * 16 + quad * 4;
;         f32x4 a = acc[nf][mf];
;         if (EPI == EPI_RESID || EPI == EPI_RESID_ATOMIC) {
;           f32x4 x = a;
;           if (EPI == EPI_RESID || kpart == 0) {
;             const u32x2 xr = *(const u32x2*)((const u16*)(p.ws + WS_XB) + (size_t)row * 1024 + col);
;             x[0] += ALPHA * blo(xr[0]); x[1] += ALPHA * bhi(xr[0]); x[2] += ALPHA * blo(xr[1]); x[3] += ALPHA * bhi(xr[1]);
;           }
;           if (EPI == EPI_RESID) *(f32x4*)((float*)(p.ws + WS_XF) + (size_t)row * 1024 + col) = x;
	v_add_u32_e32 v144, s41, v136
	v_mfma_f32_16x16x32_bf16 v[126:129], v[184:187], v[146:149], v[126:129]
	ds_read_b128 v[200:203], v144 offset:0
	v_mfma_f32_16x16x32_bf16 v[122:125], v[184:187], v[152:155], v[122:125]
	ds_read_b128 v[204:207], v144 offset:1024
	v_mfma_f32_16x16x32_bf16 v[118:121], v[184:187], v[156:159], v[118:121]
	ds_read_b128 v[208:211], v144 offset:2048
	v_mfma_f32_16x16x32_bf16 v[114:117], v[184:187], v[162:165], v[114:117]
	ds_read_b128 v[212:215], v144 offset:3072
	v_mfma_f32_16x16x32_bf16 v[110:113], v[184:187], v[166:169], v[110:113]
	ds_read_b128 v[216:219], v144 offset:4096
	v_mfma_f32_16x16x32_bf16 v[106:109], v[184:187], v[170:173], v[106:109]
	ds_read_b128 v[220:223], v144 offset:5120
	v_mfma_f32_16x16x32_bf16 v[102:105], v[184:187], v[176:179], v[102:105]
	ds_read_b128 v[224:227], v144 offset:6144
	v_mfma_f32_16x16x32_bf16 v[98:101], v[184:187], v[180:183], v[98:101]
	ds_read_b128 v[228:231], v144 offset:7168
	v_mfma_f32_16x16x32_bf16 v[94:97], v[188:191], v[146:149], v[94:97]
	v_add_u32_e32 v144, s41, v137
	v_mfma_f32_16x16x32_bf16 v[90:93], v[188:191], v[152:155], v[90:93]
	v_mfma_f32_16x16x32_bf16 v[86:89], v[188:191], v[156:159], v[86:89]
	ds_read_b128 v[232:235], v144 offset:16384
	v_mfma_f32_16x16x32_bf16 v[82:85], v[188:191], v[162:165], v[82:85]
	ds_read_b128 v[236:239], v144 offset:17408
	v_mfma_f32_16x16x32_bf16 v[78:81], v[188:191], v[166:169], v[78:81]
	ds_read_b128 v[240:243], v144 offset:18432
	v_mfma_f32_16x16x32_bf16 v[74:77], v[188:191], v[170:173], v[74:77]
	ds_read_b128 v[244:247], v144 offset:19456
	v_mfma_f32_16x16x32_bf16 v[70:73], v[188:191], v[176:179], v[70:73]
	v_mfma_f32_16x16x32_bf16 v[66:69], v[188:191], v[180:183], v[66:69]
	v_mfma_f32_16x16x32_bf16 v[62:65], v[192:195], v[146:149], v[62:65]
	v_mfma_f32_16x16x32_bf16 v[58:61], v[192:195], v[152:155], v[58:61]
	v_mfma_f32_16x16x32_bf16 v[54:57], v[192:195], v[156:159], v[54:57]
	v_mfma_f32_16x16x32_bf16 v[50:53], v[192:195], v[162:165], v[50:53]
	v_mfma_f32_16x16x32_bf16 v[46:49], v[192:195], v[166:169], v[46:49]
	v_mfma_f32_16x16x32_bf16 v[42:45], v[192:195], v[170:173], v[42:45]
	v_mfma_f32_16x16x32_bf16 v[38:41], v[192:195], v[176:179], v[38:41]
	v_mfma_f32_16x16x32_bf16 v[34:37], v[192:195], v[180:183], v[34:37]
	v_mfma_f32_16x16x32_bf16 v[30:33], v[196:199], v[146:149], v[30:33]
	v_mfma_f32_16x16x32_bf16 v[26:29], v[196:199], v[152:155], v[26:29]
	v_mfma_f32_16x16x32_bf16 v[22:25], v[196:199], v[156:159], v[22:25]
	v_mfma_f32_16x16x32_bf16 v[18:21], v[196:199], v[162:165], v[18:21]
	v_mfma_f32_16x16x32_bf16 v[14:17], v[196:199], v[166:169], v[14:17]
	v_mfma_f32_16x16x32_bf16 v[10:13], v[196:199], v[170:173], v[10:13]
	v_mfma_f32_16x16x32_bf16 v[6:9], v[196:199], v[176:179], v[6:9]
	v_mfma_f32_16x16x32_bf16 v[2:5], v[196:199], v[180:183], v[2:5]
	s_mov_b32 s42, s41
	s_add_i32 s41, s41, 0x6000
	s_cmp_eq_u32 s41, 0x12000
	s_cselect_b32 s41, 0, s41
	s_mov_b32 s4, 0x8000
	s_mov_b32 s5, 0
	s_mov_b32 s10, 0x10000
	s_mov_b32 s11, 0
	s_mov_b32 s45, 0x3fd744fd
	s_waitcnt lgkmcnt(0)
	v_mfma_f32_16x16x32_bf16 v[126:129], v[232:235], v[200:203], v[126:129]
	v_mfma_f32_16x16x32_bf16 v[122:125], v[232:235], v[204:207], v[122:125]
	v_mfma_f32_16x16x32_bf16 v[118:121], v[232:235], v[208:211], v[118:121]
	v_mfma_f32_16x16x32_bf16 v[114:117], v[232:235], v[212:215], v[114:117]
	v_mfma_f32_16x16x32_bf16 v[110:113], v[232:235], v[216:219], v[110:113]
	global_load_dwordx2 v[146:147], v[138:139], off offset:0
	v_mfma_f32_16x16x32_bf16 v[106:109], v[232:235], v[220:223], v[106:109]
	global_load_dwordx2 v[148:149], v[138:139], off offset:32
	v_mfma_f32_16x16x32_bf16 v[102:105], v[232:235], v[224:227], v[102:105]
	global_load_dwordx2 v[152:153], v[138:139], off offset:128
	v_mfma_f32_16x16x32_bf16 v[98:101], v[232:235], v[228:231], v[98:101]
	global_load_dwordx2 v[154:155], v[138:139], off offset:160
	v_lshl_add_u64 v[138:139], v[138:139], 0, s[4:5]
	v_mfma_f32_16x16x32_bf16 v[94:97], v[236:239], v[200:203], v[94:97]
	global_load_dwordx2 v[156:157], v[138:139], off offset:0
	v_mfma_f32_16x16x32_bf16 v[90:93], v[236:239], v[204:207], v[90:93]
	global_load_dwordx2 v[158:159], v[138:139], off offset:32
	v_mfma_f32_16x16x32_bf16 v[86:89], v[236:239], v[208:211], v[86:89]
	global_load_dwordx2 v[162:163], v[138:139], off offset:128
	v_mfma_f32_16x16x32_bf16 v[82:85], v[236:239], v[212:215], v[82:85]
	global_load_dwordx2 v[164:165], v[138:139], off offset:160
	v_lshl_add_u64 v[138:139], v[138:139], 0, s[4:5]
	v_mfma_f32_16x16x32_bf16 v[78:81], v[236:239], v[216:219], v[78:81]
	global_load_dwordx2 v[166:167], v[138:139], off offset:0
	v_mfma_f32_16x16x32_bf16 v[74:77], v[236:239], v[220:223], v[74:77]
	global_load_dwordx2 v[168:169], v[138:139], off offset:32
	v_mfma_f32_16x16x32_bf16 v[70:73], v[236:239], v[224:227], v[70:73]
	global_load_dwordx2 v[170:171], v[138:139], off offset:128
	v_mfma_f32_16x16x32_bf16 v[66:69], v[236:239], v[228:231], v[66:69]
	global_load_dwordx2 v[172:173], v[138:139], off offset:160
	v_lshl_add_u64 v[138:139], v[138:139], 0, s[4:5]
	v_mfma_f32_16x16x32_bf16 v[62:65], v[240:243], v[200:203], v[62:65]
	global_load_dwordx2 v[176:177], v[138:139], off offset:0
	v_mfma_f32_16x16x32_bf16 v[58:61], v[240:243], v[204:207], v[58:61]
	global_load_dwordx2 v[178:179], v[138:139], off offset:32
	v_mfma_f32_16x16x32_bf16 v[54:57], v[240:243], v[208:211], v[54:57]
	global_load_dwordx2 v[180:181], v[138:139], off offset:128
	v_mfma_f32_16x16x32_bf16 v[50:53], v[240:243], v[212:215], v[50:53]
	global_load_dwordx2 v[182:183], v[138:139], off offset:160
	v_lshl_add_u64 v[138:139], v[138:139], 0, s[4:5]
	v_mfma_f32_16x16x32_bf16 v[46:49], v[240:243], v[216:219], v[46:49]
; DEVI float blo(unsigned u) { return __uint_as_float(u << 16); }
; DEVI float bhi(unsigned u) { return __uint_as_float(u & 0xffff0000u); }
;     ...
;         if (EPI == EPI_RESID || EPI == EPI_RESID_ATOMIC) {
;           f32x4 x = a;
;           if (EPI == EPI_RESID || kpart == 0) {
;             const u32x2 xr = *(const u32x2*)((const u16*)(p.ws + WS_XB) + (size_t)row * 1024 + col);
;             x[0] += ALPHA * blo(xr[0]); x[1] += ALPHA * bhi(xr[0]); x[2] += ALPHA * blo(xr[1]); x[3] += ALPHA * bhi(xr[1]);
;           }
;           if (EPI == EPI_RESID) *(f32x4*)((float*)(p.ws + WS_XF) + (size_t)row * 1024 + col) = x;
;           else *(f32x4*)((float*)(p.ws + WS_SLAB) + ((size_t)kpart * 512 + (row - T_P)) * 1024 + col) = x;
	global_load_dwordx2 v[184:185], v[138:139], off offset:0
	v_mfma_f32_16x16x32_bf16 v[42:45], v[240:243], v[220:223], v[42:45]
	global_load_dwordx2 v[186:187], v[138:139], off offset:32
	v_mfma_f32_16x16x32_bf16 v[38:41], v[240:243], v[224:227], v[38:41]
	global_load_dwordx2 v[188:189], v[138:139], off offset:128
	v_mfma_f32_16x16x32_bf16 v[34:37], v[240:243], v[228:231], v[34:37]
	global_load_dwordx2 v[190:191], v[138:139], off offset:160
	v_lshl_add_u64 v[138:139], v[138:139], 0, s[4:5]
	v_mfma_f32_16x16x32_bf16 v[30:33], v[244:247], v[200:203], v[30:33]
	global_load_dwordx2 v[192:193], v[138:139], off offset:0
	v_mfma_f32_16x16x32_bf16 v[26:29], v[244:247], v[204:207], v[26:29]
	global_load_dwordx2 v[194:195], v[138:139], off offset:32
	v_mfma_f32_16x16x32_bf16 v[22:25], v[244:247], v[208:211], v[22:25]
	global_load_dwordx2 v[196:197], v[138:139], off offset:128
	v_mfma_f32_16x16x32_bf16 v[18:21], v[244:247], v[212:215], v[18:21]
	global_load_dwordx2 v[198:199], v[138:139], off offset:160
	v_lshl_add_u64 v[138:139], v[138:139], 0, s[4:5]
	v_mfma_f32_16x16x32_bf16 v[14:17], v[244:247], v[216:219], v[14:17]
	v_mfma_f32_16x16x32_bf16 v[10:13], v[244:247], v[220:223], v[10:13]
	v_mfma_f32_16x16x32_bf16 v[6:9], v[244:247], v[224:227], v[6:9]
	v_mfma_f32_16x16x32_bf16 v[2:5], v[244:247], v[228:231], v[2:5]
	s_mov_b32 m0, s44
	global_load_dwordx2 v[200:201], v[138:139], off offset:0
	global_load_dwordx2 v[202:203], v[138:139], off offset:32
	global_load_dwordx2 v[204:205], v[138:139], off offset:128
	global_load_dwordx2 v[206:207], v[138:139], off offset:160
	v_lshl_add_u64 v[138:139], v[138:139], 0, s[4:5]
	global_load_dwordx2 v[208:209], v[138:139], off offset:0
	global_load_dwordx2 v[210:211], v[138:139], off offset:32
	global_load_dwordx2 v[212:213], v[138:139], off offset:128
	global_load_dwordx2 v[214:215], v[138:139], off offset:160
	v_lshl_add_u64 v[138:139], v[138:139], 0, s[4:5]
	s_nop 7
	s_waitcnt vmcnt(31)
	v_lshlrev_b32_e32 v216, 16, v146
	v_and_b32_e32 v146, 0xffff0000, v146
	v_lshlrev_b32_e32 v217, 16, v147
	v_and_b32_e32 v147, 0xffff0000, v147
	v_fmac_f32_e32 v126, s45, v216
	v_fmac_f32_e32 v127, s45, v146
	v_fmac_f32_e32 v128, s45, v217
	v_fmac_f32_e32 v129, s45, v147
	global_store_dwordx4 v[140:141], v[126:129], off offset:0
	s_waitcnt vmcnt(31)
	v_lshlrev_b32_e32 v216, 16, v148
	v_and_b32_e32 v148, 0xffff0000, v148
	v_lshlrev_b32_e32 v217, 16, v149
	v_and_b32_e32 v149, 0xffff0000, v149
	v_fmac_f32_e32 v94, s45, v216
	v_fmac_f32_e32 v95, s45, v148
	v_fmac_f32_e32 v96, s45, v217
	v_fmac_f32_e32 v97, s45, v149
	global_store_dwordx4 v[140:141], v[94:97], off offset:64
	s_waitcnt vmcnt(31)
	v_lshlrev_b32_e32 v216, 16, v152
	v_and_b32_e32 v152, 0xffff0000, v152
	v_lshlrev_b32_e32 v217, 16, v153
	v_and_b32_e32 v153, 0xffff0000, v153
	v_fmac_f32_e32 v62, s45, v216
	v_fmac_f32_e32 v63, s45, v152
	v_fmac_f32_e32 v64, s45, v217
	v_fmac_f32_e32 v65, s45, v153
	global_store_dwordx4 v[140:141], v[62:65], off offset:128
	s_waitcnt vmcnt(31)
	v_lshlrev_b32_e32 v216, 16, v154
	v_and_b32_e32 v154, 0xffff0000, v154
	v_lshlrev_b32_e32 v217, 16, v155
	v_and_b32_e32 v155, 0xffff0000, v155
	v_fmac_f32_e32 v30, s45, v216
	v_fmac_f32_e32 v31, s45, v154
	v_fmac_f32_e32 v32, s45, v217
	v_fmac_f32_e32 v33, s45, v155
	global_store_dwordx4 v[140:141], v[30:33], off offset:192
	v_lshl_add_u64 v[140:141], v[140:141], 0, s[10:11]
	s_waitcnt vmcnt(31)
	v_lshlrev_b32_e32 v216, 16, v156
	v_and_b32_e32 v156, 0xffff0000, v156
	v_lshlrev_b32_e32 v217, 16, v157
	v_and_b32_e32 v157, 0xffff0000, v157
	v_fmac_f32_e32 v122, s45, v216
	v_fmac_f32_e32 v123, s45, v156
	v_fmac_f32_e32 v124, s45, v217
	v_fmac_f32_e32 v125, s45, v157
	global_store_dwordx4 v[140:141], v[122:125], off offset:0
	s_waitcnt vmcnt(31)
	v_lshlrev_b32_e32 v216, 16, v158
	v_and_b32_e32 v158, 0xffff0000, v158
	v_lshlrev_b32_e32 v217, 16, v159
	v_and_b32_e32 v159, 0xffff0000, v159
	v_fmac_f32_e32 v90, s45, v216
	v_fmac_f32_e32 v91, s45, v158
	v_fmac_f32_e32 v92, s45, v217
	v_fmac_f32_e32 v93, s45, v159
	global_store_dwordx4 v[140:141], v[90:93], off offset:64
	s_waitcnt vmcnt(31)
	v_lshlrev_b32_e32 v216, 16, v162
	v_and_b32_e32 v162, 0xffff0000, v162
	v_lshlrev_b32_e32 v217, 16, v163
	v_and_b32_e32 v163, 0xffff0000, v163
	v_fmac_f32_e32 v58, s45, v216
	v_fmac_f32_e32 v59, s45, v162
	v_fmac_f32_e32 v60, s45, v217
	v_fmac_f32_e32 v61, s45, v163
	global_store_dwordx4 v[140:141], v[58:61], off offset:128
	s_waitcnt vmcnt(31)
	v_lshlrev_b32_e32 v216, 16, v164
	v_and_b32_e32 v164, 0xffff0000, v164
	v_lshlrev_b32_e32 v217, 16, v165
	v_and_b32_e32 v165, 0xffff0000, v165
	v_fmac_f32_e32 v26, s45, v216
	v_fmac_f32_e32 v27, s45, v164
	v_fmac_f32_e32 v28, s45, v217
	v_fmac_f32_e32 v29, s45, v165
	global_store_dwordx4 v[140:141], v[26:29], off offset:192
	v_lshl_add_u64 v[140:141], v[140:141], 0, s[10:11]
	s_waitcnt vmcnt(31)
	v_lshlrev_b32_e32 v216, 16, v166
	v_and_b32_e32 v166, 0xffff0000, v166
	v_lshlrev_b32_e32 v217, 16, v167
	v_and_b32_e32 v167, 0xffff0000, v167
	v_fmac_f32_e32 v118, s45, v216
	v_fmac_f32_e32 v119, s45, v166
	v_fmac_f32_e32 v120, s45, v217
	v_fmac_f32_e32 v121, s45, v167
	global_store_dwordx4 v[140:141], v[118:121], off offset:0
	s_waitcnt vmcnt(31)
	v_lshlrev_b32_e32 v216, 16, v168
	v_and_b32_e32 v168, 0xffff0000, v168
	v_lshlrev_b32_e32 v217, 16, v169
	v_and_b32_e32 v169, 0xffff0000, v169
	v_fmac_f32_e32 v86, s45, v216
	v_fmac_f32_e32 v87, s45, v168
	v_fmac_f32_e32 v88, s45, v217
	v_fmac_f32_e32 v89, s45, v169
	global_store_dwordx4 v[140:141], v[86:89], off offset:64
	s_waitcnt vmcnt(31)
; DEVI float blo(unsigned u) { return __uint_as_float(u << 16); }
; DEVI float bhi(unsigned u) { return __uint_as_float(u & 0xffff0000u); }
;     ...
;         if (EPI == EPI_RESID || EPI == EPI_RESID_ATOMIC) {
;           f32x4 x = a;
;           if (EPI == EPI_RESID || kpart == 0) {
;             const u32x2 xr = *(const u32x2*)((const u16*)(p.ws + WS_XB) + (size_t)row * 1024 + col);
;             x[0] += ALPHA * blo(xr[0]); x[1] += ALPHA * bhi(xr[0]); x[2] += ALPHA * blo(xr[1]); x[3] += ALPHA * bhi(xr[1]);
;           }
;           if (EPI == EPI_RESID) *(f32x4*)((float*)(p.ws + WS_XF) + (size_t)row * 1024 + col) = x;
;           else *(f32x4*)((float*)(p.ws + WS_SLAB) + ((size_t)kpart * 512 + (row - T_P)) * 1024 + col) = x;
	v_lshlrev_b32_e32 v216, 16, v170
	v_and_b32_e32 v170, 0xffff0000, v170
	v_lshlrev_b32_e32 v217, 16, v171
	v_and_b32_e32 v171, 0xffff0000, v171
	v_fmac_f32_e32 v54, s45, v216
	v_fmac_f32_e32 v55, s45, v170
	v_fmac_f32_e32 v56, s45, v217
	v_fmac_f32_e32 v57, s45, v171
	global_store_dwordx4 v[140:141], v[54:57], off offset:128
	s_waitcnt vmcnt(31)
	v_lshlrev_b32_e32 v216, 16, v172
	v_and_b32_e32 v172, 0xffff0000, v172
	v_lshlrev_b32_e32 v217, 16, v173
	v_and_b32_e32 v173, 0xffff0000, v173
	v_fmac_f32_e32 v22, s45, v216
	v_fmac_f32_e32 v23, s45, v172
	v_fmac_f32_e32 v24, s45, v217
	v_fmac_f32_e32 v25, s45, v173
	global_store_dwordx4 v[140:141], v[22:25], off offset:192
	v_lshl_add_u64 v[140:141], v[140:141], 0, s[10:11]
	s_waitcnt vmcnt(31)
	v_lshlrev_b32_e32 v216, 16, v176
	v_and_b32_e32 v176, 0xffff0000, v176
	v_lshlrev_b32_e32 v217, 16, v177
	v_and_b32_e32 v177, 0xffff0000, v177
	v_fmac_f32_e32 v114, s45, v216
	v_fmac_f32_e32 v115, s45, v176
	v_fmac_f32_e32 v116, s45, v217
	v_fmac_f32_e32 v117, s45, v177
	global_store_dwordx4 v[140:141], v[114:117], off offset:0
	s_waitcnt vmcnt(31)
	v_lshlrev_b32_e32 v216, 16, v178
	v_and_b32_e32 v178, 0xffff0000, v178
	v_lshlrev_b32_e32 v217, 16, v179
	v_and_b32_e32 v179, 0xffff0000, v179
	v_fmac_f32_e32 v82, s45, v216
	v_fmac_f32_e32 v83, s45, v178
	v_fmac_f32_e32 v84, s45, v217
	v_fmac_f32_e32 v85, s45, v179
	global_store_dwordx4 v[140:141], v[82:85], off offset:64
	s_waitcnt vmcnt(31)
	v_lshlrev_b32_e32 v216, 16, v180
	v_and_b32_e32 v180, 0xffff0000, v180
	v_lshlrev_b32_e32 v217, 16, v181
	v_and_b32_e32 v181, 0xffff0000, v181
	v_fmac_f32_e32 v50, s45, v216
	v_fmac_f32_e32 v51, s45, v180
	v_fmac_f32_e32 v52, s45, v217
	v_fmac_f32_e32 v53, s45, v181
	global_store_dwordx4 v[140:141], v[50:53], off offset:128
	s_waitcnt vmcnt(31)
	v_lshlrev_b32_e32 v216, 16, v182
	v_and_b32_e32 v182, 0xffff0000, v182
	v_lshlrev_b32_e32 v217, 16, v183
	v_and_b32_e32 v183, 0xffff0000, v183
	v_fmac_f32_e32 v18, s45, v216
	v_fmac_f32_e32 v19, s45, v182
	v_fmac_f32_e32 v20, s45, v217
	v_fmac_f32_e32 v21, s45, v183
	global_store_dwordx4 v[140:141], v[18:21], off offset:192
	v_lshl_add_u64 v[140:141], v[140:141], 0, s[10:11]
	s_waitcnt vmcnt(31)
	v_lshlrev_b32_e32 v216, 16, v184
	v_and_b32_e32 v184, 0xffff0000, v184
	v_lshlrev_b32_e32 v217, 16, v185
	v_and_b32_e32 v185, 0xffff0000, v185
	v_fmac_f32_e32 v110, s45, v216
	v_fmac_f32_e32 v111, s45, v184
	v_fmac_f32_e32 v112, s45, v217
	v_fmac_f32_e32 v113, s45, v185
	global_store_dwordx4 v[140:141], v[110:113], off offset:0
	s_waitcnt vmcnt(31)
	v_lshlrev_b32_e32 v216, 16, v186
	v_and_b32_e32 v186, 0xffff0000, v186
	v_lshlrev_b32_e32 v217, 16, v187
	v_and_b32_e32 v187, 0xffff0000, v187
	v_fmac_f32_e32 v78, s45, v216
	v_fmac_f32_e32 v79, s45, v186
	v_fmac_f32_e32 v80, s45, v217
	v_fmac_f32_e32 v81, s45, v187
	global_store_dwordx4 v[140:141], v[78:81], off offset:64
	s_waitcnt vmcnt(31)
	v_lshlrev_b32_e32 v216, 16, v188
	v_and_b32_e32 v188, 0xffff0000, v188
	v_lshlrev_b32_e32 v217, 16, v189
	v_and_b32_e32 v189, 0xffff0000, v189
	v_fmac_f32_e32 v46, s45, v216
	v_fmac_f32_e32 v47, s45, v188
	v_fmac_f32_e32 v48, s45, v217
	v_fmac_f32_e32 v49, s45, v189
	global_store_dwordx4 v[140:141], v[46:49], off offset:128
	s_waitcnt vmcnt(31)
	v_lshlrev_b32_e32 v216, 16, v190
	v_and_b32_e32 v190, 0xffff0000, v190
	v_lshlrev_b32_e32 v217, 16, v191
	v_and_b32_e32 v191, 0xffff0000, v191
	v_fmac_f32_e32 v14, s45, v216
	v_fmac_f32_e32 v15, s45, v190
	v_fmac_f32_e32 v16, s45, v217
	v_fmac_f32_e32 v17, s45, v191
	global_store_dwordx4 v[140:141], v[14:17], off offset:192
	v_lshl_add_u64 v[140:141], v[140:141], 0, s[10:11]
	s_waitcnt vmcnt(31)
	v_lshlrev_b32_e32 v216, 16, v192
	v_and_b32_e32 v192, 0xffff0000, v192
	v_lshlrev_b32_e32 v217, 16, v193
	v_and_b32_e32 v193, 0xffff0000, v193
	v_fmac_f32_e32 v106, s45, v216
	v_fmac_f32_e32 v107, s45, v192
	v_fmac_f32_e32 v108, s45, v217
	v_fmac_f32_e32 v109, s45, v193
	global_store_dwordx4 v[140:141], v[106:109], off offset:0
	s_waitcnt vmcnt(31)
; DEVI unsigned pack2(float a, float b) { return __builtin_bit_cast(unsigned, __builtin_convertvector((f32x2_t){a, b}, bf16x2_t)); }
; DEVI float blo(unsigned u) { return __uint_as_float(u << 16); }
; DEVI float bhi(unsigned u) { return __uint_as_float(u & 0xffff0000u); }
; DEVI float siluf_(float x) { return x * __builtin_amdgcn_rcpf(1.f + __expf(-x)); }
;     ...
; #pragma unroll
;   for (int mf = 0; mf < 8; mf++) {
;     const int row = m0 + wm * 128 + mf * 16 + r16;
;     if (EPI == EPI_SWIGLU) {
; #pragma unroll
;       for (int nf = 0; nf < 2; nf++) {
;         const int hcol = (n0 >> 1) + wn * 32 + nf * 16 + quad * 4;
;         f32x4 g = acc[nf][mf], u = acc[nf + 2][mf];
;         u32x2 pk;
;         pk[0] = pack2(siluf_(g[0]) * u[0], siluf_(g[1]) * u[1]);
;         pk[1] = pack2(siluf_(g[2]) * u[2], siluf_(g[3]) * u[3]);
;         *(u32x2*)(outb + (size_t)row * DFF + hcol) = pk;
;       }
;     } else {
; #pragma unroll
;       for (int nf = 0; nf < 4; nf++) {
;         const int col = n0 + wn * 64 + nf * 16 + quad * 4;
;         f32x4 a = acc[nf][mf];
;         if (EPI == EPI_RESID || EPI == EPI_RESID_ATOMIC) {
;           f32x4 x = a;
;           if (EPI == EPI_RESID || kpart == 0) {
;             const u32x2 xr = *(const u32x2*)((const u16*)(p.ws + WS_XB) + (size_t)row * 1024 + col);
;             x[0] += ALPHA * blo(xr[0]); x[1] += ALPHA * bhi(xr[0]); x[2] += ALPHA * blo(xr[1]); x[3] += ALPHA * bhi(xr[1]);
;           }
;           if (EPI == EPI_RESID) *(f32x4*)((float*)(p.ws + WS_XF) + (size_t)row * 1024 + col) = x;
;           else *(f32x4*)((float*)(p.ws + WS_SLAB) + ((size_t)kpart * 512 + (row - T_P)) * 1024 + col) = x;
	v_lshlrev_b32_e32 v216, 16, v194
	v_and_b32_e32 v194, 0xffff0000, v194
	v_lshlrev_b32_e32 v217, 16, v195
	v_and_b32_e32 v195, 0xffff0000, v195
	v_fmac_f32_e32 v74, s45, v216
	v_fmac_f32_e32 v75, s45, v194
	v_fmac_f32_e32 v76, s45, v217
	v_fmac_f32_e32 v77, s45, v195
	global_store_dwordx4 v[140:141], v[74:77], off offset:64
	s_waitcnt vmcnt(31)
	v_lshlrev_b32_e32 v216, 16, v196
	v_and_b32_e32 v196, 0xffff0000, v196
	v_lshlrev_b32_e32 v217, 16, v197
	v_and_b32_e32 v197, 0xffff0000, v197
	v_fmac_f32_e32 v42, s45, v216
	v_fmac_f32_e32 v43, s45, v196
	v_fmac_f32_e32 v44, s45, v217
	v_fmac_f32_e32 v45, s45, v197
	global_store_dwordx4 v[140:141], v[42:45], off offset:128
	s_waitcnt vmcnt(31)
	v_lshlrev_b32_e32 v216, 16, v198
	v_and_b32_e32 v198, 0xffff0000, v198
	v_lshlrev_b32_e32 v217, 16, v199
	v_and_b32_e32 v199, 0xffff0000, v199
	v_fmac_f32_e32 v10, s45, v216
	v_fmac_f32_e32 v11, s45, v198
	v_fmac_f32_e32 v12, s45, v217
	v_fmac_f32_e32 v13, s45, v199
	global_store_dwordx4 v[140:141], v[10:13], off offset:192
	v_lshl_add_u64 v[140:141], v[140:141], 0, s[10:11]
	s_waitcnt vmcnt(31)
	v_lshlrev_b32_e32 v216, 16, v200
	v_and_b32_e32 v200, 0xffff0000, v200
	v_lshlrev_b32_e32 v217, 16, v201
	v_and_b32_e32 v201, 0xffff0000, v201
	v_fmac_f32_e32 v102, s45, v216
	v_fmac_f32_e32 v103, s45, v200
	v_fmac_f32_e32 v104, s45, v217
	v_fmac_f32_e32 v105, s45, v201
	global_store_dwordx4 v[140:141], v[102:105], off offset:0
	s_waitcnt vmcnt(31)
	v_lshlrev_b32_e32 v216, 16, v202
	v_and_b32_e32 v202, 0xffff0000, v202
	v_lshlrev_b32_e32 v217, 16, v203
	v_and_b32_e32 v203, 0xffff0000, v203
	v_fmac_f32_e32 v70, s45, v216
	v_fmac_f32_e32 v71, s45, v202
	v_fmac_f32_e32 v72, s45, v217
	v_fmac_f32_e32 v73, s45, v203
	global_store_dwordx4 v[140:141], v[70:73], off offset:64
	s_waitcnt vmcnt(31)
	v_lshlrev_b32_e32 v216, 16, v204
	v_and_b32_e32 v204, 0xffff0000, v204
	v_lshlrev_b32_e32 v217, 16, v205
	v_and_b32_e32 v205, 0xffff0000, v205
	v_fmac_f32_e32 v38, s45, v216
	v_fmac_f32_e32 v39, s45, v204
	v_fmac_f32_e32 v40, s45, v217
	v_fmac_f32_e32 v41, s45, v205
	global_store_dwordx4 v[140:141], v[38:41], off offset:128
	s_waitcnt vmcnt(31)
	v_lshlrev_b32_e32 v216, 16, v206
	v_and_b32_e32 v206, 0xffff0000, v206
	v_lshlrev_b32_e32 v217, 16, v207
	v_and_b32_e32 v207, 0xffff0000, v207
	v_fmac_f32_e32 v6, s45, v216
	v_fmac_f32_e32 v7, s45, v206
	v_fmac_f32_e32 v8, s45, v217
	v_fmac_f32_e32 v9, s45, v207
	global_store_dwordx4 v[140:141], v[6:9], off offset:192
	v_lshl_add_u64 v[140:141], v[140:141], 0, s[10:11]
	s_waitcnt vmcnt(31)
	v_lshlrev_b32_e32 v216, 16, v208
	v_and_b32_e32 v208, 0xffff0000, v208
	v_lshlrev_b32_e32 v217, 16, v209
	v_and_b32_e32 v209, 0xffff0000, v209
	v_fmac_f32_e32 v98, s45, v216
	v_fmac_f32_e32 v99, s45, v208
	v_fmac_f32_e32 v100, s45, v217
	v_fmac_f32_e32 v101, s45, v209
	global_store_dwordx4 v[140:141], v[98:101], off offset:0
	s_waitcnt vmcnt(31)
	v_lshlrev_b32_e32 v216, 16, v210
	v_and_b32_e32 v210, 0xffff0000, v210
	v_lshlrev_b32_e32 v217, 16, v211
	v_and_b32_e32 v211, 0xffff0000, v211
	v_fmac_f32_e32 v66, s45, v216
	v_fmac_f32_e32 v67, s45, v210
	v_fmac_f32_e32 v68, s45, v217
	v_fmac_f32_e32 v69, s45, v211
	global_store_dwordx4 v[140:141], v[66:69], off offset:64
	s_waitcnt vmcnt(31)
	v_lshlrev_b32_e32 v216, 16, v212
	v_and_b32_e32 v212, 0xffff0000, v212
	v_lshlrev_b32_e32 v217, 16, v213
	v_and_b32_e32 v213, 0xffff0000, v213
	v_fmac_f32_e32 v34, s45, v216
	v_fmac_f32_e32 v35, s45, v212
	v_fmac_f32_e32 v36, s45, v217
	v_fmac_f32_e32 v37, s45, v213
	global_store_dwordx4 v[140:141], v[34:37], off offset:128
	s_waitcnt vmcnt(31)
	v_lshlrev_b32_e32 v216, 16, v214
	v_and_b32_e32 v214, 0xffff0000, v214
	v_lshlrev_b32_e32 v217, 16, v215
	v_and_b32_e32 v215, 0xffff0000, v215
	v_fmac_f32_e32 v2, s45, v216
	v_fmac_f32_e32 v3, s45, v214
	v_fmac_f32_e32 v4, s45, v217
	v_fmac_f32_e32 v5, s45, v215
	global_store_dwordx4 v[140:141], v[2:5], off offset:192
	s_branch .LBB0_757

; #define LAS __attribute__((address_space(3)))
; DEVI int xcd_first_tile() { return (blockIdx.x & 7) * (gridDim.x >> 3) + (blockIdx.x >> 3); }
;     ...
;   const int lrow = tid >> 2, lpc = tid & 3;
;   const int lch = lpc ^ ((0x78 >> (((lrow >> 2) & 3) * 2)) & 3);
;   const u16* ga = A + (size_t)(m0 + lrow) * lda + kbeg + lch * 8;
;   const u16* gb = Bt + (size_t)(n0 + lrow) * K + kbeg + lch * 8;
;   const size_t ga1 = (size_t)64 * lda, gb1 = (size_t)64 * K;
;   const unsigned lds0 = (unsigned)(uintptr_t)(LAS char*)smem + (unsigned)__builtin_amdgcn_readfirstlane(wid) * 1024u;
;     ...
;   __syncthreads();
;   G2_STAGE(0); G2_STAGE(1);
;   const int fsw = (0x78 >> (((r16 >> 2) & 3) * 2)) & 3;
;   const int aoff = (wm * 128 + r16) * 64 + ((quad ^ fsw) << 4);
;   const int boff = 16384 + (wn * 64 + r16) * 64 + ((quad ^ fsw) << 4);
; DEVI void run_phase(const Params& p, int ph, char* smem) {
;     ...
;     case 0: {
;       const u16* Bt = (const u16*)(p.ws + WS_WIN) + (size_t)l * 2560 * 1024;
;       const int n1 = 66 * 20;
;       const int n2 = (l == 0) ? 16 * 16 : 0;
;       for (int t = xcd_first_tile(); t < n1 + n2; t += xcd_tile_step()) {
;         if (t < n1) { int mt_, nt_; tile_coords(t, 66, 20, mt_, nt_); gemm_tile256<EPI_BF16>(p, xb, 1024, Bt, 1024, mt_ * 256, nt_ * 128, proj, DIN, smem); }
.LBB0_909:
	s_and_b64 vcc, exec, s[2:3]
	s_cbranch_vccz .LBB0_886
	s_lshr_b32 s43, s14, 5
	s_mul_i32 s43, s43, 52
	s_lshr_b32 s43, s43, 8
	s_cmp_lt_u32 s43, 8
	s_cbranch_scc0 .Lt0_rem
	s_mul_i32 s44, s43, 160
	s_sub_i32 s44, s14, s44
	s_lshr_b32 s40, s44, 3
	s_and_b32 s44, s44, 7
	s_lshl_b32 s43, s43, 3
	s_add_i32 s43, s43, s44
	s_branch .Lt0_crd
.Lt0_rem:
	s_sub_i32 s44, s14, 1280
	s_lshr_b32 s40, s44, 1
	s_and_b32 s44, s44, 1
	s_add_i32 s43, s44, 64
.Lt0_crd:
	s_cmp_lt_u32 s43, 64
	s_cselect_b32 s42, 1, 0
	v_readlane_b32 s2, v250, 5
	v_readlane_b32 s3, v250, 6
	v_readlane_b32 s44, v254, 62
	s_mul_i32 s38, s43, 0x80000
	s_add_u32 s8, s2, s38
	s_addc_u32 s9, s3, 0
	s_add_u32 s8, s8, 0x4200000
	s_addc_u32 s9, s9, 0
	s_mul_i32 s38, s44, 0x500000
	s_mul_i32 s39, s40, 0x40000
	s_add_i32 s38, s38, s39
	s_add_u32 s10, s2, s38
	s_addc_u32 s11, s3, 0
	s_add_u32 s10, s10, 0x14a00000
	s_addc_u32 s11, s11, 0
	s_movk_i32 s15, 0x78
	v_lshrrev_b32_e32 v0, 2, v145
	v_and_b32_e32 v131, 3, v145
	v_bfe_u32 v136, v145, 4, 2
	v_lshlrev_b32_e32 v136, 1, v136
	v_lshrrev_b32_e64 v136, v136, s15
	v_and_b32_e32 v136, 3, v136
	v_xor_b32_e32 v131, v131, v136
	v_lshlrev_b32_e32 v131, 4, v131
	s_movk_i32 s39, 0x800
	v_mad_u32_u24 v0, v0, s39, v131
	v_bfe_u32 v137, v145, 2, 1
	s_movk_i32 s39, 0x7c0
	v_mul_u32_u24_e32 v136, s39, v137
	v_sub_u32_e32 v136, v0, v136
	v_mov_b32_e32 v137, 0
	v_lshl_add_u64 v[134:135], s[10:11], 0, v[136:137]
	v_bfe_u32 v137, v145, 2, 1
	s_mul_i32 s39, s42, 0x7c0
	v_mul_u32_u24_e32 v136, s39, v137
	v_sub_u32_e32 v0, v0, v136
	s_lshl_b32 s36, s42, 6
	s_add_i32 s36, s36, 64
	s_mov_b32 s37, 0
	v_lshl_add_u64 v[132:133], s[8:9], 0, v[0:1]
	v_bfe_u32 v136, v145, 2, 2
	v_lshlrev_b32_e32 v136, 1, v136
	v_lshrrev_b32_e64 v136, v136, s15
	v_and_b32_e32 v136, 3, v136
	v_bfe_u32 v137, v145, 4, 2
	v_xor_b32_e32 v136, v136, v137
	v_lshlrev_b32_e32 v136, 4, v136
	v_and_b32_e32 v131, 15, v145
	v_lshl_or_b32 v136, v131, 6, v136
	v_bfe_u32 v137, v145, 6, 1
	v_lshl_or_b32 v137, v137, 12, v136
	v_lshrrev_b32_e32 v0, 7, v145
	v_lshl_or_b32 v136, v0, 13, v136
	v_and_b32_e32 v140, 1, v131
	v_lshl_or_b32 v131, v0, 7, v131
	v_bfe_u32 v0, v145, 4, 2
	v_lshlrev_b32_e32 v0, 3, v0
	v_bfe_u32 v141, v145, 6, 1
	s_mul_i32 s38, s43, 0x140000
	s_lshl_b32 s39, s40, 8
	s_add_i32 s38, s38, s39
	s_add_u32 s10, s2, s38
	s_addc_u32 s11, s3, 0
	s_add_u32 s10, s10, 0x6300000
	s_addc_u32 s11, s11, 0
	s_movk_i32 s39, 5120
	v_mad_u32_u24 v138, v131, s39, v0
	v_lshl_add_u32 v138, v141, 7, v138
	v_mov_b32_e32 v139, 0
	v_lshl_add_u64 v[140:141], s[10:11], 0, v[138:139]
	s_mov_b32 s2, 0x20000
	s_mov_b32 s3, 0
	v_lshrrev_b32_e32 v0, 6, v145
	v_lshlrev_b32_e32 v0, 10, v0
	s_nop 0
	v_readfirstlane_b32 s44, v0
	s_mov_b32 s41, m0
	s_mov_b32 s8, 128
	s_mov_b32 s9, 0
	v_mov_b32_e32 v2, 0
	v_mov_b32_e32 v3, 0
	v_mov_b32_e32 v4, 0
	v_mov_b32_e32 v5, 0
	v_mov_b32_e32 v6, 0
	v_mov_b32_e32 v7, 0
	v_mov_b32_e32 v8, 0
	v_mov_b32_e32 v9, 0
	v_mov_b32_e32 v10, 0
	v_mov_b32_e32 v11, 0
	v_mov_b32_e32 v12, 0
	v_mov_b32_e32 v13, 0
	v_mov_b32_e32 v14, 0
	v_mov_b32_e32 v15, 0
	v_mov_b32_e32 v16, 0
	v_mov_b32_e32 v17, 0
	v_mov_b32_e32 v18, 0
	v_mov_b32_e32 v19, 0
	v_mov_b32_e32 v20, 0
	v_mov_b32_e32 v21, 0
	v_mov_b32_e32 v22, 0
	v_mov_b32_e32 v23, 0
	v_mov_b32_e32 v24, 0
	v_mov_b32_e32 v25, 0
	v_mov_b32_e32 v26, 0
	v_mov_b32_e32 v27, 0
	v_mov_b32_e32 v28, 0
	v_mov_b32_e32 v29, 0
	v_mov_b32_e32 v30, 0
	v_mov_b32_e32 v31, 0
	v_mov_b32_e32 v32, 0
	v_mov_b32_e32 v33, 0
	v_mov_b32_e32 v34, 0
	v_mov_b32_e32 v35, 0
	v_mov_b32_e32 v36, 0
	v_mov_b32_e32 v37, 0
	v_mov_b32_e32 v38, 0
	v_mov_b32_e32 v39, 0
	v_mov_b32_e32 v40, 0
	v_mov_b32_e32 v41, 0
	v_mov_b32_e32 v42, 0
	v_mov_b32_e32 v43, 0
	v_mov_b32_e32 v44, 0
	v_mov_b32_e32 v45, 0
	v_mov_b32_e32 v46, 0
	v_mov_b32_e32 v47, 0
	v_mov_b32_e32 v48, 0
	v_mov_b32_e32 v49, 0
	v_mov_b32_e32 v50, 0
	v_mov_b32_e32 v51, 0
	v_mov_b32_e32 v52, 0
	v_mov_b32_e32 v53, 0
	v_mov_b32_e32 v54, 0
	v_mov_b32_e32 v55, 0
	v_mov_b32_e32 v56, 0
	v_mov_b32_e32 v57, 0
	v_mov_b32_e32 v58, 0
	v_mov_b32_e32 v59, 0
	v_mov_b32_e32 v60, 0
	v_mov_b32_e32 v61, 0
	v_mov_b32_e32 v62, 0
	v_mov_b32_e32 v63, 0
	v_mov_b32_e32 v64, 0
	v_mov_b32_e32 v65, 0
	v_mov_b32_e32 v66, 0
	v_mov_b32_e32 v67, 0
	v_mov_b32_e32 v68, 0
	v_mov_b32_e32 v69, 0
	v_mov_b32_e32 v70, 0
	v_mov_b32_e32 v71, 0
	v_mov_b32_e32 v72, 0
	v_mov_b32_e32 v73, 0
	v_mov_b32_e32 v74, 0
	v_mov_b32_e32 v75, 0
	v_mov_b32_e32 v76, 0
	v_mov_b32_e32 v77, 0
	v_mov_b32_e32 v78, 0
	v_mov_b32_e32 v79, 0
	v_mov_b32_e32 v80, 0
	v_mov_b32_e32 v81, 0
	v_mov_b32_e32 v82, 0
	v_mov_b32_e32 v83, 0
	v_mov_b32_e32 v84, 0
	v_mov_b32_e32 v85, 0
	v_mov_b32_e32 v86, 0
	v_mov_b32_e32 v87, 0
	v_mov_b32_e32 v88, 0
	v_mov_b32_e32 v89, 0
	v_mov_b32_e32 v90, 0
	v_mov_b32_e32 v91, 0
	v_mov_b32_e32 v92, 0
	v_mov_b32_e32 v93, 0
	v_mov_b32_e32 v94, 0
	v_mov_b32_e32 v95, 0
	v_mov_b32_e32 v96, 0
	v_mov_b32_e32 v97, 0
	v_mov_b32_e32 v98, 0
	v_mov_b32_e32 v99, 0
	v_mov_b32_e32 v100, 0
	v_mov_b32_e32 v101, 0
	v_mov_b32_e32 v102, 0
	v_mov_b32_e32 v103, 0
	v_mov_b32_e32 v104, 0
	v_mov_b32_e32 v105, 0
	v_mov_b32_e32 v106, 0
	v_mov_b32_e32 v107, 0
	v_mov_b32_e32 v108, 0
	v_mov_b32_e32 v109, 0
	v_mov_b32_e32 v110, 0
	v_mov_b32_e32 v111, 0
	v_mov_b32_e32 v112, 0
	v_mov_b32_e32 v113, 0
	v_mov_b32_e32 v114, 0
	v_mov_b32_e32 v115, 0
	v_mov_b32_e32 v116, 0
	v_mov_b32_e32 v117, 0
	v_mov_b32_e32 v118, 0
	v_mov_b32_e32 v119, 0
	v_mov_b32_e32 v120, 0
	v_mov_b32_e32 v121, 0
	v_mov_b32_e32 v122, 0
	v_mov_b32_e32 v123, 0
	v_mov_b32_e32 v124, 0
	v_mov_b32_e32 v125, 0
	v_mov_b32_e32 v126, 0
	v_mov_b32_e32 v127, 0
	v_mov_b32_e32 v128, 0
	v_mov_b32_e32 v129, 0
	s_barrier
;     ...
;   __syncthreads();
;   G2_STAGE(0); G2_STAGE(1);
;   const int fsw = (0x78 >> (((r16 >> 2) & 3) * 2)) & 3;
;   const int aoff = (wm * 128 + r16) * 64 + ((quad ^ fsw) << 4);
;   const int boff = 16384 + (wn * 64 + r16) * 64 + ((quad ^ fsw) << 4);
;   for (int kt = 0; kt < nk; kt++) {
;     if (kt + 1 < nk) asm volatile("s_waitcnt vmcnt(6)" ::: "memory");
;     else asm volatile("s_waitcnt vmcnt(0)" ::: "memory");
;     __builtin_amdgcn_s_barrier();
;     asm volatile("" ::: "memory");
;     if (kt + 2 < nk) G2_STAGE(kt + 2);
;     const char* cS = smem + (kt % 3) * 24576;
;     bf16x8 xa[8], wb[4];
; #pragma unroll
;     for (int f = 0; f < 8; f++) xa[f] = *(const bf16x8*)(cS + aoff + f * 1024);
; #pragma unroll
;     for (int f = 0; f < 4; f++) wb[f] = *(const bf16x8*)(cS + boff + f * 1024);
; #pragma unroll
;     for (int nf = 0; nf < 4; nf++)
; #pragma unroll
;       for (int mf = 0; mf < 8; mf++)
;         acc[nf][mf] = __builtin_amdgcn_mfma_f32_16x16x32_bf16(wb[nf], xa[mf], acc[nf][mf], 0, 0, 0);
;   }
	s_add_i32 s40, s44, 0x0
	s_mov_b32 m0, s40
	v_lshl_add_u64 v[142:143], v[132:133], 0, s[2:3]
	global_load_lds_dwordx4 v[132:133], off
	s_addk_i32 m0, 0x1000
	s_nop 0
	global_load_lds_dwordx4 v[142:143], off
	v_lshl_add_u64 v[142:143], v[142:143], 0, s[2:3]
	s_addk_i32 m0, 0x1000
	s_nop 0
	global_load_lds_dwordx4 v[142:143], off
	v_lshl_add_u64 v[142:143], v[142:143], 0, s[2:3]
	s_addk_i32 m0, 0x1000
	s_nop 0
	global_load_lds_dwordx4 v[142:143], off
	s_addk_i32 m0, 0x1000
	v_lshl_add_u64 v[142:143], v[134:135], 0, s[2:3]
	s_nop 0
	global_load_lds_dwordx4 v[134:135], off
	s_addk_i32 m0, 0x1000
	v_lshl_add_u64 v[132:133], v[132:133], 0, s[36:37]
	s_nop 0
	global_load_lds_dwordx4 v[142:143], off
	v_lshl_add_u64 v[134:135], v[134:135], 0, s[8:9]
	s_nop 0
	s_add_i32 s40, s44, 0x6000
	s_mov_b32 m0, s40
	v_lshl_add_u64 v[142:143], v[132:133], 0, s[2:3]
	global_load_lds_dwordx4 v[132:133], off
	s_addk_i32 m0, 0x1000
	s_nop 0
	global_load_lds_dwordx4 v[142:143], off
	v_lshl_add_u64 v[142:143], v[142:143], 0, s[2:3]
	s_addk_i32 m0, 0x1000
	s_nop 0
	global_load_lds_dwordx4 v[142:143], off
	v_lshl_add_u64 v[142:143], v[142:143], 0, s[2:3]
	s_addk_i32 m0, 0x1000
	s_nop 0
	global_load_lds_dwordx4 v[142:143], off
	s_addk_i32 m0, 0x1000
	v_lshl_add_u64 v[142:143], v[134:135], 0, s[2:3]
	s_nop 0
	global_load_lds_dwordx4 v[134:135], off
	s_addk_i32 m0, 0x1000
	v_lshl_add_u64 v[132:133], v[132:133], 0, s[36:37]
	s_nop 0
	global_load_lds_dwordx4 v[142:143], off
	v_lshl_add_u64 v[134:135], v[134:135], 0, s[8:9]
	s_nop 0
	s_add_i32 s40, s44, 0xc000
	s_mov_b32 m0, s40
	v_lshl_add_u64 v[142:143], v[132:133], 0, s[2:3]
	global_load_lds_dwordx4 v[132:133], off
	s_addk_i32 m0, 0x1000
	s_nop 0
	global_load_lds_dwordx4 v[142:143], off
	v_lshl_add_u64 v[142:143], v[142:143], 0, s[2:3]
	s_addk_i32 m0, 0x1000
	s_nop 0
	global_load_lds_dwordx4 v[142:143], off
	v_lshl_add_u64 v[142:143], v[142:143], 0, s[2:3]
	s_addk_i32 m0, 0x1000
	s_nop 0
	global_load_lds_dwordx4 v[142:143], off
	s_addk_i32 m0, 0x1000
	v_lshl_add_u64 v[142:143], v[134:135], 0, s[2:3]
	s_nop 0
	global_load_lds_dwordx4 v[134:135], off
	s_addk_i32 m0, 0x1000
	v_lshl_add_u64 v[132:133], v[132:133], 0, s[36:37]
	s_nop 0
	global_load_lds_dwordx4 v[142:143], off
	v_lshl_add_u64 v[134:135], v[134:135], 0, s[8:9]
	s_nop 0
	s_waitcnt vmcnt(12)
	s_barrier
	ds_read_b128 v[146:149], v136 offset:0
	ds_read_b128 v[152:155], v136 offset:1024
	ds_read_b128 v[156:159], v136 offset:2048
	ds_read_b128 v[162:165], v136 offset:3072
	ds_read_b128 v[166:169], v136 offset:4096
	ds_read_b128 v[170:173], v136 offset:5120
	ds_read_b128 v[176:179], v136 offset:6144
	ds_read_b128 v[180:183], v136 offset:7168
	ds_read_b128 v[184:187], v137 offset:16384
	ds_read_b128 v[188:191], v137 offset:17408
	ds_read_b128 v[192:195], v137 offset:18432
	ds_read_b128 v[196:199], v137 offset:19456
	s_movk_i32 s38, 0x6000
	s_mov_b32 s39, 0
	s_movk_i32 s15, 14
.Lt0_loop:
	s_waitcnt vmcnt(6) lgkmcnt(0)
	s_barrier
	v_add_u32_e32 v144, s38, v136
	v_mfma_f32_16x16x32_bf16 v[126:129], v[184:187], v[146:149], v[126:129]
	ds_read_b128 v[200:203], v144 offset:0
	v_mfma_f32_16x16x32_bf16 v[122:125], v[184:187], v[152:155], v[122:125]
	ds_read_b128 v[204:207], v144 offset:1024
	v_mfma_f32_16x16x32_bf16 v[118:121], v[184:187], v[156:159], v[118:121]
	ds_read_b128 v[208:211], v144 offset:2048
	v_mfma_f32_16x16x32_bf16 v[114:117], v[184:187], v[162:165], v[114:117]
	ds_read_b128 v[212:215], v144 offset:3072
	v_mfma_f32_16x16x32_bf16 v[110:113], v[184:187], v[166:169], v[110:113]
	ds_read_b128 v[216:219], v144 offset:4096
	v_mfma_f32_16x16x32_bf16 v[106:109], v[184:187], v[170:173], v[106:109]
	ds_read_b128 v[220:223], v144 offset:5120
	v_mfma_f32_16x16x32_bf16 v[102:105], v[184:187], v[176:179], v[102:105]
	ds_read_b128 v[224:227], v144 offset:6144
	v_mfma_f32_16x16x32_bf16 v[98:101], v[184:187], v[180:183], v[98:101]
	ds_read_b128 v[228:231], v144 offset:7168
	v_mfma_f32_16x16x32_bf16 v[94:97], v[188:191], v[146:149], v[94:97]
	v_add_u32_e32 v144, s38, v137
	v_mfma_f32_16x16x32_bf16 v[90:93], v[188:191], v[152:155], v[90:93]
	v_mfma_f32_16x16x32_bf16 v[86:89], v[188:191], v[156:159], v[86:89]
	ds_read_b128 v[232:235], v144 offset:16384
	v_mfma_f32_16x16x32_bf16 v[82:85], v[188:191], v[162:165], v[82:85]
	ds_read_b128 v[236:239], v144 offset:17408
	v_mfma_f32_16x16x32_bf16 v[78:81], v[188:191], v[166:169], v[78:81]
	ds_read_b128 v[240:243], v144 offset:18432
	v_mfma_f32_16x16x32_bf16 v[74:77], v[188:191], v[170:173], v[74:77]
	ds_read_b128 v[244:247], v144 offset:19456
	s_add_i32 s40, s44, s39
	v_mfma_f32_16x16x32_bf16 v[70:73], v[188:191], v[176:179], v[70:73]
	s_mov_b32 m0, s40
	v_lshl_add_u64 v[142:143], v[132:133], 0, s[2:3]
	v_mfma_f32_16x16x32_bf16 v[66:69], v[188:191], v[180:183], v[66:69]
	global_load_lds_dwordx4 v[132:133], off
	s_addk_i32 m0, 0x1000
	v_mfma_f32_16x16x32_bf16 v[62:65], v[192:195], v[146:149], v[62:65]
	v_mfma_f32_16x16x32_bf16 v[58:61], v[192:195], v[152:155], v[58:61]
	v_mfma_f32_16x16x32_bf16 v[54:57], v[192:195], v[156:159], v[54:57]
	global_load_lds_dwordx4 v[142:143], off
	v_lshl_add_u64 v[142:143], v[142:143], 0, s[2:3]
	s_addk_i32 m0, 0x1000
	v_mfma_f32_16x16x32_bf16 v[50:53], v[192:195], v[162:165], v[50:53]
	v_mfma_f32_16x16x32_bf16 v[46:49], v[192:195], v[166:169], v[46:49]
	v_mfma_f32_16x16x32_bf16 v[42:45], v[192:195], v[170:173], v[42:45]
	global_load_lds_dwordx4 v[142:143], off
	v_lshl_add_u64 v[142:143], v[142:143], 0, s[2:3]
	s_addk_i32 m0, 0x1000
	v_mfma_f32_16x16x32_bf16 v[38:41], v[192:195], v[176:179], v[38:41]
	v_mfma_f32_16x16x32_bf16 v[34:37], v[192:195], v[180:183], v[34:37]
	v_mfma_f32_16x16x32_bf16 v[30:33], v[196:199], v[146:149], v[30:33]
	global_load_lds_dwordx4 v[142:143], off
	s_addk_i32 m0, 0x1000
	v_lshl_add_u64 v[142:143], v[134:135], 0, s[2:3]
	v_mfma_f32_16x16x32_bf16 v[26:29], v[196:199], v[152:155], v[26:29]
	v_mfma_f32_16x16x32_bf16 v[22:25], v[196:199], v[156:159], v[22:25]
	v_mfma_f32_16x16x32_bf16 v[18:21], v[196:199], v[162:165], v[18:21]
	global_load_lds_dwordx4 v[134:135], off
	s_addk_i32 m0, 0x1000
	v_lshl_add_u64 v[132:133], v[132:133], 0, s[36:37]
	v_mfma_f32_16x16x32_bf16 v[14:17], v[196:199], v[166:169], v[14:17]
	v_mfma_f32_16x16x32_bf16 v[10:13], v[196:199], v[170:173], v[10:13]
	v_mfma_f32_16x16x32_bf16 v[6:9], v[196:199], v[176:179], v[6:9]
	global_load_lds_dwordx4 v[142:143], off
	v_lshl_add_u64 v[134:135], v[134:135], 0, s[8:9]
	v_mfma_f32_16x16x32_bf16 v[2:5], v[196:199], v[180:183], v[2:5]
	s_mov_b32 s39, s38
	s_add_i32 s38, s38, 0x6000
	s_cmp_eq_u32 s38, 0x12000
	s_cselect_b32 s38, 0, s38
	s_waitcnt vmcnt(6) lgkmcnt(0)
	s_barrier
;     ...
;   __syncthreads();
;   G2_STAGE(0); G2_STAGE(1);
;   const int fsw = (0x78 >> (((r16 >> 2) & 3) * 2)) & 3;
;   const int aoff = (wm * 128 + r16) * 64 + ((quad ^ fsw) << 4);
;   const int boff = 16384 + (wn * 64 + r16) * 64 + ((quad ^ fsw) << 4);
;   for (int kt = 0; kt < nk; kt++) {
;     if (kt + 1 < nk) asm volatile("s_waitcnt vmcnt(6)" ::: "memory");
;     else asm volatile("s_waitcnt vmcnt(0)" ::: "memory");
;     __builtin_amdgcn_s_barrier();
;     asm volatile("" ::: "memory");
;     if (kt + 2 < nk) G2_STAGE(kt + 2);
;     const char* cS = smem + (kt % 3) * 24576;
;     bf16x8 xa[8], wb[4];
; #pragma unroll
;     for (int f = 0; f < 8; f++) xa[f] = *(const bf16x8*)(cS + aoff + f * 1024);
; #pragma unroll
;     for (int f = 0; f < 4; f++) wb[f] = *(const bf16x8*)(cS + boff + f * 1024);
; #pragma unroll
;     for (int nf = 0; nf < 4; nf++)
; #pragma unroll
;       for (int mf = 0; mf < 8; mf++)
;         acc[nf][mf] = __builtin_amdgcn_mfma_f32_16x16x32_bf16(wb[nf], xa[mf], acc[nf][mf], 0, 0, 0);
;   }
	v_add_u32_e32 v144, s38, v136
	v_mfma_f32_16x16x32_bf16 v[126:129], v[232:235], v[200:203], v[126:129]
	ds_read_b128 v[146:149], v144 offset:0
	v_mfma_f32_16x16x32_bf16 v[122:125], v[232:235], v[204:207], v[122:125]
	ds_read_b128 v[152:155], v144 offset:1024
	v_mfma_f32_16x16x32_bf16 v[118:121], v[232:235], v[208:211], v[118:121]
	ds_read_b128 v[156:159], v144 offset:2048
	v_mfma_f32_16x16x32_bf16 v[114:117], v[232:235], v[212:215], v[114:117]
	ds_read_b128 v[162:165], v144 offset:3072
	v_mfma_f32_16x16x32_bf16 v[110:113], v[232:235], v[216:219], v[110:113]
	ds_read_b128 v[166:169], v144 offset:4096
	v_mfma_f32_16x16x32_bf16 v[106:109], v[232:235], v[220:223], v[106:109]
	ds_read_b128 v[170:173], v144 offset:5120
	v_mfma_f32_16x16x32_bf16 v[102:105], v[232:235], v[224:227], v[102:105]
	ds_read_b128 v[176:179], v144 offset:6144
	v_mfma_f32_16x16x32_bf16 v[98:101], v[232:235], v[228:231], v[98:101]
	ds_read_b128 v[180:183], v144 offset:7168
	v_mfma_f32_16x16x32_bf16 v[94:97], v[236:239], v[200:203], v[94:97]
	v_add_u32_e32 v144, s38, v137
	v_mfma_f32_16x16x32_bf16 v[90:93], v[236:239], v[204:207], v[90:93]
	v_mfma_f32_16x16x32_bf16 v[86:89], v[236:239], v[208:211], v[86:89]
	ds_read_b128 v[184:187], v144 offset:16384
	v_mfma_f32_16x16x32_bf16 v[82:85], v[236:239], v[212:215], v[82:85]
	ds_read_b128 v[188:191], v144 offset:17408
	v_mfma_f32_16x16x32_bf16 v[78:81], v[236:239], v[216:219], v[78:81]
	ds_read_b128 v[192:195], v144 offset:18432
	v_mfma_f32_16x16x32_bf16 v[74:77], v[236:239], v[220:223], v[74:77]
	ds_read_b128 v[196:199], v144 offset:19456
	s_add_i32 s40, s44, s39
	v_mfma_f32_16x16x32_bf16 v[70:73], v[236:239], v[224:227], v[70:73]
	s_mov_b32 m0, s40
	v_lshl_add_u64 v[142:143], v[132:133], 0, s[2:3]
	v_mfma_f32_16x16x32_bf16 v[66:69], v[236:239], v[228:231], v[66:69]
	global_load_lds_dwordx4 v[132:133], off
	s_addk_i32 m0, 0x1000
	v_mfma_f32_16x16x32_bf16 v[62:65], v[240:243], v[200:203], v[62:65]
	v_mfma_f32_16x16x32_bf16 v[58:61], v[240:243], v[204:207], v[58:61]
	v_mfma_f32_16x16x32_bf16 v[54:57], v[240:243], v[208:211], v[54:57]
	global_load_lds_dwordx4 v[142:143], off
	v_lshl_add_u64 v[142:143], v[142:143], 0, s[2:3]
	s_addk_i32 m0, 0x1000
	v_mfma_f32_16x16x32_bf16 v[50:53], v[240:243], v[212:215], v[50:53]
	v_mfma_f32_16x16x32_bf16 v[46:49], v[240:243], v[216:219], v[46:49]
	v_mfma_f32_16x16x32_bf16 v[42:45], v[240:243], v[220:223], v[42:45]
	global_load_lds_dwordx4 v[142:143], off
	v_lshl_add_u64 v[142:143], v[142:143], 0, s[2:3]
	s_addk_i32 m0, 0x1000
	v_mfma_f32_16x16x32_bf16 v[38:41], v[240:243], v[224:227], v[38:41]
	v_mfma_f32_16x16x32_bf16 v[34:37], v[240:243], v[228:231], v[34:37]
	v_mfma_f32_16x16x32_bf16 v[30:33], v[244:247], v[200:203], v[30:33]
	global_load_lds_dwordx4 v[142:143], off
	s_addk_i32 m0, 0x1000
	v_lshl_add_u64 v[142:143], v[134:135], 0, s[2:3]
	v_mfma_f32_16x16x32_bf16 v[26:29], v[244:247], v[204:207], v[26:29]
	v_mfma_f32_16x16x32_bf16 v[22:25], v[244:247], v[208:211], v[22:25]
	v_mfma_f32_16x16x32_bf16 v[18:21], v[244:247], v[212:215], v[18:21]
	global_load_lds_dwordx4 v[134:135], off
	s_addk_i32 m0, 0x1000
	v_lshl_add_u64 v[132:133], v[132:133], 0, s[36:37]
	v_mfma_f32_16x16x32_bf16 v[14:17], v[244:247], v[216:219], v[14:17]
	v_mfma_f32_16x16x32_bf16 v[10:13], v[244:247], v[220:223], v[10:13]
	v_mfma_f32_16x16x32_bf16 v[6:9], v[244:247], v[224:227], v[6:9]
	global_load_lds_dwordx4 v[142:143], off
	v_lshl_add_u64 v[134:135], v[134:135], 0, s[8:9]
	v_mfma_f32_16x16x32_bf16 v[2:5], v[244:247], v[228:231], v[2:5]
	s_mov_b32 s39, s38
	s_add_i32 s38, s38, 0x6000
	s_cmp_eq_u32 s38, 0x12000
	s_cselect_b32 s38, 0, s38
	s_sub_i32 s15, s15, 1
	s_cmp_lg_u32 s15, 0
	s_cbranch_scc1 .Lt0_loop
	s_waitcnt vmcnt(6) lgkmcnt(0)
	s_barrier
	v_add_u32_e32 v144, s38, v136
	v_mfma_f32_16x16x32_bf16 v[126:129], v[184:187], v[146:149], v[126:129]
	ds_read_b128 v[200:203], v144 offset:0
	v_mfma_f32_16x16x32_bf16 v[122:125], v[184:187], v[152:155], v[122:125]
	ds_read_b128 v[204:207], v144 offset:1024
	v_mfma_f32_16x16x32_bf16 v[118:121], v[184:187], v[156:159], v[118:121]
	ds_read_b128 v[208:211], v144 offset:2048
	v_mfma_f32_16x16x32_bf16 v[114:117], v[184:187], v[162:165], v[114:117]
	ds_read_b128 v[212:215], v144 offset:3072
	v_mfma_f32_16x16x32_bf16 v[110:113], v[184:187], v[166:169], v[110:113]
	ds_read_b128 v[216:219], v144 offset:4096
	v_mfma_f32_16x16x32_bf16 v[106:109], v[184:187], v[170:173], v[106:109]
	ds_read_b128 v[220:223], v144 offset:5120
	v_mfma_f32_16x16x32_bf16 v[102:105], v[184:187], v[176:179], v[102:105]
	ds_read_b128 v[224:227], v144 offset:6144
	v_mfma_f32_16x16x32_bf16 v[98:101], v[184:187], v[180:183], v[98:101]
	ds_read_b128 v[228:231], v144 offset:7168
	v_mfma_f32_16x16x32_bf16 v[94:97], v[188:191], v[146:149], v[94:97]
	v_add_u32_e32 v144, s38, v137
	v_mfma_f32_16x16x32_bf16 v[90:93], v[188:191], v[152:155], v[90:93]
	v_mfma_f32_16x16x32_bf16 v[86:89], v[188:191], v[156:159], v[86:89]
	ds_read_b128 v[232:235], v144 offset:16384
	v_mfma_f32_16x16x32_bf16 v[82:85], v[188:191], v[162:165], v[82:85]
	ds_read_b128 v[236:239], v144 offset:17408
	v_mfma_f32_16x16x32_bf16 v[78:81], v[188:191], v[166:169], v[78:81]
	ds_read_b128 v[240:243], v144 offset:18432
	v_mfma_f32_16x16x32_bf16 v[74:77], v[188:191], v[170:173], v[74:77]
	ds_read_b128 v[244:247], v144 offset:19456
	s_add_i32 s40, s44, s39
	v_mfma_f32_16x16x32_bf16 v[70:73], v[188:191], v[176:179], v[70:73]
	s_mov_b32 m0, s40
	v_lshl_add_u64 v[142:143], v[132:133], 0, s[2:3]
	v_mfma_f32_16x16x32_bf16 v[66:69], v[188:191], v[180:183], v[66:69]
	global_load_lds_dwordx4 v[132:133], off
	s_addk_i32 m0, 0x1000
	v_mfma_f32_16x16x32_bf16 v[62:65], v[192:195], v[146:149], v[62:65]
;     ...
;   for (int kt = 0; kt < nk; kt++) {
;     if (kt + 1 < nk) asm volatile("s_waitcnt vmcnt(6)" ::: "memory");
;     else asm volatile("s_waitcnt vmcnt(0)" ::: "memory");
;     __builtin_amdgcn_s_barrier();
;     asm volatile("" ::: "memory");
;     if (kt + 2 < nk) G2_STAGE(kt + 2);
;     const char* cS = smem + (kt % 3) * 24576;
;     bf16x8 xa[8], wb[4];
; #pragma unroll
;     for (int f = 0; f < 8; f++) xa[f] = *(const bf16x8*)(cS + aoff + f * 1024);
; #pragma unroll
;     for (int f = 0; f < 4; f++) wb[f] = *(const bf16x8*)(cS + boff + f * 1024);
; #pragma unroll
;     for (int nf = 0; nf < 4; nf++)
; #pragma unroll
;       for (int mf = 0; mf < 8; mf++)
;         acc[nf][mf] = __builtin_amdgcn_mfma_f32_16x16x32_bf16(wb[nf], xa[mf], acc[nf][mf], 0, 0, 0);
;   }
	v_mfma_f32_16x16x32_bf16 v[58:61], v[192:195], v[152:155], v[58:61]
	v_mfma_f32_16x16x32_bf16 v[54:57], v[192:195], v[156:159], v[54:57]
	global_load_lds_dwordx4 v[142:143], off
	v_lshl_add_u64 v[142:143], v[142:143], 0, s[2:3]
	s_addk_i32 m0, 0x1000
	v_mfma_f32_16x16x32_bf16 v[50:53], v[192:195], v[162:165], v[50:53]
	v_mfma_f32_16x16x32_bf16 v[46:49], v[192:195], v[166:169], v[46:49]
	v_mfma_f32_16x16x32_bf16 v[42:45], v[192:195], v[170:173], v[42:45]
	global_load_lds_dwordx4 v[142:143], off
	v_lshl_add_u64 v[142:143], v[142:143], 0, s[2:3]
	s_addk_i32 m0, 0x1000
	v_mfma_f32_16x16x32_bf16 v[38:41], v[192:195], v[176:179], v[38:41]
	v_mfma_f32_16x16x32_bf16 v[34:37], v[192:195], v[180:183], v[34:37]
	v_mfma_f32_16x16x32_bf16 v[30:33], v[196:199], v[146:149], v[30:33]
	global_load_lds_dwordx4 v[142:143], off
	s_addk_i32 m0, 0x1000
	v_lshl_add_u64 v[142:143], v[134:135], 0, s[2:3]
	v_mfma_f32_16x16x32_bf16 v[26:29], v[196:199], v[152:155], v[26:29]
	v_mfma_f32_16x16x32_bf16 v[22:25], v[196:199], v[156:159], v[22:25]
	v_mfma_f32_16x16x32_bf16 v[18:21], v[196:199], v[162:165], v[18:21]
	global_load_lds_dwordx4 v[134:135], off
	s_addk_i32 m0, 0x1000
	v_lshl_add_u64 v[132:133], v[132:133], 0, s[36:37]
	v_mfma_f32_16x16x32_bf16 v[14:17], v[196:199], v[166:169], v[14:17]
	v_mfma_f32_16x16x32_bf16 v[10:13], v[196:199], v[170:173], v[10:13]
	v_mfma_f32_16x16x32_bf16 v[6:9], v[196:199], v[176:179], v[6:9]
	global_load_lds_dwordx4 v[142:143], off
	v_lshl_add_u64 v[134:135], v[134:135], 0, s[8:9]
	v_mfma_f32_16x16x32_bf16 v[2:5], v[196:199], v[180:183], v[2:5]
	s_mov_b32 s39, s38
	s_add_i32 s38, s38, 0x6000
	s_cmp_eq_u32 s38, 0x12000
	s_cselect_b32 s38, 0, s38
	s_waitcnt vmcnt(6) lgkmcnt(0)
	s_barrier
	v_add_u32_e32 v144, s38, v136
	v_mfma_f32_16x16x32_bf16 v[126:129], v[232:235], v[200:203], v[126:129]
	ds_read_b128 v[146:149], v144 offset:0
	v_mfma_f32_16x16x32_bf16 v[122:125], v[232:235], v[204:207], v[122:125]
	ds_read_b128 v[152:155], v144 offset:1024
	v_mfma_f32_16x16x32_bf16 v[118:121], v[232:235], v[208:211], v[118:121]
	ds_read_b128 v[156:159], v144 offset:2048
	v_mfma_f32_16x16x32_bf16 v[114:117], v[232:235], v[212:215], v[114:117]
	ds_read_b128 v[162:165], v144 offset:3072
	v_mfma_f32_16x16x32_bf16 v[110:113], v[232:235], v[216:219], v[110:113]
	ds_read_b128 v[166:169], v144 offset:4096
	v_mfma_f32_16x16x32_bf16 v[106:109], v[232:235], v[220:223], v[106:109]
	ds_read_b128 v[170:173], v144 offset:5120
	v_mfma_f32_16x16x32_bf16 v[102:105], v[232:235], v[224:227], v[102:105]
	ds_read_b128 v[176:179], v144 offset:6144
	v_mfma_f32_16x16x32_bf16 v[98:101], v[232:235], v[228:231], v[98:101]
	ds_read_b128 v[180:183], v144 offset:7168
	v_mfma_f32_16x16x32_bf16 v[94:97], v[236:239], v[200:203], v[94:97]
	v_add_u32_e32 v144, s38, v137
	v_mfma_f32_16x16x32_bf16 v[90:93], v[236:239], v[204:207], v[90:93]
	v_mfma_f32_16x16x32_bf16 v[86:89], v[236:239], v[208:211], v[86:89]
	ds_read_b128 v[184:187], v144 offset:16384
	v_mfma_f32_16x16x32_bf16 v[82:85], v[236:239], v[212:215], v[82:85]
	ds_read_b128 v[188:191], v144 offset:17408
	v_mfma_f32_16x16x32_bf16 v[78:81], v[236:239], v[216:219], v[78:81]
	ds_read_b128 v[192:195], v144 offset:18432
	v_mfma_f32_16x16x32_bf16 v[74:77], v[236:239], v[220:223], v[74:77]
	ds_read_b128 v[196:199], v144 offset:19456
	v_mfma_f32_16x16x32_bf16 v[70:73], v[236:239], v[224:227], v[70:73]
	v_mfma_f32_16x16x32_bf16 v[66:69], v[236:239], v[228:231], v[66:69]
	v_mfma_f32_16x16x32_bf16 v[62:65], v[240:243], v[200:203], v[62:65]
	v_mfma_f32_16x16x32_bf16 v[58:61], v[240:243], v[204:207], v[58:61]
	v_mfma_f32_16x16x32_bf16 v[54:57], v[240:243], v[208:211], v[54:57]
	v_mfma_f32_16x16x32_bf16 v[50:53], v[240:243], v[212:215], v[50:53]
	v_mfma_f32_16x16x32_bf16 v[46:49], v[240:243], v[216:219], v[46:49]
	v_mfma_f32_16x16x32_bf16 v[42:45], v[240:243], v[220:223], v[42:45]
	v_mfma_f32_16x16x32_bf16 v[38:41], v[240:243], v[224:227], v[38:41]
	v_mfma_f32_16x16x32_bf16 v[34:37], v[240:243], v[228:231], v[34:37]
	v_mfma_f32_16x16x32_bf16 v[30:33], v[244:247], v[200:203], v[30:33]
	v_mfma_f32_16x16x32_bf16 v[26:29], v[244:247], v[204:207], v[26:29]
	v_mfma_f32_16x16x32_bf16 v[22:25], v[244:247], v[208:211], v[22:25]
	v_mfma_f32_16x16x32_bf16 v[18:21], v[244:247], v[212:215], v[18:21]
	v_mfma_f32_16x16x32_bf16 v[14:17], v[244:247], v[216:219], v[14:17]
	v_mfma_f32_16x16x32_bf16 v[10:13], v[244:247], v[220:223], v[10:13]
	v_mfma_f32_16x16x32_bf16 v[6:9], v[244:247], v[224:227], v[6:9]
	v_mfma_f32_16x16x32_bf16 v[2:5], v[244:247], v[228:231], v[2:5]
	s_mov_b32 s39, s38
	s_add_i32 s38, s38, 0x6000
	s_cmp_eq_u32 s38, 0x12000
	s_cselect_b32 s38, 0, s38
	s_waitcnt vmcnt(0) lgkmcnt(0)
	s_barrier
;     ...
;   for (int kt = 0; kt < nk; kt++) {
;     if (kt + 1 < nk) asm volatile("s_waitcnt vmcnt(6)" ::: "memory");
;     else asm volatile("s_waitcnt vmcnt(0)" ::: "memory");
;     __builtin_amdgcn_s_barrier();
;     asm volatile("" ::: "memory");
;     if (kt + 2 < nk) G2_STAGE(kt + 2);
;     const char* cS = smem + (kt % 3) * 24576;
;     bf16x8 xa[8], wb[4];
; #pragma unroll
;     for (int f = 0; f < 8; f++) xa[f] = *(const bf16x8*)(cS + aoff + f * 1024);
; #pragma unroll
;     for (int f = 0; f < 4; f++) wb[f] = *(const bf16x8*)(cS + boff + f * 1024);
; #pragma unroll
;     for (int nf = 0; nf < 4; nf++)
; #pragma unroll
;       for (int mf = 0; mf < 8; mf++)
;         acc[nf][mf] = __builtin_amdgcn_mfma_f32_16x16x32_bf16(wb[nf], xa[mf], acc[nf][mf], 0, 0, 0);
;   }
	v_add_u32_e32 v144, s38, v136
	v_mfma_f32_16x16x32_bf16 v[126:129], v[184:187], v[146:149], v[126:129]
	ds_read_b128 v[200:203], v144 offset:0
	v_mfma_f32_16x16x32_bf16 v[122:125], v[184:187], v[152:155], v[122:125]
	ds_read_b128 v[204:207], v144 offset:1024
	v_mfma_f32_16x16x32_bf16 v[118:121], v[184:187], v[156:159], v[118:121]
	ds_read_b128 v[208:211], v144 offset:2048
	v_mfma_f32_16x16x32_bf16 v[114:117], v[184:187], v[162:165], v[114:117]
	ds_read_b128 v[212:215], v144 offset:3072
	v_mfma_f32_16x16x32_bf16 v[110:113], v[184:187], v[166:169], v[110:113]
	ds_read_b128 v[216:219], v144 offset:4096
	v_mfma_f32_16x16x32_bf16 v[106:109], v[184:187], v[170:173], v[106:109]
	ds_read_b128 v[220:223], v144 offset:5120
	v_mfma_f32_16x16x32_bf16 v[102:105], v[184:187], v[176:179], v[102:105]
	ds_read_b128 v[224:227], v144 offset:6144
	v_mfma_f32_16x16x32_bf16 v[98:101], v[184:187], v[180:183], v[98:101]
	ds_read_b128 v[228:231], v144 offset:7168
	v_mfma_f32_16x16x32_bf16 v[94:97], v[188:191], v[146:149], v[94:97]
	v_add_u32_e32 v144, s38, v137
	v_mfma_f32_16x16x32_bf16 v[90:93], v[188:191], v[152:155], v[90:93]
	v_mfma_f32_16x16x32_bf16 v[86:89], v[188:191], v[156:159], v[86:89]
	ds_read_b128 v[232:235], v144 offset:16384
	v_mfma_f32_16x16x32_bf16 v[82:85], v[188:191], v[162:165], v[82:85]
	ds_read_b128 v[236:239], v144 offset:17408
	v_mfma_f32_16x16x32_bf16 v[78:81], v[188:191], v[166:169], v[78:81]
	ds_read_b128 v[240:243], v144 offset:18432
	v_mfma_f32_16x16x32_bf16 v[74:77], v[188:191], v[170:173], v[74:77]
	ds_read_b128 v[244:247], v144 offset:19456
	v_mfma_f32_16x16x32_bf16 v[70:73], v[188:191], v[176:179], v[70:73]
	v_mfma_f32_16x16x32_bf16 v[66:69], v[188:191], v[180:183], v[66:69]
	v_mfma_f32_16x16x32_bf16 v[62:65], v[192:195], v[146:149], v[62:65]
	v_mfma_f32_16x16x32_bf16 v[58:61], v[192:195], v[152:155], v[58:61]
	v_mfma_f32_16x16x32_bf16 v[54:57], v[192:195], v[156:159], v[54:57]
	v_mfma_f32_16x16x32_bf16 v[50:53], v[192:195], v[162:165], v[50:53]
	v_mfma_f32_16x16x32_bf16 v[46:49], v[192:195], v[166:169], v[46:49]
	v_mfma_f32_16x16x32_bf16 v[42:45], v[192:195], v[170:173], v[42:45]
	v_mfma_f32_16x16x32_bf16 v[38:41], v[192:195], v[176:179], v[38:41]
	v_mfma_f32_16x16x32_bf16 v[34:37], v[192:195], v[180:183], v[34:37]
	v_mfma_f32_16x16x32_bf16 v[30:33], v[196:199], v[146:149], v[30:33]
	v_mfma_f32_16x16x32_bf16 v[26:29], v[196:199], v[152:155], v[26:29]
	v_mfma_f32_16x16x32_bf16 v[22:25], v[196:199], v[156:159], v[22:25]
	v_mfma_f32_16x16x32_bf16 v[18:21], v[196:199], v[162:165], v[18:21]
	v_mfma_f32_16x16x32_bf16 v[14:17], v[196:199], v[166:169], v[14:17]
	v_mfma_f32_16x16x32_bf16 v[10:13], v[196:199], v[170:173], v[10:13]
	v_mfma_f32_16x16x32_bf16 v[6:9], v[196:199], v[176:179], v[6:9]
	v_mfma_f32_16x16x32_bf16 v[2:5], v[196:199], v[180:183], v[2:5]
	s_mov_b32 s39, s38
	s_add_i32 s38, s38, 0x6000
	s_cmp_eq_u32 s38, 0x12000
	s_cselect_b32 s38, 0, s38
	s_waitcnt lgkmcnt(0)
; DEVI unsigned pack2(float a, float b) { return __builtin_bit_cast(unsigned, __builtin_convertvector((f32x2_t){a, b}, bf16x2_t)); }
;     ...
;   for (int kt = 0; kt < nk; kt++) {
;     if (kt + 1 < nk) asm volatile("s_waitcnt vmcnt(6)" ::: "memory");
;     else asm volatile("s_waitcnt vmcnt(0)" ::: "memory");
;     __builtin_amdgcn_s_barrier();
;     asm volatile("" ::: "memory");
;     if (kt + 2 < nk) G2_STAGE(kt + 2);
;     const char* cS = smem + (kt % 3) * 24576;
;     bf16x8 xa[8], wb[4];
; #pragma unroll
;     for (int f = 0; f < 8; f++) xa[f] = *(const bf16x8*)(cS + aoff + f * 1024);
; #pragma unroll
;     for (int f = 0; f < 4; f++) wb[f] = *(const bf16x8*)(cS + boff + f * 1024);
; #pragma unroll
;     for (int nf = 0; nf < 4; nf++)
; #pragma unroll
;       for (int mf = 0; mf < 8; mf++)
;         acc[nf][mf] = __builtin_amdgcn_mfma_f32_16x16x32_bf16(wb[nf], xa[mf], acc[nf][mf], 0, 0, 0);
;   }
;     ...
; #pragma unroll
;   for (int mf = 0; mf < 8; mf++) {
;     const int row = m0 + wm * 128 + mf * 16 + r16;
;     if (EPI == EPI_SWIGLU) {
; #pragma unroll
;       for (int nf = 0; nf < 2; nf++) {
;         const int hcol = (n0 >> 1) + wn * 32 + nf * 16 + quad * 4;
;         f32x4 g = acc[nf][mf], u = acc[nf + 2][mf];
;         u32x2 pk;
;         pk[0] = pack2(siluf_(g[0]) * u[0], siluf_(g[1]) * u[1]);
;         pk[1] = pack2(siluf_(g[2]) * u[2], siluf_(g[3]) * u[3]);
;         *(u32x2*)(outb + (size_t)row * DFF + hcol) = pk;
;       }
;     } else {
; #pragma unroll
;       for (int nf = 0; nf < 4; nf++) {
;         const int col = n0 + wn * 64 + nf * 16 + quad * 4;
;         f32x4 a = acc[nf][mf];
;         if (EPI == EPI_RESID || EPI == EPI_RESID_ATOMIC) {
;           f32x4 x = a;
;           if (EPI == EPI_RESID || kpart == 0) {
;             const u32x2 xr = *(const u32x2*)((const u16*)(p.ws + WS_XB) + (size_t)row * 1024 + col);
;             x[0] += ALPHA * blo(xr[0]); x[1] += ALPHA * bhi(xr[0]); x[2] += ALPHA * blo(xr[1]); x[3] += ALPHA * bhi(xr[1]);
;           }
;           if (EPI == EPI_RESID) *(f32x4*)((float*)(p.ws + WS_XF) + (size_t)row * 1024 + col) = x;
;           else *(f32x4*)((float*)(p.ws + WS_SLAB) + ((size_t)kpart * 512 + (row - T_P)) * 1024 + col) = x;
;         } else {
;           u32x2 pk; pk[0] = pack2(a[0], a[1]); pk[1] = pack2(a[2], a[3]);
;           *(u32x2*)(outb + (size_t)row * ldc + col) = pk;
	v_mfma_f32_16x16x32_bf16 v[126:129], v[232:235], v[200:203], v[126:129]
	v_mfma_f32_16x16x32_bf16 v[122:125], v[232:235], v[204:207], v[122:125]
	v_mfma_f32_16x16x32_bf16 v[118:121], v[232:235], v[208:211], v[118:121]
	v_mfma_f32_16x16x32_bf16 v[114:117], v[232:235], v[212:215], v[114:117]
	v_mfma_f32_16x16x32_bf16 v[110:113], v[232:235], v[216:219], v[110:113]
	v_mfma_f32_16x16x32_bf16 v[106:109], v[232:235], v[220:223], v[106:109]
	v_mfma_f32_16x16x32_bf16 v[102:105], v[232:235], v[224:227], v[102:105]
	v_mfma_f32_16x16x32_bf16 v[98:101], v[232:235], v[228:231], v[98:101]
	v_mfma_f32_16x16x32_bf16 v[94:97], v[236:239], v[200:203], v[94:97]
	v_mfma_f32_16x16x32_bf16 v[90:93], v[236:239], v[204:207], v[90:93]
	v_mfma_f32_16x16x32_bf16 v[86:89], v[236:239], v[208:211], v[86:89]
	v_mfma_f32_16x16x32_bf16 v[82:85], v[236:239], v[212:215], v[82:85]
	v_mfma_f32_16x16x32_bf16 v[78:81], v[236:239], v[216:219], v[78:81]
	v_mfma_f32_16x16x32_bf16 v[74:77], v[236:239], v[220:223], v[74:77]
	v_mfma_f32_16x16x32_bf16 v[70:73], v[236:239], v[224:227], v[70:73]
	v_mfma_f32_16x16x32_bf16 v[66:69], v[236:239], v[228:231], v[66:69]
	v_mfma_f32_16x16x32_bf16 v[62:65], v[240:243], v[200:203], v[62:65]
	v_mfma_f32_16x16x32_bf16 v[58:61], v[240:243], v[204:207], v[58:61]
	v_mfma_f32_16x16x32_bf16 v[54:57], v[240:243], v[208:211], v[54:57]
	v_mfma_f32_16x16x32_bf16 v[50:53], v[240:243], v[212:215], v[50:53]
	v_mfma_f32_16x16x32_bf16 v[46:49], v[240:243], v[216:219], v[46:49]
	v_mfma_f32_16x16x32_bf16 v[42:45], v[240:243], v[220:223], v[42:45]
	v_mfma_f32_16x16x32_bf16 v[38:41], v[240:243], v[224:227], v[38:41]
	v_mfma_f32_16x16x32_bf16 v[34:37], v[240:243], v[228:231], v[34:37]
	v_mfma_f32_16x16x32_bf16 v[30:33], v[244:247], v[200:203], v[30:33]
	v_mfma_f32_16x16x32_bf16 v[26:29], v[244:247], v[204:207], v[26:29]
	v_mfma_f32_16x16x32_bf16 v[22:25], v[244:247], v[208:211], v[22:25]
	v_mfma_f32_16x16x32_bf16 v[18:21], v[244:247], v[212:215], v[18:21]
	v_mfma_f32_16x16x32_bf16 v[14:17], v[244:247], v[216:219], v[14:17]
	v_mfma_f32_16x16x32_bf16 v[10:13], v[244:247], v[220:223], v[10:13]
	v_mfma_f32_16x16x32_bf16 v[6:9], v[244:247], v[224:227], v[6:9]
	v_mfma_f32_16x16x32_bf16 v[2:5], v[244:247], v[228:231], v[2:5]
	s_mov_b32 m0, s41
	s_mov_b32 s8, 0x14000
	s_mov_b32 s9, 0
	s_nop 7
	v_cvt_pk_bf16_f32 v126, v126, v127
	v_cvt_pk_bf16_f32 v127, v128, v129
	global_store_dwordx2 v[140:141], v[126:127], off offset:0
	v_cvt_pk_bf16_f32 v94, v94, v95
	v_cvt_pk_bf16_f32 v95, v96, v97
	global_store_dwordx2 v[140:141], v[94:95], off offset:32
	v_cvt_pk_bf16_f32 v62, v62, v63
	v_cvt_pk_bf16_f32 v63, v64, v65
	global_store_dwordx2 v[140:141], v[62:63], off offset:64
	v_cvt_pk_bf16_f32 v30, v30, v31
	v_cvt_pk_bf16_f32 v31, v32, v33
	global_store_dwordx2 v[140:141], v[30:31], off offset:96
	v_lshl_add_u64 v[140:141], v[140:141], 0, s[8:9]
	v_cvt_pk_bf16_f32 v122, v122, v123
	v_cvt_pk_bf16_f32 v123, v124, v125
	global_store_dwordx2 v[140:141], v[122:123], off offset:0
	v_cvt_pk_bf16_f32 v90, v90, v91
	v_cvt_pk_bf16_f32 v91, v92, v93
	global_store_dwordx2 v[140:141], v[90:91], off offset:32
	v_cvt_pk_bf16_f32 v58, v58, v59
	v_cvt_pk_bf16_f32 v59, v60, v61
	global_store_dwordx2 v[140:141], v[58:59], off offset:64
	v_cvt_pk_bf16_f32 v26, v26, v27
	v_cvt_pk_bf16_f32 v27, v28, v29
	global_store_dwordx2 v[140:141], v[26:27], off offset:96
	v_lshl_add_u64 v[140:141], v[140:141], 0, s[8:9]
	v_cvt_pk_bf16_f32 v118, v118, v119
	v_cvt_pk_bf16_f32 v119, v120, v121
	global_store_dwordx2 v[140:141], v[118:119], off offset:0
	v_cvt_pk_bf16_f32 v86, v86, v87
	v_cvt_pk_bf16_f32 v87, v88, v89
	global_store_dwordx2 v[140:141], v[86:87], off offset:32
	v_cvt_pk_bf16_f32 v54, v54, v55
	v_cvt_pk_bf16_f32 v55, v56, v57
	global_store_dwordx2 v[140:141], v[54:55], off offset:64
	v_cvt_pk_bf16_f32 v22, v22, v23
	v_cvt_pk_bf16_f32 v23, v24, v25
	global_store_dwordx2 v[140:141], v[22:23], off offset:96
	v_lshl_add_u64 v[140:141], v[140:141], 0, s[8:9]
	v_cvt_pk_bf16_f32 v114, v114, v115
	v_cvt_pk_bf16_f32 v115, v116, v117
	global_store_dwordx2 v[140:141], v[114:115], off offset:0
	v_cvt_pk_bf16_f32 v82, v82, v83
	v_cvt_pk_bf16_f32 v83, v84, v85
	global_store_dwordx2 v[140:141], v[82:83], off offset:32
	v_cvt_pk_bf16_f32 v50, v50, v51
	v_cvt_pk_bf16_f32 v51, v52, v53
	global_store_dwordx2 v[140:141], v[50:51], off offset:64
	v_cvt_pk_bf16_f32 v18, v18, v19
	v_cvt_pk_bf16_f32 v19, v20, v21
	global_store_dwordx2 v[140:141], v[18:19], off offset:96
	v_lshl_add_u64 v[140:141], v[140:141], 0, s[8:9]
	v_cvt_pk_bf16_f32 v110, v110, v111
	v_cvt_pk_bf16_f32 v111, v112, v113
	global_store_dwordx2 v[140:141], v[110:111], off offset:0
	v_cvt_pk_bf16_f32 v78, v78, v79
	v_cvt_pk_bf16_f32 v79, v80, v81
	global_store_dwordx2 v[140:141], v[78:79], off offset:32
	v_cvt_pk_bf16_f32 v46, v46, v47
	v_cvt_pk_bf16_f32 v47, v48, v49
	global_store_dwordx2 v[140:141], v[46:47], off offset:64
	v_cvt_pk_bf16_f32 v14, v14, v15
	v_cvt_pk_bf16_f32 v15, v16, v17
	global_store_dwordx2 v[140:141], v[14:15], off offset:96
	v_lshl_add_u64 v[140:141], v[140:141], 0, s[8:9]
	v_cvt_pk_bf16_f32 v106, v106, v107
	v_cvt_pk_bf16_f32 v107, v108, v109
	global_store_dwordx2 v[140:141], v[106:107], off offset:0
	v_cvt_pk_bf16_f32 v74, v74, v75
	v_cvt_pk_bf16_f32 v75, v76, v77
	global_store_dwordx2 v[140:141], v[74:75], off offset:32
	v_cvt_pk_bf16_f32 v42, v42, v43
	v_cvt_pk_bf16_f32 v43, v44, v45
	global_store_dwordx2 v[140:141], v[42:43], off offset:64
	v_cvt_pk_bf16_f32 v10, v10, v11
	v_cvt_pk_bf16_f32 v11, v12, v13
	global_store_dwordx2 v[140:141], v[10:11], off offset:96
	v_lshl_add_u64 v[140:141], v[140:141], 0, s[8:9]
	v_cvt_pk_bf16_f32 v102, v102, v103
	v_cvt_pk_bf16_f32 v103, v104, v105
	global_store_dwordx2 v[140:141], v[102:103], off offset:0
	v_cvt_pk_bf16_f32 v70, v70, v71
	v_cvt_pk_bf16_f32 v71, v72, v73
	global_store_dwordx2 v[140:141], v[70:71], off offset:32
	v_cvt_pk_bf16_f32 v38, v38, v39
	v_cvt_pk_bf16_f32 v39, v40, v41
	global_store_dwordx2 v[140:141], v[38:39], off offset:64
	v_cvt_pk_bf16_f32 v6, v6, v7
	v_cvt_pk_bf16_f32 v7, v8, v9
	global_store_dwordx2 v[140:141], v[6:7], off offset:96
	v_lshl_add_u64 v[140:141], v[140:141], 0, s[8:9]
	v_cvt_pk_bf16_f32 v98, v98, v99
	v_cvt_pk_bf16_f32 v99, v100, v101
	global_store_dwordx2 v[140:141], v[98:99], off offset:0
	v_cvt_pk_bf16_f32 v66, v66, v67
	v_cvt_pk_bf16_f32 v67, v68, v69
	global_store_dwordx2 v[140:141], v[66:67], off offset:32
	v_cvt_pk_bf16_f32 v34, v34, v35
	v_cvt_pk_bf16_f32 v35, v36, v37
	global_store_dwordx2 v[140:141], v[34:35], off offset:64
	v_cvt_pk_bf16_f32 v2, v2, v3
	v_cvt_pk_bf16_f32 v3, v4, v5
	global_store_dwordx2 v[140:141], v[2:3], off offset:96
	s_branch .LBB0_886

; DEVI unsigned pack2(float a, float b) { return __builtin_bit_cast(unsigned, __builtin_convertvector((f32x2_t){a, b}, bf16x2_t)); }
; DEVI void stnt4(float* p_, f32x4 v) { __builtin_nontemporal_store(v, (f32x4*)p_); }
;     ...
;     float s = 0.f, q = 0.f;
; #pragma unroll
;     for (int i = 0; i < 4; i++) {
;       s += v[i].x + v[i].y + v[i].z + v[i].w;
;       q += v[i].x * v[i].x + v[i].y * v[i].y + v[i].z * v[i].z + v[i].w * v[i].w;
;     }
; #pragma unroll
;     for (int o = 32; o > 0; o >>= 1) { const float s2 = __shfl_xor(s, o), q2 = __shfl_xor(q, o); s += s2; q += q2; }
;     const float mu = s * (1.f / 1024.f);
;     const float var = fmaxf(q * (1.f / 1024.f) - mu * mu, 0.f);
;     const float rs = rsqrtf(var + 1e-5f);
; #pragma unroll
;     for (int i = 0; i < 4; i++) {
;       float4 o;
;       o.x = (v[i].x - mu) * rs * gg[i].x + bb[i].x; o.y = (v[i].y - mu) * rs * gg[i].y + bb[i].y;
;       o.z = (v[i].z - mu) * rs * gg[i].z + bb[i].z; o.w = (v[i].w - mu) * rs * gg[i].w + bb[i].w;
;       uint2 pk; pk.x = pack2(o.x, o.y); pk.y = pack2(o.z, o.w);
;       if (mode != 2) ((uint2*)(xb + (size_t)r * 1024))[lane + 64 * i] = pk;
;       if (mode == 2) stnt4(p.out + O_Y + (size_t)r * 1024 + (size_t)(lane + 64 * i) * 4, (f32x4){o.x, o.y, o.z, o.w});
;     }
; #pragma unroll
;     for (int i = 0; i < 4; i++) v[i] = vn[i];
.LBB0_1892:
	s_or_b64 exec, exec, s[8:9]
	v_lshrrev_b32_e32 v118, 14, v66
	v_xor_b32_e32 v118, 1, v118
	v_and_b32_e32 v119, 1, v66
	v_mul_u32_u24_e32 v119, 0x7c0, v119
	v_bfe_u32 v110, v145, 3, 3
	v_lshlrev_b32_e32 v110, 6, v110
	v_sub_u32_e32 v110, v110, v119
	v_mul_i32_i24_e32 v110, v110, v118
	v_lshlrev_b32_e32 v119, 9, v118
	v_add_u32_e32 v112, v110, v119
	v_add_u32_e32 v114, v112, v119
	v_add_u32_e32 v116, v114, v119
	v_ashrrev_i32_e32 v111, 31, v110
	v_ashrrev_i32_e32 v113, 31, v112
	v_ashrrev_i32_e32 v115, 31, v114
	v_ashrrev_i32_e32 v117, 31, v116
	s_waitcnt vmcnt(3)
	v_pk_add_f32 v[82:83], v[38:39], v[38:39] op_sel:[0,1] op_sel_hi:[1,0]
	v_pk_mul_f32 v[84:85], v[38:39], v[38:39]
	s_waitcnt vmcnt(2)
	v_mov_b32_e32 v67, v46
	v_mul_f32_e32 v0, v47, v47
	v_pk_mul_f32 v[86:87], v[40:41], v[40:41]
	v_pk_add_f32 v[88:89], v[66:67], v[46:47]
	v_pk_fma_f32 v[90:91], v[46:47], v[46:47], v[0:1] op_sel_hi:[1,1,0]
	v_pk_mul_f32 v[92:93], v[48:49], v[48:49]
	s_waitcnt vmcnt(1)
	v_mul_f32_e32 v0, v43, v43
	v_mov_b32_e32 v104, v84
	v_mov_b32_e32 v105, v82
	v_pk_mov_b32 v[82:83], v[84:85], v[40:41] op_sel:[1,0]
	v_mov_b32_e32 v67, v42
	v_pk_fma_f32 v[96:97], v[42:43], v[42:43], v[0:1] op_sel_hi:[1,1,0]
	s_waitcnt vmcnt(0)
	v_mul_f32_e32 v0, v35, v35
	v_pk_add_f32 v[82:83], v[104:105], v[82:83]
	v_mov_b32_e32 v84, v86
	v_mov_b32_e32 v85, v41
	v_mov_b32_e32 v88, v92
	v_mov_b32_e32 v91, v48
	v_pk_add_f32 v[94:95], v[66:67], v[42:43]
	v_pk_mul_f32 v[98:99], v[44:45], v[44:45]
	v_pk_fma_f32 v[100:101], v[34:35], v[34:35], v[0:1] op_sel_hi:[1,1,0]
	v_pk_add_f32 v[82:83], v[82:83], v[84:85]
	v_mov_b32_e32 v0, v87
	v_pk_add_f32 v[84:85], v[88:89], v[90:91]
	v_mov_b32_e32 v86, v93
	v_mov_b32_e32 v87, v49
	v_mov_b32_e32 v80, v36
	v_mov_b32_e32 v81, v34
	v_pk_add_f32 v[82:83], v[82:83], v[0:1]
	v_pk_add_f32 v[84:85], v[84:85], v[86:87]
	v_mov_b32_e32 v94, v98
	v_mov_b32_e32 v97, v44
	v_pk_mul_f32 v[102:103], v[36:37], v[36:37]
	v_pk_add_f32 v[82:83], v[82:83], v[84:85]
	v_pk_add_f32 v[84:85], v[94:95], v[96:97]
	v_mov_b32_e32 v86, v99
	v_mov_b32_e32 v87, v45
	v_pk_add_f32 v[80:81], v[80:81], v[34:35]
	v_pk_add_f32 v[84:85], v[84:85], v[86:87]
	v_mov_b32_e32 v80, v102
	v_mov_b32_e32 v101, v36
	v_pk_add_f32 v[82:83], v[82:83], v[84:85]
	v_pk_add_f32 v[80:81], v[80:81], v[100:101]
	v_mov_b32_e32 v84, v103
	v_mov_b32_e32 v85, v37
	v_pk_add_f32 v[80:81], v[80:81], v[84:85]
	s_mov_b32 s0, 0x3a800000
	v_pk_add_f32 v[80:81], v[82:83], v[80:81]
	ds_bpermute_b32 v83, v74, v81
	ds_bpermute_b32 v82, v74, v80
	v_readlane_b32 s2, v254, 21
	v_readlane_b32 s8, v254, 19
	v_readlane_b32 s3, v254, 22
	v_add_u32_e32 v66, s2, v66
	s_waitcnt lgkmcnt(0)
	v_pk_add_f32 v[80:81], v[80:81], v[82:83]
	ds_bpermute_b32 v83, v75, v81
	ds_bpermute_b32 v82, v75, v80
	v_readlane_b32 s9, v254, 20
	v_lshl_add_u64 v[70:71], v[70:71], 0, s[2:3]
	s_waitcnt lgkmcnt(0)
	v_pk_add_f32 v[80:81], v[80:81], v[82:83]
	ds_bpermute_b32 v83, v76, v81
	ds_bpermute_b32 v82, v76, v80
	s_waitcnt lgkmcnt(0)
	v_pk_add_f32 v[80:81], v[80:81], v[82:83]
	ds_bpermute_b32 v83, v77, v81
	ds_bpermute_b32 v82, v77, v80
	s_waitcnt lgkmcnt(0)
	v_pk_add_f32 v[80:81], v[80:81], v[82:83]
	ds_bpermute_b32 v83, v78, v81
	ds_bpermute_b32 v82, v78, v80
	s_waitcnt lgkmcnt(0)
	v_pk_add_f32 v[80:81], v[80:81], v[82:83]
	ds_bpermute_b32 v83, v79, v81
	ds_bpermute_b32 v82, v79, v80
	s_waitcnt lgkmcnt(0)
	v_pk_add_f32 v[80:81], v[80:81], v[82:83]
	s_nop 0
	v_pk_mul_f32 v[80:81], v[80:81], s[0:1] op_sel_hi:[1,0]
	s_mov_b32 s0, 0x800000
	v_fma_f32 v0, -v81, v81, v80
	v_max_f32_e32 v0, 0, v0
	v_add_f32_e32 v0, 0x3727c5ac, v0
	v_mul_f32_e32 v67, 0x4b800000, v0
	v_cmp_gt_f32_e32 vcc, s0, v0
	v_pk_add_f32 v[38:39], v[38:39], v[80:81] op_sel:[0,1] neg_lo:[0,1] neg_hi:[0,1]
	v_pk_add_f32 v[40:41], v[40:41], v[80:81] op_sel:[0,1] neg_lo:[0,1] neg_hi:[0,1]
	v_cndmask_b32_e32 v0, v0, v67, vcc
	v_rsq_f32_e32 v0, v0
	v_pk_add_f32 v[34:35], v[34:35], v[80:81] op_sel:[0,1] neg_lo:[0,1] neg_hi:[0,1]
	v_pk_add_f32 v[36:37], v[36:37], v[80:81] op_sel:[0,1] neg_lo:[0,1] neg_hi:[0,1]
	s_movk_i32 s0, 0x41ff
	v_mul_f32_e32 v67, 0x45800000, v0
	v_cndmask_b32_e32 v0, v0, v67, vcc
	v_pk_mul_f32 v[38:39], v[38:39], v[0:1] op_sel_hi:[1,0]
	v_pk_mul_f32 v[40:41], v[40:41], v[0:1] op_sel_hi:[1,0]
	v_pk_fma_f32 v[38:39], v[2:3], v[38:39], v[6:7]
	v_pk_fma_f32 v[40:41], v[4:5], v[40:41], v[8:9]
	v_pk_mul_f32 v[34:35], v[34:35], v[0:1] op_sel_hi:[1,0]
	v_cvt_pk_bf16_f32 v41, v40, v41
	v_cvt_pk_bf16_f32 v40, v38, v39
	v_lshl_add_u64 v[118:119], v[68:69], 0, v[110:111]
	global_store_dwordx2 v[118:119], v[40:41], off
	v_pk_add_f32 v[38:39], v[46:47], v[80:81] op_sel:[0,1] neg_lo:[0,1] neg_hi:[0,1]
	v_pk_add_f32 v[40:41], v[48:49], v[80:81] op_sel:[0,1] neg_lo:[0,1] neg_hi:[0,1]
	v_pk_mul_f32 v[38:39], v[38:39], v[0:1] op_sel_hi:[1,0]
	v_pk_mul_f32 v[40:41], v[40:41], v[0:1] op_sel_hi:[1,0]
	v_pk_fma_f32 v[38:39], v[10:11], v[38:39], v[14:15]
	v_pk_fma_f32 v[40:41], v[12:13], v[40:41], v[16:17]
	v_pk_mul_f32 v[36:37], v[36:37], v[0:1] op_sel_hi:[1,0]
	v_cvt_pk_bf16_f32 v41, v40, v41
	v_cvt_pk_bf16_f32 v40, v38, v39
	v_lshl_add_u64 v[118:119], v[68:69], 0, v[112:113]
	global_store_dwordx2 v[118:119], v[40:41], off offset:512
	v_pk_add_f32 v[38:39], v[42:43], v[80:81] op_sel:[0,1] neg_lo:[0,1] neg_hi:[0,1]
	v_pk_add_f32 v[40:41], v[44:45], v[80:81] op_sel:[0,1] neg_lo:[0,1] neg_hi:[0,1]
	v_pk_mul_f32 v[38:39], v[38:39], v[0:1] op_sel_hi:[1,0]
	v_pk_mul_f32 v[40:41], v[40:41], v[0:1] op_sel_hi:[1,0]
	v_pk_fma_f32 v[38:39], v[18:19], v[38:39], v[22:23]
	v_pk_fma_f32 v[40:41], v[20:21], v[40:41], v[24:25]
	v_pk_fma_f32 v[34:35], v[26:27], v[34:35], v[30:31]
	v_pk_fma_f32 v[36:37], v[28:29], v[36:37], v[32:33]
	v_cvt_pk_bf16_f32 v41, v40, v41
	v_cvt_pk_bf16_f32 v40, v38, v39
	v_cvt_pk_bf16_f32 v37, v36, v37
	v_cvt_pk_bf16_f32 v36, v34, v35
	v_cmp_lt_i32_e32 vcc, s0, v66
	v_lshl_add_u64 v[118:119], v[68:69], 0, v[114:115]
	global_store_dwordx2 v[118:119], v[40:41], off offset:1024
	v_lshl_add_u64 v[118:119], v[68:69], 0, v[116:117]
	global_store_dwordx2 v[118:119], v[36:37], off offset:1536
	v_lshl_add_u64 v[68:69], v[68:69], 0, s[8:9]
	s_or_b64 s[6:7], vcc, s[6:7]
	v_mov_b32_e32 v38, v50
	v_mov_b32_e32 v39, v51
	v_mov_b32_e32 v40, v52
	v_mov_b32_e32 v41, v53
	v_mov_b32_e32 v34, v62
	v_mov_b32_e32 v35, v63
	v_mov_b32_e32 v42, v58
	v_mov_b32_e32 v43, v59
	v_mov_b32_e32 v46, v54
	v_mov_b32_e32 v47, v55
	v_mov_b32_e32 v48, v56
	v_mov_b32_e32 v49, v57
	v_mov_b32_e32 v44, v60
	v_mov_b32_e32 v45, v61
	v_mov_b32_e32 v36, v64
	v_mov_b32_e32 v37, v65
	s_andn2_b64 exec, exec, s[6:7]
	s_cbranch_execz .LBB0_1895

; DEVI unsigned pack2(float a, float b) { return __builtin_bit_cast(unsigned, __builtin_convertvector((f32x2_t){a, b}, bf16x2_t)); }
; DEVI void prologue_phase(const Params& p, char* smem) {
;     ...
; #pragma unroll
;       for (int i = 0; i < 16; i++) { int idx = tid + i * 256; tile[(idx >> 6) * 65 + (idx & 63)] = rc[i]; }
;       __syncthreads();
; #pragma unroll
;       for (int i = 0; i < 2; i++) {
;         int idx = tid + i * 256; int nr = idx >> 3, kc = (idx & 7) * 8;
;         int n = jc.n0 + nr;
;         int drow = (jc.mode == 0) ? n : ((n >> 5) * 64 + (n & 31) + (jc.mode == 2 ? 32 : 0));
;         uint4 o;
;         o.x = pack2(tile[(kc + 0) * 65 + nr], tile[(kc + 1) * 65 + nr]);
;         o.y = pack2(tile[(kc + 2) * 65 + nr], tile[(kc + 3) * 65 + nr]);
;         o.z = pack2(tile[(kc + 4) * 65 + nr], tile[(kc + 5) * 65 + nr]);
;         o.w = pack2(tile[(kc + 6) * 65 + nr], tile[(kc + 7) * 65 + nr]);
;         *(uint4*)(jc.dst + (size_t)drow * jc.K + jc.k0 + kc) = o;
;       }
;       __syncthreads();
;       jc = jn;
; #pragma unroll
;       for (int i = 0; i < 16; i++) rc[i] = rn[i];
.LBB0_1913:
	s_cmp_eq_u32 s37, 0
	s_cselect_b64 vcc, -1, 0
	s_cmp_eq_u32 s37, 2
	s_cselect_b32 s3, 32, 0
	s_ashr_i32 s9, s8, 31
	s_lshl_b64 s[8:9], s[8:9], 1
	s_add_u32 s4, s4, s8
	s_waitcnt vmcnt(15)
	ds_write_b32 v24, v3
	s_waitcnt vmcnt(14)
	ds_write_b32 v25, v38
	s_waitcnt vmcnt(13)
	ds_write_b32 v26, v41
	s_waitcnt vmcnt(12)
	ds_write_b32 v27, v42
	s_waitcnt vmcnt(11)
	ds_write_b32 v28, v43
	s_waitcnt vmcnt(10)
	ds_write_b32 v29, v44
	s_waitcnt vmcnt(9)
	ds_write_b32 v30, v45
	s_waitcnt vmcnt(8)
	ds_write_b32 v31, v46
	s_waitcnt vmcnt(7)
	ds_write_b32 v32, v47
	s_waitcnt vmcnt(6)
	ds_write_b32 v33, v48
	s_waitcnt vmcnt(5)
	ds_write_b32 v34, v49
	s_waitcnt vmcnt(4)
	ds_write_b32 v35, v50
	s_waitcnt vmcnt(3)
	ds_write_b32 v36, v51
	s_waitcnt vmcnt(2)
	ds_write_b32 v37, v52
	s_waitcnt vmcnt(1)
	ds_write_b32 v39, v53
	s_waitcnt vmcnt(0)
	ds_write_b32 v40, v54
	s_addc_u32 s5, s5, s9
	v_readlane_b32 s99, v250, 5
	s_sub_u32 s98, s4, s99
	s_sub_u32 s99, s98, 0x14a00000
	s_cmp_lt_u32 s99, 0x1400000
	s_cselect_b32 s99, 1, 0
	s_sub_u32 s98, s98, 0x16e00000
	s_cmp_lt_u32 s98, 0x2c00000
	s_cselect_b32 s98, 1, s99
	s_and_b32 s99, s8, 0xffffffc0
	s_mul_i32 s99, s99, s98
	s_mul_i32 s9, s98, 0x3e0
	s_lshl_b32 s98, s98, 6
	v_mov_b32_e32 v3, v1
	s_waitcnt lgkmcnt(0)
	s_barrier
	v_lshl_add_u64 v[46:47], s[4:5], 0, v[2:3]
	v_and_b32_e32 v76, s98, v2
	v_add_u32_e32 v76, s99, v76
	v_mov_b32_e32 v77, 0
	v_lshl_add_u64 v[46:47], v[46:47], 0, v[76:77]
	v_add_u32_e32 v3, s6, v20
	ds_read2_b32 v[42:43], v21 offset1:65
	ds_read2_b32 v[44:45], v21 offset0:130 offset1:195
	v_lshlrev_b32_e32 v38, 1, v3
	v_and_b32_e32 v38, 0xffffffc0, v38
	v_and_b32_e32 v41, 31, v3
	v_or3_b32 v38, v41, v38, s3
	v_cndmask_b32_e32 v3, v38, v3, vcc
	v_add_u32_e32 v38, 0x400, v21
	s_waitcnt lgkmcnt(1)
	v_cvt_pk_bf16_f32 v42, v42, v43
	s_waitcnt lgkmcnt(0)
	v_cvt_pk_bf16_f32 v43, v44, v45
	ds_read2_b32 v[44:45], v38 offset0:4 offset1:69
	ds_read2_b32 v[48:49], v38 offset0:134 offset1:199
	v_ashrrev_i32_e32 v41, 31, v3
	s_mov_b32 s37, s42
	s_mov_b32 s8, s2
	s_waitcnt lgkmcnt(1)
	v_cvt_pk_bf16_f32 v44, v44, v45
	s_waitcnt lgkmcnt(0)
	v_cvt_pk_bf16_f32 v45, v48, v49
	v_mad_u64_u32 v[48:49], s[4:5], v3, s0, 0
	v_mov_b32_e32 v38, v49
	v_mad_u64_u32 v[50:51], s[4:5], v41, s0, v[38:39]
	v_mov_b32_e32 v49, v50
	v_and_b32_e32 v78, 1, v3
	v_mul_u32_u24_e32 v78, s9, v78
	v_sub_u32_e32 v48, v48, v78
	v_lshl_add_u64 v[48:49], v[48:49], 1, v[46:47]
	global_store_dwordx4 v[48:49], v[42:45], off
	v_add_u32_e32 v3, s6, v22
	ds_read2_b32 v[42:43], v23 offset1:65
	ds_read2_b32 v[44:45], v23 offset0:130 offset1:195
	v_lshlrev_b32_e32 v38, 1, v3
	v_and_b32_e32 v38, 0xffffffc0, v38
	v_and_b32_e32 v41, 31, v3
	v_or3_b32 v38, v41, v38, s3
	v_cndmask_b32_e32 v3, v38, v3, vcc
	v_add_u32_e32 v38, 0x400, v23
	s_waitcnt lgkmcnt(1)
	v_cvt_pk_bf16_f32 v42, v42, v43
	s_waitcnt lgkmcnt(0)
	v_cvt_pk_bf16_f32 v43, v44, v45
	ds_read2_b32 v[44:45], v38 offset0:4 offset1:69
	ds_read2_b32 v[48:49], v38 offset0:134 offset1:199
	v_ashrrev_i32_e32 v41, 31, v3
	s_andn2_b64 vcc, exec, s[12:13]
	s_mov_b32 s6, s38
	s_waitcnt lgkmcnt(1)
	v_cvt_pk_bf16_f32 v44, v44, v45
	s_waitcnt lgkmcnt(0)
	v_cvt_pk_bf16_f32 v45, v48, v49
	v_mad_u64_u32 v[48:49], s[4:5], v3, s0, 0
	v_mov_b32_e32 v38, v49
	v_mad_u64_u32 v[50:51], s[4:5], v41, s0, v[38:39]
	v_mov_b32_e32 v49, v50
	v_and_b32_e32 v78, 1, v3
	v_mul_u32_u24_e32 v78, s9, v78
	v_sub_u32_e32 v48, v48, v78
	v_lshl_add_u64 v[46:47], v[48:49], 1, v[46:47]
	global_store_dwordx4 v[46:47], v[42:45], off
	s_mov_b64 s[4:5], s[10:11]
	s_mov_b32 s0, s36
	v_mov_b32_e32 v3, v55
	v_mov_b32_e32 v38, v56
	v_mov_b32_e32 v41, v57
	v_mov_b32_e32 v42, v58
	v_mov_b32_e32 v43, v59
	v_mov_b32_e32 v44, v60
	v_mov_b32_e32 v45, v61
	v_mov_b32_e32 v46, v62
	v_mov_b32_e32 v47, v63
	v_mov_b32_e32 v48, v64
	v_mov_b32_e32 v49, v65
	v_mov_b32_e32 v50, v66
	v_mov_b32_e32 v51, v67
	v_mov_b32_e32 v52, v68
	v_mov_b32_e32 v53, v69
	v_mov_b32_e32 v54, v70
	s_barrier
	s_cbranch_vccz .LBB0_1947
